# speedup vs baseline: 1.0135x; 1.0135x over previous
; template <class Epi, class Sched>
; __device__ __forceinline__ void gemm_phase(LAS unsigned char* lds, const Gemm g, const Sched& S, const Epi& E) {
;     int tid_ = threadIdx.x; asm volatile("" : "+v"(tid_));
;     const int tid = tid_, wid = __builtin_amdgcn_readfirstlane(tid >> 6), lane = tid & 63, wr = wid >> 2, wc = wid & 3, fr = lane & 15, fq = lane >> 4;
.LBB0_14:
	s_nop 0
	v_readfirstlane_b32 s100, v204
	s_nop 3
	s_lshr_b32 s100, s100, 6
	s_cmp_ge_u32 s100, 4
	s_cbranch_scc0 .Lmy_prio_done
	s_setprio 1

; #define PG8_STAGE(bufoff, gbase, voff) do { _Pragma("unroll") for (int _i = 0; _i < 2; ++_i) \
;         __builtin_amdgcn_global_load_lds((const unsigned*)((const char*)(gbase) + (voff)[_i]), (LAS unsigned*)(lds + (bufoff) + ldsw + _i * 8192), 16, 0, 0); } while (0)
; #define PG8_LDA(dst, b, h) do { _Pragma("unroll") for (int m = 0; m < 4; ++m) _Pragma("unroll") for (int k = 0; k < 2; ++k) dst[m][k] = *(const LAS bf16x8*)(lds + PG8_SA(b, h) + aoff + m * 2048 + k * 1024); } while (0)
; #define PG8_LDB(dst, b, h) do { _Pragma("unroll") for (int n = 0; n < 2; ++n) _Pragma("unroll") for (int k = 0; k < 2; ++k) dst[n][k] = *(const LAS bf16x8*)(lds + PG8_SB(b, h) + boff + n * 2048 + k * 1024); } while (0)
; #define PG8_MMA(ai, bj, At, Bt) do { __builtin_amdgcn_s_setprio(1); _Pragma("unroll") for (int m = 0; m < 4; ++m) _Pragma("unroll") for (int n = 0; n < 2; ++n) _Pragma("unroll") for (int k = 0; k < 2; ++k) \
;         acc[ai][bj][m][n] = __builtin_amdgcn_mfma_f32_16x16x32_bf16(Bt[n][k], At[m][k], acc[ai][bj][m][n], 0, 0, 0); __builtin_amdgcn_s_setprio(0); } while (0)
; #define PG8_WAIT_L(n) asm volatile("s_waitcnt lgkmcnt(" #n ")" ::: "memory")
; #define PG8_BAR __builtin_amdgcn_s_barrier()
; #define PG8_SCHED __builtin_amdgcn_sched_barrier(0)
; template <class Epi, class Sched>
; __device__ __forceinline__ void gemm_phase(LAS unsigned char* lds, const Gemm g, const Sched& S, const Epi& E) {
;     ...
;             PG8_LDB(B0, 0, 0); PG8_SCHED; PG8_LDA(At, 0, 0); PG8_STAGE(PG8_SA(1, 1), a1 + hstep, voffA);
;             PG8_WAIT_L(8); PG8_BAR; PG8_WAIT_L(0); PG8_MMA(0, 0, At, B0); PG8_BAR; PG8_SCHED;
;             PG8_LDB(B1, 0, 1); PG8_STAGE(PG8_SB(0, 0), b2, voffB);
;             PG8_BAR; PG8_WAIT_L(0); PG8_MMA(0, 1, At, B1); PG8_BAR;
;             PG8_LDA(At, 0, 1); PG8_STAGE(PG8_SA(0, 0), a2, voffA);
;             PG8_BAR; PG8_WAIT_L(0); PG8_MMA(1, 0, At, B0); PG8_BAR; PG8_SCHED;
.LBB0_135:
	ds_read_b128 v[154:157], v150
	ds_read_b128 v[158:161], v150 offset:1024
	ds_read_b128 v[162:165], v150 offset:2048
	ds_read_b128 v[170:173], v150 offset:3072
	s_add_u32 s36, s28, 0x4000
	s_addc_u32 s37, s29, 0
	s_cmp_eq_u32 s63, 28
	s_cselect_b32 s40, s33, s36
	s_cselect_b32 s41, s13, s37
	s_cselect_b32 s36, s60, s61
	s_cselect_b32 s37, s11, s62
	s_add_u32 s38, s40, 0x8000
	s_addc_u32 s39, s41, 0
	v_lshl_add_u64 v[166:167], s[28:29], 0, v[138:139]
	s_add_i32 m0, s48, 0xc000
	ds_read_b128 v[174:177], v151
	ds_read_b128 v[178:181], v151 offset:1024
	ds_read_b128 v[182:185], v151 offset:2048
	ds_read_b128 v[186:189], v151 offset:3072
	ds_read_b128 v[190:193], v151 offset:4096
	ds_read_b128 v[194:197], v151 offset:5120
	ds_read_b128 v[198:201], v151 offset:6144
	ds_read_b128 v[206:209], v151 offset:7168
	global_load_lds_dwordx4 v[166:167], off
	v_lshl_add_u64 v[166:167], s[28:29], 0, v[140:141]
	s_add_i32 m0, s48, 0xe000
	s_nop 0
	global_load_lds_dwordx4 v[166:167], off
	s_waitcnt lgkmcnt(8)
	s_barrier
	s_waitcnt lgkmcnt(0)
	s_waitcnt lgkmcnt(0)
	v_mfma_f32_16x16x32_bf16 v[124:127], v[154:157], v[174:177], v[124:127]
	v_mfma_f32_16x16x32_bf16 v[120:123], v[162:165], v[174:177], v[120:123]
	v_mfma_f32_16x16x32_bf16 v[108:111], v[154:157], v[182:185], v[108:111]
	v_mfma_f32_16x16x32_bf16 v[104:107], v[162:165], v[182:185], v[104:107]
	v_mfma_f32_16x16x32_bf16 v[92:95], v[154:157], v[190:193], v[92:95]
	v_mfma_f32_16x16x32_bf16 v[88:91], v[162:165], v[190:193], v[88:91]
	v_mfma_f32_16x16x32_bf16 v[76:79], v[154:157], v[198:201], v[76:79]
	v_mfma_f32_16x16x32_bf16 v[72:75], v[162:165], v[198:201], v[72:75]
	v_mfma_f32_16x16x32_bf16 v[124:127], v[158:161], v[178:181], v[124:127]
	v_mfma_f32_16x16x32_bf16 v[120:123], v[170:173], v[178:181], v[120:123]
	v_mfma_f32_16x16x32_bf16 v[108:111], v[158:161], v[186:189], v[108:111]
	v_mfma_f32_16x16x32_bf16 v[104:107], v[170:173], v[186:189], v[104:107]
	v_mfma_f32_16x16x32_bf16 v[92:95], v[158:161], v[194:197], v[92:95]
	v_mfma_f32_16x16x32_bf16 v[88:91], v[170:173], v[194:197], v[88:91]
	v_mfma_f32_16x16x32_bf16 v[76:79], v[158:161], v[206:209], v[76:79]
	v_mfma_f32_16x16x32_bf16 v[72:75], v[170:173], v[206:209], v[72:75]
	s_barrier
	s_add_i32 s64, s57, s46
	v_lshl_add_u64 v[166:167], s[36:37], 0, v[132:133]
	s_mov_b32 m0, s64
	ds_read_b128 v[210:213], v152
	ds_read_b128 v[214:217], v152 offset:1024
	ds_read_b128 v[218:221], v152 offset:2048
	ds_read_b128 v[222:225], v152 offset:3072
	global_load_lds_dwordx4 v[166:167], off
	v_lshl_add_u64 v[166:167], s[36:37], 0, v[128:129]
	s_add_i32 m0, s64, 0x2000
	s_nop 0
	global_load_lds_dwordx4 v[166:167], off
	s_barrier
	s_waitcnt lgkmcnt(0)
	s_waitcnt lgkmcnt(0)
	v_mfma_f32_16x16x32_bf16 v[116:119], v[210:213], v[174:177], v[116:119]
	v_mfma_f32_16x16x32_bf16 v[112:115], v[218:221], v[174:177], v[112:115]
	v_mfma_f32_16x16x32_bf16 v[100:103], v[210:213], v[182:185], v[100:103]
	v_mfma_f32_16x16x32_bf16 v[96:99], v[218:221], v[182:185], v[96:99]
	v_mfma_f32_16x16x32_bf16 v[84:87], v[210:213], v[190:193], v[84:87]
	v_mfma_f32_16x16x32_bf16 v[80:83], v[218:221], v[190:193], v[80:83]
	v_mfma_f32_16x16x32_bf16 v[68:71], v[210:213], v[198:201], v[68:71]
	v_mfma_f32_16x16x32_bf16 v[64:67], v[218:221], v[198:201], v[64:67]
	v_mfma_f32_16x16x32_bf16 v[116:119], v[214:217], v[178:181], v[116:119]
	v_mfma_f32_16x16x32_bf16 v[112:115], v[222:225], v[178:181], v[112:115]
	v_mfma_f32_16x16x32_bf16 v[100:103], v[214:217], v[186:189], v[100:103]
	v_mfma_f32_16x16x32_bf16 v[96:99], v[222:225], v[186:189], v[96:99]
	v_mfma_f32_16x16x32_bf16 v[84:87], v[214:217], v[194:197], v[84:87]
	v_mfma_f32_16x16x32_bf16 v[80:83], v[222:225], v[194:197], v[80:83]
	v_mfma_f32_16x16x32_bf16 v[68:71], v[214:217], v[206:209], v[68:71]
	v_mfma_f32_16x16x32_bf16 v[64:67], v[222:225], v[206:209], v[64:67]
	s_mov_b32 m0, s48
	v_lshl_add_u64 v[166:167], s[40:41], 0, v[134:135]
	s_barrier
	ds_read_b128 v[174:177], v151 offset:16384
	ds_read_b128 v[178:181], v151 offset:17408
	ds_read_b128 v[182:185], v151 offset:18432
	ds_read_b128 v[186:189], v151 offset:19456
	ds_read_b128 v[190:193], v151 offset:20480
	ds_read_b128 v[194:197], v151 offset:21504
	ds_read_b128 v[198:201], v151 offset:22528
	ds_read_b128 v[206:209], v151 offset:23552
	global_load_lds_dwordx4 v[166:167], off
	v_lshl_add_u64 v[166:167], s[40:41], 0, v[130:131]
	s_mov_b32 m0, s49
	s_nop 0
	global_load_lds_dwordx4 v[166:167], off
	s_barrier
	s_waitcnt lgkmcnt(0)
	s_waitcnt lgkmcnt(0)
	v_mfma_f32_16x16x32_bf16 v[60:63], v[154:157], v[174:177], v[60:63]
	v_mfma_f32_16x16x32_bf16 v[56:59], v[162:165], v[174:177], v[56:59]
	v_mfma_f32_16x16x32_bf16 v[44:47], v[154:157], v[182:185], v[44:47]
	v_mfma_f32_16x16x32_bf16 v[40:43], v[162:165], v[182:185], v[40:43]
	v_mfma_f32_16x16x32_bf16 v[28:31], v[154:157], v[190:193], v[28:31]
	v_mfma_f32_16x16x32_bf16 v[24:27], v[162:165], v[190:193], v[24:27]
	v_mfma_f32_16x16x32_bf16 v[12:15], v[154:157], v[198:201], v[12:15]
	v_mfma_f32_16x16x32_bf16 v[8:11], v[162:165], v[198:201], v[8:11]
	v_mfma_f32_16x16x32_bf16 v[60:63], v[158:161], v[178:181], v[60:63]
	v_mfma_f32_16x16x32_bf16 v[56:59], v[170:173], v[178:181], v[56:59]
	v_mfma_f32_16x16x32_bf16 v[44:47], v[158:161], v[186:189], v[44:47]
	v_mfma_f32_16x16x32_bf16 v[40:43], v[170:173], v[186:189], v[40:43]
	v_mfma_f32_16x16x32_bf16 v[28:31], v[158:161], v[194:197], v[28:31]
	v_mfma_f32_16x16x32_bf16 v[24:27], v[170:173], v[194:197], v[24:27]
	v_mfma_f32_16x16x32_bf16 v[12:15], v[158:161], v[206:209], v[12:15]
	v_mfma_f32_16x16x32_bf16 v[8:11], v[170:173], v[206:209], v[8:11]
	s_barrier
; #define PG8_STAGE(bufoff, gbase, voff) do { _Pragma("unroll") for (int _i = 0; _i < 2; ++_i) \
;         __builtin_amdgcn_global_load_lds((const unsigned*)((const char*)(gbase) + (voff)[_i]), (LAS unsigned*)(lds + (bufoff) + ldsw + _i * 8192), 16, 0, 0); } while (0)
; #define PG8_LDA(dst, b, h) do { _Pragma("unroll") for (int m = 0; m < 4; ++m) _Pragma("unroll") for (int k = 0; k < 2; ++k) dst[m][k] = *(const LAS bf16x8*)(lds + PG8_SA(b, h) + aoff + m * 2048 + k * 1024); } while (0)
; #define PG8_LDB(dst, b, h) do { _Pragma("unroll") for (int n = 0; n < 2; ++n) _Pragma("unroll") for (int k = 0; k < 2; ++k) dst[n][k] = *(const LAS bf16x8*)(lds + PG8_SB(b, h) + boff + n * 2048 + k * 1024); } while (0)
; #define PG8_MMA(ai, bj, At, Bt) do { __builtin_amdgcn_s_setprio(1); _Pragma("unroll") for (int m = 0; m < 4; ++m) _Pragma("unroll") for (int n = 0; n < 2; ++n) _Pragma("unroll") for (int k = 0; k < 2; ++k) \
;         acc[ai][bj][m][n] = __builtin_amdgcn_mfma_f32_16x16x32_bf16(Bt[n][k], At[m][k], acc[ai][bj][m][n], 0, 0, 0); __builtin_amdgcn_s_setprio(0); } while (0)
; #define PG8_WAIT_V(n) asm volatile("s_waitcnt vmcnt(" #n ")" ::: "memory")
; #define PG8_WAIT_L(n) asm volatile("s_waitcnt lgkmcnt(" #n ")" ::: "memory")
; #define PG8_BAR __builtin_amdgcn_s_barrier()
; #define PG8_SCHED __builtin_amdgcn_sched_barrier(0)
; template <class Epi, class Sched>
; __device__ __forceinline__ void gemm_phase(LAS unsigned char* lds, const Gemm g, const Sched& S, const Epi& E) {
;     ...
;             PG8_STAGE(PG8_SB(0, 1), b2 + hstep, voffB);
;             PG8_WAIT_V(6); PG8_BAR; PG8_MMA(1, 1, At, B1); PG8_BAR;
;             PG8_LDB(B0, 1, 0); PG8_SCHED; PG8_LDA(At, 1, 0); PG8_STAGE(PG8_SA(0, 1), a2 + hstep, voffA);
;             PG8_WAIT_L(8); PG8_BAR; PG8_WAIT_L(0); PG8_MMA(0, 0, At, B0); PG8_BAR; PG8_SCHED;
;             PG8_LDB(B1, 1, 1); PG8_STAGE(PG8_SB(1, 0), b3, voffB);
;             PG8_BAR; PG8_WAIT_L(0); PG8_MMA(0, 1, At, B1); PG8_BAR;
;             PG8_LDA(At, 1, 1); PG8_STAGE(PG8_SA(1, 0), a3, voffA);
	s_add_u32 s64, s36, 0x4000
	s_addc_u32 s65, s37, 0
	s_add_i32 s66, s58, s46
	v_lshl_add_u64 v[154:155], s[64:65], 0, v[132:133]
	s_mov_b32 m0, s66
	s_nop 0
	global_load_lds_dwordx4 v[154:155], off
	v_lshl_add_u64 v[154:155], s[64:65], 0, v[128:129]
	s_add_i32 m0, s66, 0x2000
	s_nop 0
	global_load_lds_dwordx4 v[154:155], off
	s_waitcnt vmcnt(6)
	s_barrier
	v_mfma_f32_16x16x32_bf16 v[52:55], v[210:213], v[174:177], v[52:55]
	v_mfma_f32_16x16x32_bf16 v[48:51], v[218:221], v[174:177], v[48:51]
	v_mfma_f32_16x16x32_bf16 v[36:39], v[210:213], v[182:185], v[36:39]
	v_mfma_f32_16x16x32_bf16 v[32:35], v[218:221], v[182:185], v[32:35]
	v_mfma_f32_16x16x32_bf16 v[20:23], v[210:213], v[190:193], v[20:23]
	v_mfma_f32_16x16x32_bf16 v[16:19], v[218:221], v[190:193], v[16:19]
	v_mfma_f32_16x16x32_bf16 v[4:7], v[210:213], v[198:201], v[4:7]
	v_mfma_f32_16x16x32_bf16 v[0:3], v[218:221], v[198:201], v[0:3]
	v_mfma_f32_16x16x32_bf16 v[52:55], v[214:217], v[178:181], v[52:55]
	v_mfma_f32_16x16x32_bf16 v[48:51], v[222:225], v[178:181], v[48:51]
	v_mfma_f32_16x16x32_bf16 v[36:39], v[214:217], v[186:189], v[36:39]
	v_mfma_f32_16x16x32_bf16 v[32:35], v[222:225], v[186:189], v[32:35]
	v_mfma_f32_16x16x32_bf16 v[20:23], v[214:217], v[194:197], v[20:23]
	v_mfma_f32_16x16x32_bf16 v[16:19], v[222:225], v[194:197], v[16:19]
	v_mfma_f32_16x16x32_bf16 v[4:7], v[214:217], v[206:209], v[4:7]
	v_mfma_f32_16x16x32_bf16 v[0:3], v[222:225], v[206:209], v[0:3]
	s_add_i32 s64, 0, 0x18000
	v_add_u32_e32 v136, s64, v149
	s_barrier
	ds_read_b128 v[154:157], v136
	ds_read_b128 v[158:161], v136 offset:1024
	ds_read_b128 v[162:165], v136 offset:2048
	ds_read_b128 v[170:173], v136 offset:3072
	s_add_u32 s40, s40, 0x4000
	s_addc_u32 s41, s41, 0
	s_mov_b32 m0, s50
	v_lshl_add_u64 v[166:167], s[40:41], 0, v[134:135]
	ds_read_b128 v[174:177], v151 offset:32768
	ds_read_b128 v[178:181], v151 offset:33792
	ds_read_b128 v[182:185], v151 offset:34816
	ds_read_b128 v[186:189], v151 offset:35840
	ds_read_b128 v[190:193], v151 offset:36864
	ds_read_b128 v[194:197], v151 offset:37888
	ds_read_b128 v[198:201], v151 offset:38912
	ds_read_b128 v[206:209], v151 offset:39936
	global_load_lds_dwordx4 v[166:167], off
	v_lshl_add_u64 v[166:167], s[40:41], 0, v[130:131]
	s_mov_b32 m0, s51
	s_nop 0
	global_load_lds_dwordx4 v[166:167], off
	s_waitcnt lgkmcnt(8)
	s_barrier
	s_waitcnt lgkmcnt(0)
	s_waitcnt lgkmcnt(0)
	v_mfma_f32_16x16x32_bf16 v[124:127], v[154:157], v[174:177], v[124:127]
	v_mfma_f32_16x16x32_bf16 v[120:123], v[162:165], v[174:177], v[120:123]
	v_mfma_f32_16x16x32_bf16 v[108:111], v[154:157], v[182:185], v[108:111]
	v_mfma_f32_16x16x32_bf16 v[104:107], v[162:165], v[182:185], v[104:107]
	v_mfma_f32_16x16x32_bf16 v[92:95], v[154:157], v[190:193], v[92:95]
	v_mfma_f32_16x16x32_bf16 v[88:91], v[162:165], v[190:193], v[88:91]
	v_mfma_f32_16x16x32_bf16 v[76:79], v[154:157], v[198:201], v[76:79]
	v_mfma_f32_16x16x32_bf16 v[72:75], v[162:165], v[198:201], v[72:75]
	v_mfma_f32_16x16x32_bf16 v[124:127], v[158:161], v[178:181], v[124:127]
	v_mfma_f32_16x16x32_bf16 v[120:123], v[170:173], v[178:181], v[120:123]
	v_mfma_f32_16x16x32_bf16 v[108:111], v[158:161], v[186:189], v[108:111]
	v_mfma_f32_16x16x32_bf16 v[104:107], v[170:173], v[186:189], v[104:107]
	v_mfma_f32_16x16x32_bf16 v[92:95], v[158:161], v[194:197], v[92:95]
	v_mfma_f32_16x16x32_bf16 v[88:91], v[170:173], v[194:197], v[88:91]
	v_mfma_f32_16x16x32_bf16 v[76:79], v[158:161], v[206:209], v[76:79]
	v_mfma_f32_16x16x32_bf16 v[72:75], v[170:173], v[206:209], v[72:75]
	s_barrier
	s_add_i32 s65, 0, 0x1c000
	s_add_u32 s40, s36, 0x8000
	s_addc_u32 s41, s37, 0
	s_add_i32 s64, s64, s46
	v_add_u32_e32 v136, s65, v149
	v_lshl_add_u64 v[166:167], s[40:41], 0, v[132:133]
	s_mov_b32 m0, s64
	ds_read_b128 v[210:213], v136
	ds_read_b128 v[214:217], v136 offset:1024
	ds_read_b128 v[218:221], v136 offset:2048
	ds_read_b128 v[222:225], v136 offset:3072
	global_load_lds_dwordx4 v[166:167], off
	v_lshl_add_u64 v[166:167], s[40:41], 0, v[128:129]
	s_add_i32 m0, s64, 0x2000
	s_nop 0
	global_load_lds_dwordx4 v[166:167], off
	s_barrier
	s_waitcnt lgkmcnt(0)
	s_waitcnt lgkmcnt(0)
	v_mfma_f32_16x16x32_bf16 v[116:119], v[210:213], v[174:177], v[116:119]
	v_mfma_f32_16x16x32_bf16 v[112:115], v[218:221], v[174:177], v[112:115]
	v_mfma_f32_16x16x32_bf16 v[100:103], v[210:213], v[182:185], v[100:103]
	v_mfma_f32_16x16x32_bf16 v[96:99], v[218:221], v[182:185], v[96:99]
	v_mfma_f32_16x16x32_bf16 v[84:87], v[210:213], v[190:193], v[84:87]
	v_mfma_f32_16x16x32_bf16 v[80:83], v[218:221], v[190:193], v[80:83]
	v_mfma_f32_16x16x32_bf16 v[68:71], v[210:213], v[198:201], v[68:71]
	v_mfma_f32_16x16x32_bf16 v[64:67], v[218:221], v[198:201], v[64:67]
	v_mfma_f32_16x16x32_bf16 v[116:119], v[214:217], v[178:181], v[116:119]
	v_mfma_f32_16x16x32_bf16 v[112:115], v[222:225], v[178:181], v[112:115]
	v_mfma_f32_16x16x32_bf16 v[100:103], v[214:217], v[186:189], v[100:103]
	v_mfma_f32_16x16x32_bf16 v[96:99], v[222:225], v[186:189], v[96:99]
	v_mfma_f32_16x16x32_bf16 v[84:87], v[214:217], v[194:197], v[84:87]
	v_mfma_f32_16x16x32_bf16 v[80:83], v[222:225], v[194:197], v[80:83]
	v_mfma_f32_16x16x32_bf16 v[68:71], v[214:217], v[206:209], v[68:71]
	v_mfma_f32_16x16x32_bf16 v[64:67], v[222:225], v[206:209], v[64:67]
	s_mov_b32 m0, s55
	v_lshl_add_u64 v[166:167], s[38:39], 0, v[134:135]
	s_barrier
	ds_read_b128 v[174:177], v151 offset:49152
	ds_read_b128 v[178:181], v151 offset:50176
	ds_read_b128 v[182:185], v151 offset:51200
	ds_read_b128 v[186:189], v151 offset:52224
	ds_read_b128 v[190:193], v151 offset:53248
	ds_read_b128 v[194:197], v151 offset:54272
	ds_read_b128 v[198:201], v151 offset:55296
	ds_read_b128 v[206:209], v151 offset:56320
	global_load_lds_dwordx4 v[166:167], off
	v_lshl_add_u64 v[166:167], s[38:39], 0, v[130:131]
	s_mov_b32 m0, s56
	s_nop 0
	global_load_lds_dwordx4 v[166:167], off
	s_barrier
; __device__ __forceinline__ unsigned cvt_pk_bf16(float lo, float hi) { f32x2 v = {lo, hi}; bf16x2_t b = __builtin_convertvector(v, bf16x2_t); return __builtin_bit_cast(unsigned, b); }
; __device__ __forceinline__ float sigmoid_f(float x) { return __builtin_amdgcn_rcpf(1.0f + __expf(-x)); }
; __device__ __forceinline__ float silu_f(float x) { return x * sigmoid_f(x); }
; __device__ __forceinline__ size_t tl(int r, int c, int K) { return ((size_t)(r >> 8) * (size_t)(K >> 6) + (size_t)(c >> 6)) * 16384 + (size_t)((r & 255) << 6) + (size_t)(c & 63); }
; #define PG8_STAGE(bufoff, gbase, voff) do { _Pragma("unroll") for (int _i = 0; _i < 2; ++_i) \
;         __builtin_amdgcn_global_load_lds((const unsigned*)((const char*)(gbase) + (voff)[_i]), (LAS unsigned*)(lds + (bufoff) + ldsw + _i * 8192), 16, 0, 0); } while (0)
; #define PG8_WAIT_V(n) asm volatile("s_waitcnt vmcnt(" #n ")" ::: "memory")
; #define PG8_WAIT_L(n) asm volatile("s_waitcnt lgkmcnt(" #n ")" ::: "memory")
; #define PG8_BAR __builtin_amdgcn_s_barrier()
; template <class Epi, class Sched>
; __device__ __forceinline__ void gemm_phase(LAS unsigned char* lds, const Gemm g, const Sched& S, const Epi& E) {
;     ...
;             PG8_BAR; PG8_WAIT_L(0); PG8_MMA(1, 0, At, B0); PG8_BAR; PG8_SCHED;
;             PG8_STAGE(PG8_SB(1, 1), b3 + hstep, voffB);
;             PG8_WAIT_V(6); PG8_BAR; PG8_MMA(1, 1, At, B1); PG8_BAR;
;         }
;     __device__ __forceinline__ void operator()(const f32x4 (&acc)[2][2][4][2], const Unit& u, int wr, int wc, int fr, int fq) const {
;         const int row0 = u.pm * BM + wr * 64 + fr, col0 = u.pn * 128 + wc * 32 + 8 * fq;
; #pragma unroll
;         for (int ai = 0; ai < 2; ++ai)
; #pragma unroll
;             for (int m = 0; m < 4; ++m) {
;                 bf16_t* rowp = MODE == 0 ? O + tl(row0 + ai * HALF + m * 16, col0, ldo) : O + (size_t)(row0 + ai * HALF + m * 16) * ldo + col0;
;                 float v[8];
; #pragma unroll
;                 for (int n = 0; n < 2; ++n)
; #pragma unroll
;                     for (int j = 0; j < 4; ++j) { const float a = acc[ai][0][m][n][j], b = acc[ai][1][m][n][j]; v[n * 4 + j] = MODE == 0 ? silu_f(a) * b : a * sigmoid_f(b); }
;                 u32x4 w; w.x = cvt_pk_bf16(v[0], v[1]); w.y = cvt_pk_bf16(v[2], v[3]); w.z = cvt_pk_bf16(v[4], v[5]); w.w = cvt_pk_bf16(v[6], v[7]);
;                 *(u32x4*)rowp = w;
	s_waitcnt lgkmcnt(0)
	s_waitcnt lgkmcnt(0)
	v_mfma_f32_16x16x32_bf16 v[60:63], v[154:157], v[174:177], v[60:63]
	v_mfma_f32_16x16x32_bf16 v[56:59], v[162:165], v[174:177], v[56:59]
	v_mfma_f32_16x16x32_bf16 v[44:47], v[154:157], v[182:185], v[44:47]
	v_mfma_f32_16x16x32_bf16 v[40:43], v[162:165], v[182:185], v[40:43]
	v_mfma_f32_16x16x32_bf16 v[28:31], v[154:157], v[190:193], v[28:31]
	v_mfma_f32_16x16x32_bf16 v[24:27], v[162:165], v[190:193], v[24:27]
	v_mfma_f32_16x16x32_bf16 v[12:15], v[154:157], v[198:201], v[12:15]
	v_mfma_f32_16x16x32_bf16 v[8:11], v[162:165], v[198:201], v[8:11]
	v_mfma_f32_16x16x32_bf16 v[60:63], v[158:161], v[178:181], v[60:63]
	v_mfma_f32_16x16x32_bf16 v[56:59], v[170:173], v[178:181], v[56:59]
	v_mfma_f32_16x16x32_bf16 v[44:47], v[158:161], v[186:189], v[44:47]
	v_mfma_f32_16x16x32_bf16 v[40:43], v[170:173], v[186:189], v[40:43]
	v_mfma_f32_16x16x32_bf16 v[28:31], v[158:161], v[194:197], v[28:31]
	v_mfma_f32_16x16x32_bf16 v[24:27], v[170:173], v[194:197], v[24:27]
	v_mfma_f32_16x16x32_bf16 v[12:15], v[158:161], v[206:209], v[12:15]
	v_mfma_f32_16x16x32_bf16 v[8:11], v[170:173], v[206:209], v[8:11]
	s_barrier
	s_add_u32 s36, s36, 0xc000
	s_addc_u32 s37, s37, 0
	s_add_i32 s38, s65, s46
	v_lshl_add_u64 v[154:155], s[36:37], 0, v[132:133]
	s_mov_b32 m0, s38
	s_nop 0
	global_load_lds_dwordx4 v[154:155], off
	v_lshl_add_u64 v[154:155], s[36:37], 0, v[128:129]
	s_add_i32 m0, s38, 0x2000
	s_nop 0
	global_load_lds_dwordx4 v[154:155], off
	s_waitcnt vmcnt(6)
	s_barrier
	v_mfma_f32_16x16x32_bf16 v[52:55], v[210:213], v[174:177], v[52:55]
	v_mfma_f32_16x16x32_bf16 v[48:51], v[218:221], v[174:177], v[48:51]
	v_mfma_f32_16x16x32_bf16 v[36:39], v[210:213], v[182:185], v[36:39]
	v_mfma_f32_16x16x32_bf16 v[32:35], v[218:221], v[182:185], v[32:35]
	v_mfma_f32_16x16x32_bf16 v[20:23], v[210:213], v[190:193], v[20:23]
	v_mfma_f32_16x16x32_bf16 v[16:19], v[218:221], v[190:193], v[16:19]
	v_mfma_f32_16x16x32_bf16 v[4:7], v[210:213], v[198:201], v[4:7]
	v_mfma_f32_16x16x32_bf16 v[0:3], v[218:221], v[198:201], v[0:3]
	v_mfma_f32_16x16x32_bf16 v[52:55], v[214:217], v[178:181], v[52:55]
	v_mfma_f32_16x16x32_bf16 v[48:51], v[222:225], v[178:181], v[48:51]
	v_mfma_f32_16x16x32_bf16 v[36:39], v[214:217], v[186:189], v[36:39]
	v_mfma_f32_16x16x32_bf16 v[32:35], v[222:225], v[186:189], v[32:35]
	v_mfma_f32_16x16x32_bf16 v[20:23], v[214:217], v[194:197], v[20:23]
	v_mfma_f32_16x16x32_bf16 v[16:19], v[222:225], v[194:197], v[16:19]
	v_mfma_f32_16x16x32_bf16 v[4:7], v[214:217], v[206:209], v[4:7]
	v_mfma_f32_16x16x32_bf16 v[0:3], v[222:225], v[206:209], v[0:3]
	s_add_i32 s63, s63, 2
	s_add_u32 s28, s28, 0x10000
	s_addc_u32 s29, s29, 0
	s_add_u32 s61, s61, 0x10000
	s_addc_u32 s62, s62, 0
	s_cmp_gt_u32 s63, 29
	s_barrier
	s_cbranch_scc0 .LBB0_135
	s_lshl_b32 s11, s18, 8
	s_add_i32 s11, s11, s53
	s_lshl_b32 s13, s19, 7
	v_mul_f32_e32 v136, 0xbfb8aa3b, v124
	v_or_b32_e32 v153, s11, v148
	s_or_b32 s13, s13, s54
	s_ashr_i32 s11, s11, 8
	v_exp_f32_e32 v136, v136
	v_mul_f32_e32 v147, 0xbfb8aa3b, v125
	s_ashr_i32 s18, s13, 6
	s_mulk_i32 s11, 0x56
	v_exp_f32_e32 v147, v147
	s_ashr_i32 s19, s18, 31
	s_ashr_i32 s13, s11, 31
	s_add_u32 s28, s11, s18
	s_addc_u32 s29, s13, s19
	v_add_f32_e32 v136, 1.0, v136
	s_lshl_b64 s[28:29], s[28:29], 15
	v_rcp_f32_e32 v154, v136
	v_add_f32_e32 v136, 1.0, v147
	s_add_u32 s28, s8, s28
	v_rcp_f32_e32 v155, v136
	v_lshlrev_b32_e32 v136, 7, v153
	s_addc_u32 s29, s9, s29
	v_and_b32_e32 v136, 0x6780, v136
	v_lshl_add_u64 v[156:157], s[28:29], 0, v[136:137]
	v_mul_f32_e32 v136, 0xbfb8aa3b, v126
	v_mul_f32_e32 v147, 0xbfb8aa3b, v127
	v_exp_f32_e32 v136, v136
	v_exp_f32_e32 v147, v147
	v_pk_mul_f32 v[124:125], v[124:125], v[154:155]
	s_mov_b64 s[36:37], s[16:17]
	v_pk_mul_f32 v[116:117], v[124:125], v[116:117]
	v_add_f32_e32 v124, 1.0, v136
	v_add_f32_e32 v125, 1.0, v147
	v_mul_f32_e32 v136, 0xbfb8aa3b, v120
	v_rcp_f32_e32 v124, v124
	v_rcp_f32_e32 v125, v125
	v_exp_f32_e32 v136, v136
	v_mul_f32_e32 v147, 0xbfb8aa3b, v121
	v_exp_f32_e32 v147, v147
	v_pk_mul_f32 v[124:125], v[126:127], v[124:125]
	v_add_f32_e32 v126, 1.0, v136
	v_mul_f32_e32 v136, 0xbfb8aa3b, v122
	v_add_f32_e32 v127, 1.0, v147
	v_exp_f32_e32 v136, v136
	v_mul_f32_e32 v147, 0xbfb8aa3b, v123
	v_exp_f32_e32 v147, v147
	v_rcp_f32_e32 v126, v126
	v_add_f32_e32 v136, 1.0, v136
	v_rcp_f32_e32 v127, v127
	v_rcp_f32_e32 v154, v136
	v_add_f32_e32 v136, 1.0, v147
	v_rcp_f32_e32 v155, v136
	v_pk_mul_f32 v[120:121], v[120:121], v[126:127]
	v_pk_mul_f32 v[118:119], v[124:125], v[118:119]
	v_pk_mul_f32 v[120:121], v[120:121], v[112:113]
	v_pk_mul_f32 v[112:113], v[122:123], v[154:155]
	v_mov_b32_e32 v147, v137
	v_pk_mul_f32 v[122:123], v[112:113], v[114:115]
	v_mul_f32_e32 v113, 0xbfb8aa3b, v108
	v_exp_f32_e32 v114, v113
	v_mul_f32_e32 v113, 0xbfb8aa3b, v109
	v_exp_f32_e32 v115, v113
	v_cvt_pk_bf16_f32 v112, v116, v117
	v_add_f32_e32 v114, 1.0, v114
	v_rcp_f32_e32 v116, v114
	v_add_f32_e32 v114, 1.0, v115
	v_lshl_add_u64 v[124:125], v[156:157], 0, v[146:147]
	v_cvt_pk_bf16_f32 v113, v118, v119
	v_rcp_f32_e32 v117, v114
	v_cvt_pk_bf16_f32 v114, v120, v121
	v_cvt_pk_bf16_f32 v115, v122, v123
	global_store_dwordx4 v[124:125], v[112:115], off
	v_pk_mul_f32 v[108:109], v[108:109], v[116:117]
	s_mov_b64 s[28:29], s[14:15]
	v_mul_f32_e32 v112, 0xbfb8aa3b, v110
	v_mul_f32_e32 v113, 0xbfb8aa3b, v111
	v_exp_f32_e32 v112, v112
	v_exp_f32_e32 v113, v113
	v_pk_mul_f32 v[100:101], v[108:109], v[100:101]
	v_add_f32_e32 v108, 1.0, v112
	v_add_f32_e32 v109, 1.0, v113
	v_mul_f32_e32 v112, 0xbfb8aa3b, v104
	v_mul_f32_e32 v113, 0xbfb8aa3b, v105
	v_rcp_f32_e32 v108, v108
	v_rcp_f32_e32 v109, v109
; __device__ __forceinline__ unsigned cvt_pk_bf16(float lo, float hi) { f32x2 v = {lo, hi}; bf16x2_t b = __builtin_convertvector(v, bf16x2_t); return __builtin_bit_cast(unsigned, b); }
; __device__ __forceinline__ size_t tl(int r, int c, int K) { return ((size_t)(r >> 8) * (size_t)(K >> 6) + (size_t)(c >> 6)) * 16384 + (size_t)((r & 255) << 6) + (size_t)(c & 63); }
; __device__ __forceinline__ float sigmoid_f(float x) { return __builtin_amdgcn_rcpf(1.0f + __expf(-x)); }
; __device__ __forceinline__ float silu_f(float x) { return x * sigmoid_f(x); }
;     __device__ __forceinline__ void operator()(const f32x4 (&acc)[2][2][4][2], const Unit& u, int wr, int wc, int fr, int fq) const {
;         const int row0 = u.pm * BM + wr * 64 + fr, col0 = u.pn * 128 + wc * 32 + 8 * fq;
; #pragma unroll
;         for (int ai = 0; ai < 2; ++ai)
; #pragma unroll
;             for (int m = 0; m < 4; ++m) {
;                 bf16_t* rowp = MODE == 0 ? O + tl(row0 + ai * HALF + m * 16, col0, ldo) : O + (size_t)(row0 + ai * HALF + m * 16) * ldo + col0;
;                 float v[8];
; #pragma unroll
;                 for (int n = 0; n < 2; ++n)
; #pragma unroll
;                     for (int j = 0; j < 4; ++j) { const float a = acc[ai][0][m][n][j], b = acc[ai][1][m][n][j]; v[n * 4 + j] = MODE == 0 ? silu_f(a) * b : a * sigmoid_f(b); }
;                 u32x4 w; w.x = cvt_pk_bf16(v[0], v[1]); w.y = cvt_pk_bf16(v[2], v[3]); w.z = cvt_pk_bf16(v[4], v[5]); w.w = cvt_pk_bf16(v[6], v[7]);
;                 *(u32x4*)rowp = w;
	v_exp_f32_e32 v112, v112
	v_exp_f32_e32 v113, v113
	v_pk_mul_f32 v[108:109], v[110:111], v[108:109]
	v_add_f32_e32 v110, 1.0, v112
	v_add_f32_e32 v111, 1.0, v113
	v_mul_f32_e32 v112, 0xbfb8aa3b, v106
	v_mul_f32_e32 v113, 0xbfb8aa3b, v107
	v_exp_f32_e32 v112, v112
	v_exp_f32_e32 v113, v113
	v_rcp_f32_e32 v110, v110
	v_rcp_f32_e32 v111, v111
	v_add_f32_e32 v112, 1.0, v112
	v_add_f32_e32 v113, 1.0, v113
	v_rcp_f32_e32 v112, v112
	v_rcp_f32_e32 v113, v113
	v_pk_mul_f32 v[104:105], v[104:105], v[110:111]
	v_pk_mul_f32 v[102:103], v[108:109], v[102:103]
	v_pk_mul_f32 v[104:105], v[104:105], v[96:97]
	v_pk_mul_f32 v[96:97], v[106:107], v[112:113]
	s_nop 0
	v_pk_mul_f32 v[106:107], v[96:97], v[98:99]
	v_mul_f32_e32 v97, 0xbfb8aa3b, v92
	v_exp_f32_e32 v98, v97
	v_mul_f32_e32 v97, 0xbfb8aa3b, v93
	v_exp_f32_e32 v99, v97
	v_cvt_pk_bf16_f32 v96, v100, v101
	v_add_f32_e32 v98, 1.0, v98
	v_rcp_f32_e32 v100, v98
	v_add_f32_e32 v98, 1.0, v99
	v_cvt_pk_bf16_f32 v97, v102, v103
	v_rcp_f32_e32 v101, v98
	v_cvt_pk_bf16_f32 v98, v104, v105
	v_cvt_pk_bf16_f32 v99, v106, v107
	global_store_dwordx4 v[124:125], v[96:99], off offset:2048
	v_pk_mul_f32 v[92:93], v[92:93], v[100:101]
	s_nop 0
	v_mul_f32_e32 v96, 0xbfb8aa3b, v94
	v_mul_f32_e32 v97, 0xbfb8aa3b, v95
	v_exp_f32_e32 v96, v96
	v_exp_f32_e32 v97, v97
	v_pk_mul_f32 v[84:85], v[92:93], v[84:85]
	v_add_f32_e32 v92, 1.0, v96
	v_add_f32_e32 v93, 1.0, v97
	v_mul_f32_e32 v96, 0xbfb8aa3b, v88
	v_mul_f32_e32 v97, 0xbfb8aa3b, v89
	v_rcp_f32_e32 v92, v92
	v_rcp_f32_e32 v93, v93
	v_exp_f32_e32 v96, v96
	v_exp_f32_e32 v97, v97
	v_pk_mul_f32 v[92:93], v[94:95], v[92:93]
	v_add_f32_e32 v94, 1.0, v96
	v_add_f32_e32 v95, 1.0, v97
	v_mul_f32_e32 v96, 0xbfb8aa3b, v90
	v_mul_f32_e32 v97, 0xbfb8aa3b, v91
	v_exp_f32_e32 v96, v96
	v_exp_f32_e32 v97, v97
	v_rcp_f32_e32 v94, v94
	v_rcp_f32_e32 v95, v95
	v_add_f32_e32 v96, 1.0, v96
	v_add_f32_e32 v97, 1.0, v97
	v_rcp_f32_e32 v96, v96
	v_rcp_f32_e32 v97, v97
	v_pk_mul_f32 v[88:89], v[88:89], v[94:95]
	v_pk_mul_f32 v[86:87], v[92:93], v[86:87]
	v_pk_mul_f32 v[88:89], v[88:89], v[80:81]
	v_pk_mul_f32 v[80:81], v[90:91], v[96:97]
	s_nop 0
	v_pk_mul_f32 v[90:91], v[80:81], v[82:83]
	v_mul_f32_e32 v83, 0xbfb8aa3b, v76
	v_cvt_pk_bf16_f32 v80, v84, v85
	v_exp_f32_e32 v84, v83
	v_mul_f32_e32 v83, 0xbfb8aa3b, v77
	v_exp_f32_e32 v85, v83
	v_cvt_pk_bf16_f32 v81, v86, v87
	v_add_co_u32_e32 v86, vcc, s59, v124
	v_cvt_pk_bf16_f32 v82, v88, v89
	v_cvt_pk_bf16_f32 v83, v90, v91
	v_add_f32_e32 v84, 1.0, v84
	v_add_f32_e32 v85, 1.0, v85
	v_addc_co_u32_e32 v87, vcc, 0, v125, vcc
	v_rcp_f32_e32 v84, v84
	v_rcp_f32_e32 v85, v85
	global_store_dwordx4 v[86:87], v[80:83], off
	v_pk_mul_f32 v[76:77], v[76:77], v[84:85]
	s_nop 0
	v_mul_f32_e32 v80, 0xbfb8aa3b, v78
	v_mul_f32_e32 v81, 0xbfb8aa3b, v79
	v_exp_f32_e32 v80, v80
	v_exp_f32_e32 v81, v81
	v_pk_mul_f32 v[68:69], v[76:77], v[68:69]
	v_add_f32_e32 v76, 1.0, v80
	v_add_f32_e32 v77, 1.0, v81
	v_mul_f32_e32 v80, 0xbfb8aa3b, v72
	v_mul_f32_e32 v81, 0xbfb8aa3b, v73
	v_rcp_f32_e32 v76, v76
	v_rcp_f32_e32 v77, v77
	v_exp_f32_e32 v80, v80
	v_exp_f32_e32 v81, v81
	v_pk_mul_f32 v[76:77], v[78:79], v[76:77]
	v_add_f32_e32 v78, 1.0, v80
	v_add_f32_e32 v79, 1.0, v81
	v_mul_f32_e32 v80, 0xbfb8aa3b, v74
	v_mul_f32_e32 v81, 0xbfb8aa3b, v75
	v_exp_f32_e32 v80, v80
	v_exp_f32_e32 v81, v81
	v_rcp_f32_e32 v78, v78
	v_rcp_f32_e32 v79, v79
	v_add_f32_e32 v80, 1.0, v80
	v_add_f32_e32 v81, 1.0, v81
	v_rcp_f32_e32 v80, v80
	v_rcp_f32_e32 v81, v81
	v_pk_mul_f32 v[72:73], v[72:73], v[78:79]
	v_pk_mul_f32 v[70:71], v[76:77], v[70:71]
	v_pk_mul_f32 v[72:73], v[72:73], v[64:65]
	v_pk_mul_f32 v[64:65], v[74:75], v[80:81]
	s_nop 0
	v_pk_mul_f32 v[74:75], v[64:65], v[66:67]
	v_cvt_pk_bf16_f32 v64, v68, v69
	v_cvt_pk_bf16_f32 v65, v70, v71
	v_cvt_pk_bf16_f32 v66, v72, v73
	v_cvt_pk_bf16_f32 v67, v74, v75
	global_store_dwordx4 v[86:87], v[64:67], off offset:2048
	v_add_u32_e32 v68, 0x80, v153
	s_nop 0
	v_mul_f32_e32 v66, 0xbfb8aa3b, v60
	v_mul_f32_e32 v67, 0xbfb8aa3b, v61
	v_exp_f32_e32 v66, v66
	v_exp_f32_e32 v67, v67
	v_lshrrev_b32_e32 v64, 8, v68
	v_mul_i32_i24_e32 v64, 0x56, v64
	v_add_f32_e32 v66, 1.0, v66
	v_add_f32_e32 v67, 1.0, v67
	v_rcp_f32_e32 v66, v66
	v_rcp_f32_e32 v67, v67
	v_ashrrev_i32_e32 v65, 31, v64
	v_lshl_add_u64 v[64:65], v[64:65], 0, s[18:19]
	v_lshlrev_b64 v[64:65], 15, v[64:65]
	v_pk_mul_f32 v[60:61], v[60:61], v[66:67]
	v_mul_f32_e32 v66, 0xbfb8aa3b, v62
	v_mul_f32_e32 v67, 0xbfb8aa3b, v63
	v_exp_f32_e32 v66, v66
	v_exp_f32_e32 v67, v67
	v_pk_mul_f32 v[52:53], v[60:61], v[52:53]
	v_lshlrev_b32_e32 v68, 7, v68
	v_add_f32_e32 v60, 1.0, v66
	v_add_f32_e32 v61, 1.0, v67
	v_mul_f32_e32 v66, 0xbfb8aa3b, v56
	v_mul_f32_e32 v67, 0xbfb8aa3b, v57
	v_rcp_f32_e32 v60, v60
	v_rcp_f32_e32 v61, v61
	v_exp_f32_e32 v66, v66
	v_exp_f32_e32 v67, v67
	v_lshl_add_u64 v[64:65], s[8:9], 0, v[64:65]
	v_pk_mul_f32 v[60:61], v[62:63], v[60:61]
	v_add_f32_e32 v62, 1.0, v66
	v_add_f32_e32 v63, 1.0, v67
	v_mul_f32_e32 v66, 0xbfb8aa3b, v58
	v_mul_f32_e32 v67, 0xbfb8aa3b, v59
	v_exp_f32_e32 v66, v66
	v_exp_f32_e32 v67, v67
	v_rcp_f32_e32 v62, v62
	v_rcp_f32_e32 v63, v63
	v_add_f32_e32 v66, 1.0, v66
; __device__ __forceinline__ unsigned cvt_pk_bf16(float lo, float hi) { f32x2 v = {lo, hi}; bf16x2_t b = __builtin_convertvector(v, bf16x2_t); return __builtin_bit_cast(unsigned, b); }
; __device__ __forceinline__ float sigmoid_f(float x) { return __builtin_amdgcn_rcpf(1.0f + __expf(-x)); }
; __device__ __forceinline__ float silu_f(float x) { return x * sigmoid_f(x); }
; __device__ __forceinline__ size_t tl(int r, int c, int K) { return ((size_t)(r >> 8) * (size_t)(K >> 6) + (size_t)(c >> 6)) * 16384 + (size_t)((r & 255) << 6) + (size_t)(c & 63); }
; #define PG8_WAIT_V(n) asm volatile("s_waitcnt vmcnt(" #n ")" ::: "memory")
; #define PG8_BAR __builtin_amdgcn_s_barrier()
; template <class Epi, class Sched>
; __device__ __forceinline__ void gemm_phase(LAS unsigned char* lds, const Gemm g, const Sched& S, const Epi& E) {
;     ...
;         if (!has_next) break;
; #pragma unroll
;         for (int a = 0; a < 2; ++a)
; #pragma unroll
;             for (int b = 0; b < 2; ++b)
; #pragma unroll
;                 for (int m = 0; m < 4; ++m)
; #pragma unroll
;                     for (int n = 0; n < 2; ++n) acc[a][b][m][n] = (f32x4){0.f, 0.f, 0.f, 0.f};
;         cur = nxt; cA = nA; cB = nB; ++ui;
;     }
;     PG8_WAIT_V(0);
;     if (wr == 0) PG8_BAR;
;     PG8_BAR;
;     __device__ __forceinline__ void operator()(const f32x4 (&acc)[2][2][4][2], const Unit& u, int wr, int wc, int fr, int fq) const {
;         const int row0 = u.pm * BM + wr * 64 + fr, col0 = u.pn * 128 + wc * 32 + 8 * fq;
; #pragma unroll
;         for (int ai = 0; ai < 2; ++ai)
; #pragma unroll
;             for (int m = 0; m < 4; ++m) {
;                 bf16_t* rowp = MODE == 0 ? O + tl(row0 + ai * HALF + m * 16, col0, ldo) : O + (size_t)(row0 + ai * HALF + m * 16) * ldo + col0;
;                 float v[8];
; #pragma unroll
;                 for (int n = 0; n < 2; ++n)
; #pragma unroll
;                     for (int j = 0; j < 4; ++j) { const float a = acc[ai][0][m][n][j], b = acc[ai][1][m][n][j]; v[n * 4 + j] = MODE == 0 ? silu_f(a) * b : a * sigmoid_f(b); }
;                 u32x4 w; w.x = cvt_pk_bf16(v[0], v[1]); w.y = cvt_pk_bf16(v[2], v[3]); w.z = cvt_pk_bf16(v[4], v[5]); w.w = cvt_pk_bf16(v[6], v[7]);
;                 *(u32x4*)rowp = w;
	v_add_f32_e32 v67, 1.0, v67
	v_rcp_f32_e32 v66, v66
	v_rcp_f32_e32 v67, v67
	v_pk_mul_f32 v[56:57], v[56:57], v[62:63]
	v_and_b32_e32 v136, 0x6780, v68
	v_pk_mul_f32 v[56:57], v[56:57], v[48:49]
	v_pk_mul_f32 v[48:49], v[58:59], v[66:67]
	v_lshl_add_u64 v[64:65], v[64:65], 0, v[136:137]
	v_pk_mul_f32 v[58:59], v[48:49], v[50:51]
	v_mul_f32_e32 v49, 0xbfb8aa3b, v44
	v_exp_f32_e32 v50, v49
	v_mul_f32_e32 v49, 0xbfb8aa3b, v45
	v_exp_f32_e32 v51, v49
	v_pk_mul_f32 v[54:55], v[60:61], v[54:55]
	v_add_f32_e32 v50, 1.0, v50
	v_cvt_pk_bf16_f32 v48, v52, v53
	v_rcp_f32_e32 v52, v50
	v_add_f32_e32 v50, 1.0, v51
	v_lshl_add_u64 v[60:61], v[64:65], 0, v[146:147]
	v_cvt_pk_bf16_f32 v49, v54, v55
	v_rcp_f32_e32 v53, v50
	v_cvt_pk_bf16_f32 v50, v56, v57
	v_cvt_pk_bf16_f32 v51, v58, v59
	global_store_dwordx4 v[60:61], v[48:51], off
	v_pk_mul_f32 v[44:45], v[44:45], v[52:53]
	s_mov_b32 s19, s10
	v_mul_f32_e32 v48, 0xbfb8aa3b, v46
	v_mul_f32_e32 v49, 0xbfb8aa3b, v47
	v_exp_f32_e32 v48, v48
	v_exp_f32_e32 v49, v49
	v_pk_mul_f32 v[36:37], v[44:45], v[36:37]
	s_mov_b32 s18, s12
	v_add_f32_e32 v44, 1.0, v48
	v_add_f32_e32 v45, 1.0, v49
	v_mul_f32_e32 v48, 0xbfb8aa3b, v40
	v_mul_f32_e32 v49, 0xbfb8aa3b, v41
	v_rcp_f32_e32 v44, v44
	v_rcp_f32_e32 v45, v45
	v_exp_f32_e32 v48, v48
	v_exp_f32_e32 v49, v49
	v_pk_mul_f32 v[44:45], v[46:47], v[44:45]
	v_add_f32_e32 v46, 1.0, v48
	v_add_f32_e32 v47, 1.0, v49
	v_mul_f32_e32 v48, 0xbfb8aa3b, v42
	v_mul_f32_e32 v49, 0xbfb8aa3b, v43
	v_exp_f32_e32 v48, v48
	v_exp_f32_e32 v49, v49
	v_rcp_f32_e32 v46, v46
	v_rcp_f32_e32 v47, v47
	v_add_f32_e32 v48, 1.0, v48
	v_add_f32_e32 v49, 1.0, v49
	v_rcp_f32_e32 v48, v48
	v_rcp_f32_e32 v49, v49
	v_pk_mul_f32 v[40:41], v[40:41], v[46:47]
	v_pk_mul_f32 v[38:39], v[44:45], v[38:39]
	v_pk_mul_f32 v[40:41], v[40:41], v[32:33]
	v_pk_mul_f32 v[32:33], v[42:43], v[48:49]
	s_nop 0
	v_pk_mul_f32 v[42:43], v[32:33], v[34:35]
	v_mul_f32_e32 v33, 0xbfb8aa3b, v28
	v_exp_f32_e32 v34, v33
	v_mul_f32_e32 v33, 0xbfb8aa3b, v29
	v_exp_f32_e32 v35, v33
	v_cvt_pk_bf16_f32 v32, v36, v37
	v_add_f32_e32 v34, 1.0, v34
	v_rcp_f32_e32 v36, v34
	v_add_f32_e32 v34, 1.0, v35
	v_cvt_pk_bf16_f32 v33, v38, v39
	v_rcp_f32_e32 v37, v34
	v_cvt_pk_bf16_f32 v34, v40, v41
	v_cvt_pk_bf16_f32 v35, v42, v43
	global_store_dwordx4 v[60:61], v[32:35], off offset:2048
	v_pk_mul_f32 v[28:29], v[28:29], v[36:37]
	s_nop 0
	v_mul_f32_e32 v32, 0xbfb8aa3b, v30
	v_mul_f32_e32 v33, 0xbfb8aa3b, v31
	v_exp_f32_e32 v32, v32
	v_exp_f32_e32 v33, v33
	v_pk_mul_f32 v[20:21], v[28:29], v[20:21]
	v_add_f32_e32 v28, 1.0, v32
	v_add_f32_e32 v29, 1.0, v33
	v_mul_f32_e32 v32, 0xbfb8aa3b, v24
	v_mul_f32_e32 v33, 0xbfb8aa3b, v25
	v_rcp_f32_e32 v28, v28
	v_rcp_f32_e32 v29, v29
	v_exp_f32_e32 v32, v32
	v_exp_f32_e32 v33, v33
	v_pk_mul_f32 v[28:29], v[30:31], v[28:29]
	v_add_f32_e32 v30, 1.0, v32
	v_add_f32_e32 v31, 1.0, v33
	v_mul_f32_e32 v32, 0xbfb8aa3b, v26
	v_mul_f32_e32 v33, 0xbfb8aa3b, v27
	v_exp_f32_e32 v32, v32
	v_exp_f32_e32 v33, v33
	v_rcp_f32_e32 v30, v30
	v_rcp_f32_e32 v31, v31
	v_add_f32_e32 v32, 1.0, v32
	v_add_f32_e32 v33, 1.0, v33
	v_rcp_f32_e32 v32, v32
	v_rcp_f32_e32 v33, v33
	v_pk_mul_f32 v[24:25], v[24:25], v[30:31]
	v_pk_mul_f32 v[22:23], v[28:29], v[22:23]
	v_pk_mul_f32 v[24:25], v[24:25], v[16:17]
	v_pk_mul_f32 v[16:17], v[26:27], v[32:33]
	s_nop 0
	v_pk_mul_f32 v[26:27], v[16:17], v[18:19]
	v_mul_f32_e32 v19, 0xbfb8aa3b, v12
	v_cvt_pk_bf16_f32 v16, v20, v21
	v_exp_f32_e32 v20, v19
	v_mul_f32_e32 v19, 0xbfb8aa3b, v13
	v_exp_f32_e32 v21, v19
	v_cvt_pk_bf16_f32 v17, v22, v23
	v_add_co_u32_e32 v22, vcc, s59, v60
	v_cvt_pk_bf16_f32 v18, v24, v25
	v_cvt_pk_bf16_f32 v19, v26, v27
	v_add_f32_e32 v20, 1.0, v20
	v_add_f32_e32 v21, 1.0, v21
	v_addc_co_u32_e32 v23, vcc, 0, v61, vcc
	v_rcp_f32_e32 v20, v20
	v_rcp_f32_e32 v21, v21
	global_store_dwordx4 v[22:23], v[16:19], off
	s_and_b64 vcc, exec, s[6:7]
	v_pk_mul_f32 v[12:13], v[12:13], v[20:21]
	v_mul_f32_e32 v16, 0xbfb8aa3b, v14
	v_mul_f32_e32 v17, 0xbfb8aa3b, v15
	v_exp_f32_e32 v16, v16
	v_exp_f32_e32 v17, v17
	v_pk_mul_f32 v[4:5], v[12:13], v[4:5]
	v_add_f32_e32 v12, 1.0, v16
	v_add_f32_e32 v13, 1.0, v17
	v_mul_f32_e32 v16, 0xbfb8aa3b, v8
	v_mul_f32_e32 v17, 0xbfb8aa3b, v9
	v_rcp_f32_e32 v12, v12
	v_rcp_f32_e32 v13, v13
	v_exp_f32_e32 v16, v16
	v_exp_f32_e32 v17, v17
	v_pk_mul_f32 v[12:13], v[14:15], v[12:13]
	v_add_f32_e32 v14, 1.0, v16
	v_add_f32_e32 v15, 1.0, v17
	v_mul_f32_e32 v16, 0xbfb8aa3b, v10
	v_mul_f32_e32 v17, 0xbfb8aa3b, v11
	v_exp_f32_e32 v16, v16
	v_exp_f32_e32 v17, v17
	v_rcp_f32_e32 v14, v14
	v_rcp_f32_e32 v15, v15
	v_add_f32_e32 v16, 1.0, v16
	v_add_f32_e32 v17, 1.0, v17
	v_rcp_f32_e32 v16, v16
	v_rcp_f32_e32 v17, v17
	v_pk_mul_f32 v[8:9], v[8:9], v[14:15]
	v_pk_mul_f32 v[6:7], v[12:13], v[6:7]
	v_pk_mul_f32 v[8:9], v[8:9], v[0:1]
	v_pk_mul_f32 v[0:1], v[10:11], v[16:17]
	s_nop 0
	v_pk_mul_f32 v[10:11], v[0:1], v[2:3]
	v_cvt_pk_bf16_f32 v0, v4, v5
	v_cvt_pk_bf16_f32 v1, v6, v7
	v_cvt_pk_bf16_f32 v2, v8, v9
	v_cvt_pk_bf16_f32 v3, v10, v11
	global_store_dwordx4 v[22:23], v[0:3], off offset:2048
	s_cbranch_vccz .LBB0_132
	s_waitcnt vmcnt(0)
	s_cmpk_gt_u32 s25, 0xff
	s_cbranch_scc1 .LBB0_139
	s_barrier

; #define PG8_STAGE(bufoff, gbase, voff) do { _Pragma("unroll") for (int _i = 0; _i < 2; ++_i) \
;         __builtin_amdgcn_global_load_lds((const unsigned*)((const char*)(gbase) + (voff)[_i]), (LAS unsigned*)(lds + (bufoff) + ldsw + _i * 8192), 16, 0, 0); } while (0)
; #define PG8_LDA(dst, b, h) do { _Pragma("unroll") for (int m = 0; m < 4; ++m) _Pragma("unroll") for (int k = 0; k < 2; ++k) dst[m][k] = *(const LAS bf16x8*)(lds + PG8_SA(b, h) + aoff + m * 2048 + k * 1024); } while (0)
; #define PG8_LDB(dst, b, h) do { _Pragma("unroll") for (int n = 0; n < 2; ++n) _Pragma("unroll") for (int k = 0; k < 2; ++k) dst[n][k] = *(const LAS bf16x8*)(lds + PG8_SB(b, h) + boff + n * 2048 + k * 1024); } while (0)
; #define PG8_MMA(ai, bj, At, Bt) do { __builtin_amdgcn_s_setprio(1); _Pragma("unroll") for (int m = 0; m < 4; ++m) _Pragma("unroll") for (int n = 0; n < 2; ++n) _Pragma("unroll") for (int k = 0; k < 2; ++k) \
;         acc[ai][bj][m][n] = __builtin_amdgcn_mfma_f32_16x16x32_bf16(Bt[n][k], At[m][k], acc[ai][bj][m][n], 0, 0, 0); __builtin_amdgcn_s_setprio(0); } while (0)
; #define PG8_WAIT_L(n) asm volatile("s_waitcnt lgkmcnt(" #n ")" ::: "memory")
; #define PG8_BAR __builtin_amdgcn_s_barrier()
; #define PG8_SCHED __builtin_amdgcn_sched_barrier(0)
; template <class Epi, class Sched>
; __device__ __forceinline__ void gemm_phase(LAS unsigned char* lds, const Gemm g, const Sched& S, const Epi& E) {
;     ...
;         for (int t = 0; t < nt; t += 2) {
;             const bool last = (t == nt - 2);
;             const char* a1 = cA + (size_t)(t + 1) * kstep;
;             const char* a2 = last ? nA : cA + (size_t)(t + 2) * kstep; const char* b2 = last ? nB : cB + (size_t)(t + 2) * kstep;
;             const char* a3 = a2 + kstep; const char* b3 = b2 + kstep;
;             PG8_LDB(B0, 0, 0); PG8_SCHED; PG8_LDA(At, 0, 0); PG8_STAGE(PG8_SA(1, 1), a1 + hstep, voffA);
;             PG8_WAIT_L(8); PG8_BAR; PG8_WAIT_L(0); PG8_MMA(0, 0, At, B0); PG8_BAR; PG8_SCHED;
;             PG8_LDB(B1, 0, 1); PG8_STAGE(PG8_SB(0, 0), b2, voffB);
;             PG8_BAR; PG8_WAIT_L(0); PG8_MMA(0, 1, At, B1); PG8_BAR;
;             PG8_LDA(At, 0, 1); PG8_STAGE(PG8_SA(0, 0), a2, voffA);
;             PG8_BAR; PG8_WAIT_L(0); PG8_MMA(1, 0, At, B0); PG8_BAR; PG8_SCHED;
.LBB0_148:
	ds_read_b128 v[146:149], v143
	ds_read_b128 v[150:153], v143 offset:1024
	ds_read_b128 v[154:157], v143 offset:2048
	ds_read_b128 v[158:161], v143 offset:3072
	s_add_u32 s38, s36, 0x4000
	s_addc_u32 s39, s37, 0
	s_cmp_eq_u32 s65, 28
	s_cselect_b32 s42, s61, s38
	s_cselect_b32 s43, s17, s39
	s_cselect_b32 s38, s62, s63
	s_cselect_b32 s39, s15, s64
	s_add_u32 s40, s42, 0x8000
	s_addc_u32 s41, s43, 0
	v_lshl_add_u64 v[166:167], s[36:37], 0, v[136:137]
	s_add_i32 m0, s11, 0xc000
	ds_read_b128 v[162:165], v144
	ds_read_b128 v[170:173], v144 offset:1024
	ds_read_b128 v[174:177], v144 offset:2048
	ds_read_b128 v[178:181], v144 offset:3072
	ds_read_b128 v[182:185], v144 offset:4096
	ds_read_b128 v[186:189], v144 offset:5120
	ds_read_b128 v[190:193], v144 offset:6144
	ds_read_b128 v[194:197], v144 offset:7168
	global_load_lds_dwordx4 v[166:167], off
	v_lshl_add_u64 v[166:167], s[36:37], 0, v[138:139]
	s_add_i32 m0, s11, 0xe000
	s_nop 0
	global_load_lds_dwordx4 v[166:167], off
	s_waitcnt lgkmcnt(8)
	s_barrier
	s_waitcnt lgkmcnt(0)
	s_waitcnt lgkmcnt(0)
	v_mfma_f32_16x16x32_bf16 v[124:127], v[146:149], v[162:165], v[124:127]
	v_mfma_f32_16x16x32_bf16 v[120:123], v[154:157], v[162:165], v[120:123]
	v_mfma_f32_16x16x32_bf16 v[116:119], v[146:149], v[174:177], v[116:119]
	v_mfma_f32_16x16x32_bf16 v[112:115], v[154:157], v[174:177], v[112:115]
	v_mfma_f32_16x16x32_bf16 v[100:103], v[146:149], v[182:185], v[100:103]
	v_mfma_f32_16x16x32_bf16 v[96:99], v[154:157], v[182:185], v[96:99]
	v_mfma_f32_16x16x32_bf16 v[84:87], v[146:149], v[190:193], v[84:87]
	v_mfma_f32_16x16x32_bf16 v[80:83], v[154:157], v[190:193], v[80:83]
	v_mfma_f32_16x16x32_bf16 v[124:127], v[150:153], v[170:173], v[124:127]
	v_mfma_f32_16x16x32_bf16 v[120:123], v[158:161], v[170:173], v[120:123]
	v_mfma_f32_16x16x32_bf16 v[116:119], v[150:153], v[178:181], v[116:119]
	v_mfma_f32_16x16x32_bf16 v[112:115], v[158:161], v[178:181], v[112:115]
	v_mfma_f32_16x16x32_bf16 v[100:103], v[150:153], v[186:189], v[100:103]
	v_mfma_f32_16x16x32_bf16 v[96:99], v[158:161], v[186:189], v[96:99]
	v_mfma_f32_16x16x32_bf16 v[84:87], v[150:153], v[194:197], v[84:87]
	v_mfma_f32_16x16x32_bf16 v[80:83], v[158:161], v[194:197], v[80:83]
	s_barrier
	s_add_i32 s66, s57, s50
	v_lshl_add_u64 v[166:167], s[38:39], 0, v[130:131]
	s_mov_b32 m0, s66
	ds_read_b128 v[198:201], v145
	ds_read_b128 v[206:209], v145 offset:1024
	ds_read_b128 v[210:213], v145 offset:2048
	ds_read_b128 v[214:217], v145 offset:3072
	global_load_lds_dwordx4 v[166:167], off
	v_lshl_add_u64 v[166:167], s[38:39], 0, v[134:135]
	s_add_i32 m0, s66, 0x2000
	s_nop 0
	global_load_lds_dwordx4 v[166:167], off
	s_barrier
	s_waitcnt lgkmcnt(0)
	s_waitcnt lgkmcnt(0)
	v_mfma_f32_16x16x32_bf16 v[108:111], v[198:201], v[162:165], v[108:111]
	v_mfma_f32_16x16x32_bf16 v[104:107], v[210:213], v[162:165], v[104:107]
	v_mfma_f32_16x16x32_bf16 v[92:95], v[198:201], v[174:177], v[92:95]
	v_mfma_f32_16x16x32_bf16 v[88:91], v[210:213], v[174:177], v[88:91]
	v_mfma_f32_16x16x32_bf16 v[76:79], v[198:201], v[182:185], v[76:79]
	v_mfma_f32_16x16x32_bf16 v[72:75], v[210:213], v[182:185], v[72:75]
	v_mfma_f32_16x16x32_bf16 v[68:71], v[198:201], v[190:193], v[68:71]
	v_mfma_f32_16x16x32_bf16 v[64:67], v[210:213], v[190:193], v[64:67]
	v_mfma_f32_16x16x32_bf16 v[108:111], v[206:209], v[170:173], v[108:111]
	v_mfma_f32_16x16x32_bf16 v[104:107], v[214:217], v[170:173], v[104:107]
	v_mfma_f32_16x16x32_bf16 v[92:95], v[206:209], v[178:181], v[92:95]
	v_mfma_f32_16x16x32_bf16 v[88:91], v[214:217], v[178:181], v[88:91]
	v_mfma_f32_16x16x32_bf16 v[76:79], v[206:209], v[186:189], v[76:79]
	v_mfma_f32_16x16x32_bf16 v[72:75], v[214:217], v[186:189], v[72:75]
	v_mfma_f32_16x16x32_bf16 v[68:71], v[206:209], v[194:197], v[68:71]
	v_mfma_f32_16x16x32_bf16 v[64:67], v[214:217], v[194:197], v[64:67]
	s_mov_b32 m0, s11
	v_lshl_add_u64 v[166:167], s[42:43], 0, v[128:129]
	s_barrier
	ds_read_b128 v[162:165], v144 offset:16384
	ds_read_b128 v[170:173], v144 offset:17408
	ds_read_b128 v[174:177], v144 offset:18432
	ds_read_b128 v[178:181], v144 offset:19456
	ds_read_b128 v[182:185], v144 offset:20480
	ds_read_b128 v[186:189], v144 offset:21504
	ds_read_b128 v[190:193], v144 offset:22528
	ds_read_b128 v[194:197], v144 offset:23552
	global_load_lds_dwordx4 v[166:167], off
	v_lshl_add_u64 v[166:167], s[42:43], 0, v[132:133]
	s_mov_b32 m0, s52
	s_nop 0
	global_load_lds_dwordx4 v[166:167], off
	s_barrier
	s_waitcnt lgkmcnt(0)
	s_waitcnt lgkmcnt(0)
	v_mfma_f32_16x16x32_bf16 v[60:63], v[146:149], v[162:165], v[60:63]
	v_mfma_f32_16x16x32_bf16 v[56:59], v[154:157], v[162:165], v[56:59]
	v_mfma_f32_16x16x32_bf16 v[52:55], v[146:149], v[174:177], v[52:55]
	v_mfma_f32_16x16x32_bf16 v[48:51], v[154:157], v[174:177], v[48:51]
	v_mfma_f32_16x16x32_bf16 v[36:39], v[146:149], v[182:185], v[36:39]
	v_mfma_f32_16x16x32_bf16 v[32:35], v[154:157], v[182:185], v[32:35]
	v_mfma_f32_16x16x32_bf16 v[20:23], v[146:149], v[190:193], v[20:23]
	v_mfma_f32_16x16x32_bf16 v[16:19], v[154:157], v[190:193], v[16:19]
	v_mfma_f32_16x16x32_bf16 v[60:63], v[150:153], v[170:173], v[60:63]
	v_mfma_f32_16x16x32_bf16 v[56:59], v[158:161], v[170:173], v[56:59]
	v_mfma_f32_16x16x32_bf16 v[52:55], v[150:153], v[178:181], v[52:55]
	v_mfma_f32_16x16x32_bf16 v[48:51], v[158:161], v[178:181], v[48:51]
	v_mfma_f32_16x16x32_bf16 v[36:39], v[150:153], v[186:189], v[36:39]
	v_mfma_f32_16x16x32_bf16 v[32:35], v[158:161], v[186:189], v[32:35]
	v_mfma_f32_16x16x32_bf16 v[20:23], v[150:153], v[194:197], v[20:23]
	v_mfma_f32_16x16x32_bf16 v[16:19], v[158:161], v[194:197], v[16:19]
	s_barrier
; #define PG8_STAGE(bufoff, gbase, voff) do { _Pragma("unroll") for (int _i = 0; _i < 2; ++_i) \
;         __builtin_amdgcn_global_load_lds((const unsigned*)((const char*)(gbase) + (voff)[_i]), (LAS unsigned*)(lds + (bufoff) + ldsw + _i * 8192), 16, 0, 0); } while (0)
; #define PG8_LDA(dst, b, h) do { _Pragma("unroll") for (int m = 0; m < 4; ++m) _Pragma("unroll") for (int k = 0; k < 2; ++k) dst[m][k] = *(const LAS bf16x8*)(lds + PG8_SA(b, h) + aoff + m * 2048 + k * 1024); } while (0)
; #define PG8_LDB(dst, b, h) do { _Pragma("unroll") for (int n = 0; n < 2; ++n) _Pragma("unroll") for (int k = 0; k < 2; ++k) dst[n][k] = *(const LAS bf16x8*)(lds + PG8_SB(b, h) + boff + n * 2048 + k * 1024); } while (0)
; #define PG8_MMA(ai, bj, At, Bt) do { __builtin_amdgcn_s_setprio(1); _Pragma("unroll") for (int m = 0; m < 4; ++m) _Pragma("unroll") for (int n = 0; n < 2; ++n) _Pragma("unroll") for (int k = 0; k < 2; ++k) \
;         acc[ai][bj][m][n] = __builtin_amdgcn_mfma_f32_16x16x32_bf16(Bt[n][k], At[m][k], acc[ai][bj][m][n], 0, 0, 0); __builtin_amdgcn_s_setprio(0); } while (0)
; #define PG8_WAIT_V(n) asm volatile("s_waitcnt vmcnt(" #n ")" ::: "memory")
; #define PG8_WAIT_L(n) asm volatile("s_waitcnt lgkmcnt(" #n ")" ::: "memory")
; #define PG8_BAR __builtin_amdgcn_s_barrier()
; #define PG8_SCHED __builtin_amdgcn_sched_barrier(0)
; template <class Epi, class Sched>
; __device__ __forceinline__ void gemm_phase(LAS unsigned char* lds, const Gemm g, const Sched& S, const Epi& E) {
;     ...
;             PG8_STAGE(PG8_SB(0, 1), b2 + hstep, voffB);
;             PG8_WAIT_V(6); PG8_BAR; PG8_MMA(1, 1, At, B1); PG8_BAR;
;             PG8_LDB(B0, 1, 0); PG8_SCHED; PG8_LDA(At, 1, 0); PG8_STAGE(PG8_SA(0, 1), a2 + hstep, voffA);
;             PG8_WAIT_L(8); PG8_BAR; PG8_WAIT_L(0); PG8_MMA(0, 0, At, B0); PG8_BAR; PG8_SCHED;
;             PG8_LDB(B1, 1, 1); PG8_STAGE(PG8_SB(1, 0), b3, voffB);
;             PG8_BAR; PG8_WAIT_L(0); PG8_MMA(0, 1, At, B1); PG8_BAR;
;             PG8_LDA(At, 1, 1); PG8_STAGE(PG8_SA(1, 0), a3, voffA);
	s_add_u32 s66, s38, 0x4000
	s_addc_u32 s67, s39, 0
	s_add_i32 s68, s58, s50
	v_lshl_add_u64 v[146:147], s[66:67], 0, v[130:131]
	s_mov_b32 m0, s68
	s_nop 0
	global_load_lds_dwordx4 v[146:147], off
	v_lshl_add_u64 v[146:147], s[66:67], 0, v[134:135]
	s_add_i32 m0, s68, 0x2000
	s_nop 0
	global_load_lds_dwordx4 v[146:147], off
	s_waitcnt vmcnt(6)
	s_barrier
	v_mfma_f32_16x16x32_bf16 v[44:47], v[198:201], v[162:165], v[44:47]
	v_mfma_f32_16x16x32_bf16 v[40:43], v[210:213], v[162:165], v[40:43]
	v_mfma_f32_16x16x32_bf16 v[28:31], v[198:201], v[174:177], v[28:31]
	v_mfma_f32_16x16x32_bf16 v[24:27], v[210:213], v[174:177], v[24:27]
	v_mfma_f32_16x16x32_bf16 v[12:15], v[198:201], v[182:185], v[12:15]
	v_mfma_f32_16x16x32_bf16 v[8:11], v[210:213], v[182:185], v[8:11]
	v_mfma_f32_16x16x32_bf16 v[4:7], v[198:201], v[190:193], v[4:7]
	v_mfma_f32_16x16x32_bf16 v[0:3], v[210:213], v[190:193], v[0:3]
	v_mfma_f32_16x16x32_bf16 v[44:47], v[206:209], v[170:173], v[44:47]
	v_mfma_f32_16x16x32_bf16 v[40:43], v[214:217], v[170:173], v[40:43]
	v_mfma_f32_16x16x32_bf16 v[28:31], v[206:209], v[178:181], v[28:31]
	v_mfma_f32_16x16x32_bf16 v[24:27], v[214:217], v[178:181], v[24:27]
	v_mfma_f32_16x16x32_bf16 v[12:15], v[206:209], v[186:189], v[12:15]
	v_mfma_f32_16x16x32_bf16 v[8:11], v[214:217], v[186:189], v[8:11]
	v_mfma_f32_16x16x32_bf16 v[4:7], v[206:209], v[194:197], v[4:7]
	v_mfma_f32_16x16x32_bf16 v[0:3], v[214:217], v[194:197], v[0:3]
	s_add_i32 s66, 0, 0x18000
	v_add_u32_e32 v158, s66, v141
	s_barrier
	ds_read_b128 v[146:149], v158
	ds_read_b128 v[150:153], v158 offset:1024
	ds_read_b128 v[154:157], v158 offset:2048
	ds_read_b128 v[158:161], v158 offset:3072
	s_add_u32 s42, s42, 0x4000
	s_addc_u32 s43, s43, 0
	s_mov_b32 m0, s53
	v_lshl_add_u64 v[166:167], s[42:43], 0, v[128:129]
	ds_read_b128 v[162:165], v144 offset:32768
	ds_read_b128 v[170:173], v144 offset:33792
	ds_read_b128 v[174:177], v144 offset:34816
	ds_read_b128 v[178:181], v144 offset:35840
	ds_read_b128 v[182:185], v144 offset:36864
	ds_read_b128 v[186:189], v144 offset:37888
	ds_read_b128 v[190:193], v144 offset:38912
	ds_read_b128 v[194:197], v144 offset:39936
	global_load_lds_dwordx4 v[166:167], off
	v_lshl_add_u64 v[166:167], s[42:43], 0, v[132:133]
	s_mov_b32 m0, s33
	s_nop 0
	global_load_lds_dwordx4 v[166:167], off
	s_waitcnt lgkmcnt(8)
	s_barrier
	s_waitcnt lgkmcnt(0)
	s_waitcnt lgkmcnt(0)
	v_mfma_f32_16x16x32_bf16 v[124:127], v[146:149], v[162:165], v[124:127]
	v_mfma_f32_16x16x32_bf16 v[120:123], v[154:157], v[162:165], v[120:123]
	v_mfma_f32_16x16x32_bf16 v[116:119], v[146:149], v[174:177], v[116:119]
	v_mfma_f32_16x16x32_bf16 v[112:115], v[154:157], v[174:177], v[112:115]
	v_mfma_f32_16x16x32_bf16 v[100:103], v[146:149], v[182:185], v[100:103]
	v_mfma_f32_16x16x32_bf16 v[96:99], v[154:157], v[182:185], v[96:99]
	v_mfma_f32_16x16x32_bf16 v[84:87], v[146:149], v[190:193], v[84:87]
	v_mfma_f32_16x16x32_bf16 v[80:83], v[154:157], v[190:193], v[80:83]
	v_mfma_f32_16x16x32_bf16 v[124:127], v[150:153], v[170:173], v[124:127]
	v_mfma_f32_16x16x32_bf16 v[120:123], v[158:161], v[170:173], v[120:123]
	v_mfma_f32_16x16x32_bf16 v[116:119], v[150:153], v[178:181], v[116:119]
	v_mfma_f32_16x16x32_bf16 v[112:115], v[158:161], v[178:181], v[112:115]
	v_mfma_f32_16x16x32_bf16 v[100:103], v[150:153], v[186:189], v[100:103]
	v_mfma_f32_16x16x32_bf16 v[96:99], v[158:161], v[186:189], v[96:99]
	v_mfma_f32_16x16x32_bf16 v[84:87], v[150:153], v[194:197], v[84:87]
	v_mfma_f32_16x16x32_bf16 v[80:83], v[158:161], v[194:197], v[80:83]
	s_barrier
	s_add_i32 s67, 0, 0x1c000
	s_add_u32 s42, s38, 0x8000
	v_add_u32_e32 v166, s67, v141
	s_addc_u32 s43, s39, 0
	s_add_i32 s66, s66, s50
	ds_read_b128 v[198:201], v166
	ds_read_b128 v[206:209], v166 offset:1024
	ds_read_b128 v[210:213], v166 offset:2048
	ds_read_b128 v[214:217], v166 offset:3072
	v_lshl_add_u64 v[166:167], s[42:43], 0, v[130:131]
	s_mov_b32 m0, s66
	s_nop 0
	global_load_lds_dwordx4 v[166:167], off
	v_lshl_add_u64 v[166:167], s[42:43], 0, v[134:135]
	s_add_i32 m0, s66, 0x2000
	s_nop 0
	global_load_lds_dwordx4 v[166:167], off
	s_barrier
	s_waitcnt lgkmcnt(0)
	s_waitcnt lgkmcnt(0)
	v_mfma_f32_16x16x32_bf16 v[108:111], v[198:201], v[162:165], v[108:111]
	v_mfma_f32_16x16x32_bf16 v[104:107], v[210:213], v[162:165], v[104:107]
	v_mfma_f32_16x16x32_bf16 v[92:95], v[198:201], v[174:177], v[92:95]
	v_mfma_f32_16x16x32_bf16 v[88:91], v[210:213], v[174:177], v[88:91]
	v_mfma_f32_16x16x32_bf16 v[76:79], v[198:201], v[182:185], v[76:79]
	v_mfma_f32_16x16x32_bf16 v[72:75], v[210:213], v[182:185], v[72:75]
	v_mfma_f32_16x16x32_bf16 v[68:71], v[198:201], v[190:193], v[68:71]
	v_mfma_f32_16x16x32_bf16 v[64:67], v[210:213], v[190:193], v[64:67]
	v_mfma_f32_16x16x32_bf16 v[108:111], v[206:209], v[170:173], v[108:111]
	v_mfma_f32_16x16x32_bf16 v[104:107], v[214:217], v[170:173], v[104:107]
	v_mfma_f32_16x16x32_bf16 v[92:95], v[206:209], v[178:181], v[92:95]
	v_mfma_f32_16x16x32_bf16 v[88:91], v[214:217], v[178:181], v[88:91]
	v_mfma_f32_16x16x32_bf16 v[76:79], v[206:209], v[186:189], v[76:79]
	v_mfma_f32_16x16x32_bf16 v[72:75], v[214:217], v[186:189], v[72:75]
	v_mfma_f32_16x16x32_bf16 v[68:71], v[206:209], v[194:197], v[68:71]
	v_mfma_f32_16x16x32_bf16 v[64:67], v[214:217], v[194:197], v[64:67]
	s_mov_b32 m0, s55
	v_lshl_add_u64 v[166:167], s[40:41], 0, v[128:129]
	s_barrier
	ds_read_b128 v[162:165], v144 offset:49152
	ds_read_b128 v[170:173], v144 offset:50176
	ds_read_b128 v[174:177], v144 offset:51200
	ds_read_b128 v[178:181], v144 offset:52224
	ds_read_b128 v[182:185], v144 offset:53248
	ds_read_b128 v[186:189], v144 offset:54272
	ds_read_b128 v[190:193], v144 offset:55296
	ds_read_b128 v[194:197], v144 offset:56320
	global_load_lds_dwordx4 v[166:167], off
	v_lshl_add_u64 v[166:167], s[40:41], 0, v[132:133]
	s_mov_b32 m0, s56
	s_nop 0
	global_load_lds_dwordx4 v[166:167], off
	s_barrier
; #define PG8_STAGE(bufoff, gbase, voff) do { _Pragma("unroll") for (int _i = 0; _i < 2; ++_i) \
;         __builtin_amdgcn_global_load_lds((const unsigned*)((const char*)(gbase) + (voff)[_i]), (LAS unsigned*)(lds + (bufoff) + ldsw + _i * 8192), 16, 0, 0); } while (0)
; #define PG8_MMA(ai, bj, At, Bt) do { __builtin_amdgcn_s_setprio(1); _Pragma("unroll") for (int m = 0; m < 4; ++m) _Pragma("unroll") for (int n = 0; n < 2; ++n) _Pragma("unroll") for (int k = 0; k < 2; ++k) \
;         acc[ai][bj][m][n] = __builtin_amdgcn_mfma_f32_16x16x32_bf16(Bt[n][k], At[m][k], acc[ai][bj][m][n], 0, 0, 0); __builtin_amdgcn_s_setprio(0); } while (0)
; #define PG8_WAIT_V(n) asm volatile("s_waitcnt vmcnt(" #n ")" ::: "memory")
; #define PG8_WAIT_L(n) asm volatile("s_waitcnt lgkmcnt(" #n ")" ::: "memory")
; #define PG8_BAR __builtin_amdgcn_s_barrier()
; #define PG8_SCHED __builtin_amdgcn_sched_barrier(0)
; template <class Epi, class Sched>
; __device__ __forceinline__ void gemm_phase(LAS unsigned char* lds, const Gemm g, const Sched& S, const Epi& E) {
;     ...
;             PG8_BAR; PG8_WAIT_L(0); PG8_MMA(1, 0, At, B0); PG8_BAR; PG8_SCHED;
;             PG8_STAGE(PG8_SB(1, 1), b3 + hstep, voffB);
;             PG8_WAIT_V(6); PG8_BAR; PG8_MMA(1, 1, At, B1); PG8_BAR;
;         }
	s_waitcnt lgkmcnt(0)
	s_waitcnt lgkmcnt(0)
	v_mfma_f32_16x16x32_bf16 v[60:63], v[146:149], v[162:165], v[60:63]
	v_mfma_f32_16x16x32_bf16 v[56:59], v[154:157], v[162:165], v[56:59]
	v_mfma_f32_16x16x32_bf16 v[52:55], v[146:149], v[174:177], v[52:55]
	v_mfma_f32_16x16x32_bf16 v[48:51], v[154:157], v[174:177], v[48:51]
	v_mfma_f32_16x16x32_bf16 v[36:39], v[146:149], v[182:185], v[36:39]
	v_mfma_f32_16x16x32_bf16 v[32:35], v[154:157], v[182:185], v[32:35]
	v_mfma_f32_16x16x32_bf16 v[20:23], v[146:149], v[190:193], v[20:23]
	v_mfma_f32_16x16x32_bf16 v[16:19], v[154:157], v[190:193], v[16:19]
	v_mfma_f32_16x16x32_bf16 v[60:63], v[150:153], v[170:173], v[60:63]
	v_mfma_f32_16x16x32_bf16 v[56:59], v[158:161], v[170:173], v[56:59]
	v_mfma_f32_16x16x32_bf16 v[52:55], v[150:153], v[178:181], v[52:55]
	v_mfma_f32_16x16x32_bf16 v[48:51], v[158:161], v[178:181], v[48:51]
	v_mfma_f32_16x16x32_bf16 v[36:39], v[150:153], v[186:189], v[36:39]
	v_mfma_f32_16x16x32_bf16 v[32:35], v[158:161], v[186:189], v[32:35]
	v_mfma_f32_16x16x32_bf16 v[20:23], v[150:153], v[194:197], v[20:23]
	v_mfma_f32_16x16x32_bf16 v[16:19], v[158:161], v[194:197], v[16:19]
	s_barrier
	s_add_u32 s38, s38, 0xc000
	s_addc_u32 s39, s39, 0
	s_add_i32 s40, s67, s50
	v_lshl_add_u64 v[146:147], s[38:39], 0, v[130:131]
	s_mov_b32 m0, s40
	s_nop 0
	global_load_lds_dwordx4 v[146:147], off
	v_lshl_add_u64 v[146:147], s[38:39], 0, v[134:135]
	s_add_i32 m0, s40, 0x2000
	s_nop 0
	global_load_lds_dwordx4 v[146:147], off
	s_waitcnt vmcnt(6)
	s_barrier
	v_mfma_f32_16x16x32_bf16 v[44:47], v[198:201], v[162:165], v[44:47]
	v_mfma_f32_16x16x32_bf16 v[40:43], v[210:213], v[162:165], v[40:43]
	v_mfma_f32_16x16x32_bf16 v[28:31], v[198:201], v[174:177], v[28:31]
	v_mfma_f32_16x16x32_bf16 v[24:27], v[210:213], v[174:177], v[24:27]
	v_mfma_f32_16x16x32_bf16 v[12:15], v[198:201], v[182:185], v[12:15]
	v_mfma_f32_16x16x32_bf16 v[8:11], v[210:213], v[182:185], v[8:11]
	v_mfma_f32_16x16x32_bf16 v[4:7], v[198:201], v[190:193], v[4:7]
	v_mfma_f32_16x16x32_bf16 v[0:3], v[210:213], v[190:193], v[0:3]
	v_mfma_f32_16x16x32_bf16 v[44:47], v[206:209], v[170:173], v[44:47]
	v_mfma_f32_16x16x32_bf16 v[40:43], v[214:217], v[170:173], v[40:43]
	v_mfma_f32_16x16x32_bf16 v[28:31], v[206:209], v[178:181], v[28:31]
	v_mfma_f32_16x16x32_bf16 v[24:27], v[214:217], v[178:181], v[24:27]
	v_mfma_f32_16x16x32_bf16 v[12:15], v[206:209], v[186:189], v[12:15]
	v_mfma_f32_16x16x32_bf16 v[8:11], v[214:217], v[186:189], v[8:11]
	v_mfma_f32_16x16x32_bf16 v[4:7], v[206:209], v[194:197], v[4:7]
	v_mfma_f32_16x16x32_bf16 v[0:3], v[214:217], v[194:197], v[0:3]
	s_add_i32 s65, s65, 2
	s_add_u32 s36, s36, 0x10000
	s_addc_u32 s37, s37, 0
	s_add_u32 s63, s63, 0x10000
	s_addc_u32 s64, s64, 0
	s_cmp_gt_u32 s65, 29
	s_barrier
	s_cbranch_scc0 .LBB0_148
; __device__ __forceinline__ unsigned cvt_pk_bf16(float lo, float hi) { f32x2 v = {lo, hi}; bf16x2_t b = __builtin_convertvector(v, bf16x2_t); return __builtin_bit_cast(unsigned, b); }
; __device__ __forceinline__ float gelu_f(float x) { const float u = 1.5957691216f * (x + 0.044715f * x * x * x); return x * sigmoid_f(u); }
;     __device__ __forceinline__ void operator()(const f32x4 (&acc)[2][2][4][2], const Unit& u, int wr, int wc, int fr, int fq) const {
;         const int row0 = u.pm * BM + wr * 64 + fr, col0 = u.pn * BM + wc * 32 + 8 * fq;
;         const int kind = ACT == 0 ? 0 : (u.pn < 4 ? 0 : (u.pn < 12 ? 1 : 2));
; #pragma unroll
;         for (int ai = 0; ai < 2; ++ai)
; #pragma unroll
;             for (int m = 0; m < 4; ++m) {
;                 bf16_t* rowp = O + (size_t)(row0 + ai * HALF + m * 16) * ldo + col0;
; #pragma unroll
;                 for (int bj = 0; bj < 2; ++bj) {
;                     float v[8];
; #pragma unroll
;                     for (int n = 0; n < 2; ++n)
; #pragma unroll
;                         for (int j = 0; j < 4; ++j) { const float a = acc[ai][bj][m][n][j]; v[n * 4 + j] = kind == 1 ? gelu_f(a) : (kind == 2 ? a * 0.0625f : a); }
;                     u32x4 w; w.x = cvt_pk_bf16(v[0], v[1]); w.y = cvt_pk_bf16(v[2], v[3]); w.z = cvt_pk_bf16(v[4], v[5]); w.w = cvt_pk_bf16(v[6], v[7]);
;                     *(u32x4*)(rowp + bj * HALF) = w;
;                 }
	v_lshl_add_u32 v152, s10, 8, v140
	v_lshl_or_b32 v146, s60, 8, v142
	v_ashrrev_i32_e32 v147, 31, v146
	v_mov_b64_e32 v[148:149], s[8:9]
	v_cvt_pk_bf16_f32 v68, v68, v69
	v_cvt_pk_bf16_f32 v69, v70, v71
	v_cvt_pk_bf16_f32 v70, v64, v65
	v_add_u32_e32 v64, 0x80, v152
	v_mad_i64_i32 v[150:151], s[36:37], v152, s59, v[148:149]
	v_lshlrev_b64 v[146:147], 1, v[146:147]
	v_cvt_pk_bf16_f32 v108, v108, v109
	v_cvt_pk_bf16_f32 v109, v110, v111
	v_cvt_pk_bf16_f32 v110, v104, v105
	v_or_b32_e32 v104, 16, v152
	v_mad_i64_i32 v[64:65], s[36:37], v64, s59, v[148:149]
	v_cvt_pk_bf16_f32 v44, v44, v45
	v_cvt_pk_bf16_f32 v45, v46, v47
	v_cvt_pk_bf16_f32 v46, v40, v41
	v_add_u32_e32 v40, 0x90, v152
	v_lshl_add_u64 v[150:151], v[150:151], 0, v[146:147]
	v_cvt_pk_bf16_f32 v111, v106, v107
	v_mad_i64_i32 v[104:105], s[36:37], v104, s59, v[148:149]
	v_cvt_pk_bf16_f32 v92, v92, v93
	v_cvt_pk_bf16_f32 v93, v94, v95
	v_cvt_pk_bf16_f32 v94, v88, v89
	v_or_b32_e32 v88, 32, v152
	v_lshl_add_u64 v[64:65], v[64:65], 0, v[146:147]
	v_cvt_pk_bf16_f32 v47, v42, v43
	v_mad_i64_i32 v[40:41], s[36:37], v40, s59, v[148:149]
	v_cvt_pk_bf16_f32 v28, v28, v29
	v_cvt_pk_bf16_f32 v29, v30, v31
	v_cvt_pk_bf16_f32 v30, v24, v25
	v_add_u32_e32 v24, 0xa0, v152
	global_store_dwordx4 v[150:151], v[108:111], off offset:256
	v_cvt_pk_bf16_f32 v95, v90, v91
	v_mad_i64_i32 v[88:89], s[36:37], v88, s59, v[148:149]
	v_lshl_add_u64 v[108:109], v[104:105], 0, v[146:147]
	v_cvt_pk_bf16_f32 v76, v76, v77
	v_cvt_pk_bf16_f32 v77, v78, v79
	v_cvt_pk_bf16_f32 v78, v72, v73
	v_or_b32_e32 v72, 48, v152
	global_store_dwordx4 v[64:65], v[44:47], off offset:256
	v_cvt_pk_bf16_f32 v31, v26, v27
	v_mad_i64_i32 v[24:25], s[36:37], v24, s59, v[148:149]
	v_lshl_add_u64 v[44:45], v[40:41], 0, v[146:147]
	v_cvt_pk_bf16_f32 v12, v12, v13
	v_cvt_pk_bf16_f32 v13, v14, v15
	v_cvt_pk_bf16_f32 v14, v8, v9
	v_add_u32_e32 v8, 0xb0, v152
	global_store_dwordx4 v[108:109], v[92:95], off offset:256
	v_cvt_pk_bf16_f32 v79, v74, v75
	v_mad_i64_i32 v[72:73], s[36:37], v72, s59, v[148:149]
	v_lshl_add_u64 v[92:93], v[88:89], 0, v[146:147]
	global_store_dwordx4 v[44:45], v[28:31], off offset:256
	v_cvt_pk_bf16_f32 v15, v10, v11
	v_mad_i64_i32 v[8:9], s[36:37], v8, s59, v[148:149]
	v_lshl_add_u64 v[28:29], v[24:25], 0, v[146:147]
	v_cvt_pk_bf16_f32 v124, v124, v125
	v_cvt_pk_bf16_f32 v125, v126, v127
	v_cvt_pk_bf16_f32 v126, v120, v121
	v_cvt_pk_bf16_f32 v127, v122, v123
	v_cvt_pk_bf16_f32 v104, v116, v117
	v_cvt_pk_bf16_f32 v105, v118, v119
	v_cvt_pk_bf16_f32 v106, v112, v113
	v_cvt_pk_bf16_f32 v107, v114, v115
	v_cvt_pk_bf16_f32 v88, v100, v101
	v_cvt_pk_bf16_f32 v89, v102, v103
	v_cvt_pk_bf16_f32 v90, v96, v97
	v_cvt_pk_bf16_f32 v91, v98, v99
	global_store_dwordx4 v[92:93], v[76:79], off offset:256
	v_cvt_pk_bf16_f32 v74, v80, v81
	v_cvt_pk_bf16_f32 v75, v82, v83
	v_lshl_add_u64 v[76:77], v[72:73], 0, v[146:147]
	v_cvt_pk_bf16_f32 v72, v84, v85
	v_cvt_pk_bf16_f32 v73, v86, v87
	v_cvt_pk_bf16_f32 v71, v66, v67
	v_cvt_pk_bf16_f32 v60, v60, v61
	v_cvt_pk_bf16_f32 v61, v62, v63
	v_cvt_pk_bf16_f32 v62, v56, v57
	v_cvt_pk_bf16_f32 v63, v58, v59
	v_cvt_pk_bf16_f32 v40, v52, v53
	v_cvt_pk_bf16_f32 v41, v54, v55
	v_cvt_pk_bf16_f32 v42, v48, v49
	v_cvt_pk_bf16_f32 v43, v50, v51
	v_cvt_pk_bf16_f32 v24, v36, v37
	v_cvt_pk_bf16_f32 v25, v38, v39
	v_cvt_pk_bf16_f32 v26, v32, v33
	v_cvt_pk_bf16_f32 v27, v34, v35
	global_store_dwordx4 v[28:29], v[12:15], off offset:256
	v_cvt_pk_bf16_f32 v10, v16, v17
	v_cvt_pk_bf16_f32 v11, v18, v19
	v_lshl_add_u64 v[12:13], v[8:9], 0, v[146:147]
	v_cvt_pk_bf16_f32 v8, v20, v21
	v_cvt_pk_bf16_f32 v9, v22, v23
	v_cvt_pk_bf16_f32 v4, v4, v5
	v_cvt_pk_bf16_f32 v5, v6, v7
	v_cvt_pk_bf16_f32 v6, v0, v1
	v_cvt_pk_bf16_f32 v7, v2, v3
	s_and_b64 vcc, exec, s[12:13]
	s_mov_b32 s60, s14
	s_mov_b32 s10, s16
	s_mov_b64 s[38:39], s[28:29]
	s_mov_b64 s[36:37], s[18:19]
	global_store_dwordx4 v[150:151], v[124:127], off
	global_store_dwordx4 v[108:109], v[104:107], off
	global_store_dwordx4 v[92:93], v[88:91], off
	global_store_dwordx4 v[76:77], v[72:75], off
	global_store_dwordx4 v[76:77], v[68:71], off offset:256
	global_store_dwordx4 v[64:65], v[60:63], off
	global_store_dwordx4 v[44:45], v[40:43], off
	global_store_dwordx4 v[28:29], v[24:27], off
	global_store_dwordx4 v[12:13], v[8:11], off
	global_store_dwordx4 v[12:13], v[4:7], off offset:256
	s_cbranch_vccz .LBB0_145
	s_waitcnt vmcnt(0)
	s_cmpk_gt_u32 s47, 0xff
	s_cbranch_scc1 .LBB0_152
	s_barrier

; #define PG8_STAGE(bufoff, gbase, voff) do { _Pragma("unroll") for (int _i = 0; _i < 2; ++_i) \
;         __builtin_amdgcn_global_load_lds((const unsigned*)((const char*)(gbase) + (voff)[_i]), (LAS unsigned*)(lds + (bufoff) + ldsw + _i * 8192), 16, 0, 0); } while (0)
; #define PG8_LDA(dst, b, h) do { _Pragma("unroll") for (int m = 0; m < 4; ++m) _Pragma("unroll") for (int k = 0; k < 2; ++k) dst[m][k] = *(const LAS bf16x8*)(lds + PG8_SA(b, h) + aoff + m * 2048 + k * 1024); } while (0)
; #define PG8_LDB(dst, b, h) do { _Pragma("unroll") for (int n = 0; n < 2; ++n) _Pragma("unroll") for (int k = 0; k < 2; ++k) dst[n][k] = *(const LAS bf16x8*)(lds + PG8_SB(b, h) + boff + n * 2048 + k * 1024); } while (0)
; #define PG8_MMA(ai, bj, At, Bt) do { __builtin_amdgcn_s_setprio(1); _Pragma("unroll") for (int m = 0; m < 4; ++m) _Pragma("unroll") for (int n = 0; n < 2; ++n) _Pragma("unroll") for (int k = 0; k < 2; ++k) \
;         acc[ai][bj][m][n] = __builtin_amdgcn_mfma_f32_16x16x32_bf16(Bt[n][k], At[m][k], acc[ai][bj][m][n], 0, 0, 0); __builtin_amdgcn_s_setprio(0); } while (0)
; #define PG8_WAIT_L(n) asm volatile("s_waitcnt lgkmcnt(" #n ")" ::: "memory")
; #define PG8_BAR __builtin_amdgcn_s_barrier()
; #define PG8_SCHED __builtin_amdgcn_sched_barrier(0)
; template <class Epi, class Sched>
; __device__ __forceinline__ void gemm_phase(LAS unsigned char* lds, const Gemm g, const Sched& S, const Epi& E) {
;     ...
;         for (int t = 0; t < nt; t += 2) {
;             const bool last = (t == nt - 2);
;             const char* a1 = cA + (size_t)(t + 1) * kstep;
;             const char* a2 = last ? nA : cA + (size_t)(t + 2) * kstep; const char* b2 = last ? nB : cB + (size_t)(t + 2) * kstep;
;             const char* a3 = a2 + kstep; const char* b3 = b2 + kstep;
;             PG8_LDB(B0, 0, 0); PG8_SCHED; PG8_LDA(At, 0, 0); PG8_STAGE(PG8_SA(1, 1), a1 + hstep, voffA);
;             PG8_WAIT_L(8); PG8_BAR; PG8_WAIT_L(0); PG8_MMA(0, 0, At, B0); PG8_BAR; PG8_SCHED;
;             PG8_LDB(B1, 0, 1); PG8_STAGE(PG8_SB(0, 0), b2, voffB);
;             PG8_BAR; PG8_WAIT_L(0); PG8_MMA(0, 1, At, B1); PG8_BAR;
;             PG8_LDA(At, 0, 1); PG8_STAGE(PG8_SA(0, 0), a2, voffA);
;             PG8_BAR; PG8_WAIT_L(0); PG8_MMA(1, 0, At, B0); PG8_BAR; PG8_SCHED;
.LBB0_161:
	ds_read_b128 v[146:149], v143
	ds_read_b128 v[150:153], v143 offset:1024
	ds_read_b128 v[154:157], v143 offset:2048
	ds_read_b128 v[158:161], v143 offset:3072
	s_add_u32 s44, s42, 0x4000
	s_addc_u32 s45, s43, 0
	s_cmp_eq_u32 s73, 28
	s_cselect_b32 s48, s69, s44
	s_cselect_b32 s49, s37, s45
	s_cselect_b32 s44, s70, s71
	s_cselect_b32 s45, s29, s72
	s_add_u32 s46, s48, 0x8000
	s_addc_u32 s47, s49, 0
	v_lshl_add_u64 v[166:167], s[42:43], 0, v[136:137]
	s_add_i32 m0, s56, 0xc000
	ds_read_b128 v[162:165], v144
	ds_read_b128 v[170:173], v144 offset:1024
	ds_read_b128 v[174:177], v144 offset:2048
	ds_read_b128 v[178:181], v144 offset:3072
	ds_read_b128 v[182:185], v144 offset:4096
	ds_read_b128 v[186:189], v144 offset:5120
	ds_read_b128 v[190:193], v144 offset:6144
	ds_read_b128 v[194:197], v144 offset:7168
	global_load_lds_dwordx4 v[166:167], off
	v_lshl_add_u64 v[166:167], s[42:43], 0, v[138:139]
	s_add_i32 m0, s56, 0xe000
	s_nop 0
	global_load_lds_dwordx4 v[166:167], off
	s_waitcnt lgkmcnt(8)
	s_barrier
	s_waitcnt lgkmcnt(0)
	s_waitcnt lgkmcnt(0)
	v_mfma_f32_16x16x32_bf16 v[124:127], v[146:149], v[162:165], v[124:127]
	v_mfma_f32_16x16x32_bf16 v[120:123], v[154:157], v[162:165], v[120:123]
	v_mfma_f32_16x16x32_bf16 v[116:119], v[146:149], v[174:177], v[116:119]
	v_mfma_f32_16x16x32_bf16 v[108:111], v[154:157], v[174:177], v[108:111]
	v_mfma_f32_16x16x32_bf16 v[100:103], v[146:149], v[182:185], v[100:103]
	v_mfma_f32_16x16x32_bf16 v[92:95], v[154:157], v[182:185], v[92:95]
	v_mfma_f32_16x16x32_bf16 v[84:87], v[146:149], v[190:193], v[84:87]
	v_mfma_f32_16x16x32_bf16 v[76:79], v[154:157], v[190:193], v[76:79]
	v_mfma_f32_16x16x32_bf16 v[124:127], v[150:153], v[170:173], v[124:127]
	v_mfma_f32_16x16x32_bf16 v[120:123], v[158:161], v[170:173], v[120:123]
	v_mfma_f32_16x16x32_bf16 v[116:119], v[150:153], v[178:181], v[116:119]
	v_mfma_f32_16x16x32_bf16 v[108:111], v[158:161], v[178:181], v[108:111]
	v_mfma_f32_16x16x32_bf16 v[100:103], v[150:153], v[186:189], v[100:103]
	v_mfma_f32_16x16x32_bf16 v[92:95], v[158:161], v[186:189], v[92:95]
	v_mfma_f32_16x16x32_bf16 v[84:87], v[150:153], v[194:197], v[84:87]
	v_mfma_f32_16x16x32_bf16 v[76:79], v[158:161], v[194:197], v[76:79]
	s_barrier
	s_add_i32 s74, s62, s55
	v_lshl_add_u64 v[166:167], s[44:45], 0, v[130:131]
	s_mov_b32 m0, s74
	ds_read_b128 v[198:201], v145
	ds_read_b128 v[206:209], v145 offset:1024
	ds_read_b128 v[210:213], v145 offset:2048
	ds_read_b128 v[214:217], v145 offset:3072
	global_load_lds_dwordx4 v[166:167], off
	v_lshl_add_u64 v[166:167], s[44:45], 0, v[134:135]
	s_add_i32 m0, s74, 0x2000
	s_nop 0
	global_load_lds_dwordx4 v[166:167], off
	s_barrier
	s_waitcnt lgkmcnt(0)
	s_waitcnt lgkmcnt(0)
	v_mfma_f32_16x16x32_bf16 v[112:115], v[198:201], v[162:165], v[112:115]
	v_mfma_f32_16x16x32_bf16 v[104:107], v[210:213], v[162:165], v[104:107]
	v_mfma_f32_16x16x32_bf16 v[96:99], v[198:201], v[174:177], v[96:99]
	v_mfma_f32_16x16x32_bf16 v[88:91], v[210:213], v[174:177], v[88:91]
	v_mfma_f32_16x16x32_bf16 v[80:83], v[198:201], v[182:185], v[80:83]
	v_mfma_f32_16x16x32_bf16 v[72:75], v[210:213], v[182:185], v[72:75]
	v_mfma_f32_16x16x32_bf16 v[68:71], v[198:201], v[190:193], v[68:71]
	v_mfma_f32_16x16x32_bf16 v[64:67], v[210:213], v[190:193], v[64:67]
	v_mfma_f32_16x16x32_bf16 v[112:115], v[206:209], v[170:173], v[112:115]
	v_mfma_f32_16x16x32_bf16 v[104:107], v[214:217], v[170:173], v[104:107]
	v_mfma_f32_16x16x32_bf16 v[96:99], v[206:209], v[178:181], v[96:99]
	v_mfma_f32_16x16x32_bf16 v[88:91], v[214:217], v[178:181], v[88:91]
	v_mfma_f32_16x16x32_bf16 v[80:83], v[206:209], v[186:189], v[80:83]
	v_mfma_f32_16x16x32_bf16 v[72:75], v[214:217], v[186:189], v[72:75]
	v_mfma_f32_16x16x32_bf16 v[68:71], v[206:209], v[194:197], v[68:71]
	v_mfma_f32_16x16x32_bf16 v[64:67], v[214:217], v[194:197], v[64:67]
	s_mov_b32 m0, s56
	v_lshl_add_u64 v[166:167], s[48:49], 0, v[128:129]
	s_barrier
	ds_read_b128 v[162:165], v144 offset:16384
	ds_read_b128 v[170:173], v144 offset:17408
	ds_read_b128 v[174:177], v144 offset:18432
	ds_read_b128 v[178:181], v144 offset:19456
	ds_read_b128 v[182:185], v144 offset:20480
	ds_read_b128 v[186:189], v144 offset:21504
	ds_read_b128 v[190:193], v144 offset:22528
	ds_read_b128 v[194:197], v144 offset:23552
	global_load_lds_dwordx4 v[166:167], off
	v_lshl_add_u64 v[166:167], s[48:49], 0, v[132:133]
	s_mov_b32 m0, s57
	s_nop 0
	global_load_lds_dwordx4 v[166:167], off
	s_barrier
	s_waitcnt lgkmcnt(0)
	s_waitcnt lgkmcnt(0)
	v_mfma_f32_16x16x32_bf16 v[60:63], v[146:149], v[162:165], v[60:63]
	v_mfma_f32_16x16x32_bf16 v[56:59], v[154:157], v[162:165], v[56:59]
	v_mfma_f32_16x16x32_bf16 v[52:55], v[146:149], v[174:177], v[52:55]
	v_mfma_f32_16x16x32_bf16 v[48:51], v[154:157], v[174:177], v[48:51]
	v_mfma_f32_16x16x32_bf16 v[36:39], v[146:149], v[182:185], v[36:39]
	v_mfma_f32_16x16x32_bf16 v[32:35], v[154:157], v[182:185], v[32:35]
	v_mfma_f32_16x16x32_bf16 v[20:23], v[146:149], v[190:193], v[20:23]
	v_mfma_f32_16x16x32_bf16 v[16:19], v[154:157], v[190:193], v[16:19]
	v_mfma_f32_16x16x32_bf16 v[60:63], v[150:153], v[170:173], v[60:63]
	v_mfma_f32_16x16x32_bf16 v[56:59], v[158:161], v[170:173], v[56:59]
	v_mfma_f32_16x16x32_bf16 v[52:55], v[150:153], v[178:181], v[52:55]
	v_mfma_f32_16x16x32_bf16 v[48:51], v[158:161], v[178:181], v[48:51]
	v_mfma_f32_16x16x32_bf16 v[36:39], v[150:153], v[186:189], v[36:39]
	v_mfma_f32_16x16x32_bf16 v[32:35], v[158:161], v[186:189], v[32:35]
	v_mfma_f32_16x16x32_bf16 v[20:23], v[150:153], v[194:197], v[20:23]
	v_mfma_f32_16x16x32_bf16 v[16:19], v[158:161], v[194:197], v[16:19]
	s_barrier
; #define PG8_STAGE(bufoff, gbase, voff) do { _Pragma("unroll") for (int _i = 0; _i < 2; ++_i) \
;         __builtin_amdgcn_global_load_lds((const unsigned*)((const char*)(gbase) + (voff)[_i]), (LAS unsigned*)(lds + (bufoff) + ldsw + _i * 8192), 16, 0, 0); } while (0)
; #define PG8_LDA(dst, b, h) do { _Pragma("unroll") for (int m = 0; m < 4; ++m) _Pragma("unroll") for (int k = 0; k < 2; ++k) dst[m][k] = *(const LAS bf16x8*)(lds + PG8_SA(b, h) + aoff + m * 2048 + k * 1024); } while (0)
; #define PG8_LDB(dst, b, h) do { _Pragma("unroll") for (int n = 0; n < 2; ++n) _Pragma("unroll") for (int k = 0; k < 2; ++k) dst[n][k] = *(const LAS bf16x8*)(lds + PG8_SB(b, h) + boff + n * 2048 + k * 1024); } while (0)
; #define PG8_MMA(ai, bj, At, Bt) do { __builtin_amdgcn_s_setprio(1); _Pragma("unroll") for (int m = 0; m < 4; ++m) _Pragma("unroll") for (int n = 0; n < 2; ++n) _Pragma("unroll") for (int k = 0; k < 2; ++k) \
;         acc[ai][bj][m][n] = __builtin_amdgcn_mfma_f32_16x16x32_bf16(Bt[n][k], At[m][k], acc[ai][bj][m][n], 0, 0, 0); __builtin_amdgcn_s_setprio(0); } while (0)
; #define PG8_WAIT_V(n) asm volatile("s_waitcnt vmcnt(" #n ")" ::: "memory")
; #define PG8_WAIT_L(n) asm volatile("s_waitcnt lgkmcnt(" #n ")" ::: "memory")
; #define PG8_BAR __builtin_amdgcn_s_barrier()
; #define PG8_SCHED __builtin_amdgcn_sched_barrier(0)
; template <class Epi, class Sched>
; __device__ __forceinline__ void gemm_phase(LAS unsigned char* lds, const Gemm g, const Sched& S, const Epi& E) {
;     ...
;             PG8_STAGE(PG8_SB(0, 1), b2 + hstep, voffB);
;             PG8_WAIT_V(6); PG8_BAR; PG8_MMA(1, 1, At, B1); PG8_BAR;
;             PG8_LDB(B0, 1, 0); PG8_SCHED; PG8_LDA(At, 1, 0); PG8_STAGE(PG8_SA(0, 1), a2 + hstep, voffA);
;             PG8_WAIT_L(8); PG8_BAR; PG8_WAIT_L(0); PG8_MMA(0, 0, At, B0); PG8_BAR; PG8_SCHED;
;             PG8_LDB(B1, 1, 1); PG8_STAGE(PG8_SB(1, 0), b3, voffB);
;             PG8_BAR; PG8_WAIT_L(0); PG8_MMA(0, 1, At, B1); PG8_BAR;
;             PG8_LDA(At, 1, 1); PG8_STAGE(PG8_SA(1, 0), a3, voffA);
	s_add_u32 s74, s44, 0x4000
	s_addc_u32 s75, s45, 0
	s_add_i32 s76, s63, s55
	v_lshl_add_u64 v[146:147], s[74:75], 0, v[130:131]
	s_mov_b32 m0, s76
	s_nop 0
	global_load_lds_dwordx4 v[146:147], off
	v_lshl_add_u64 v[146:147], s[74:75], 0, v[134:135]
	s_add_i32 m0, s76, 0x2000
	s_nop 0
	global_load_lds_dwordx4 v[146:147], off
	s_waitcnt vmcnt(6)
	s_barrier
	v_mfma_f32_16x16x32_bf16 v[44:47], v[198:201], v[162:165], v[44:47]
	v_mfma_f32_16x16x32_bf16 v[40:43], v[210:213], v[162:165], v[40:43]
	v_mfma_f32_16x16x32_bf16 v[28:31], v[198:201], v[174:177], v[28:31]
	v_mfma_f32_16x16x32_bf16 v[24:27], v[210:213], v[174:177], v[24:27]
	v_mfma_f32_16x16x32_bf16 v[12:15], v[198:201], v[182:185], v[12:15]
	v_mfma_f32_16x16x32_bf16 v[8:11], v[210:213], v[182:185], v[8:11]
	v_mfma_f32_16x16x32_bf16 v[4:7], v[198:201], v[190:193], v[4:7]
	v_mfma_f32_16x16x32_bf16 v[0:3], v[210:213], v[190:193], v[0:3]
	v_mfma_f32_16x16x32_bf16 v[44:47], v[206:209], v[170:173], v[44:47]
	v_mfma_f32_16x16x32_bf16 v[40:43], v[214:217], v[170:173], v[40:43]
	v_mfma_f32_16x16x32_bf16 v[28:31], v[206:209], v[178:181], v[28:31]
	v_mfma_f32_16x16x32_bf16 v[24:27], v[214:217], v[178:181], v[24:27]
	v_mfma_f32_16x16x32_bf16 v[12:15], v[206:209], v[186:189], v[12:15]
	v_mfma_f32_16x16x32_bf16 v[8:11], v[214:217], v[186:189], v[8:11]
	v_mfma_f32_16x16x32_bf16 v[4:7], v[206:209], v[194:197], v[4:7]
	v_mfma_f32_16x16x32_bf16 v[0:3], v[214:217], v[194:197], v[0:3]
	s_add_i32 s74, 0, 0x18000
	v_add_u32_e32 v158, s74, v141
	s_barrier
	ds_read_b128 v[146:149], v158
	ds_read_b128 v[150:153], v158 offset:1024
	ds_read_b128 v[154:157], v158 offset:2048
	ds_read_b128 v[158:161], v158 offset:3072
	s_add_u32 s48, s48, 0x4000
	s_addc_u32 s49, s49, 0
	s_mov_b32 m0, s58
	v_lshl_add_u64 v[166:167], s[48:49], 0, v[128:129]
	ds_read_b128 v[162:165], v144 offset:32768
	ds_read_b128 v[170:173], v144 offset:33792
	ds_read_b128 v[174:177], v144 offset:34816
	ds_read_b128 v[178:181], v144 offset:35840
	ds_read_b128 v[182:185], v144 offset:36864
	ds_read_b128 v[186:189], v144 offset:37888
	ds_read_b128 v[190:193], v144 offset:38912
	ds_read_b128 v[194:197], v144 offset:39936
	global_load_lds_dwordx4 v[166:167], off
	v_lshl_add_u64 v[166:167], s[48:49], 0, v[132:133]
	s_mov_b32 m0, s59
	s_nop 0
	global_load_lds_dwordx4 v[166:167], off
	s_waitcnt lgkmcnt(8)
	s_barrier
	s_waitcnt lgkmcnt(0)
	s_waitcnt lgkmcnt(0)
	v_mfma_f32_16x16x32_bf16 v[124:127], v[146:149], v[162:165], v[124:127]
	v_mfma_f32_16x16x32_bf16 v[120:123], v[154:157], v[162:165], v[120:123]
	v_mfma_f32_16x16x32_bf16 v[116:119], v[146:149], v[174:177], v[116:119]
	v_mfma_f32_16x16x32_bf16 v[108:111], v[154:157], v[174:177], v[108:111]
	v_mfma_f32_16x16x32_bf16 v[100:103], v[146:149], v[182:185], v[100:103]
	v_mfma_f32_16x16x32_bf16 v[92:95], v[154:157], v[182:185], v[92:95]
	v_mfma_f32_16x16x32_bf16 v[84:87], v[146:149], v[190:193], v[84:87]
	v_mfma_f32_16x16x32_bf16 v[76:79], v[154:157], v[190:193], v[76:79]
	v_mfma_f32_16x16x32_bf16 v[124:127], v[150:153], v[170:173], v[124:127]
	v_mfma_f32_16x16x32_bf16 v[120:123], v[158:161], v[170:173], v[120:123]
	v_mfma_f32_16x16x32_bf16 v[116:119], v[150:153], v[178:181], v[116:119]
	v_mfma_f32_16x16x32_bf16 v[108:111], v[158:161], v[178:181], v[108:111]
	v_mfma_f32_16x16x32_bf16 v[100:103], v[150:153], v[186:189], v[100:103]
	v_mfma_f32_16x16x32_bf16 v[92:95], v[158:161], v[186:189], v[92:95]
	v_mfma_f32_16x16x32_bf16 v[84:87], v[150:153], v[194:197], v[84:87]
	v_mfma_f32_16x16x32_bf16 v[76:79], v[158:161], v[194:197], v[76:79]
	s_barrier
	s_add_i32 s75, 0, 0x1c000
	s_add_u32 s48, s44, 0x8000
	v_add_u32_e32 v166, s75, v141
	s_addc_u32 s49, s45, 0
	s_add_i32 s74, s74, s55
	ds_read_b128 v[198:201], v166
	ds_read_b128 v[206:209], v166 offset:1024
	ds_read_b128 v[210:213], v166 offset:2048
	ds_read_b128 v[214:217], v166 offset:3072
	v_lshl_add_u64 v[166:167], s[48:49], 0, v[130:131]
	s_mov_b32 m0, s74
	s_nop 0
	global_load_lds_dwordx4 v[166:167], off
	v_lshl_add_u64 v[166:167], s[48:49], 0, v[134:135]
	s_add_i32 m0, s74, 0x2000
	s_nop 0
	global_load_lds_dwordx4 v[166:167], off
	s_barrier
	s_waitcnt lgkmcnt(0)
	s_waitcnt lgkmcnt(0)
	v_mfma_f32_16x16x32_bf16 v[112:115], v[198:201], v[162:165], v[112:115]
	v_mfma_f32_16x16x32_bf16 v[104:107], v[210:213], v[162:165], v[104:107]
	v_mfma_f32_16x16x32_bf16 v[96:99], v[198:201], v[174:177], v[96:99]
	v_mfma_f32_16x16x32_bf16 v[88:91], v[210:213], v[174:177], v[88:91]
	v_mfma_f32_16x16x32_bf16 v[80:83], v[198:201], v[182:185], v[80:83]
	v_mfma_f32_16x16x32_bf16 v[72:75], v[210:213], v[182:185], v[72:75]
	v_mfma_f32_16x16x32_bf16 v[68:71], v[198:201], v[190:193], v[68:71]
	v_mfma_f32_16x16x32_bf16 v[64:67], v[210:213], v[190:193], v[64:67]
	v_mfma_f32_16x16x32_bf16 v[112:115], v[206:209], v[170:173], v[112:115]
	v_mfma_f32_16x16x32_bf16 v[104:107], v[214:217], v[170:173], v[104:107]
	v_mfma_f32_16x16x32_bf16 v[96:99], v[206:209], v[178:181], v[96:99]
	v_mfma_f32_16x16x32_bf16 v[88:91], v[214:217], v[178:181], v[88:91]
	v_mfma_f32_16x16x32_bf16 v[80:83], v[206:209], v[186:189], v[80:83]
	v_mfma_f32_16x16x32_bf16 v[72:75], v[214:217], v[186:189], v[72:75]
	v_mfma_f32_16x16x32_bf16 v[68:71], v[206:209], v[194:197], v[68:71]
	v_mfma_f32_16x16x32_bf16 v[64:67], v[214:217], v[194:197], v[64:67]
	s_mov_b32 m0, s33
	v_lshl_add_u64 v[166:167], s[46:47], 0, v[128:129]
	s_barrier
	ds_read_b128 v[162:165], v144 offset:49152
	ds_read_b128 v[170:173], v144 offset:50176
	ds_read_b128 v[174:177], v144 offset:51200
	ds_read_b128 v[178:181], v144 offset:52224
	ds_read_b128 v[182:185], v144 offset:53248
	ds_read_b128 v[186:189], v144 offset:54272
	ds_read_b128 v[190:193], v144 offset:55296
	ds_read_b128 v[194:197], v144 offset:56320
	global_load_lds_dwordx4 v[166:167], off
	v_lshl_add_u64 v[166:167], s[46:47], 0, v[132:133]
	s_mov_b32 m0, s60
	s_nop 0
	global_load_lds_dwordx4 v[166:167], off
	s_barrier
; #define PG8_STAGE(bufoff, gbase, voff) do { _Pragma("unroll") for (int _i = 0; _i < 2; ++_i) \
;         __builtin_amdgcn_global_load_lds((const unsigned*)((const char*)(gbase) + (voff)[_i]), (LAS unsigned*)(lds + (bufoff) + ldsw + _i * 8192), 16, 0, 0); } while (0)
; #define PG8_MMA(ai, bj, At, Bt) do { __builtin_amdgcn_s_setprio(1); _Pragma("unroll") for (int m = 0; m < 4; ++m) _Pragma("unroll") for (int n = 0; n < 2; ++n) _Pragma("unroll") for (int k = 0; k < 2; ++k) \
;         acc[ai][bj][m][n] = __builtin_amdgcn_mfma_f32_16x16x32_bf16(Bt[n][k], At[m][k], acc[ai][bj][m][n], 0, 0, 0); __builtin_amdgcn_s_setprio(0); } while (0)
; #define PG8_WAIT_V(n) asm volatile("s_waitcnt vmcnt(" #n ")" ::: "memory")
; #define PG8_WAIT_L(n) asm volatile("s_waitcnt lgkmcnt(" #n ")" ::: "memory")
; #define PG8_BAR __builtin_amdgcn_s_barrier()
; #define PG8_SCHED __builtin_amdgcn_sched_barrier(0)
; template <class Epi, class Sched>
; __device__ __forceinline__ void gemm_phase(LAS unsigned char* lds, const Gemm g, const Sched& S, const Epi& E) {
;     ...
;             PG8_BAR; PG8_WAIT_L(0); PG8_MMA(1, 0, At, B0); PG8_BAR; PG8_SCHED;
;             PG8_STAGE(PG8_SB(1, 1), b3 + hstep, voffB);
;             PG8_WAIT_V(6); PG8_BAR; PG8_MMA(1, 1, At, B1); PG8_BAR;
;         }
	s_waitcnt lgkmcnt(0)
	s_waitcnt lgkmcnt(0)
	v_mfma_f32_16x16x32_bf16 v[60:63], v[146:149], v[162:165], v[60:63]
	v_mfma_f32_16x16x32_bf16 v[56:59], v[154:157], v[162:165], v[56:59]
	v_mfma_f32_16x16x32_bf16 v[52:55], v[146:149], v[174:177], v[52:55]
	v_mfma_f32_16x16x32_bf16 v[48:51], v[154:157], v[174:177], v[48:51]
	v_mfma_f32_16x16x32_bf16 v[36:39], v[146:149], v[182:185], v[36:39]
	v_mfma_f32_16x16x32_bf16 v[32:35], v[154:157], v[182:185], v[32:35]
	v_mfma_f32_16x16x32_bf16 v[20:23], v[146:149], v[190:193], v[20:23]
	v_mfma_f32_16x16x32_bf16 v[16:19], v[154:157], v[190:193], v[16:19]
	v_mfma_f32_16x16x32_bf16 v[60:63], v[150:153], v[170:173], v[60:63]
	v_mfma_f32_16x16x32_bf16 v[56:59], v[158:161], v[170:173], v[56:59]
	v_mfma_f32_16x16x32_bf16 v[52:55], v[150:153], v[178:181], v[52:55]
	v_mfma_f32_16x16x32_bf16 v[48:51], v[158:161], v[178:181], v[48:51]
	v_mfma_f32_16x16x32_bf16 v[36:39], v[150:153], v[186:189], v[36:39]
	v_mfma_f32_16x16x32_bf16 v[32:35], v[158:161], v[186:189], v[32:35]
	v_mfma_f32_16x16x32_bf16 v[20:23], v[150:153], v[194:197], v[20:23]
	v_mfma_f32_16x16x32_bf16 v[16:19], v[158:161], v[194:197], v[16:19]
	s_barrier
	s_add_u32 s44, s44, 0xc000
	s_addc_u32 s45, s45, 0
	s_add_i32 s46, s75, s55
	v_lshl_add_u64 v[146:147], s[44:45], 0, v[130:131]
	s_mov_b32 m0, s46
	s_nop 0
	global_load_lds_dwordx4 v[146:147], off
	v_lshl_add_u64 v[146:147], s[44:45], 0, v[134:135]
	s_add_i32 m0, s46, 0x2000
	s_nop 0
	global_load_lds_dwordx4 v[146:147], off
	s_waitcnt vmcnt(6)
	s_barrier
	v_mfma_f32_16x16x32_bf16 v[44:47], v[198:201], v[162:165], v[44:47]
	v_mfma_f32_16x16x32_bf16 v[40:43], v[210:213], v[162:165], v[40:43]
	v_mfma_f32_16x16x32_bf16 v[28:31], v[198:201], v[174:177], v[28:31]
	v_mfma_f32_16x16x32_bf16 v[24:27], v[210:213], v[174:177], v[24:27]
	v_mfma_f32_16x16x32_bf16 v[12:15], v[198:201], v[182:185], v[12:15]
	v_mfma_f32_16x16x32_bf16 v[8:11], v[210:213], v[182:185], v[8:11]
	v_mfma_f32_16x16x32_bf16 v[4:7], v[198:201], v[190:193], v[4:7]
	v_mfma_f32_16x16x32_bf16 v[0:3], v[210:213], v[190:193], v[0:3]
	v_mfma_f32_16x16x32_bf16 v[44:47], v[206:209], v[170:173], v[44:47]
	v_mfma_f32_16x16x32_bf16 v[40:43], v[214:217], v[170:173], v[40:43]
	v_mfma_f32_16x16x32_bf16 v[28:31], v[206:209], v[178:181], v[28:31]
	v_mfma_f32_16x16x32_bf16 v[24:27], v[214:217], v[178:181], v[24:27]
	v_mfma_f32_16x16x32_bf16 v[12:15], v[206:209], v[186:189], v[12:15]
	v_mfma_f32_16x16x32_bf16 v[8:11], v[214:217], v[186:189], v[8:11]
	v_mfma_f32_16x16x32_bf16 v[4:7], v[206:209], v[194:197], v[4:7]
	v_mfma_f32_16x16x32_bf16 v[0:3], v[214:217], v[194:197], v[0:3]
	s_add_i32 s73, s73, 2
	s_add_u32 s42, s42, 0x10000
	s_addc_u32 s43, s43, 0
	s_add_u32 s71, s71, 0x10000
	s_addc_u32 s72, s72, 0
	s_cmp_gt_u32 s73, 29
	s_barrier
	s_cbranch_scc0 .LBB0_161
; __device__ __forceinline__ unsigned cvt_pk_bf16(float lo, float hi) { f32x2 v = {lo, hi}; bf16x2_t b = __builtin_convertvector(v, bf16x2_t); return __builtin_bit_cast(unsigned, b); }
; __device__ __forceinline__ float gelu_f(float x) { const float u = 1.5957691216f * (x + 0.044715f * x * x * x); return x * sigmoid_f(u); }
;     __device__ __forceinline__ void operator()(const f32x4 (&acc)[2][2][4][2], const Unit& u, int wr, int wc, int fr, int fq) const {
;         const int row0 = u.pm * BM + wr * 64 + fr, col0 = u.pn * BM + wc * 32 + 8 * fq;
;         const int kind = ACT == 0 ? 0 : (u.pn < 4 ? 0 : (u.pn < 12 ? 1 : 2));
; #pragma unroll
;         for (int ai = 0; ai < 2; ++ai)
; #pragma unroll
;             for (int m = 0; m < 4; ++m) {
;                 bf16_t* rowp = O + (size_t)(row0 + ai * HALF + m * 16) * ldo + col0;
; #pragma unroll
;                 for (int bj = 0; bj < 2; ++bj) {
;                     float v[8];
; #pragma unroll
;                     for (int n = 0; n < 2; ++n)
; #pragma unroll
;                         for (int j = 0; j < 4; ++j) { const float a = acc[ai][bj][m][n][j]; v[n * 4 + j] = kind == 1 ? gelu_f(a) : (kind == 2 ? a * 0.0625f : a); }
;                     u32x4 w; w.x = cvt_pk_bf16(v[0], v[1]); w.y = cvt_pk_bf16(v[2], v[3]); w.z = cvt_pk_bf16(v[4], v[5]); w.w = cvt_pk_bf16(v[6], v[7]);
;                     *(u32x4*)(rowp + bj * HALF) = w;
;                 }
	v_lshl_add_u32 v146, s6, 8, v140
	v_lshl_or_b32 v148, s68, 8, v142
	v_ashrrev_i32_e32 v147, 31, v146
	v_ashrrev_i32_e32 v149, 31, v148
	v_lshlrev_b64 v[150:151], 11, v[146:147]
	v_lshl_add_u64 v[150:151], s[8:9], 0, v[150:151]
	v_lshlrev_b64 v[148:149], 1, v[148:149]
	v_lshl_add_u64 v[150:151], v[150:151], 0, v[148:149]
	v_cvt_pk_bf16_f32 v60, v60, v61
	v_cvt_pk_bf16_f32 v61, v62, v63
	v_cvt_pk_bf16_f32 v62, v56, v57
	v_add_co_u32_e32 v56, vcc, s64, v150
	v_cvt_pk_bf16_f32 v68, v68, v69
	v_cvt_pk_bf16_f32 v69, v70, v71
	v_cvt_pk_bf16_f32 v70, v64, v65
	v_lshl_add_u64 v[64:65], v[150:151], 0, s[10:11]
	v_addc_co_u32_e32 v57, vcc, 0, v151, vcc
	v_cvt_pk_bf16_f32 v44, v44, v45
	v_cvt_pk_bf16_f32 v45, v46, v47
	v_cvt_pk_bf16_f32 v46, v40, v41
	v_cvt_pk_bf16_f32 v47, v42, v43
	v_cvt_pk_bf16_f32 v112, v112, v113
	v_cvt_pk_bf16_f32 v113, v114, v115
	v_cvt_pk_bf16_f32 v114, v104, v105
	v_or_b32_e32 v104, 16, v146
	global_store_dwordx4 v[64:65], v[44:47], off offset:256
	v_ashrrev_i32_e32 v105, 31, v104
	v_cvt_pk_bf16_f32 v96, v96, v97
	v_add_co_u32_e32 v46, vcc, s65, v150
	v_cvt_pk_bf16_f32 v97, v98, v99
	v_cvt_pk_bf16_f32 v98, v88, v89
	v_or_b32_e32 v88, 32, v146
	v_lshl_add_u64 v[44:45], v[150:151], 0, s[12:13]
	v_addc_co_u32_e32 v47, vcc, 0, v151, vcc
	v_cvt_pk_bf16_f32 v28, v28, v29
	v_cvt_pk_bf16_f32 v29, v30, v31
	v_cvt_pk_bf16_f32 v30, v24, v25
	v_cvt_pk_bf16_f32 v31, v26, v27
	v_lshlrev_b64 v[104:105], 11, v[104:105]
	v_ashrrev_i32_e32 v89, 31, v88
	v_cvt_pk_bf16_f32 v80, v80, v81
	v_cvt_pk_bf16_f32 v81, v82, v83
	v_cvt_pk_bf16_f32 v82, v72, v73
	v_or_b32_e32 v72, 48, v146
	global_store_dwordx4 v[44:45], v[28:31], off offset:256
	v_cvt_pk_bf16_f32 v115, v106, v107
	v_lshl_add_u64 v[104:105], s[8:9], 0, v[104:105]
	v_add_co_u32_e32 v30, vcc, s66, v150
	v_lshlrev_b64 v[88:89], 11, v[88:89]
	v_ashrrev_i32_e32 v73, 31, v72
	v_lshl_add_u64 v[28:29], v[150:151], 0, s[14:15]
	v_addc_co_u32_e32 v31, vcc, 0, v151, vcc
	v_cvt_pk_bf16_f32 v12, v12, v13
	v_cvt_pk_bf16_f32 v13, v14, v15
	v_cvt_pk_bf16_f32 v14, v8, v9
	v_cvt_pk_bf16_f32 v15, v10, v11
	global_store_dwordx4 v[150:151], v[112:115], off offset:256
	v_cvt_pk_bf16_f32 v99, v90, v91
	v_lshl_add_u64 v[88:89], s[8:9], 0, v[88:89]
	v_lshl_add_u64 v[112:113], v[104:105], 0, v[148:149]
	v_lshlrev_b64 v[72:73], 11, v[72:73]
	global_store_dwordx4 v[28:29], v[12:15], off offset:256
	global_store_dwordx4 v[112:113], v[96:99], off offset:256
	v_cvt_pk_bf16_f32 v83, v74, v75
	v_add_co_u32_e32 v14, vcc, s67, v150
	v_lshl_add_u64 v[96:97], v[88:89], 0, v[148:149]
	v_lshl_add_u64 v[72:73], s[8:9], 0, v[72:73]
	v_addc_co_u32_e32 v15, vcc, 0, v151, vcc
	v_cvt_pk_bf16_f32 v124, v124, v125
	v_cvt_pk_bf16_f32 v125, v126, v127
	v_cvt_pk_bf16_f32 v126, v120, v121
	v_cvt_pk_bf16_f32 v127, v122, v123
	v_cvt_pk_bf16_f32 v104, v116, v117
	v_cvt_pk_bf16_f32 v105, v118, v119
	v_cvt_pk_bf16_f32 v106, v108, v109
	v_cvt_pk_bf16_f32 v107, v110, v111
	v_cvt_pk_bf16_f32 v88, v100, v101
	v_cvt_pk_bf16_f32 v89, v102, v103
	v_cvt_pk_bf16_f32 v90, v92, v93
	v_cvt_pk_bf16_f32 v91, v94, v95
	global_store_dwordx4 v[96:97], v[80:83], off offset:256
	v_cvt_pk_bf16_f32 v74, v76, v77
	v_cvt_pk_bf16_f32 v75, v78, v79
	v_lshl_add_u64 v[80:81], v[72:73], 0, v[148:149]
	v_cvt_pk_bf16_f32 v72, v84, v85
	v_cvt_pk_bf16_f32 v73, v86, v87
	v_cvt_pk_bf16_f32 v71, v66, v67
	v_cvt_pk_bf16_f32 v63, v58, v59
	v_cvt_pk_bf16_f32 v40, v52, v53
	v_cvt_pk_bf16_f32 v41, v54, v55
	v_cvt_pk_bf16_f32 v42, v48, v49
	v_cvt_pk_bf16_f32 v43, v50, v51
	v_cvt_pk_bf16_f32 v24, v36, v37
	v_cvt_pk_bf16_f32 v25, v38, v39
	v_cvt_pk_bf16_f32 v26, v32, v33
	v_cvt_pk_bf16_f32 v27, v34, v35
	v_lshl_add_u64 v[12:13], v[150:151], 0, s[16:17]
	v_cvt_pk_bf16_f32 v8, v20, v21
	v_cvt_pk_bf16_f32 v9, v22, v23
	v_cvt_pk_bf16_f32 v10, v16, v17
	v_cvt_pk_bf16_f32 v11, v18, v19
	v_cvt_pk_bf16_f32 v4, v4, v5
	v_cvt_pk_bf16_f32 v5, v6, v7
	v_cvt_pk_bf16_f32 v6, v0, v1
	v_cvt_pk_bf16_f32 v7, v2, v3
	s_and_b64 vcc, exec, s[18:19]
	s_mov_b32 s68, s28
	s_mov_b32 s6, s36
	s_mov_b64 s[44:45], s[40:41]
	s_mov_b64 s[42:43], s[38:39]
	global_store_dwordx4 v[150:151], v[124:127], off
	global_store_dwordx4 v[112:113], v[104:107], off
	global_store_dwordx4 v[96:97], v[88:91], off
	global_store_dwordx4 v[80:81], v[72:75], off
	global_store_dwordx4 v[80:81], v[68:71], off offset:256
	global_store_dwordx4 v[56:57], v[60:63], off
	global_store_dwordx4 v[46:47], v[40:43], off
	global_store_dwordx4 v[30:31], v[24:27], off
	global_store_dwordx4 v[14:15], v[8:11], off
	global_store_dwordx4 v[12:13], v[4:7], off offset:256
	s_cbranch_vccz .LBB0_158
	s_waitcnt vmcnt(0)
	s_cmpk_gt_u32 s50, 0xff
	s_cbranch_scc1 .LBB0_165
	s_barrier

; #define PG8_STAGE(bufoff, gbase, voff) do { _Pragma("unroll") for (int _i = 0; _i < 2; ++_i) \
;         __builtin_amdgcn_global_load_lds((const unsigned*)((const char*)(gbase) + (voff)[_i]), (LAS unsigned*)(lds + (bufoff) + ldsw + _i * 8192), 16, 0, 0); } while (0)
; #define PG8_LDA(dst, b, h) do { _Pragma("unroll") for (int m = 0; m < 4; ++m) _Pragma("unroll") for (int k = 0; k < 2; ++k) dst[m][k] = *(const LAS bf16x8*)(lds + PG8_SA(b, h) + aoff + m * 2048 + k * 1024); } while (0)
; #define PG8_LDB(dst, b, h) do { _Pragma("unroll") for (int n = 0; n < 2; ++n) _Pragma("unroll") for (int k = 0; k < 2; ++k) dst[n][k] = *(const LAS bf16x8*)(lds + PG8_SB(b, h) + boff + n * 2048 + k * 1024); } while (0)
; #define PG8_MMA(ai, bj, At, Bt) do { __builtin_amdgcn_s_setprio(1); _Pragma("unroll") for (int m = 0; m < 4; ++m) _Pragma("unroll") for (int n = 0; n < 2; ++n) _Pragma("unroll") for (int k = 0; k < 2; ++k) \
;         acc[ai][bj][m][n] = __builtin_amdgcn_mfma_f32_16x16x32_bf16(Bt[n][k], At[m][k], acc[ai][bj][m][n], 0, 0, 0); __builtin_amdgcn_s_setprio(0); } while (0)
; #define PG8_WAIT_L(n) asm volatile("s_waitcnt lgkmcnt(" #n ")" ::: "memory")
; #define PG8_BAR __builtin_amdgcn_s_barrier()
; #define PG8_SCHED __builtin_amdgcn_sched_barrier(0)
; template <class Epi, class Sched>
; __device__ __forceinline__ void gemm_phase(LAS unsigned char* lds, const Gemm g, const Sched& S, const Epi& E) {
;     ...
;         for (int t = 0; t < nt; t += 2) {
;             const bool last = (t == nt - 2);
;             const char* a1 = cA + (size_t)(t + 1) * kstep;
;             const char* a2 = last ? nA : cA + (size_t)(t + 2) * kstep; const char* b2 = last ? nB : cB + (size_t)(t + 2) * kstep;
;             const char* a3 = a2 + kstep; const char* b3 = b2 + kstep;
;             PG8_LDB(B0, 0, 0); PG8_SCHED; PG8_LDA(At, 0, 0); PG8_STAGE(PG8_SA(1, 1), a1 + hstep, voffA);
;             PG8_WAIT_L(8); PG8_BAR; PG8_WAIT_L(0); PG8_MMA(0, 0, At, B0); PG8_BAR; PG8_SCHED;
;             PG8_LDB(B1, 0, 1); PG8_STAGE(PG8_SB(0, 0), b2, voffB);
;             PG8_BAR; PG8_WAIT_L(0); PG8_MMA(0, 1, At, B1); PG8_BAR;
;             PG8_LDA(At, 0, 1); PG8_STAGE(PG8_SA(0, 0), a2, voffA);
;             PG8_BAR; PG8_WAIT_L(0); PG8_MMA(1, 0, At, B0); PG8_BAR; PG8_SCHED;
.LBB0_240:
	ds_read_b128 v[128:131], v172
	ds_read_b128 v[132:135], v172 offset:1024
	ds_read_b128 v[136:139], v172 offset:2048
	ds_read_b128 v[140:143], v172 offset:3072
	s_add_u32 s38, s36, 0x4000
	s_addc_u32 s39, s37, 0
	s_cmpk_eq_i32 s68, 0x52
	s_cselect_b32 s42, s8, s38
	s_cselect_b32 s43, s9, s39
	s_cselect_b32 s38, s10, s66
	s_cselect_b32 s39, s11, s67
	s_add_u32 s40, s42, 0x8000
	s_addc_u32 s41, s43, 0
	v_lshl_add_u64 v[166:167], s[36:37], 0, v[150:151]
	s_add_i32 m0, s48, 0xc000
	ds_read_b128 v[158:161], v173
	ds_read_b128 v[162:165], v173 offset:1024
	ds_read_b128 v[176:179], v173 offset:2048
	ds_read_b128 v[180:183], v173 offset:3072
	ds_read_b128 v[184:187], v173 offset:4096
	ds_read_b128 v[188:191], v173 offset:5120
	ds_read_b128 v[192:195], v173 offset:6144
	ds_read_b128 v[196:199], v173 offset:7168
	global_load_lds_dwordx4 v[166:167], off
	v_lshl_add_u64 v[166:167], s[36:37], 0, v[152:153]
	s_add_i32 m0, s48, 0xe000
	s_nop 0
	global_load_lds_dwordx4 v[166:167], off
	s_waitcnt lgkmcnt(8)
	s_barrier
	s_waitcnt lgkmcnt(0)
	s_waitcnt lgkmcnt(0)
	v_mfma_f32_16x16x32_bf16 v[124:127], v[128:131], v[158:161], v[124:127]
	v_mfma_f32_16x16x32_bf16 v[120:123], v[136:139], v[158:161], v[120:123]
	v_mfma_f32_16x16x32_bf16 v[108:111], v[128:131], v[176:179], v[108:111]
	v_mfma_f32_16x16x32_bf16 v[104:107], v[136:139], v[176:179], v[104:107]
	v_mfma_f32_16x16x32_bf16 v[92:95], v[128:131], v[184:187], v[92:95]
	v_mfma_f32_16x16x32_bf16 v[88:91], v[136:139], v[184:187], v[88:91]
	v_mfma_f32_16x16x32_bf16 v[84:87], v[128:131], v[192:195], v[84:87]
	v_mfma_f32_16x16x32_bf16 v[80:83], v[136:139], v[192:195], v[80:83]
	v_mfma_f32_16x16x32_bf16 v[124:127], v[132:135], v[162:165], v[124:127]
	v_mfma_f32_16x16x32_bf16 v[120:123], v[140:143], v[162:165], v[120:123]
	v_mfma_f32_16x16x32_bf16 v[108:111], v[132:135], v[180:183], v[108:111]
	v_mfma_f32_16x16x32_bf16 v[104:107], v[140:143], v[180:183], v[104:107]
	v_mfma_f32_16x16x32_bf16 v[92:95], v[132:135], v[188:191], v[92:95]
	v_mfma_f32_16x16x32_bf16 v[88:91], v[140:143], v[188:191], v[88:91]
	v_mfma_f32_16x16x32_bf16 v[84:87], v[132:135], v[196:199], v[84:87]
	v_mfma_f32_16x16x32_bf16 v[80:83], v[140:143], v[196:199], v[80:83]
	s_barrier
	s_add_i32 s69, s56, s47
	v_lshl_add_u64 v[166:167], s[38:39], 0, v[144:145]
	s_mov_b32 m0, s69
	ds_read_b128 v[200:203], v174
	ds_read_b128 v[206:209], v174 offset:1024
	ds_read_b128 v[210:213], v174 offset:2048
	ds_read_b128 v[214:217], v174 offset:3072
	global_load_lds_dwordx4 v[166:167], off
	v_lshl_add_u64 v[166:167], s[38:39], 0, v[146:147]
	s_add_i32 m0, s69, 0x2000
	s_nop 0
	global_load_lds_dwordx4 v[166:167], off
	s_barrier
	s_waitcnt lgkmcnt(0)
	s_waitcnt lgkmcnt(0)
	v_mfma_f32_16x16x32_bf16 v[116:119], v[200:203], v[158:161], v[116:119]
	v_mfma_f32_16x16x32_bf16 v[112:115], v[210:213], v[158:161], v[112:115]
	v_mfma_f32_16x16x32_bf16 v[100:103], v[200:203], v[176:179], v[100:103]
	v_mfma_f32_16x16x32_bf16 v[96:99], v[210:213], v[176:179], v[96:99]
	v_mfma_f32_16x16x32_bf16 v[76:79], v[200:203], v[184:187], v[76:79]
	v_mfma_f32_16x16x32_bf16 v[72:75], v[210:213], v[184:187], v[72:75]
	v_mfma_f32_16x16x32_bf16 v[68:71], v[200:203], v[192:195], v[68:71]
	v_mfma_f32_16x16x32_bf16 v[64:67], v[210:213], v[192:195], v[64:67]
	v_mfma_f32_16x16x32_bf16 v[116:119], v[206:209], v[162:165], v[116:119]
	v_mfma_f32_16x16x32_bf16 v[112:115], v[214:217], v[162:165], v[112:115]
	v_mfma_f32_16x16x32_bf16 v[100:103], v[206:209], v[180:183], v[100:103]
	v_mfma_f32_16x16x32_bf16 v[96:99], v[214:217], v[180:183], v[96:99]
	v_mfma_f32_16x16x32_bf16 v[76:79], v[206:209], v[188:191], v[76:79]
	v_mfma_f32_16x16x32_bf16 v[72:75], v[214:217], v[188:191], v[72:75]
	v_mfma_f32_16x16x32_bf16 v[68:71], v[206:209], v[196:199], v[68:71]
	v_mfma_f32_16x16x32_bf16 v[64:67], v[214:217], v[196:199], v[64:67]
	s_mov_b32 m0, s48
	v_lshl_add_u64 v[166:167], s[42:43], 0, v[144:145]
	s_barrier
	ds_read_b128 v[158:161], v173 offset:16384
	ds_read_b128 v[162:165], v173 offset:17408
	ds_read_b128 v[176:179], v173 offset:18432
	ds_read_b128 v[180:183], v173 offset:19456
	ds_read_b128 v[184:187], v173 offset:20480
	ds_read_b128 v[188:191], v173 offset:21504
	ds_read_b128 v[192:195], v173 offset:22528
	ds_read_b128 v[196:199], v173 offset:23552
	global_load_lds_dwordx4 v[166:167], off
	v_lshl_add_u64 v[166:167], s[42:43], 0, v[146:147]
	s_mov_b32 m0, s49
	s_nop 0
	global_load_lds_dwordx4 v[166:167], off
	s_barrier
	s_waitcnt lgkmcnt(0)
	s_waitcnt lgkmcnt(0)
	v_mfma_f32_16x16x32_bf16 v[60:63], v[128:131], v[158:161], v[60:63]
	v_mfma_f32_16x16x32_bf16 v[56:59], v[136:139], v[158:161], v[56:59]
	v_mfma_f32_16x16x32_bf16 v[44:47], v[128:131], v[176:179], v[44:47]
	v_mfma_f32_16x16x32_bf16 v[40:43], v[136:139], v[176:179], v[40:43]
	v_mfma_f32_16x16x32_bf16 v[28:31], v[128:131], v[184:187], v[28:31]
	v_mfma_f32_16x16x32_bf16 v[24:27], v[136:139], v[184:187], v[24:27]
	v_mfma_f32_16x16x32_bf16 v[20:23], v[128:131], v[192:195], v[20:23]
	v_mfma_f32_16x16x32_bf16 v[16:19], v[136:139], v[192:195], v[16:19]
	v_mfma_f32_16x16x32_bf16 v[60:63], v[132:135], v[162:165], v[60:63]
	v_mfma_f32_16x16x32_bf16 v[56:59], v[140:143], v[162:165], v[56:59]
	v_mfma_f32_16x16x32_bf16 v[44:47], v[132:135], v[180:183], v[44:47]
	v_mfma_f32_16x16x32_bf16 v[40:43], v[140:143], v[180:183], v[40:43]
	v_mfma_f32_16x16x32_bf16 v[28:31], v[132:135], v[188:191], v[28:31]
	v_mfma_f32_16x16x32_bf16 v[24:27], v[140:143], v[188:191], v[24:27]
	v_mfma_f32_16x16x32_bf16 v[20:23], v[132:135], v[196:199], v[20:23]
	v_mfma_f32_16x16x32_bf16 v[16:19], v[140:143], v[196:199], v[16:19]
	s_barrier
; #define PG8_STAGE(bufoff, gbase, voff) do { _Pragma("unroll") for (int _i = 0; _i < 2; ++_i) \
;         __builtin_amdgcn_global_load_lds((const unsigned*)((const char*)(gbase) + (voff)[_i]), (LAS unsigned*)(lds + (bufoff) + ldsw + _i * 8192), 16, 0, 0); } while (0)
; #define PG8_LDA(dst, b, h) do { _Pragma("unroll") for (int m = 0; m < 4; ++m) _Pragma("unroll") for (int k = 0; k < 2; ++k) dst[m][k] = *(const LAS bf16x8*)(lds + PG8_SA(b, h) + aoff + m * 2048 + k * 1024); } while (0)
; #define PG8_LDB(dst, b, h) do { _Pragma("unroll") for (int n = 0; n < 2; ++n) _Pragma("unroll") for (int k = 0; k < 2; ++k) dst[n][k] = *(const LAS bf16x8*)(lds + PG8_SB(b, h) + boff + n * 2048 + k * 1024); } while (0)
; #define PG8_MMA(ai, bj, At, Bt) do { __builtin_amdgcn_s_setprio(1); _Pragma("unroll") for (int m = 0; m < 4; ++m) _Pragma("unroll") for (int n = 0; n < 2; ++n) _Pragma("unroll") for (int k = 0; k < 2; ++k) \
;         acc[ai][bj][m][n] = __builtin_amdgcn_mfma_f32_16x16x32_bf16(Bt[n][k], At[m][k], acc[ai][bj][m][n], 0, 0, 0); __builtin_amdgcn_s_setprio(0); } while (0)
; #define PG8_WAIT_V(n) asm volatile("s_waitcnt vmcnt(" #n ")" ::: "memory")
; #define PG8_WAIT_L(n) asm volatile("s_waitcnt lgkmcnt(" #n ")" ::: "memory")
; #define PG8_BAR __builtin_amdgcn_s_barrier()
; #define PG8_SCHED __builtin_amdgcn_sched_barrier(0)
; template <class Epi, class Sched>
; __device__ __forceinline__ void gemm_phase(LAS unsigned char* lds, const Gemm g, const Sched& S, const Epi& E) {
;     ...
;             PG8_STAGE(PG8_SB(0, 1), b2 + hstep, voffB);
;             PG8_WAIT_V(6); PG8_BAR; PG8_MMA(1, 1, At, B1); PG8_BAR;
;             PG8_LDB(B0, 1, 0); PG8_SCHED; PG8_LDA(At, 1, 0); PG8_STAGE(PG8_SA(0, 1), a2 + hstep, voffA);
;             PG8_WAIT_L(8); PG8_BAR; PG8_WAIT_L(0); PG8_MMA(0, 0, At, B0); PG8_BAR; PG8_SCHED;
;             PG8_LDB(B1, 1, 1); PG8_STAGE(PG8_SB(1, 0), b3, voffB);
;             PG8_BAR; PG8_WAIT_L(0); PG8_MMA(0, 1, At, B1); PG8_BAR;
;             PG8_LDA(At, 1, 1); PG8_STAGE(PG8_SA(1, 0), a3, voffA);
	s_add_u32 s70, s38, 0x4000
	s_addc_u32 s71, s39, 0
	s_add_i32 s69, s57, s47
	v_lshl_add_u64 v[128:129], s[70:71], 0, v[144:145]
	s_mov_b32 m0, s69
	s_nop 0
	global_load_lds_dwordx4 v[128:129], off
	v_lshl_add_u64 v[128:129], s[70:71], 0, v[146:147]
	s_add_i32 m0, s69, 0x2000
	s_nop 0
	global_load_lds_dwordx4 v[128:129], off
	s_waitcnt vmcnt(6)
	s_barrier
	v_mfma_f32_16x16x32_bf16 v[52:55], v[200:203], v[158:161], v[52:55]
	v_mfma_f32_16x16x32_bf16 v[48:51], v[210:213], v[158:161], v[48:51]
	v_mfma_f32_16x16x32_bf16 v[36:39], v[200:203], v[176:179], v[36:39]
	v_mfma_f32_16x16x32_bf16 v[32:35], v[210:213], v[176:179], v[32:35]
	v_mfma_f32_16x16x32_bf16 v[12:15], v[200:203], v[184:187], v[12:15]
	v_mfma_f32_16x16x32_bf16 v[8:11], v[210:213], v[184:187], v[8:11]
	v_mfma_f32_16x16x32_bf16 v[4:7], v[200:203], v[192:195], v[4:7]
	v_mfma_f32_16x16x32_bf16 v[0:3], v[210:213], v[192:195], v[0:3]
	v_mfma_f32_16x16x32_bf16 v[52:55], v[206:209], v[162:165], v[52:55]
	v_mfma_f32_16x16x32_bf16 v[48:51], v[214:217], v[162:165], v[48:51]
	v_mfma_f32_16x16x32_bf16 v[36:39], v[206:209], v[180:183], v[36:39]
	v_mfma_f32_16x16x32_bf16 v[32:35], v[214:217], v[180:183], v[32:35]
	v_mfma_f32_16x16x32_bf16 v[12:15], v[206:209], v[188:191], v[12:15]
	v_mfma_f32_16x16x32_bf16 v[8:11], v[214:217], v[188:191], v[8:11]
	v_mfma_f32_16x16x32_bf16 v[4:7], v[206:209], v[196:199], v[4:7]
	v_mfma_f32_16x16x32_bf16 v[0:3], v[214:217], v[196:199], v[0:3]
	s_add_i32 s69, 0, 0x18000
	v_add_u32_e32 v140, s69, v170
	s_barrier
	ds_read_b128 v[128:131], v140
	ds_read_b128 v[132:135], v140 offset:1024
	ds_read_b128 v[136:139], v140 offset:2048
	ds_read_b128 v[140:143], v140 offset:3072
	s_add_u32 s42, s42, 0x4000
	s_addc_u32 s43, s43, 0
	s_mov_b32 m0, s50
	v_lshl_add_u64 v[166:167], s[42:43], 0, v[144:145]
	ds_read_b128 v[158:161], v173 offset:32768
	ds_read_b128 v[162:165], v173 offset:33792
	ds_read_b128 v[176:179], v173 offset:34816
	ds_read_b128 v[180:183], v173 offset:35840
	ds_read_b128 v[184:187], v173 offset:36864
	ds_read_b128 v[188:191], v173 offset:37888
	ds_read_b128 v[192:195], v173 offset:38912
	ds_read_b128 v[196:199], v173 offset:39936
	global_load_lds_dwordx4 v[166:167], off
	v_lshl_add_u64 v[166:167], s[42:43], 0, v[146:147]
	s_mov_b32 m0, s51
	s_nop 0
	global_load_lds_dwordx4 v[166:167], off
	s_waitcnt lgkmcnt(8)
	s_barrier
	s_waitcnt lgkmcnt(0)
	s_waitcnt lgkmcnt(0)
	v_mfma_f32_16x16x32_bf16 v[124:127], v[128:131], v[158:161], v[124:127]
	v_mfma_f32_16x16x32_bf16 v[120:123], v[136:139], v[158:161], v[120:123]
	v_mfma_f32_16x16x32_bf16 v[108:111], v[128:131], v[176:179], v[108:111]
	v_mfma_f32_16x16x32_bf16 v[104:107], v[136:139], v[176:179], v[104:107]
	v_mfma_f32_16x16x32_bf16 v[92:95], v[128:131], v[184:187], v[92:95]
	v_mfma_f32_16x16x32_bf16 v[88:91], v[136:139], v[184:187], v[88:91]
	v_mfma_f32_16x16x32_bf16 v[84:87], v[128:131], v[192:195], v[84:87]
	v_mfma_f32_16x16x32_bf16 v[80:83], v[136:139], v[192:195], v[80:83]
	v_mfma_f32_16x16x32_bf16 v[124:127], v[132:135], v[162:165], v[124:127]
	v_mfma_f32_16x16x32_bf16 v[120:123], v[140:143], v[162:165], v[120:123]
	v_mfma_f32_16x16x32_bf16 v[108:111], v[132:135], v[180:183], v[108:111]
	v_mfma_f32_16x16x32_bf16 v[104:107], v[140:143], v[180:183], v[104:107]
	v_mfma_f32_16x16x32_bf16 v[92:95], v[132:135], v[188:191], v[92:95]
	v_mfma_f32_16x16x32_bf16 v[88:91], v[140:143], v[188:191], v[88:91]
	v_mfma_f32_16x16x32_bf16 v[84:87], v[132:135], v[196:199], v[84:87]
	v_mfma_f32_16x16x32_bf16 v[80:83], v[140:143], v[196:199], v[80:83]
	s_barrier
	s_add_i32 s70, 0, 0x1c000
	s_add_u32 s42, s38, 0x8000
	s_addc_u32 s43, s39, 0
	s_add_i32 s69, s69, s47
	v_add_u32_e32 v148, s70, v170
	v_lshl_add_u64 v[166:167], s[42:43], 0, v[144:145]
	s_mov_b32 m0, s69
	ds_read_b128 v[200:203], v148
	ds_read_b128 v[206:209], v148 offset:1024
	ds_read_b128 v[210:213], v148 offset:2048
	ds_read_b128 v[214:217], v148 offset:3072
	global_load_lds_dwordx4 v[166:167], off
	v_lshl_add_u64 v[166:167], s[42:43], 0, v[146:147]
	s_add_i32 m0, s69, 0x2000
	s_nop 0
	global_load_lds_dwordx4 v[166:167], off
	s_barrier
	s_waitcnt lgkmcnt(0)
	s_waitcnt lgkmcnt(0)
	v_mfma_f32_16x16x32_bf16 v[116:119], v[200:203], v[158:161], v[116:119]
	v_mfma_f32_16x16x32_bf16 v[112:115], v[210:213], v[158:161], v[112:115]
	v_mfma_f32_16x16x32_bf16 v[100:103], v[200:203], v[176:179], v[100:103]
	v_mfma_f32_16x16x32_bf16 v[96:99], v[210:213], v[176:179], v[96:99]
	v_mfma_f32_16x16x32_bf16 v[76:79], v[200:203], v[184:187], v[76:79]
	v_mfma_f32_16x16x32_bf16 v[72:75], v[210:213], v[184:187], v[72:75]
	v_mfma_f32_16x16x32_bf16 v[68:71], v[200:203], v[192:195], v[68:71]
	v_mfma_f32_16x16x32_bf16 v[64:67], v[210:213], v[192:195], v[64:67]
	v_mfma_f32_16x16x32_bf16 v[116:119], v[206:209], v[162:165], v[116:119]
	v_mfma_f32_16x16x32_bf16 v[112:115], v[214:217], v[162:165], v[112:115]
	v_mfma_f32_16x16x32_bf16 v[100:103], v[206:209], v[180:183], v[100:103]
	v_mfma_f32_16x16x32_bf16 v[96:99], v[214:217], v[180:183], v[96:99]
	v_mfma_f32_16x16x32_bf16 v[76:79], v[206:209], v[188:191], v[76:79]
	v_mfma_f32_16x16x32_bf16 v[72:75], v[214:217], v[188:191], v[72:75]
	v_mfma_f32_16x16x32_bf16 v[68:71], v[206:209], v[196:199], v[68:71]
	v_mfma_f32_16x16x32_bf16 v[64:67], v[214:217], v[196:199], v[64:67]
	s_mov_b32 m0, s54
	v_lshl_add_u64 v[166:167], s[40:41], 0, v[144:145]
	s_barrier
	ds_read_b128 v[158:161], v173 offset:49152
	ds_read_b128 v[162:165], v173 offset:50176
	ds_read_b128 v[176:179], v173 offset:51200
	ds_read_b128 v[180:183], v173 offset:52224
	ds_read_b128 v[184:187], v173 offset:53248
	ds_read_b128 v[188:191], v173 offset:54272
	ds_read_b128 v[192:195], v173 offset:55296
	ds_read_b128 v[196:199], v173 offset:56320
	global_load_lds_dwordx4 v[166:167], off
	v_lshl_add_u64 v[166:167], s[40:41], 0, v[146:147]
	s_mov_b32 m0, s55
	s_nop 0
	global_load_lds_dwordx4 v[166:167], off
	s_barrier
; #define PG8_STAGE(bufoff, gbase, voff) do { _Pragma("unroll") for (int _i = 0; _i < 2; ++_i) \
;         __builtin_amdgcn_global_load_lds((const unsigned*)((const char*)(gbase) + (voff)[_i]), (LAS unsigned*)(lds + (bufoff) + ldsw + _i * 8192), 16, 0, 0); } while (0)
; #define PG8_MMA(ai, bj, At, Bt) do { __builtin_amdgcn_s_setprio(1); _Pragma("unroll") for (int m = 0; m < 4; ++m) _Pragma("unroll") for (int n = 0; n < 2; ++n) _Pragma("unroll") for (int k = 0; k < 2; ++k) \
;         acc[ai][bj][m][n] = __builtin_amdgcn_mfma_f32_16x16x32_bf16(Bt[n][k], At[m][k], acc[ai][bj][m][n], 0, 0, 0); __builtin_amdgcn_s_setprio(0); } while (0)
; #define PG8_WAIT_V(n) asm volatile("s_waitcnt vmcnt(" #n ")" ::: "memory")
; template <class Epi, class Sched>
; __device__ __forceinline__ void gemm_phase(LAS unsigned char* lds, const Gemm g, const Sched& S, const Epi& E) {
;     ...
;             PG8_BAR; PG8_WAIT_L(0); PG8_MMA(1, 0, At, B0); PG8_BAR; PG8_SCHED;
;             PG8_STAGE(PG8_SB(1, 1), b3 + hstep, voffB);
;             PG8_WAIT_V(6); PG8_BAR; PG8_MMA(1, 1, At, B1); PG8_BAR;
;         }
;     __device__ __forceinline__ void operator()(const f32x4 (&acc)[2][2][4][2], const Unit& u, int wr, int wc, int fr, int fq) const {
;         const int row0 = u.pm * BM + wr * 64 + fr, col0 = u.pn * BM + wc * 32 + 4 * fq;
;         f32x4 gv[2][2], bv[2][2];
;         if (MODE == 1) {
; #pragma unroll
;             for (int bj = 0; bj < 2; ++bj)
; #pragma unroll
;                 for (int n = 0; n < 2; ++n) { gv[bj][n] = *(const f32x4*)(g + col0 + bj * HALF + n * 16); bv[bj][n] = *(const f32x4*)(b + col0 + bj * HALF + n * 16); }
;         }
; #pragma unroll
;         for (int ai = 0; ai < 2; ++ai)
; #pragma unroll
;             for (int mh = 0; mh < 2; ++mh) {
;                 f32x4 rv[2][2][2]; f32x2 st[2];
; #pragma unroll
;                 for (int mm = 0; mm < 2; ++mm) {
;                     const int r = row0 + ai * HALF + (mh * 2 + mm) * 16;
;                     const float* rp = MODE == 0 ? ((r < 8192 ? x0 + (size_t)r * DM : x1 + (size_t)(r - 8192) * DM) + col0) : (Z + (size_t)r * DM + col0);
;                     if (MODE == 1) st[mm] = stats[r];
; #pragma unroll
;                     for (int bj = 0; bj < 2; ++bj)
; #pragma unroll
;                         for (int n = 0; n < 2; ++n) rv[mm][bj][n] = *(const f32x4*)(rp + bj * HALF + n * 16);
	s_waitcnt lgkmcnt(0)
	s_waitcnt lgkmcnt(0)
	v_mfma_f32_16x16x32_bf16 v[60:63], v[128:131], v[158:161], v[60:63]
	v_mfma_f32_16x16x32_bf16 v[56:59], v[136:139], v[158:161], v[56:59]
	v_mfma_f32_16x16x32_bf16 v[44:47], v[128:131], v[176:179], v[44:47]
	v_mfma_f32_16x16x32_bf16 v[40:43], v[136:139], v[176:179], v[40:43]
	v_mfma_f32_16x16x32_bf16 v[28:31], v[128:131], v[184:187], v[28:31]
	v_mfma_f32_16x16x32_bf16 v[24:27], v[136:139], v[184:187], v[24:27]
	v_mfma_f32_16x16x32_bf16 v[20:23], v[128:131], v[192:195], v[20:23]
	v_mfma_f32_16x16x32_bf16 v[16:19], v[136:139], v[192:195], v[16:19]
	v_mfma_f32_16x16x32_bf16 v[60:63], v[132:135], v[162:165], v[60:63]
	v_mfma_f32_16x16x32_bf16 v[56:59], v[140:143], v[162:165], v[56:59]
	v_mfma_f32_16x16x32_bf16 v[44:47], v[132:135], v[180:183], v[44:47]
	v_mfma_f32_16x16x32_bf16 v[40:43], v[140:143], v[180:183], v[40:43]
	v_mfma_f32_16x16x32_bf16 v[28:31], v[132:135], v[188:191], v[28:31]
	v_mfma_f32_16x16x32_bf16 v[24:27], v[140:143], v[188:191], v[24:27]
	v_mfma_f32_16x16x32_bf16 v[20:23], v[132:135], v[196:199], v[20:23]
	v_mfma_f32_16x16x32_bf16 v[16:19], v[140:143], v[196:199], v[16:19]
	s_barrier
	s_add_u32 s38, s38, 0xc000
	s_addc_u32 s39, s39, 0
	s_add_i32 s40, s70, s47
	v_lshl_add_u64 v[128:129], s[38:39], 0, v[144:145]
	s_mov_b32 m0, s40
	s_nop 0
	global_load_lds_dwordx4 v[128:129], off
	v_lshl_add_u64 v[128:129], s[38:39], 0, v[146:147]
	s_add_i32 m0, s40, 0x2000
	s_nop 0
	global_load_lds_dwordx4 v[128:129], off
	s_waitcnt vmcnt(6)
	s_barrier
	v_mfma_f32_16x16x32_bf16 v[52:55], v[200:203], v[158:161], v[52:55]
	v_mfma_f32_16x16x32_bf16 v[48:51], v[210:213], v[158:161], v[48:51]
	v_mfma_f32_16x16x32_bf16 v[36:39], v[200:203], v[176:179], v[36:39]
	v_mfma_f32_16x16x32_bf16 v[32:35], v[210:213], v[176:179], v[32:35]
	v_mfma_f32_16x16x32_bf16 v[12:15], v[200:203], v[184:187], v[12:15]
	v_mfma_f32_16x16x32_bf16 v[8:11], v[210:213], v[184:187], v[8:11]
	v_mfma_f32_16x16x32_bf16 v[4:7], v[200:203], v[192:195], v[4:7]
	v_mfma_f32_16x16x32_bf16 v[0:3], v[210:213], v[192:195], v[0:3]
	v_mfma_f32_16x16x32_bf16 v[52:55], v[206:209], v[162:165], v[52:55]
	v_mfma_f32_16x16x32_bf16 v[48:51], v[214:217], v[162:165], v[48:51]
	v_mfma_f32_16x16x32_bf16 v[36:39], v[206:209], v[180:183], v[36:39]
	v_mfma_f32_16x16x32_bf16 v[32:35], v[214:217], v[180:183], v[32:35]
	v_mfma_f32_16x16x32_bf16 v[12:15], v[206:209], v[188:191], v[12:15]
	v_mfma_f32_16x16x32_bf16 v[8:11], v[214:217], v[188:191], v[8:11]
	v_mfma_f32_16x16x32_bf16 v[4:7], v[206:209], v[196:199], v[4:7]
	v_mfma_f32_16x16x32_bf16 v[0:3], v[214:217], v[196:199], v[0:3]
	s_add_i32 s68, s68, 2
	s_add_u32 s36, s36, 0x10000
	s_addc_u32 s37, s37, 0
	s_add_u32 s66, s66, 0x10000
	s_addc_u32 s67, s67, 0
	s_cmpk_gt_u32 s68, 0x53
	s_barrier
	s_cbranch_scc0 .LBB0_240
	v_lshl_add_u32 v160, s33, 8, v169
	v_add_u32_e32 v128, 0xffffe000, v160
	v_ashrrev_i32_e32 v161, 31, v160
	v_cmp_gt_i32_e32 vcc, s52, v160
	v_mov_b32_e32 v130, s19
	v_mov_b32_e32 v131, s17
	v_cndmask_b32_e32 v129, 0, v161, vcc
	v_cndmask_b32_e32 v128, v128, v160, vcc
	v_cndmask_b32_e32 v131, v130, v131, vcc
	v_mov_b32_e32 v130, s18
	v_mov_b32_e32 v132, s16
	v_lshl_or_b32 v158, s65, 8, v171
	v_cndmask_b32_e32 v130, v130, v132, vcc
	v_lshlrev_b64 v[128:129], 13, v[128:129]
	v_ashrrev_i32_e32 v159, 31, v158
	v_lshl_add_u64 v[128:129], v[130:131], 0, v[128:129]
	v_lshl_add_u64 v[128:129], v[158:159], 2, v[128:129]
	global_load_dwordx4 v[140:143], v[128:129], off
	global_load_dwordx4 v[136:139], v[128:129], off offset:64
	global_load_dwordx4 v[132:135], v[128:129], off offset:512
	s_nop 0
	global_load_dwordx4 v[128:131], v[128:129], off offset:576
	v_or_b32_e32 v164, 16, v160
	v_cmp_lt_i32_e32 vcc, s58, v164
	s_and_saveexec_b64 s[36:37], vcc
	s_xor_b64 s[36:37], exec, s[36:37]
	v_add_u32_e32 v148, 0xffffe010, v160
	v_lshlrev_b64 v[162:163], 13, v[148:149]
	v_mov_b32_e32 v165, v149
	v_lshl_add_u64 v[166:167], s[18:19], 0, v[162:163]
	v_lshlrev_b64 v[162:163], 13, v[164:165]
	s_andn2_saveexec_b64 s[36:37], s[36:37]
	v_ashrrev_i32_e32 v165, 31, v164
	v_lshlrev_b64 v[162:163], 13, v[164:165]
	v_lshl_add_u64 v[166:167], s[16:17], 0, v[162:163]
	s_or_b64 exec, exec, s[36:37]
	v_lshlrev_b64 v[158:159], 2, v[158:159]
	v_lshl_add_u64 v[184:185], v[166:167], 0, v[158:159]
	global_load_dwordx4 v[164:167], v[184:185], off
	global_load_dwordx4 v[176:179], v[184:185], off offset:64
	global_load_dwordx4 v[180:183], v[184:185], off offset:512
	s_nop 0
	global_load_dwordx4 v[184:187], v[184:185], off offset:576
	v_lshlrev_b64 v[188:189], 13, v[160:161]
	s_waitcnt vmcnt(0)
;     __device__ __forceinline__ void operator()(const f32x4 (&acc)[2][2][4][2], const Unit& u, int wr, int wc, int fr, int fq) const {
;     ...
;                     const int r = row0 + ai * HALF + (mh * 2 + mm) * 16;
;                     const float* rp = MODE == 0 ? ((r < 8192 ? x0 + (size_t)r * DM : x1 + (size_t)(r - 8192) * DM) + col0) : (Z + (size_t)r * DM + col0);
;                     if (MODE == 1) st[mm] = stats[r];
; #pragma unroll
;                     for (int bj = 0; bj < 2; ++bj)
; #pragma unroll
;                         for (int n = 0; n < 2; ++n) rv[mm][bj][n] = *(const f32x4*)(rp + bj * HALF + n * 16);
;     ...
; #pragma unroll
;                 for (int mm = 0; mm < 2; ++mm) {
;                     const int m = mh * 2 + mm, r = row0 + ai * HALF + m * 16;
;                     float* zp = Z + (size_t)r * DM + col0;
; #pragma unroll
;                     for (int bj = 0; bj < 2; ++bj)
; #pragma unroll
;                         for (int n = 0; n < 2; ++n) {
;                             f32x4 res = rv[mm][bj][n];
;                             if (MODE == 1) res = (res - st[mm].x) * st[mm].y * gv[bj][n] + bv[bj][n];
;                             *(f32x4*)(zp + bj * HALF + n * 16) = res * ALPHA + acc[ai][bj][m][n] * scale;
	v_pk_mul_f32 v[142:143], v[142:143], s[14:15] op_sel_hi:[1,0]
	v_pk_mul_f32 v[140:141], v[140:141], s[14:15] op_sel_hi:[1,0]
	v_pk_mul_f32 v[132:133], v[132:133], s[14:15] op_sel_hi:[1,0]
	v_pk_mul_f32 v[130:131], v[130:131], s[14:15] op_sel_hi:[1,0]
	v_or_b32_e32 v190, 32, v160
	v_lshl_add_u64 v[188:189], s[12:13], 0, v[188:189]
	v_pk_mul_f32 v[138:139], v[138:139], s[14:15] op_sel_hi:[1,0]
	v_pk_mul_f32 v[136:137], v[136:137], s[14:15] op_sel_hi:[1,0]
	v_pk_mul_f32 v[134:135], v[134:135], s[14:15] op_sel_hi:[1,0]
	v_pk_mul_f32 v[128:129], v[128:129], s[14:15] op_sel_hi:[1,0]
	v_add_u32_e32 v148, 0xffffe020, v160
	v_mov_b32_e32 v161, s19
	v_mov_b32_e32 v175, s17
	v_mov_b32_e32 v194, s18
	v_mov_b32_e32 v195, s16
	v_or_b32_e32 v192, 48, v160
	v_pk_fma_f32 v[126:127], v[126:127], 0.5, v[142:143] op_sel_hi:[1,0,1]
	v_pk_fma_f32 v[124:125], v[124:125], 0.5, v[140:141] op_sel_hi:[1,0,1]
	v_pk_fma_f32 v[116:117], v[116:117], 0.5, v[132:133] op_sel_hi:[1,0,1]
	v_pk_fma_f32 v[114:115], v[114:115], 0.5, v[130:131] op_sel_hi:[1,0,1]
	v_ashrrev_i32_e32 v191, 31, v190
	v_lshl_add_u64 v[130:131], v[188:189], 0, v[158:159]
	v_cmp_gt_i32_e32 vcc, s52, v190
	v_lshl_add_u64 v[162:163], s[12:13], 0, v[162:163]
	v_add_u32_e32 v196, 0xffffe030, v160
	v_pk_fma_f32 v[122:123], v[122:123], 0.5, v[138:139] op_sel_hi:[1,0,1]
	v_pk_fma_f32 v[120:121], v[120:121], 0.5, v[136:137] op_sel_hi:[1,0,1]
	v_pk_fma_f32 v[118:119], v[118:119], 0.5, v[134:135] op_sel_hi:[1,0,1]
	v_pk_fma_f32 v[112:113], v[112:113], 0.5, v[128:129] op_sel_hi:[1,0,1]
	v_ashrrev_i32_e32 v193, 31, v192
	v_cndmask_b32_e32 v133, 0, v191, vcc
	v_cndmask_b32_e32 v132, v148, v190, vcc
	v_cndmask_b32_e32 v135, v161, v175, vcc
	v_cndmask_b32_e32 v134, v194, v195, vcc
	v_cmp_gt_i32_e32 vcc, s52, v192
	global_store_dwordx4 v[130:131], v[124:127], off
	global_store_dwordx4 v[130:131], v[120:123], off offset:64
	global_store_dwordx4 v[130:131], v[116:119], off offset:512
	global_store_dwordx4 v[130:131], v[112:115], off offset:576
	v_lshl_add_u64 v[128:129], v[162:163], 0, v[158:159]
	v_cndmask_b32_e32 v137, 0, v193, vcc
	v_cndmask_b32_e32 v136, v196, v192, vcc
	v_lshlrev_b64 v[112:113], 13, v[132:133]
	v_cndmask_b32_e32 v139, v161, v175, vcc
	v_lshl_add_u64 v[112:113], v[134:135], 0, v[112:113]
	v_cndmask_b32_e32 v138, v194, v195, vcc
	v_lshl_add_u64 v[112:113], v[112:113], 0, v[158:159]
	v_add_u32_e32 v134, 0xffffe080, v160
	v_cmp_gt_i32_e32 vcc, s59, v160
	v_lshlrev_b64 v[132:133], 13, v[192:193]
	v_lshl_add_u64 v[132:133], s[12:13], 0, v[132:133]
	v_lshl_add_u64 v[132:133], v[132:133], 0, v[158:159]
	v_pk_mul_f32 v[114:115], v[166:167], s[14:15] op_sel_hi:[1,0]
	v_pk_mul_f32 v[116:117], v[164:165], s[14:15] op_sel_hi:[1,0]
	v_pk_mul_f32 v[118:119], v[178:179], s[14:15] op_sel_hi:[1,0]
	v_pk_mul_f32 v[130:131], v[184:185], s[14:15] op_sel_hi:[1,0]
	v_pk_mul_f32 v[120:121], v[176:177], s[14:15] op_sel_hi:[1,0]
	v_pk_mul_f32 v[122:123], v[182:183], s[14:15] op_sel_hi:[1,0]
	v_pk_mul_f32 v[124:125], v[180:181], s[14:15] op_sel_hi:[1,0]
	v_pk_mul_f32 v[126:127], v[186:187], s[14:15] op_sel_hi:[1,0]
	v_pk_fma_f32 v[108:109], v[108:109], 0.5, v[116:117] op_sel_hi:[1,0,1]
	v_pk_fma_f32 v[110:111], v[110:111], 0.5, v[114:115] op_sel_hi:[1,0,1]
	v_pk_fma_f32 v[96:97], v[96:97], 0.5, v[130:131] op_sel_hi:[1,0,1]
	v_pk_fma_f32 v[104:105], v[104:105], 0.5, v[120:121] op_sel_hi:[1,0,1]
	v_pk_fma_f32 v[106:107], v[106:107], 0.5, v[118:119] op_sel_hi:[1,0,1]
	v_pk_fma_f32 v[100:101], v[100:101], 0.5, v[124:125] op_sel_hi:[1,0,1]
	v_pk_fma_f32 v[102:103], v[102:103], 0.5, v[122:123] op_sel_hi:[1,0,1]
	v_pk_fma_f32 v[98:99], v[98:99], 0.5, v[126:127] op_sel_hi:[1,0,1]
	global_store_dwordx4 v[128:129], v[108:111], off
	global_store_dwordx4 v[128:129], v[104:107], off offset:64
	global_store_dwordx4 v[128:129], v[100:103], off offset:512
	global_store_dwordx4 v[128:129], v[96:99], off offset:576
	global_load_dwordx4 v[98:101], v[112:113], off
	v_lshlrev_b64 v[130:131], 13, v[190:191]
	v_lshlrev_b64 v[96:97], 13, v[136:137]
	v_lshl_add_u64 v[96:97], v[138:139], 0, v[96:97]
	v_lshl_add_u64 v[96:97], v[96:97], 0, v[158:159]
	global_load_dwordx4 v[102:105], v[112:113], off offset:64
	global_load_dwordx4 v[106:109], v[112:113], off offset:512
	v_cndmask_b32_e32 v137, v161, v175, vcc
	global_load_dwordx4 v[110:113], v[112:113], off offset:576
	s_nop 0
	global_load_dwordx4 v[114:117], v[96:97], off
	global_load_dwordx4 v[118:121], v[96:97], off offset:64
	global_load_dwordx4 v[122:125], v[96:97], off offset:512
	global_load_dwordx4 v[126:129], v[96:97], off offset:576
	v_add_u32_e32 v96, 0x80, v160
	v_ashrrev_i32_e32 v97, 31, v96
	v_cndmask_b32_e32 v135, 0, v97, vcc
	v_cndmask_b32_e32 v134, v134, v96, vcc
	v_cndmask_b32_e32 v136, v194, v195, vcc
	v_lshl_add_u64 v[130:131], s[12:13], 0, v[130:131]
	v_lshlrev_b64 v[134:135], 13, v[134:135]
	v_lshl_add_u64 v[130:131], v[130:131], 0, v[158:159]
	v_lshl_add_u64 v[134:135], v[136:137], 0, v[134:135]
	v_lshl_add_u64 v[134:135], v[134:135], 0, v[158:159]
	v_cmp_lt_i32_e32 vcc, s60, v160
	s_waitcnt vmcnt(0)
;     __device__ __forceinline__ void operator()(const f32x4 (&acc)[2][2][4][2], const Unit& u, int wr, int wc, int fr, int fq) const {
;     ...
;                     const int r = row0 + ai * HALF + (mh * 2 + mm) * 16;
;                     const float* rp = MODE == 0 ? ((r < 8192 ? x0 + (size_t)r * DM : x1 + (size_t)(r - 8192) * DM) + col0) : (Z + (size_t)r * DM + col0);
;                     if (MODE == 1) st[mm] = stats[r];
; #pragma unroll
;                     for (int bj = 0; bj < 2; ++bj)
; #pragma unroll
;                         for (int n = 0; n < 2; ++n) rv[mm][bj][n] = *(const f32x4*)(rp + bj * HALF + n * 16);
;     ...
; #pragma unroll
;                 for (int mm = 0; mm < 2; ++mm) {
;                     const int m = mh * 2 + mm, r = row0 + ai * HALF + m * 16;
;                     float* zp = Z + (size_t)r * DM + col0;
; #pragma unroll
;                     for (int bj = 0; bj < 2; ++bj)
; #pragma unroll
;                         for (int n = 0; n < 2; ++n) {
;                             f32x4 res = rv[mm][bj][n];
;                             if (MODE == 1) res = (res - st[mm].x) * st[mm].y * gv[bj][n] + bv[bj][n];
;                             *(f32x4*)(zp + bj * HALF + n * 16) = res * ALPHA + acc[ai][bj][m][n] * scale;
	v_pk_mul_f32 v[100:101], v[100:101], s[14:15] op_sel_hi:[1,0]
	v_pk_mul_f32 v[98:99], v[98:99], s[14:15] op_sel_hi:[1,0]
	v_pk_fma_f32 v[94:95], v[94:95], 0.5, v[100:101] op_sel_hi:[1,0,1]
	v_pk_fma_f32 v[92:93], v[92:93], 0.5, v[98:99] op_sel_hi:[1,0,1]
	v_pk_mul_f32 v[104:105], v[104:105], s[14:15] op_sel_hi:[1,0]
	v_pk_mul_f32 v[102:103], v[102:103], s[14:15] op_sel_hi:[1,0]
	v_pk_mul_f32 v[108:109], v[108:109], s[14:15] op_sel_hi:[1,0]
	v_pk_mul_f32 v[106:107], v[106:107], s[14:15] op_sel_hi:[1,0]
	v_pk_mul_f32 v[112:113], v[112:113], s[14:15] op_sel_hi:[1,0]
	v_pk_mul_f32 v[110:111], v[110:111], s[14:15] op_sel_hi:[1,0]
	v_pk_mul_f32 v[116:117], v[116:117], s[14:15] op_sel_hi:[1,0]
	v_pk_mul_f32 v[114:115], v[114:115], s[14:15] op_sel_hi:[1,0]
	v_pk_mul_f32 v[120:121], v[120:121], s[14:15] op_sel_hi:[1,0]
	v_pk_mul_f32 v[118:119], v[118:119], s[14:15] op_sel_hi:[1,0]
	v_pk_mul_f32 v[124:125], v[124:125], s[14:15] op_sel_hi:[1,0]
	v_pk_mul_f32 v[122:123], v[122:123], s[14:15] op_sel_hi:[1,0]
	v_pk_mul_f32 v[128:129], v[128:129], s[14:15] op_sel_hi:[1,0]
	v_pk_mul_f32 v[126:127], v[126:127], s[14:15] op_sel_hi:[1,0]
	v_pk_fma_f32 v[90:91], v[90:91], 0.5, v[104:105] op_sel_hi:[1,0,1]
	v_pk_fma_f32 v[88:89], v[88:89], 0.5, v[102:103] op_sel_hi:[1,0,1]
	v_pk_fma_f32 v[78:79], v[78:79], 0.5, v[108:109] op_sel_hi:[1,0,1]
	v_pk_fma_f32 v[76:77], v[76:77], 0.5, v[106:107] op_sel_hi:[1,0,1]
	v_pk_fma_f32 v[74:75], v[74:75], 0.5, v[112:113] op_sel_hi:[1,0,1]
	v_pk_fma_f32 v[72:73], v[72:73], 0.5, v[110:111] op_sel_hi:[1,0,1]
	v_pk_fma_f32 v[86:87], v[86:87], 0.5, v[116:117] op_sel_hi:[1,0,1]
	v_pk_fma_f32 v[84:85], v[84:85], 0.5, v[114:115] op_sel_hi:[1,0,1]
	v_pk_fma_f32 v[82:83], v[82:83], 0.5, v[120:121] op_sel_hi:[1,0,1]
	v_pk_fma_f32 v[80:81], v[80:81], 0.5, v[118:119] op_sel_hi:[1,0,1]
	v_pk_fma_f32 v[70:71], v[70:71], 0.5, v[124:125] op_sel_hi:[1,0,1]
	v_pk_fma_f32 v[68:69], v[68:69], 0.5, v[122:123] op_sel_hi:[1,0,1]
	v_pk_fma_f32 v[66:67], v[66:67], 0.5, v[128:129] op_sel_hi:[1,0,1]
	v_pk_fma_f32 v[64:65], v[64:65], 0.5, v[126:127] op_sel_hi:[1,0,1]
	global_store_dwordx4 v[130:131], v[92:95], off
	global_store_dwordx4 v[130:131], v[88:91], off offset:64
	global_store_dwordx4 v[130:131], v[76:79], off offset:512
	global_store_dwordx4 v[130:131], v[72:75], off offset:576
	global_store_dwordx4 v[132:133], v[84:87], off
	global_store_dwordx4 v[132:133], v[80:83], off offset:64
	global_store_dwordx4 v[132:133], v[68:71], off offset:512
	global_store_dwordx4 v[132:133], v[64:67], off offset:576
	global_load_dwordx4 v[76:79], v[134:135], off
	global_load_dwordx4 v[72:75], v[134:135], off offset:64
	s_nop 0
	global_load_dwordx4 v[68:71], v[134:135], off offset:512
	global_load_dwordx4 v[64:67], v[134:135], off offset:576
	v_add_u32_e32 v82, 0x90, v160
	s_and_saveexec_b64 s[36:37], vcc
	s_xor_b64 s[36:37], exec, s[36:37]
	v_add_u32_e32 v148, 0xffffe090, v160
	v_lshlrev_b64 v[80:81], 13, v[148:149]
	v_mov_b32_e32 v83, v149
	v_lshl_add_u64 v[84:85], s[18:19], 0, v[80:81]
	v_lshlrev_b64 v[80:81], 13, v[82:83]
	s_andn2_saveexec_b64 s[36:37], s[36:37]
	s_cbranch_execz .LBB0_228
	v_ashrrev_i32_e32 v83, 31, v82
	v_lshlrev_b64 v[80:81], 13, v[82:83]
	v_lshl_add_u64 v[84:85], s[16:17], 0, v[80:81]
	s_branch .LBB0_228

; #define PG8_STAGE(bufoff, gbase, voff) do { _Pragma("unroll") for (int _i = 0; _i < 2; ++_i) \
;         __builtin_amdgcn_global_load_lds((const unsigned*)((const char*)(gbase) + (voff)[_i]), (LAS unsigned*)(lds + (bufoff) + ldsw + _i * 8192), 16, 0, 0); } while (0)
; #define PG8_LDA(dst, b, h) do { _Pragma("unroll") for (int m = 0; m < 4; ++m) _Pragma("unroll") for (int k = 0; k < 2; ++k) dst[m][k] = *(const LAS bf16x8*)(lds + PG8_SA(b, h) + aoff + m * 2048 + k * 1024); } while (0)
; #define PG8_LDB(dst, b, h) do { _Pragma("unroll") for (int n = 0; n < 2; ++n) _Pragma("unroll") for (int k = 0; k < 2; ++k) dst[n][k] = *(const LAS bf16x8*)(lds + PG8_SB(b, h) + boff + n * 2048 + k * 1024); } while (0)
; #define PG8_MMA(ai, bj, At, Bt) do { __builtin_amdgcn_s_setprio(1); _Pragma("unroll") for (int m = 0; m < 4; ++m) _Pragma("unroll") for (int n = 0; n < 2; ++n) _Pragma("unroll") for (int k = 0; k < 2; ++k) \
;         acc[ai][bj][m][n] = __builtin_amdgcn_mfma_f32_16x16x32_bf16(Bt[n][k], At[m][k], acc[ai][bj][m][n], 0, 0, 0); __builtin_amdgcn_s_setprio(0); } while (0)
; #define PG8_WAIT_L(n) asm volatile("s_waitcnt lgkmcnt(" #n ")" ::: "memory")
; #define PG8_BAR __builtin_amdgcn_s_barrier()
; #define PG8_SCHED __builtin_amdgcn_sched_barrier(0)
; template <class Epi, class Sched>
; __device__ __forceinline__ void gemm_phase(LAS unsigned char* lds, const Gemm g, const Sched& S, const Epi& E) {
;     ...
;         for (int t = 0; t < nt; t += 2) {
;             const bool last = (t == nt - 2);
;             const char* a1 = cA + (size_t)(t + 1) * kstep;
;             const char* a2 = last ? nA : cA + (size_t)(t + 2) * kstep; const char* b2 = last ? nB : cB + (size_t)(t + 2) * kstep;
;             const char* a3 = a2 + kstep; const char* b3 = b2 + kstep;
;             PG8_LDB(B0, 0, 0); PG8_SCHED; PG8_LDA(At, 0, 0); PG8_STAGE(PG8_SA(1, 1), a1 + hstep, voffA);
;             PG8_WAIT_L(8); PG8_BAR; PG8_WAIT_L(0); PG8_MMA(0, 0, At, B0); PG8_BAR; PG8_SCHED;
;             PG8_LDB(B1, 0, 1); PG8_STAGE(PG8_SB(0, 0), b2, voffB);
;             PG8_BAR; PG8_WAIT_L(0); PG8_MMA(0, 1, At, B1); PG8_BAR;
;             PG8_LDA(At, 0, 1); PG8_STAGE(PG8_SA(0, 0), a2, voffA);
;             PG8_BAR; PG8_WAIT_L(0); PG8_MMA(1, 0, At, B0); PG8_BAR; PG8_SCHED;
.LBB0_429:
	ds_read_b128 v[150:153], v147
	ds_read_b128 v[154:157], v147 offset:1024
	ds_read_b128 v[158:161], v147 offset:2048
	ds_read_b128 v[162:165], v147 offset:3072
	s_add_u32 s10, s8, 0x4000
	s_addc_u32 s11, s9, 0
	s_cmp_eq_u32 s67, 28
	s_cselect_b32 s52, s41, s10
	s_cselect_b32 s53, s33, s11
	s_cselect_b32 s10, s47, s65
	s_cselect_b32 s11, s39, s66
	s_add_u32 s50, s52, 0x8000
	s_addc_u32 s51, s53, 0
	v_lshl_add_u64 v[166:167], s[8:9], 0, v[136:137]
	s_add_i32 m0, s49, 0xc000
	ds_read_b128 v[170:173], v148
	ds_read_b128 v[174:177], v148 offset:1024
	ds_read_b128 v[178:181], v148 offset:2048
	ds_read_b128 v[182:185], v148 offset:3072
	ds_read_b128 v[186:189], v148 offset:4096
	ds_read_b128 v[190:193], v148 offset:5120
	ds_read_b128 v[194:197], v148 offset:6144
	ds_read_b128 v[198:201], v148 offset:7168
	global_load_lds_dwordx4 v[166:167], off
	v_lshl_add_u64 v[166:167], s[8:9], 0, v[138:139]
	s_add_i32 m0, s49, 0xe000
	s_nop 0
	global_load_lds_dwordx4 v[166:167], off
	s_waitcnt lgkmcnt(8)
	s_barrier
	s_waitcnt lgkmcnt(0)
	s_waitcnt lgkmcnt(0)
	v_mfma_f32_16x16x32_bf16 v[124:127], v[150:153], v[170:173], v[124:127]
	v_mfma_f32_16x16x32_bf16 v[120:123], v[158:161], v[170:173], v[120:123]
	v_mfma_f32_16x16x32_bf16 v[108:111], v[150:153], v[178:181], v[108:111]
	v_mfma_f32_16x16x32_bf16 v[104:107], v[158:161], v[178:181], v[104:107]
	v_mfma_f32_16x16x32_bf16 v[92:95], v[150:153], v[186:189], v[92:95]
	v_mfma_f32_16x16x32_bf16 v[88:91], v[158:161], v[186:189], v[88:91]
	v_mfma_f32_16x16x32_bf16 v[76:79], v[150:153], v[194:197], v[76:79]
	v_mfma_f32_16x16x32_bf16 v[72:75], v[158:161], v[194:197], v[72:75]
	v_mfma_f32_16x16x32_bf16 v[124:127], v[154:157], v[174:177], v[124:127]
	v_mfma_f32_16x16x32_bf16 v[120:123], v[162:165], v[174:177], v[120:123]
	v_mfma_f32_16x16x32_bf16 v[108:111], v[154:157], v[182:185], v[108:111]
	v_mfma_f32_16x16x32_bf16 v[104:107], v[162:165], v[182:185], v[104:107]
	v_mfma_f32_16x16x32_bf16 v[92:95], v[154:157], v[190:193], v[92:95]
	v_mfma_f32_16x16x32_bf16 v[88:91], v[162:165], v[190:193], v[88:91]
	v_mfma_f32_16x16x32_bf16 v[76:79], v[154:157], v[198:201], v[76:79]
	v_mfma_f32_16x16x32_bf16 v[72:75], v[162:165], v[198:201], v[72:75]
	s_barrier
	s_add_i32 s68, s63, s56
	v_lshl_add_u64 v[166:167], s[10:11], 0, v[130:131]
	s_mov_b32 m0, s68
	ds_read_b128 v[206:209], v149
	ds_read_b128 v[210:213], v149 offset:1024
	ds_read_b128 v[214:217], v149 offset:2048
	ds_read_b128 v[218:221], v149 offset:3072
	global_load_lds_dwordx4 v[166:167], off
	v_lshl_add_u64 v[166:167], s[10:11], 0, v[134:135]
	s_add_i32 m0, s68, 0x2000
	s_nop 0
	global_load_lds_dwordx4 v[166:167], off
	s_barrier
	s_waitcnt lgkmcnt(0)
	s_waitcnt lgkmcnt(0)
	v_mfma_f32_16x16x32_bf16 v[116:119], v[206:209], v[170:173], v[116:119]
	v_mfma_f32_16x16x32_bf16 v[112:115], v[214:217], v[170:173], v[112:115]
	v_mfma_f32_16x16x32_bf16 v[100:103], v[206:209], v[178:181], v[100:103]
	v_mfma_f32_16x16x32_bf16 v[96:99], v[214:217], v[178:181], v[96:99]
	v_mfma_f32_16x16x32_bf16 v[84:87], v[206:209], v[186:189], v[84:87]
	v_mfma_f32_16x16x32_bf16 v[80:83], v[214:217], v[186:189], v[80:83]
	v_mfma_f32_16x16x32_bf16 v[68:71], v[206:209], v[194:197], v[68:71]
	v_mfma_f32_16x16x32_bf16 v[64:67], v[214:217], v[194:197], v[64:67]
	v_mfma_f32_16x16x32_bf16 v[116:119], v[210:213], v[174:177], v[116:119]
	v_mfma_f32_16x16x32_bf16 v[112:115], v[218:221], v[174:177], v[112:115]
	v_mfma_f32_16x16x32_bf16 v[100:103], v[210:213], v[182:185], v[100:103]
	v_mfma_f32_16x16x32_bf16 v[96:99], v[218:221], v[182:185], v[96:99]
	v_mfma_f32_16x16x32_bf16 v[84:87], v[210:213], v[190:193], v[84:87]
	v_mfma_f32_16x16x32_bf16 v[80:83], v[218:221], v[190:193], v[80:83]
	v_mfma_f32_16x16x32_bf16 v[68:71], v[210:213], v[198:201], v[68:71]
	v_mfma_f32_16x16x32_bf16 v[64:67], v[218:221], v[198:201], v[64:67]
	s_mov_b32 m0, s49
	v_lshl_add_u64 v[166:167], s[52:53], 0, v[128:129]
	s_barrier
	ds_read_b128 v[170:173], v148 offset:16384
	ds_read_b128 v[174:177], v148 offset:17408
	ds_read_b128 v[178:181], v148 offset:18432
	ds_read_b128 v[182:185], v148 offset:19456
	ds_read_b128 v[186:189], v148 offset:20480
	ds_read_b128 v[190:193], v148 offset:21504
	ds_read_b128 v[194:197], v148 offset:22528
	ds_read_b128 v[198:201], v148 offset:23552
	global_load_lds_dwordx4 v[166:167], off
	v_lshl_add_u64 v[166:167], s[52:53], 0, v[132:133]
	s_mov_b32 m0, s57
	s_nop 0
	global_load_lds_dwordx4 v[166:167], off
	s_barrier
	s_waitcnt lgkmcnt(0)
	s_waitcnt lgkmcnt(0)
	v_mfma_f32_16x16x32_bf16 v[60:63], v[150:153], v[170:173], v[60:63]
	v_mfma_f32_16x16x32_bf16 v[56:59], v[158:161], v[170:173], v[56:59]
	v_mfma_f32_16x16x32_bf16 v[44:47], v[150:153], v[178:181], v[44:47]
	v_mfma_f32_16x16x32_bf16 v[40:43], v[158:161], v[178:181], v[40:43]
	v_mfma_f32_16x16x32_bf16 v[28:31], v[150:153], v[186:189], v[28:31]
	v_mfma_f32_16x16x32_bf16 v[24:27], v[158:161], v[186:189], v[24:27]
	v_mfma_f32_16x16x32_bf16 v[12:15], v[150:153], v[194:197], v[12:15]
	v_mfma_f32_16x16x32_bf16 v[8:11], v[158:161], v[194:197], v[8:11]
	v_mfma_f32_16x16x32_bf16 v[60:63], v[154:157], v[174:177], v[60:63]
	v_mfma_f32_16x16x32_bf16 v[56:59], v[162:165], v[174:177], v[56:59]
	v_mfma_f32_16x16x32_bf16 v[44:47], v[154:157], v[182:185], v[44:47]
	v_mfma_f32_16x16x32_bf16 v[40:43], v[162:165], v[182:185], v[40:43]
	v_mfma_f32_16x16x32_bf16 v[28:31], v[154:157], v[190:193], v[28:31]
	v_mfma_f32_16x16x32_bf16 v[24:27], v[162:165], v[190:193], v[24:27]
	v_mfma_f32_16x16x32_bf16 v[12:15], v[154:157], v[198:201], v[12:15]
	v_mfma_f32_16x16x32_bf16 v[8:11], v[162:165], v[198:201], v[8:11]
	s_barrier
; #define PG8_STAGE(bufoff, gbase, voff) do { _Pragma("unroll") for (int _i = 0; _i < 2; ++_i) \
;         __builtin_amdgcn_global_load_lds((const unsigned*)((const char*)(gbase) + (voff)[_i]), (LAS unsigned*)(lds + (bufoff) + ldsw + _i * 8192), 16, 0, 0); } while (0)
; #define PG8_LDA(dst, b, h) do { _Pragma("unroll") for (int m = 0; m < 4; ++m) _Pragma("unroll") for (int k = 0; k < 2; ++k) dst[m][k] = *(const LAS bf16x8*)(lds + PG8_SA(b, h) + aoff + m * 2048 + k * 1024); } while (0)
; #define PG8_LDB(dst, b, h) do { _Pragma("unroll") for (int n = 0; n < 2; ++n) _Pragma("unroll") for (int k = 0; k < 2; ++k) dst[n][k] = *(const LAS bf16x8*)(lds + PG8_SB(b, h) + boff + n * 2048 + k * 1024); } while (0)
; #define PG8_MMA(ai, bj, At, Bt) do { __builtin_amdgcn_s_setprio(1); _Pragma("unroll") for (int m = 0; m < 4; ++m) _Pragma("unroll") for (int n = 0; n < 2; ++n) _Pragma("unroll") for (int k = 0; k < 2; ++k) \
;         acc[ai][bj][m][n] = __builtin_amdgcn_mfma_f32_16x16x32_bf16(Bt[n][k], At[m][k], acc[ai][bj][m][n], 0, 0, 0); __builtin_amdgcn_s_setprio(0); } while (0)
; #define PG8_WAIT_V(n) asm volatile("s_waitcnt vmcnt(" #n ")" ::: "memory")
; #define PG8_WAIT_L(n) asm volatile("s_waitcnt lgkmcnt(" #n ")" ::: "memory")
; #define PG8_BAR __builtin_amdgcn_s_barrier()
; #define PG8_SCHED __builtin_amdgcn_sched_barrier(0)
; template <class Epi, class Sched>
; __device__ __forceinline__ void gemm_phase(LAS unsigned char* lds, const Gemm g, const Sched& S, const Epi& E) {
;     ...
;             PG8_STAGE(PG8_SB(0, 1), b2 + hstep, voffB);
;             PG8_WAIT_V(6); PG8_BAR; PG8_MMA(1, 1, At, B1); PG8_BAR;
;             PG8_LDB(B0, 1, 0); PG8_SCHED; PG8_LDA(At, 1, 0); PG8_STAGE(PG8_SA(0, 1), a2 + hstep, voffA);
;             PG8_WAIT_L(8); PG8_BAR; PG8_WAIT_L(0); PG8_MMA(0, 0, At, B0); PG8_BAR; PG8_SCHED;
;             PG8_LDB(B1, 1, 1); PG8_STAGE(PG8_SB(1, 0), b3, voffB);
;             PG8_BAR; PG8_WAIT_L(0); PG8_MMA(0, 1, At, B1); PG8_BAR;
;             PG8_LDA(At, 1, 1); PG8_STAGE(PG8_SA(1, 0), a3, voffA);
	s_add_u32 s68, s10, 0x4000
	s_addc_u32 s69, s11, 0
	s_add_i32 s71, s64, s56
	v_lshl_add_u64 v[150:151], s[68:69], 0, v[130:131]
	s_mov_b32 m0, s71
	s_nop 0
	global_load_lds_dwordx4 v[150:151], off
	v_lshl_add_u64 v[150:151], s[68:69], 0, v[134:135]
	s_add_i32 m0, s71, 0x2000
	s_nop 0
	global_load_lds_dwordx4 v[150:151], off
	s_waitcnt vmcnt(6)
	s_barrier
	v_mfma_f32_16x16x32_bf16 v[52:55], v[206:209], v[170:173], v[52:55]
	v_mfma_f32_16x16x32_bf16 v[48:51], v[214:217], v[170:173], v[48:51]
	v_mfma_f32_16x16x32_bf16 v[36:39], v[206:209], v[178:181], v[36:39]
	v_mfma_f32_16x16x32_bf16 v[32:35], v[214:217], v[178:181], v[32:35]
	v_mfma_f32_16x16x32_bf16 v[20:23], v[206:209], v[186:189], v[20:23]
	v_mfma_f32_16x16x32_bf16 v[16:19], v[214:217], v[186:189], v[16:19]
	v_mfma_f32_16x16x32_bf16 v[4:7], v[206:209], v[194:197], v[4:7]
	v_mfma_f32_16x16x32_bf16 v[0:3], v[214:217], v[194:197], v[0:3]
	v_mfma_f32_16x16x32_bf16 v[52:55], v[210:213], v[174:177], v[52:55]
	v_mfma_f32_16x16x32_bf16 v[48:51], v[218:221], v[174:177], v[48:51]
	v_mfma_f32_16x16x32_bf16 v[36:39], v[210:213], v[182:185], v[36:39]
	v_mfma_f32_16x16x32_bf16 v[32:35], v[218:221], v[182:185], v[32:35]
	v_mfma_f32_16x16x32_bf16 v[20:23], v[210:213], v[190:193], v[20:23]
	v_mfma_f32_16x16x32_bf16 v[16:19], v[218:221], v[190:193], v[16:19]
	v_mfma_f32_16x16x32_bf16 v[4:7], v[210:213], v[198:201], v[4:7]
	v_mfma_f32_16x16x32_bf16 v[0:3], v[218:221], v[198:201], v[0:3]
	s_add_i32 s68, 0, 0x18000
	v_add_u32_e32 v162, s68, v145
	s_barrier
	ds_read_b128 v[150:153], v162
	ds_read_b128 v[154:157], v162 offset:1024
	ds_read_b128 v[158:161], v162 offset:2048
	ds_read_b128 v[162:165], v162 offset:3072
	s_add_u32 s52, s52, 0x4000
	s_addc_u32 s53, s53, 0
	s_mov_b32 m0, s58
	v_lshl_add_u64 v[166:167], s[52:53], 0, v[128:129]
	ds_read_b128 v[170:173], v148 offset:32768
	ds_read_b128 v[174:177], v148 offset:33792
	ds_read_b128 v[178:181], v148 offset:34816
	ds_read_b128 v[182:185], v148 offset:35840
	ds_read_b128 v[186:189], v148 offset:36864
	ds_read_b128 v[190:193], v148 offset:37888
	ds_read_b128 v[194:197], v148 offset:38912
	ds_read_b128 v[198:201], v148 offset:39936
	global_load_lds_dwordx4 v[166:167], off
	v_lshl_add_u64 v[166:167], s[52:53], 0, v[132:133]
	s_mov_b32 m0, s59
	s_nop 0
	global_load_lds_dwordx4 v[166:167], off
	s_waitcnt lgkmcnt(8)
	s_barrier
	s_waitcnt lgkmcnt(0)
	s_waitcnt lgkmcnt(0)
	v_mfma_f32_16x16x32_bf16 v[124:127], v[150:153], v[170:173], v[124:127]
	v_mfma_f32_16x16x32_bf16 v[120:123], v[158:161], v[170:173], v[120:123]
	v_mfma_f32_16x16x32_bf16 v[108:111], v[150:153], v[178:181], v[108:111]
	v_mfma_f32_16x16x32_bf16 v[104:107], v[158:161], v[178:181], v[104:107]
	v_mfma_f32_16x16x32_bf16 v[92:95], v[150:153], v[186:189], v[92:95]
	v_mfma_f32_16x16x32_bf16 v[88:91], v[158:161], v[186:189], v[88:91]
	v_mfma_f32_16x16x32_bf16 v[76:79], v[150:153], v[194:197], v[76:79]
	v_mfma_f32_16x16x32_bf16 v[72:75], v[158:161], v[194:197], v[72:75]
	v_mfma_f32_16x16x32_bf16 v[124:127], v[154:157], v[174:177], v[124:127]
	v_mfma_f32_16x16x32_bf16 v[120:123], v[162:165], v[174:177], v[120:123]
	v_mfma_f32_16x16x32_bf16 v[108:111], v[154:157], v[182:185], v[108:111]
	v_mfma_f32_16x16x32_bf16 v[104:107], v[162:165], v[182:185], v[104:107]
	v_mfma_f32_16x16x32_bf16 v[92:95], v[154:157], v[190:193], v[92:95]
	v_mfma_f32_16x16x32_bf16 v[88:91], v[162:165], v[190:193], v[88:91]
	v_mfma_f32_16x16x32_bf16 v[76:79], v[154:157], v[198:201], v[76:79]
	v_mfma_f32_16x16x32_bf16 v[72:75], v[162:165], v[198:201], v[72:75]
	s_barrier
	s_add_i32 s69, 0, 0x1c000
	s_add_u32 s52, s10, 0x8000
	v_add_u32_e32 v166, s69, v145
	s_addc_u32 s53, s11, 0
	s_add_i32 s68, s68, s56
	ds_read_b128 v[206:209], v166
	ds_read_b128 v[210:213], v166 offset:1024
	ds_read_b128 v[214:217], v166 offset:2048
	ds_read_b128 v[218:221], v166 offset:3072
	v_lshl_add_u64 v[166:167], s[52:53], 0, v[130:131]
	s_mov_b32 m0, s68
	s_nop 0
	global_load_lds_dwordx4 v[166:167], off
	v_lshl_add_u64 v[166:167], s[52:53], 0, v[134:135]
	s_add_i32 m0, s68, 0x2000
	s_nop 0
	global_load_lds_dwordx4 v[166:167], off
	s_barrier
	s_waitcnt lgkmcnt(0)
	s_waitcnt lgkmcnt(0)
	v_mfma_f32_16x16x32_bf16 v[116:119], v[206:209], v[170:173], v[116:119]
	v_mfma_f32_16x16x32_bf16 v[112:115], v[214:217], v[170:173], v[112:115]
	v_mfma_f32_16x16x32_bf16 v[100:103], v[206:209], v[178:181], v[100:103]
	v_mfma_f32_16x16x32_bf16 v[96:99], v[214:217], v[178:181], v[96:99]
	v_mfma_f32_16x16x32_bf16 v[84:87], v[206:209], v[186:189], v[84:87]
	v_mfma_f32_16x16x32_bf16 v[80:83], v[214:217], v[186:189], v[80:83]
	v_mfma_f32_16x16x32_bf16 v[68:71], v[206:209], v[194:197], v[68:71]
	v_mfma_f32_16x16x32_bf16 v[64:67], v[214:217], v[194:197], v[64:67]
	v_mfma_f32_16x16x32_bf16 v[116:119], v[210:213], v[174:177], v[116:119]
	v_mfma_f32_16x16x32_bf16 v[112:115], v[218:221], v[174:177], v[112:115]
	v_mfma_f32_16x16x32_bf16 v[100:103], v[210:213], v[182:185], v[100:103]
	v_mfma_f32_16x16x32_bf16 v[96:99], v[218:221], v[182:185], v[96:99]
	v_mfma_f32_16x16x32_bf16 v[84:87], v[210:213], v[190:193], v[84:87]
	v_mfma_f32_16x16x32_bf16 v[80:83], v[218:221], v[190:193], v[80:83]
	v_mfma_f32_16x16x32_bf16 v[68:71], v[210:213], v[198:201], v[68:71]
	v_mfma_f32_16x16x32_bf16 v[64:67], v[218:221], v[198:201], v[64:67]
	s_mov_b32 m0, s61
	v_lshl_add_u64 v[166:167], s[50:51], 0, v[128:129]
	s_barrier
	ds_read_b128 v[170:173], v148 offset:49152
	ds_read_b128 v[174:177], v148 offset:50176
	ds_read_b128 v[178:181], v148 offset:51200
	ds_read_b128 v[182:185], v148 offset:52224
	ds_read_b128 v[186:189], v148 offset:53248
	ds_read_b128 v[190:193], v148 offset:54272
	ds_read_b128 v[194:197], v148 offset:55296
	ds_read_b128 v[198:201], v148 offset:56320
	global_load_lds_dwordx4 v[166:167], off
	v_lshl_add_u64 v[166:167], s[50:51], 0, v[132:133]
	s_mov_b32 m0, s62
	s_nop 0
	global_load_lds_dwordx4 v[166:167], off
	s_barrier
; #define PG8_STAGE(bufoff, gbase, voff) do { _Pragma("unroll") for (int _i = 0; _i < 2; ++_i) \
;         __builtin_amdgcn_global_load_lds((const unsigned*)((const char*)(gbase) + (voff)[_i]), (LAS unsigned*)(lds + (bufoff) + ldsw + _i * 8192), 16, 0, 0); } while (0)
; #define PG8_MMA(ai, bj, At, Bt) do { __builtin_amdgcn_s_setprio(1); _Pragma("unroll") for (int m = 0; m < 4; ++m) _Pragma("unroll") for (int n = 0; n < 2; ++n) _Pragma("unroll") for (int k = 0; k < 2; ++k) \
;         acc[ai][bj][m][n] = __builtin_amdgcn_mfma_f32_16x16x32_bf16(Bt[n][k], At[m][k], acc[ai][bj][m][n], 0, 0, 0); __builtin_amdgcn_s_setprio(0); } while (0)
; #define PG8_WAIT_V(n) asm volatile("s_waitcnt vmcnt(" #n ")" ::: "memory")
; #define PG8_WAIT_L(n) asm volatile("s_waitcnt lgkmcnt(" #n ")" ::: "memory")
; #define PG8_BAR __builtin_amdgcn_s_barrier()
; #define PG8_SCHED __builtin_amdgcn_sched_barrier(0)
; template <class Epi, class Sched>
; __device__ __forceinline__ void gemm_phase(LAS unsigned char* lds, const Gemm g, const Sched& S, const Epi& E) {
;     ...
;             PG8_BAR; PG8_WAIT_L(0); PG8_MMA(1, 0, At, B0); PG8_BAR; PG8_SCHED;
;             PG8_STAGE(PG8_SB(1, 1), b3 + hstep, voffB);
;             PG8_WAIT_V(6); PG8_BAR; PG8_MMA(1, 1, At, B1); PG8_BAR;
;         }
;     __device__ __forceinline__ void operator()(const f32x4 (&acc)[2][2][4][2], const Unit& u, int wr, int wc, int fr, int fq) const {
;     ...
;         const int kind = ACT == 0 ? 0 : (u.pn < 4 ? 0 : (u.pn < 12 ? 1 : 2));
	s_waitcnt lgkmcnt(0)
	s_waitcnt lgkmcnt(0)
	v_mfma_f32_16x16x32_bf16 v[60:63], v[150:153], v[170:173], v[60:63]
	v_mfma_f32_16x16x32_bf16 v[56:59], v[158:161], v[170:173], v[56:59]
	v_mfma_f32_16x16x32_bf16 v[44:47], v[150:153], v[178:181], v[44:47]
	v_mfma_f32_16x16x32_bf16 v[40:43], v[158:161], v[178:181], v[40:43]
	v_mfma_f32_16x16x32_bf16 v[28:31], v[150:153], v[186:189], v[28:31]
	v_mfma_f32_16x16x32_bf16 v[24:27], v[158:161], v[186:189], v[24:27]
	v_mfma_f32_16x16x32_bf16 v[12:15], v[150:153], v[194:197], v[12:15]
	v_mfma_f32_16x16x32_bf16 v[8:11], v[158:161], v[194:197], v[8:11]
	v_mfma_f32_16x16x32_bf16 v[60:63], v[154:157], v[174:177], v[60:63]
	v_mfma_f32_16x16x32_bf16 v[56:59], v[162:165], v[174:177], v[56:59]
	v_mfma_f32_16x16x32_bf16 v[44:47], v[154:157], v[182:185], v[44:47]
	v_mfma_f32_16x16x32_bf16 v[40:43], v[162:165], v[182:185], v[40:43]
	v_mfma_f32_16x16x32_bf16 v[28:31], v[154:157], v[190:193], v[28:31]
	v_mfma_f32_16x16x32_bf16 v[24:27], v[162:165], v[190:193], v[24:27]
	v_mfma_f32_16x16x32_bf16 v[12:15], v[154:157], v[198:201], v[12:15]
	v_mfma_f32_16x16x32_bf16 v[8:11], v[162:165], v[198:201], v[8:11]
	s_barrier
	s_add_u32 s10, s10, 0xc000
	s_addc_u32 s11, s11, 0
	s_add_i32 s50, s69, s56
	v_lshl_add_u64 v[150:151], s[10:11], 0, v[130:131]
	s_mov_b32 m0, s50
	s_nop 0
	global_load_lds_dwordx4 v[150:151], off
	v_lshl_add_u64 v[150:151], s[10:11], 0, v[134:135]
	s_add_i32 m0, s50, 0x2000
	s_nop 0
	global_load_lds_dwordx4 v[150:151], off
	s_waitcnt vmcnt(6)
	s_barrier
	v_mfma_f32_16x16x32_bf16 v[52:55], v[206:209], v[170:173], v[52:55]
	v_mfma_f32_16x16x32_bf16 v[48:51], v[214:217], v[170:173], v[48:51]
	v_mfma_f32_16x16x32_bf16 v[36:39], v[206:209], v[178:181], v[36:39]
	v_mfma_f32_16x16x32_bf16 v[32:35], v[214:217], v[178:181], v[32:35]
	v_mfma_f32_16x16x32_bf16 v[20:23], v[206:209], v[186:189], v[20:23]
	v_mfma_f32_16x16x32_bf16 v[16:19], v[214:217], v[186:189], v[16:19]
	v_mfma_f32_16x16x32_bf16 v[4:7], v[206:209], v[194:197], v[4:7]
	v_mfma_f32_16x16x32_bf16 v[0:3], v[214:217], v[194:197], v[0:3]
	v_mfma_f32_16x16x32_bf16 v[52:55], v[210:213], v[174:177], v[52:55]
	v_mfma_f32_16x16x32_bf16 v[48:51], v[218:221], v[174:177], v[48:51]
	v_mfma_f32_16x16x32_bf16 v[36:39], v[210:213], v[182:185], v[36:39]
	v_mfma_f32_16x16x32_bf16 v[32:35], v[218:221], v[182:185], v[32:35]
	v_mfma_f32_16x16x32_bf16 v[20:23], v[210:213], v[190:193], v[20:23]
	v_mfma_f32_16x16x32_bf16 v[16:19], v[218:221], v[190:193], v[16:19]
	v_mfma_f32_16x16x32_bf16 v[4:7], v[210:213], v[198:201], v[4:7]
	v_mfma_f32_16x16x32_bf16 v[0:3], v[218:221], v[198:201], v[0:3]
	s_add_i32 s67, s67, 2
	s_add_u32 s8, s8, 0x10000
	s_addc_u32 s9, s9, 0
	s_add_u32 s65, s65, 0x10000
	s_addc_u32 s66, s66, 0
	s_cmp_gt_u32 s67, 29
	s_barrier
	s_cbranch_scc0 .LBB0_429
	s_nop 7
	s_cmp_lt_i32 s48, 4
	s_cbranch_scc1 .Lmy_p4_store
	s_cmp_lt_i32 s48, 12
	s_cbranch_scc1 .Lmy_p4_gelu
; __device__ __forceinline__ float gelu_f(float x) { const float u = 1.5957691216f * (x + 0.044715f * x * x * x); return x * sigmoid_f(u); }
;     __device__ __forceinline__ void operator()(const f32x4 (&acc)[2][2][4][2], const Unit& u, int wr, int wc, int fr, int fq) const {
;     ...
;                         for (int j = 0; j < 4; ++j) { const float a = acc[ai][bj][m][n][j]; v[n * 4 + j] = kind == 1 ? gelu_f(a) : (kind == 2 ? a * 0.0625f : a); }
	v_mul_f32_e32 v0, 0x3d800000, v0
	v_mul_f32_e32 v1, 0x3d800000, v1
	v_mul_f32_e32 v2, 0x3d800000, v2
	v_mul_f32_e32 v3, 0x3d800000, v3
	v_mul_f32_e32 v4, 0x3d800000, v4
	v_mul_f32_e32 v5, 0x3d800000, v5
	v_mul_f32_e32 v6, 0x3d800000, v6
	v_mul_f32_e32 v7, 0x3d800000, v7
	v_mul_f32_e32 v8, 0x3d800000, v8
	v_mul_f32_e32 v9, 0x3d800000, v9
	v_mul_f32_e32 v10, 0x3d800000, v10
	v_mul_f32_e32 v11, 0x3d800000, v11
	v_mul_f32_e32 v12, 0x3d800000, v12
	v_mul_f32_e32 v13, 0x3d800000, v13
	v_mul_f32_e32 v14, 0x3d800000, v14
	v_mul_f32_e32 v15, 0x3d800000, v15
	v_mul_f32_e32 v16, 0x3d800000, v16
	v_mul_f32_e32 v17, 0x3d800000, v17
	v_mul_f32_e32 v18, 0x3d800000, v18
	v_mul_f32_e32 v19, 0x3d800000, v19
	v_mul_f32_e32 v20, 0x3d800000, v20
	v_mul_f32_e32 v21, 0x3d800000, v21
	v_mul_f32_e32 v22, 0x3d800000, v22
	v_mul_f32_e32 v23, 0x3d800000, v23
	v_mul_f32_e32 v24, 0x3d800000, v24
	v_mul_f32_e32 v25, 0x3d800000, v25
	v_mul_f32_e32 v26, 0x3d800000, v26
	v_mul_f32_e32 v27, 0x3d800000, v27
	v_mul_f32_e32 v28, 0x3d800000, v28
	v_mul_f32_e32 v29, 0x3d800000, v29
	v_mul_f32_e32 v30, 0x3d800000, v30
	v_mul_f32_e32 v31, 0x3d800000, v31
	v_mul_f32_e32 v32, 0x3d800000, v32
	v_mul_f32_e32 v33, 0x3d800000, v33
	v_mul_f32_e32 v34, 0x3d800000, v34
	v_mul_f32_e32 v35, 0x3d800000, v35
	v_mul_f32_e32 v36, 0x3d800000, v36
	v_mul_f32_e32 v37, 0x3d800000, v37
	v_mul_f32_e32 v38, 0x3d800000, v38
	v_mul_f32_e32 v39, 0x3d800000, v39
	v_mul_f32_e32 v40, 0x3d800000, v40
	v_mul_f32_e32 v41, 0x3d800000, v41
	v_mul_f32_e32 v42, 0x3d800000, v42
	v_mul_f32_e32 v43, 0x3d800000, v43
	v_mul_f32_e32 v44, 0x3d800000, v44
	v_mul_f32_e32 v45, 0x3d800000, v45
	v_mul_f32_e32 v46, 0x3d800000, v46
	v_mul_f32_e32 v47, 0x3d800000, v47
	v_mul_f32_e32 v48, 0x3d800000, v48
	v_mul_f32_e32 v49, 0x3d800000, v49
	v_mul_f32_e32 v50, 0x3d800000, v50
	v_mul_f32_e32 v51, 0x3d800000, v51
	v_mul_f32_e32 v52, 0x3d800000, v52
	v_mul_f32_e32 v53, 0x3d800000, v53
	v_mul_f32_e32 v54, 0x3d800000, v54
	v_mul_f32_e32 v55, 0x3d800000, v55
	v_mul_f32_e32 v56, 0x3d800000, v56
	v_mul_f32_e32 v57, 0x3d800000, v57
	v_mul_f32_e32 v58, 0x3d800000, v58
	v_mul_f32_e32 v59, 0x3d800000, v59
	v_mul_f32_e32 v60, 0x3d800000, v60
	v_mul_f32_e32 v61, 0x3d800000, v61
	v_mul_f32_e32 v62, 0x3d800000, v62
	v_mul_f32_e32 v63, 0x3d800000, v63
	v_mul_f32_e32 v64, 0x3d800000, v64
	v_mul_f32_e32 v65, 0x3d800000, v65
	v_mul_f32_e32 v66, 0x3d800000, v66
	v_mul_f32_e32 v67, 0x3d800000, v67
	v_mul_f32_e32 v68, 0x3d800000, v68
	v_mul_f32_e32 v69, 0x3d800000, v69
	v_mul_f32_e32 v70, 0x3d800000, v70
	v_mul_f32_e32 v71, 0x3d800000, v71
	v_mul_f32_e32 v72, 0x3d800000, v72
	v_mul_f32_e32 v73, 0x3d800000, v73
	v_mul_f32_e32 v74, 0x3d800000, v74
	v_mul_f32_e32 v75, 0x3d800000, v75
	v_mul_f32_e32 v76, 0x3d800000, v76
	v_mul_f32_e32 v77, 0x3d800000, v77
	v_mul_f32_e32 v78, 0x3d800000, v78
	v_mul_f32_e32 v79, 0x3d800000, v79
	v_mul_f32_e32 v80, 0x3d800000, v80
	v_mul_f32_e32 v81, 0x3d800000, v81
	v_mul_f32_e32 v82, 0x3d800000, v82
	v_mul_f32_e32 v83, 0x3d800000, v83
	v_mul_f32_e32 v84, 0x3d800000, v84
	v_mul_f32_e32 v85, 0x3d800000, v85
	v_mul_f32_e32 v86, 0x3d800000, v86
	v_mul_f32_e32 v87, 0x3d800000, v87
	v_mul_f32_e32 v88, 0x3d800000, v88
	v_mul_f32_e32 v89, 0x3d800000, v89
	v_mul_f32_e32 v90, 0x3d800000, v90
	v_mul_f32_e32 v91, 0x3d800000, v91
	v_mul_f32_e32 v92, 0x3d800000, v92
	v_mul_f32_e32 v93, 0x3d800000, v93
	v_mul_f32_e32 v94, 0x3d800000, v94
	v_mul_f32_e32 v95, 0x3d800000, v95
	v_mul_f32_e32 v96, 0x3d800000, v96
	v_mul_f32_e32 v97, 0x3d800000, v97
	v_mul_f32_e32 v98, 0x3d800000, v98
	v_mul_f32_e32 v99, 0x3d800000, v99
	v_mul_f32_e32 v100, 0x3d800000, v100
	v_mul_f32_e32 v101, 0x3d800000, v101
	v_mul_f32_e32 v102, 0x3d800000, v102
	v_mul_f32_e32 v103, 0x3d800000, v103
	v_mul_f32_e32 v104, 0x3d800000, v104
	v_mul_f32_e32 v105, 0x3d800000, v105
	v_mul_f32_e32 v106, 0x3d800000, v106
	v_mul_f32_e32 v107, 0x3d800000, v107
	v_mul_f32_e32 v108, 0x3d800000, v108
	v_mul_f32_e32 v109, 0x3d800000, v109
	v_mul_f32_e32 v110, 0x3d800000, v110
	v_mul_f32_e32 v111, 0x3d800000, v111
	v_mul_f32_e32 v112, 0x3d800000, v112
	v_mul_f32_e32 v113, 0x3d800000, v113
	v_mul_f32_e32 v114, 0x3d800000, v114
	v_mul_f32_e32 v115, 0x3d800000, v115
	v_mul_f32_e32 v116, 0x3d800000, v116
	v_mul_f32_e32 v117, 0x3d800000, v117
	v_mul_f32_e32 v118, 0x3d800000, v118
	v_mul_f32_e32 v119, 0x3d800000, v119
	v_mul_f32_e32 v120, 0x3d800000, v120
	v_mul_f32_e32 v121, 0x3d800000, v121
	v_mul_f32_e32 v122, 0x3d800000, v122
	v_mul_f32_e32 v123, 0x3d800000, v123
	v_mul_f32_e32 v124, 0x3d800000, v124
	v_mul_f32_e32 v125, 0x3d800000, v125
	v_mul_f32_e32 v126, 0x3d800000, v126
	v_mul_f32_e32 v127, 0x3d800000, v127
	s_branch .Lmy_p4_store

; #define PG8_STAGE(bufoff, gbase, voff) do { _Pragma("unroll") for (int _i = 0; _i < 2; ++_i) \
;         __builtin_amdgcn_global_load_lds((const unsigned*)((const char*)(gbase) + (voff)[_i]), (LAS unsigned*)(lds + (bufoff) + ldsw + _i * 8192), 16, 0, 0); } while (0)
; #define PG8_LDA(dst, b, h) do { _Pragma("unroll") for (int m = 0; m < 4; ++m) _Pragma("unroll") for (int k = 0; k < 2; ++k) dst[m][k] = *(const LAS bf16x8*)(lds + PG8_SA(b, h) + aoff + m * 2048 + k * 1024); } while (0)
; #define PG8_LDB(dst, b, h) do { _Pragma("unroll") for (int n = 0; n < 2; ++n) _Pragma("unroll") for (int k = 0; k < 2; ++k) dst[n][k] = *(const LAS bf16x8*)(lds + PG8_SB(b, h) + boff + n * 2048 + k * 1024); } while (0)
; #define PG8_MMA(ai, bj, At, Bt) do { __builtin_amdgcn_s_setprio(1); _Pragma("unroll") for (int m = 0; m < 4; ++m) _Pragma("unroll") for (int n = 0; n < 2; ++n) _Pragma("unroll") for (int k = 0; k < 2; ++k) \
;         acc[ai][bj][m][n] = __builtin_amdgcn_mfma_f32_16x16x32_bf16(Bt[n][k], At[m][k], acc[ai][bj][m][n], 0, 0, 0); __builtin_amdgcn_s_setprio(0); } while (0)
; #define PG8_WAIT_L(n) asm volatile("s_waitcnt lgkmcnt(" #n ")" ::: "memory")
; #define PG8_BAR __builtin_amdgcn_s_barrier()
; #define PG8_SCHED __builtin_amdgcn_sched_barrier(0)
; template <class Epi, class Sched>
; __device__ __forceinline__ void gemm_phase(LAS unsigned char* lds, const Gemm g, const Sched& S, const Epi& E) {
;     ...
;         for (int t = 0; t < nt; t += 2) {
;             const bool last = (t == nt - 2);
;             const char* a1 = cA + (size_t)(t + 1) * kstep;
;             const char* a2 = last ? nA : cA + (size_t)(t + 2) * kstep; const char* b2 = last ? nB : cB + (size_t)(t + 2) * kstep;
;             const char* a3 = a2 + kstep; const char* b3 = b2 + kstep;
;             PG8_LDB(B0, 0, 0); PG8_SCHED; PG8_LDA(At, 0, 0); PG8_STAGE(PG8_SA(1, 1), a1 + hstep, voffA);
;             PG8_WAIT_L(8); PG8_BAR; PG8_WAIT_L(0); PG8_MMA(0, 0, At, B0); PG8_BAR; PG8_SCHED;
;             PG8_LDB(B1, 0, 1); PG8_STAGE(PG8_SB(0, 0), b2, voffB);
;             PG8_BAR; PG8_WAIT_L(0); PG8_MMA(0, 1, At, B1); PG8_BAR;
;             PG8_LDA(At, 0, 1); PG8_STAGE(PG8_SA(0, 0), a2, voffA);
;             PG8_BAR; PG8_WAIT_L(0); PG8_MMA(1, 0, At, B0); PG8_BAR; PG8_SCHED;
.LBB0_1242:
	ds_read_b128 v[140:143], v147
	ds_read_b128 v[150:153], v147 offset:1024
	ds_read_b128 v[154:157], v147 offset:2048
	ds_read_b128 v[158:161], v147 offset:3072
	s_add_u32 s41, s42, 0x4000
	s_addc_u32 s44, s43, 0
	s_cmp_eq_u32 s35, 12
	s_cselect_b32 s48, s36, s41
	s_cselect_b32 s49, s37, s44
	s_cselect_b32 s44, s6, s31
	s_cselect_b32 s45, s7, s33
	s_add_u32 s46, s48, 0x8000
	s_addc_u32 s47, s49, 0
	v_lshl_add_u64 v[194:195], s[42:43], 0, v[136:137]
	s_add_i32 m0, s39, 0xc000
	ds_read_b128 v[162:165], v148
	ds_read_b128 v[166:169], v148 offset:1024
	ds_read_b128 v[170:173], v148 offset:2048
	ds_read_b128 v[174:177], v148 offset:3072
	ds_read_b128 v[178:181], v148 offset:4096
	ds_read_b128 v[182:185], v148 offset:5120
	ds_read_b128 v[186:189], v148 offset:6144
	ds_read_b128 v[190:193], v148 offset:7168
	global_load_lds_dwordx4 v[194:195], off
	v_lshl_add_u64 v[194:195], s[42:43], 0, v[138:139]
	s_add_i32 m0, s39, 0xe000
	s_nop 0
	global_load_lds_dwordx4 v[194:195], off
	s_waitcnt lgkmcnt(8)
	s_barrier
	s_waitcnt lgkmcnt(0)
	s_waitcnt lgkmcnt(0)
	v_mfma_f32_16x16x32_bf16 v[120:123], v[140:143], v[162:165], v[120:123]
	v_mfma_f32_16x16x32_bf16 v[116:119], v[154:157], v[162:165], v[116:119]
	v_mfma_f32_16x16x32_bf16 v[104:107], v[140:143], v[170:173], v[104:107]
	v_mfma_f32_16x16x32_bf16 v[100:103], v[154:157], v[170:173], v[100:103]
	v_mfma_f32_16x16x32_bf16 v[88:91], v[140:143], v[178:181], v[88:91]
	v_mfma_f32_16x16x32_bf16 v[84:87], v[154:157], v[178:181], v[84:87]
	v_mfma_f32_16x16x32_bf16 v[72:75], v[140:143], v[186:189], v[72:75]
	v_mfma_f32_16x16x32_bf16 v[68:71], v[154:157], v[186:189], v[68:71]
	v_mfma_f32_16x16x32_bf16 v[120:123], v[150:153], v[166:169], v[120:123]
	v_mfma_f32_16x16x32_bf16 v[116:119], v[158:161], v[166:169], v[116:119]
	v_mfma_f32_16x16x32_bf16 v[104:107], v[150:153], v[174:177], v[104:107]
	v_mfma_f32_16x16x32_bf16 v[100:103], v[158:161], v[174:177], v[100:103]
	v_mfma_f32_16x16x32_bf16 v[88:91], v[150:153], v[182:185], v[88:91]
	v_mfma_f32_16x16x32_bf16 v[84:87], v[158:161], v[182:185], v[84:87]
	v_mfma_f32_16x16x32_bf16 v[72:75], v[150:153], v[190:193], v[72:75]
	v_mfma_f32_16x16x32_bf16 v[68:71], v[158:161], v[190:193], v[68:71]
	s_barrier
	s_add_i32 s41, s71, s54
	v_lshl_add_u64 v[202:203], s[44:45], 0, v[130:131]
	s_mov_b32 m0, s41
	ds_read_b128 v[194:197], v149
	ds_read_b128 v[198:201], v149 offset:1024
	ds_read_b128 v[206:209], v149 offset:2048
	ds_read_b128 v[210:213], v149 offset:3072
	global_load_lds_dwordx4 v[202:203], off
	v_lshl_add_u64 v[202:203], s[44:45], 0, v[134:135]
	s_add_i32 m0, s41, 0x2000
	s_nop 0
	global_load_lds_dwordx4 v[202:203], off
	s_barrier
	s_waitcnt lgkmcnt(0)
	s_waitcnt lgkmcnt(0)
	v_mfma_f32_16x16x32_bf16 v[124:127], v[194:197], v[162:165], v[124:127]
	v_mfma_f32_16x16x32_bf16 v[112:115], v[206:209], v[162:165], v[112:115]
	v_mfma_f32_16x16x32_bf16 v[108:111], v[194:197], v[170:173], v[108:111]
	v_mfma_f32_16x16x32_bf16 v[96:99], v[206:209], v[170:173], v[96:99]
	v_mfma_f32_16x16x32_bf16 v[92:95], v[194:197], v[178:181], v[92:95]
	v_mfma_f32_16x16x32_bf16 v[80:83], v[206:209], v[178:181], v[80:83]
	v_mfma_f32_16x16x32_bf16 v[76:79], v[194:197], v[186:189], v[76:79]
	v_mfma_f32_16x16x32_bf16 v[64:67], v[206:209], v[186:189], v[64:67]
	v_mfma_f32_16x16x32_bf16 v[124:127], v[198:201], v[166:169], v[124:127]
	v_mfma_f32_16x16x32_bf16 v[112:115], v[210:213], v[166:169], v[112:115]
	v_mfma_f32_16x16x32_bf16 v[108:111], v[198:201], v[174:177], v[108:111]
	v_mfma_f32_16x16x32_bf16 v[96:99], v[210:213], v[174:177], v[96:99]
	v_mfma_f32_16x16x32_bf16 v[92:95], v[198:201], v[182:185], v[92:95]
	v_mfma_f32_16x16x32_bf16 v[80:83], v[210:213], v[182:185], v[80:83]
	v_mfma_f32_16x16x32_bf16 v[76:79], v[198:201], v[190:193], v[76:79]
	v_mfma_f32_16x16x32_bf16 v[64:67], v[210:213], v[190:193], v[64:67]
	s_mov_b32 m0, s39
	v_lshl_add_u64 v[202:203], s[48:49], 0, v[128:129]
	s_barrier
	ds_read_b128 v[162:165], v148 offset:16384
	ds_read_b128 v[166:169], v148 offset:17408
	ds_read_b128 v[170:173], v148 offset:18432
	ds_read_b128 v[174:177], v148 offset:19456
	ds_read_b128 v[178:181], v148 offset:20480
	ds_read_b128 v[182:185], v148 offset:21504
	ds_read_b128 v[186:189], v148 offset:22528
	ds_read_b128 v[190:193], v148 offset:23552
	global_load_lds_dwordx4 v[202:203], off
	v_lshl_add_u64 v[202:203], s[48:49], 0, v[132:133]
	s_mov_b32 m0, s55
	s_nop 0
	global_load_lds_dwordx4 v[202:203], off
	s_barrier
	s_waitcnt lgkmcnt(0)
	s_waitcnt lgkmcnt(0)
	v_mfma_f32_16x16x32_bf16 v[56:59], v[140:143], v[162:165], v[56:59]
	v_mfma_f32_16x16x32_bf16 v[52:55], v[154:157], v[162:165], v[52:55]
	v_mfma_f32_16x16x32_bf16 v[40:43], v[140:143], v[170:173], v[40:43]
	v_mfma_f32_16x16x32_bf16 v[36:39], v[154:157], v[170:173], v[36:39]
	v_mfma_f32_16x16x32_bf16 v[24:27], v[140:143], v[178:181], v[24:27]
	v_mfma_f32_16x16x32_bf16 v[20:23], v[154:157], v[178:181], v[20:23]
	v_mfma_f32_16x16x32_bf16 v[8:11], v[140:143], v[186:189], v[8:11]
	v_mfma_f32_16x16x32_bf16 v[4:7], v[154:157], v[186:189], v[4:7]
	v_mfma_f32_16x16x32_bf16 v[56:59], v[150:153], v[166:169], v[56:59]
	v_mfma_f32_16x16x32_bf16 v[52:55], v[158:161], v[166:169], v[52:55]
	v_mfma_f32_16x16x32_bf16 v[40:43], v[150:153], v[174:177], v[40:43]
	v_mfma_f32_16x16x32_bf16 v[36:39], v[158:161], v[174:177], v[36:39]
	v_mfma_f32_16x16x32_bf16 v[24:27], v[150:153], v[182:185], v[24:27]
	v_mfma_f32_16x16x32_bf16 v[20:23], v[158:161], v[182:185], v[20:23]
	v_mfma_f32_16x16x32_bf16 v[8:11], v[150:153], v[190:193], v[8:11]
	v_mfma_f32_16x16x32_bf16 v[4:7], v[158:161], v[190:193], v[4:7]
	s_barrier
; #define PG8_STAGE(bufoff, gbase, voff) do { _Pragma("unroll") for (int _i = 0; _i < 2; ++_i) \
;         __builtin_amdgcn_global_load_lds((const unsigned*)((const char*)(gbase) + (voff)[_i]), (LAS unsigned*)(lds + (bufoff) + ldsw + _i * 8192), 16, 0, 0); } while (0)
; #define PG8_LDA(dst, b, h) do { _Pragma("unroll") for (int m = 0; m < 4; ++m) _Pragma("unroll") for (int k = 0; k < 2; ++k) dst[m][k] = *(const LAS bf16x8*)(lds + PG8_SA(b, h) + aoff + m * 2048 + k * 1024); } while (0)
; #define PG8_LDB(dst, b, h) do { _Pragma("unroll") for (int n = 0; n < 2; ++n) _Pragma("unroll") for (int k = 0; k < 2; ++k) dst[n][k] = *(const LAS bf16x8*)(lds + PG8_SB(b, h) + boff + n * 2048 + k * 1024); } while (0)
; #define PG8_MMA(ai, bj, At, Bt) do { __builtin_amdgcn_s_setprio(1); _Pragma("unroll") for (int m = 0; m < 4; ++m) _Pragma("unroll") for (int n = 0; n < 2; ++n) _Pragma("unroll") for (int k = 0; k < 2; ++k) \
;         acc[ai][bj][m][n] = __builtin_amdgcn_mfma_f32_16x16x32_bf16(Bt[n][k], At[m][k], acc[ai][bj][m][n], 0, 0, 0); __builtin_amdgcn_s_setprio(0); } while (0)
; #define PG8_WAIT_V(n) asm volatile("s_waitcnt vmcnt(" #n ")" ::: "memory")
; #define PG8_WAIT_L(n) asm volatile("s_waitcnt lgkmcnt(" #n ")" ::: "memory")
; #define PG8_BAR __builtin_amdgcn_s_barrier()
; #define PG8_SCHED __builtin_amdgcn_sched_barrier(0)
; template <class Epi, class Sched>
; __device__ __forceinline__ void gemm_phase(LAS unsigned char* lds, const Gemm g, const Sched& S, const Epi& E) {
;     ...
;             PG8_STAGE(PG8_SB(0, 1), b2 + hstep, voffB);
;             PG8_WAIT_V(6); PG8_BAR; PG8_MMA(1, 1, At, B1); PG8_BAR;
;             PG8_LDB(B0, 1, 0); PG8_SCHED; PG8_LDA(At, 1, 0); PG8_STAGE(PG8_SA(0, 1), a2 + hstep, voffA);
;             PG8_WAIT_L(8); PG8_BAR; PG8_WAIT_L(0); PG8_MMA(0, 0, At, B0); PG8_BAR; PG8_SCHED;
;             PG8_LDB(B1, 1, 1); PG8_STAGE(PG8_SB(1, 0), b3, voffB);
;             PG8_BAR; PG8_WAIT_L(0); PG8_MMA(0, 1, At, B1); PG8_BAR;
;             PG8_LDA(At, 1, 1); PG8_STAGE(PG8_SA(1, 0), a3, voffA);
	s_add_u32 s68, s44, 0x4000
	s_addc_u32 s69, s45, 0
	s_add_i32 s41, s61, s54
	v_lshl_add_u64 v[140:141], s[68:69], 0, v[130:131]
	s_mov_b32 m0, s41
	s_nop 0
	global_load_lds_dwordx4 v[140:141], off
	v_lshl_add_u64 v[140:141], s[68:69], 0, v[134:135]
	s_add_i32 m0, s41, 0x2000
	s_nop 0
	global_load_lds_dwordx4 v[140:141], off
	s_waitcnt vmcnt(6)
	s_barrier
	v_mfma_f32_16x16x32_bf16 v[60:63], v[194:197], v[162:165], v[60:63]
	v_mfma_f32_16x16x32_bf16 v[48:51], v[206:209], v[162:165], v[48:51]
	v_mfma_f32_16x16x32_bf16 v[44:47], v[194:197], v[170:173], v[44:47]
	v_mfma_f32_16x16x32_bf16 v[32:35], v[206:209], v[170:173], v[32:35]
	v_mfma_f32_16x16x32_bf16 v[28:31], v[194:197], v[178:181], v[28:31]
	v_mfma_f32_16x16x32_bf16 v[16:19], v[206:209], v[178:181], v[16:19]
	v_mfma_f32_16x16x32_bf16 v[12:15], v[194:197], v[186:189], v[12:15]
	v_mfma_f32_16x16x32_bf16 v[0:3], v[206:209], v[186:189], v[0:3]
	v_mfma_f32_16x16x32_bf16 v[60:63], v[198:201], v[166:169], v[60:63]
	v_mfma_f32_16x16x32_bf16 v[48:51], v[210:213], v[166:169], v[48:51]
	v_mfma_f32_16x16x32_bf16 v[44:47], v[198:201], v[174:177], v[44:47]
	v_mfma_f32_16x16x32_bf16 v[32:35], v[210:213], v[174:177], v[32:35]
	v_mfma_f32_16x16x32_bf16 v[28:31], v[198:201], v[182:185], v[28:31]
	v_mfma_f32_16x16x32_bf16 v[16:19], v[210:213], v[182:185], v[16:19]
	v_mfma_f32_16x16x32_bf16 v[12:15], v[198:201], v[190:193], v[12:15]
	v_mfma_f32_16x16x32_bf16 v[0:3], v[210:213], v[190:193], v[0:3]
	s_add_i32 s41, 0, 0x18000
	v_add_u32_e32 v158, s41, v145
	s_barrier
	ds_read_b128 v[140:143], v158
	ds_read_b128 v[150:153], v158 offset:1024
	ds_read_b128 v[154:157], v158 offset:2048
	ds_read_b128 v[158:161], v158 offset:3072
	s_add_u32 s48, s48, 0x4000
	s_addc_u32 s49, s49, 0
	s_mov_b32 m0, s56
	v_lshl_add_u64 v[194:195], s[48:49], 0, v[128:129]
	ds_read_b128 v[162:165], v148 offset:32768
	ds_read_b128 v[166:169], v148 offset:33792
	ds_read_b128 v[170:173], v148 offset:34816
	ds_read_b128 v[174:177], v148 offset:35840
	ds_read_b128 v[178:181], v148 offset:36864
	ds_read_b128 v[182:185], v148 offset:37888
	ds_read_b128 v[186:189], v148 offset:38912
	ds_read_b128 v[190:193], v148 offset:39936
	global_load_lds_dwordx4 v[194:195], off
	v_lshl_add_u64 v[194:195], s[48:49], 0, v[132:133]
	s_mov_b32 m0, s57
	s_nop 0
	global_load_lds_dwordx4 v[194:195], off
	s_waitcnt lgkmcnt(8)
	s_barrier
	s_waitcnt lgkmcnt(0)
	s_waitcnt lgkmcnt(0)
	v_mfma_f32_16x16x32_bf16 v[120:123], v[140:143], v[162:165], v[120:123]
	v_mfma_f32_16x16x32_bf16 v[116:119], v[154:157], v[162:165], v[116:119]
	v_mfma_f32_16x16x32_bf16 v[104:107], v[140:143], v[170:173], v[104:107]
	v_mfma_f32_16x16x32_bf16 v[100:103], v[154:157], v[170:173], v[100:103]
	v_mfma_f32_16x16x32_bf16 v[88:91], v[140:143], v[178:181], v[88:91]
	v_mfma_f32_16x16x32_bf16 v[84:87], v[154:157], v[178:181], v[84:87]
	v_mfma_f32_16x16x32_bf16 v[72:75], v[140:143], v[186:189], v[72:75]
	v_mfma_f32_16x16x32_bf16 v[68:71], v[154:157], v[186:189], v[68:71]
	v_mfma_f32_16x16x32_bf16 v[120:123], v[150:153], v[166:169], v[120:123]
	v_mfma_f32_16x16x32_bf16 v[116:119], v[158:161], v[166:169], v[116:119]
	v_mfma_f32_16x16x32_bf16 v[104:107], v[150:153], v[174:177], v[104:107]
	v_mfma_f32_16x16x32_bf16 v[100:103], v[158:161], v[174:177], v[100:103]
	v_mfma_f32_16x16x32_bf16 v[88:91], v[150:153], v[182:185], v[88:91]
	v_mfma_f32_16x16x32_bf16 v[84:87], v[158:161], v[182:185], v[84:87]
	v_mfma_f32_16x16x32_bf16 v[72:75], v[150:153], v[190:193], v[72:75]
	v_mfma_f32_16x16x32_bf16 v[68:71], v[158:161], v[190:193], v[68:71]
	s_barrier
	s_add_i32 s68, 0, 0x1c000
	s_add_u32 s48, s44, 0x8000
	v_add_u32_e32 v202, s68, v145
	s_addc_u32 s49, s45, 0
	s_add_i32 s41, s41, s54
	ds_read_b128 v[194:197], v202
	ds_read_b128 v[198:201], v202 offset:1024
	ds_read_b128 v[206:209], v202 offset:2048
	ds_read_b128 v[210:213], v202 offset:3072
	v_lshl_add_u64 v[202:203], s[48:49], 0, v[130:131]
	s_mov_b32 m0, s41
	s_nop 0
	global_load_lds_dwordx4 v[202:203], off
	v_lshl_add_u64 v[202:203], s[48:49], 0, v[134:135]
	s_add_i32 m0, s41, 0x2000
	s_nop 0
	global_load_lds_dwordx4 v[202:203], off
	s_barrier
	s_waitcnt lgkmcnt(0)
	s_waitcnt lgkmcnt(0)
	v_mfma_f32_16x16x32_bf16 v[124:127], v[194:197], v[162:165], v[124:127]
	v_mfma_f32_16x16x32_bf16 v[112:115], v[206:209], v[162:165], v[112:115]
	v_mfma_f32_16x16x32_bf16 v[108:111], v[194:197], v[170:173], v[108:111]
	v_mfma_f32_16x16x32_bf16 v[96:99], v[206:209], v[170:173], v[96:99]
	v_mfma_f32_16x16x32_bf16 v[92:95], v[194:197], v[178:181], v[92:95]
	v_mfma_f32_16x16x32_bf16 v[80:83], v[206:209], v[178:181], v[80:83]
	v_mfma_f32_16x16x32_bf16 v[76:79], v[194:197], v[186:189], v[76:79]
	v_mfma_f32_16x16x32_bf16 v[64:67], v[206:209], v[186:189], v[64:67]
	v_mfma_f32_16x16x32_bf16 v[124:127], v[198:201], v[166:169], v[124:127]
	v_mfma_f32_16x16x32_bf16 v[112:115], v[210:213], v[166:169], v[112:115]
	v_mfma_f32_16x16x32_bf16 v[108:111], v[198:201], v[174:177], v[108:111]
	v_mfma_f32_16x16x32_bf16 v[96:99], v[210:213], v[174:177], v[96:99]
	v_mfma_f32_16x16x32_bf16 v[92:95], v[198:201], v[182:185], v[92:95]
	v_mfma_f32_16x16x32_bf16 v[80:83], v[210:213], v[182:185], v[80:83]
	v_mfma_f32_16x16x32_bf16 v[76:79], v[198:201], v[190:193], v[76:79]
	v_mfma_f32_16x16x32_bf16 v[64:67], v[210:213], v[190:193], v[64:67]
	s_mov_b32 m0, s59
	v_lshl_add_u64 v[202:203], s[46:47], 0, v[128:129]
	s_barrier
	ds_read_b128 v[162:165], v148 offset:49152
	ds_read_b128 v[166:169], v148 offset:50176
	ds_read_b128 v[170:173], v148 offset:51200
	ds_read_b128 v[174:177], v148 offset:52224
	ds_read_b128 v[178:181], v148 offset:53248
	ds_read_b128 v[182:185], v148 offset:54272
	ds_read_b128 v[186:189], v148 offset:55296
	ds_read_b128 v[190:193], v148 offset:56320
	global_load_lds_dwordx4 v[202:203], off
	v_lshl_add_u64 v[202:203], s[46:47], 0, v[132:133]
	s_mov_b32 m0, s60
	s_nop 0
	global_load_lds_dwordx4 v[202:203], off
	s_barrier
; #define PG8_STAGE(bufoff, gbase, voff) do { _Pragma("unroll") for (int _i = 0; _i < 2; ++_i) \
;         __builtin_amdgcn_global_load_lds((const unsigned*)((const char*)(gbase) + (voff)[_i]), (LAS unsigned*)(lds + (bufoff) + ldsw + _i * 8192), 16, 0, 0); } while (0)
; #define PG8_MMA(ai, bj, At, Bt) do { __builtin_amdgcn_s_setprio(1); _Pragma("unroll") for (int m = 0; m < 4; ++m) _Pragma("unroll") for (int n = 0; n < 2; ++n) _Pragma("unroll") for (int k = 0; k < 2; ++k) \
;         acc[ai][bj][m][n] = __builtin_amdgcn_mfma_f32_16x16x32_bf16(Bt[n][k], At[m][k], acc[ai][bj][m][n], 0, 0, 0); __builtin_amdgcn_s_setprio(0); } while (0)
; #define PG8_WAIT_V(n) asm volatile("s_waitcnt vmcnt(" #n ")" ::: "memory")
; #define PG8_WAIT_L(n) asm volatile("s_waitcnt lgkmcnt(" #n ")" ::: "memory")
; #define PG8_BAR __builtin_amdgcn_s_barrier()
; #define PG8_SCHED __builtin_amdgcn_sched_barrier(0)
; template <class Epi, class Sched>
; __device__ __forceinline__ void gemm_phase(LAS unsigned char* lds, const Gemm g, const Sched& S, const Epi& E) {
;     ...
;             PG8_BAR; PG8_WAIT_L(0); PG8_MMA(1, 0, At, B0); PG8_BAR; PG8_SCHED;
;             PG8_STAGE(PG8_SB(1, 1), b3 + hstep, voffB);
;             PG8_WAIT_V(6); PG8_BAR; PG8_MMA(1, 1, At, B1); PG8_BAR;
;         }
;     __device__ __forceinline__ void operator()(const f32x4 (&acc)[2][2][4][2], const Unit& u, int wr, int wc, int fr, int fq) const {
;         if (u.seg == 0) { EpiGlu<1> e{ya, DM}; e(acc, u, wr, wc, fr, fq); }
	s_waitcnt lgkmcnt(0)
	s_waitcnt lgkmcnt(0)
	v_mfma_f32_16x16x32_bf16 v[56:59], v[140:143], v[162:165], v[56:59]
	v_mfma_f32_16x16x32_bf16 v[52:55], v[154:157], v[162:165], v[52:55]
	v_mfma_f32_16x16x32_bf16 v[40:43], v[140:143], v[170:173], v[40:43]
	v_mfma_f32_16x16x32_bf16 v[36:39], v[154:157], v[170:173], v[36:39]
	v_mfma_f32_16x16x32_bf16 v[24:27], v[140:143], v[178:181], v[24:27]
	v_mfma_f32_16x16x32_bf16 v[20:23], v[154:157], v[178:181], v[20:23]
	v_mfma_f32_16x16x32_bf16 v[8:11], v[140:143], v[186:189], v[8:11]
	v_mfma_f32_16x16x32_bf16 v[4:7], v[154:157], v[186:189], v[4:7]
	v_mfma_f32_16x16x32_bf16 v[56:59], v[150:153], v[166:169], v[56:59]
	v_mfma_f32_16x16x32_bf16 v[52:55], v[158:161], v[166:169], v[52:55]
	v_mfma_f32_16x16x32_bf16 v[40:43], v[150:153], v[174:177], v[40:43]
	v_mfma_f32_16x16x32_bf16 v[36:39], v[158:161], v[174:177], v[36:39]
	v_mfma_f32_16x16x32_bf16 v[24:27], v[150:153], v[182:185], v[24:27]
	v_mfma_f32_16x16x32_bf16 v[20:23], v[158:161], v[182:185], v[20:23]
	v_mfma_f32_16x16x32_bf16 v[8:11], v[150:153], v[190:193], v[8:11]
	v_mfma_f32_16x16x32_bf16 v[4:7], v[158:161], v[190:193], v[4:7]
	s_barrier
	s_add_u32 s44, s44, 0xc000
	s_addc_u32 s45, s45, 0
	s_add_i32 s41, s68, s54
	v_lshl_add_u64 v[140:141], s[44:45], 0, v[130:131]
	s_mov_b32 m0, s41
	s_nop 0
	global_load_lds_dwordx4 v[140:141], off
	v_lshl_add_u64 v[140:141], s[44:45], 0, v[134:135]
	s_add_i32 m0, s41, 0x2000
	s_nop 0
	global_load_lds_dwordx4 v[140:141], off
	s_waitcnt vmcnt(6)
	s_barrier
	v_mfma_f32_16x16x32_bf16 v[60:63], v[194:197], v[162:165], v[60:63]
	v_mfma_f32_16x16x32_bf16 v[48:51], v[206:209], v[162:165], v[48:51]
	v_mfma_f32_16x16x32_bf16 v[44:47], v[194:197], v[170:173], v[44:47]
	v_mfma_f32_16x16x32_bf16 v[32:35], v[206:209], v[170:173], v[32:35]
	v_mfma_f32_16x16x32_bf16 v[28:31], v[194:197], v[178:181], v[28:31]
	v_mfma_f32_16x16x32_bf16 v[16:19], v[206:209], v[178:181], v[16:19]
	v_mfma_f32_16x16x32_bf16 v[12:15], v[194:197], v[186:189], v[12:15]
	v_mfma_f32_16x16x32_bf16 v[0:3], v[206:209], v[186:189], v[0:3]
	v_mfma_f32_16x16x32_bf16 v[60:63], v[198:201], v[166:169], v[60:63]
	v_mfma_f32_16x16x32_bf16 v[48:51], v[210:213], v[166:169], v[48:51]
	v_mfma_f32_16x16x32_bf16 v[44:47], v[198:201], v[174:177], v[44:47]
	v_mfma_f32_16x16x32_bf16 v[32:35], v[210:213], v[174:177], v[32:35]
	v_mfma_f32_16x16x32_bf16 v[28:31], v[198:201], v[182:185], v[28:31]
	v_mfma_f32_16x16x32_bf16 v[16:19], v[210:213], v[182:185], v[16:19]
	v_mfma_f32_16x16x32_bf16 v[12:15], v[198:201], v[190:193], v[12:15]
	v_mfma_f32_16x16x32_bf16 v[0:3], v[210:213], v[190:193], v[0:3]
	s_add_i32 s35, s35, 2
	s_add_u32 s42, s42, 0x10000
	s_addc_u32 s43, s43, 0
	s_add_u32 s31, s31, 0x10000
	s_addc_u32 s33, s33, 0
	s_cmp_gt_u32 s35, 13
	s_barrier
	s_cbranch_scc0 .LBB0_1242
	s_cmp_lg_u32 s67, 0
	v_lshl_add_u32 v140, s40, 8, v144
	s_cbranch_scc0 .LBB0_1245
; __device__ __forceinline__ unsigned cvt_pk_bf16(float lo, float hi) { f32x2 v = {lo, hi}; bf16x2_t b = __builtin_convertvector(v, bf16x2_t); return __builtin_bit_cast(unsigned, b); }
; __device__ __forceinline__ float gelu_f(float x) { const float u = 1.5957691216f * (x + 0.044715f * x * x * x); return x * sigmoid_f(u); }
;     __device__ __forceinline__ void operator()(const f32x4 (&acc)[2][2][4][2], const Unit& u, int wr, int wc, int fr, int fq) const {
;         const int row0 = u.pm * BM + wr * 64 + fr, col0 = u.pn * BM + wc * 32 + 8 * fq;
;         const int kind = ACT == 0 ? 0 : (u.pn < 4 ? 0 : (u.pn < 12 ? 1 : 2));
; #pragma unroll
;         for (int ai = 0; ai < 2; ++ai)
; #pragma unroll
;             for (int m = 0; m < 4; ++m) {
;                 bf16_t* rowp = O + (size_t)(row0 + ai * HALF + m * 16) * ldo + col0;
; #pragma unroll
;                 for (int bj = 0; bj < 2; ++bj) {
;                     float v[8];
; #pragma unroll
;                     for (int n = 0; n < 2; ++n)
; #pragma unroll
;                         for (int j = 0; j < 4; ++j) { const float a = acc[ai][bj][m][n][j]; v[n * 4 + j] = kind == 1 ? gelu_f(a) : (kind == 2 ? a * 0.0625f : a); }
;                     u32x4 w; w.x = cvt_pk_bf16(v[0], v[1]); w.y = cvt_pk_bf16(v[2], v[3]); w.z = cvt_pk_bf16(v[4], v[5]); w.w = cvt_pk_bf16(v[6], v[7]);
;                     *(u32x4*)(rowp + bj * HALF) = w;
;                 }
;     __device__ __forceinline__ void operator()(const f32x4 (&acc)[2][2][4][2], const Unit& u, int wr, int wc, int fr, int fq) const {
;     ...
;         else { EpiBf16<0> e{ya + (long)(u.seg == 1) * d1 + (long)(u.seg == 2) * d2, DM}; e(acc, u, wr, wc, fr, fq); }
	s_cmp_eq_u32 s67, 1
	s_cselect_b32 s31, 0x4000000, 0
	s_add_u32 s31, s8, s31
	s_addc_u32 s33, s9, 0
	s_cmp_eq_u32 s67, 2
	s_cselect_b32 s35, 0xac00000, 0
	s_add_u32 s40, s31, s35
	v_lshl_or_b32 v142, s38, 8, v146
	v_ashrrev_i32_e32 v141, 31, v140
	s_addc_u32 s41, s33, 0
	v_ashrrev_i32_e32 v143, 31, v142
	v_lshlrev_b64 v[150:151], 12, v[140:141]
	v_lshl_add_u64 v[150:151], s[40:41], 0, v[150:151]
	v_lshlrev_b64 v[142:143], 1, v[142:143]
	v_lshl_add_u64 v[154:155], v[150:151], 0, v[142:143]
	v_cvt_pk_bf16_f32 v150, v120, v121
	v_cvt_pk_bf16_f32 v151, v122, v123
	v_cvt_pk_bf16_f32 v152, v116, v117
	v_cvt_pk_bf16_f32 v153, v118, v119
	global_store_dwordx4 v[154:155], v[150:153], off
	s_nop 1
	v_cvt_pk_bf16_f32 v150, v124, v125
	v_cvt_pk_bf16_f32 v151, v126, v127
	v_cvt_pk_bf16_f32 v152, v112, v113
	v_cvt_pk_bf16_f32 v153, v114, v115
	global_store_dwordx4 v[154:155], v[150:153], off offset:256
	s_nop 1
	v_or_b32_e32 v150, 16, v140
	v_ashrrev_i32_e32 v151, 31, v150
	v_lshlrev_b64 v[150:151], 12, v[150:151]
	v_lshl_add_u64 v[150:151], s[40:41], 0, v[150:151]
	v_lshl_add_u64 v[156:157], v[150:151], 0, v[142:143]
	v_cvt_pk_bf16_f32 v150, v104, v105
	v_cvt_pk_bf16_f32 v151, v106, v107
	v_cvt_pk_bf16_f32 v152, v100, v101
	v_cvt_pk_bf16_f32 v153, v102, v103
	global_store_dwordx4 v[156:157], v[150:153], off
	s_nop 1
	v_cvt_pk_bf16_f32 v150, v108, v109
	v_cvt_pk_bf16_f32 v151, v110, v111
	v_cvt_pk_bf16_f32 v152, v96, v97
	v_cvt_pk_bf16_f32 v153, v98, v99
	global_store_dwordx4 v[156:157], v[150:153], off offset:256
	s_nop 1
	v_or_b32_e32 v150, 32, v140
	v_ashrrev_i32_e32 v151, 31, v150
	v_lshlrev_b64 v[150:151], 12, v[150:151]
	v_lshl_add_u64 v[150:151], s[40:41], 0, v[150:151]
	v_lshl_add_u64 v[156:157], v[150:151], 0, v[142:143]
	v_cvt_pk_bf16_f32 v150, v88, v89
	v_cvt_pk_bf16_f32 v151, v90, v91
	v_cvt_pk_bf16_f32 v152, v84, v85
	v_cvt_pk_bf16_f32 v153, v86, v87
	global_store_dwordx4 v[156:157], v[150:153], off
	s_nop 1
	v_cvt_pk_bf16_f32 v150, v92, v93
	v_cvt_pk_bf16_f32 v151, v94, v95
	v_cvt_pk_bf16_f32 v152, v80, v81
	v_cvt_pk_bf16_f32 v153, v82, v83
	global_store_dwordx4 v[156:157], v[150:153], off offset:256
	v_add_co_u32_e32 v156, vcc, s62, v154
	s_nop 0
	v_or_b32_e32 v150, 48, v140
	v_ashrrev_i32_e32 v151, 31, v150
	v_lshlrev_b64 v[150:151], 12, v[150:151]
	v_lshl_add_u64 v[150:151], s[40:41], 0, v[150:151]
	v_lshl_add_u64 v[142:143], v[150:151], 0, v[142:143]
	v_cvt_pk_bf16_f32 v150, v72, v73
	v_cvt_pk_bf16_f32 v151, v74, v75
	v_cvt_pk_bf16_f32 v152, v68, v69
	v_cvt_pk_bf16_f32 v153, v70, v71
	global_store_dwordx4 v[142:143], v[150:153], off
	v_addc_co_u32_e32 v157, vcc, 0, v155, vcc
	s_nop 0
	v_cvt_pk_bf16_f32 v150, v76, v77
	v_cvt_pk_bf16_f32 v151, v78, v79
	v_cvt_pk_bf16_f32 v152, v64, v65
	v_cvt_pk_bf16_f32 v153, v66, v67
	global_store_dwordx4 v[142:143], v[150:153], off offset:256
	v_lshl_add_u64 v[142:143], v[154:155], 0, s[10:11]
	s_nop 0
	v_cvt_pk_bf16_f32 v150, v56, v57
	v_cvt_pk_bf16_f32 v151, v58, v59
	v_cvt_pk_bf16_f32 v152, v52, v53
	v_cvt_pk_bf16_f32 v153, v54, v55
	global_store_dwordx4 v[156:157], v[150:153], off
	v_add_co_u32_e32 v156, vcc, s63, v154
	s_nop 0
	v_cvt_pk_bf16_f32 v150, v60, v61
	v_cvt_pk_bf16_f32 v151, v62, v63
	v_cvt_pk_bf16_f32 v152, v48, v49
	v_cvt_pk_bf16_f32 v153, v50, v51
	global_store_dwordx4 v[142:143], v[150:153], off offset:256
	v_addc_co_u32_e32 v157, vcc, 0, v155, vcc
	s_nop 0
	v_cvt_pk_bf16_f32 v150, v40, v41
	v_cvt_pk_bf16_f32 v151, v42, v43
	v_cvt_pk_bf16_f32 v152, v36, v37
	v_cvt_pk_bf16_f32 v153, v38, v39
	v_lshl_add_u64 v[142:143], v[154:155], 0, s[12:13]
	global_store_dwordx4 v[156:157], v[150:153], off
	v_add_co_u32_e32 v156, vcc, s64, v154
	s_nop 0
	v_cvt_pk_bf16_f32 v150, v44, v45
	v_cvt_pk_bf16_f32 v151, v46, v47
	v_cvt_pk_bf16_f32 v152, v32, v33
	v_cvt_pk_bf16_f32 v153, v34, v35
	global_store_dwordx4 v[142:143], v[150:153], off offset:256
	v_addc_co_u32_e32 v157, vcc, 0, v155, vcc
	s_nop 0
	v_cvt_pk_bf16_f32 v150, v24, v25
	v_cvt_pk_bf16_f32 v151, v26, v27
	v_cvt_pk_bf16_f32 v152, v20, v21
	v_cvt_pk_bf16_f32 v153, v22, v23
	v_lshl_add_u64 v[142:143], v[154:155], 0, s[14:15]
	global_store_dwordx4 v[156:157], v[150:153], off
	s_nop 1
	v_cvt_pk_bf16_f32 v150, v28, v29
	v_cvt_pk_bf16_f32 v151, v30, v31
	v_cvt_pk_bf16_f32 v152, v16, v17
	v_cvt_pk_bf16_f32 v153, v18, v19
	global_store_dwordx4 v[142:143], v[150:153], off offset:256
	v_lshl_add_u64 v[142:143], v[154:155], 0, s[16:17]
	v_add_co_u32_e32 v154, vcc, s65, v154
	v_cvt_pk_bf16_f32 v150, v8, v9
	v_cvt_pk_bf16_f32 v151, v10, v11
	v_cvt_pk_bf16_f32 v152, v4, v5
	v_cvt_pk_bf16_f32 v153, v6, v7
	v_addc_co_u32_e32 v155, vcc, 0, v155, vcc
	global_store_dwordx4 v[154:155], v[150:153], off
	s_nop 1
	v_cvt_pk_bf16_f32 v150, v12, v13
	v_cvt_pk_bf16_f32 v151, v14, v15
	v_cvt_pk_bf16_f32 v152, v0, v1
	v_cvt_pk_bf16_f32 v153, v2, v3
	global_store_dwordx4 v[142:143], v[150:153], off offset:256
	s_cbranch_execnz .LBB0_1223
	s_branch .LBB0_1246

; #define PG8_STAGE(bufoff, gbase, voff) do { _Pragma("unroll") for (int _i = 0; _i < 2; ++_i) \
;         __builtin_amdgcn_global_load_lds((const unsigned*)((const char*)(gbase) + (voff)[_i]), (LAS unsigned*)(lds + (bufoff) + ldsw + _i * 8192), 16, 0, 0); } while (0)
; #define PG8_LDA(dst, b, h) do { _Pragma("unroll") for (int m = 0; m < 4; ++m) _Pragma("unroll") for (int k = 0; k < 2; ++k) dst[m][k] = *(const LAS bf16x8*)(lds + PG8_SA(b, h) + aoff + m * 2048 + k * 1024); } while (0)
; #define PG8_LDB(dst, b, h) do { _Pragma("unroll") for (int n = 0; n < 2; ++n) _Pragma("unroll") for (int k = 0; k < 2; ++k) dst[n][k] = *(const LAS bf16x8*)(lds + PG8_SB(b, h) + boff + n * 2048 + k * 1024); } while (0)
; #define PG8_MMA(ai, bj, At, Bt) do { __builtin_amdgcn_s_setprio(1); _Pragma("unroll") for (int m = 0; m < 4; ++m) _Pragma("unroll") for (int n = 0; n < 2; ++n) _Pragma("unroll") for (int k = 0; k < 2; ++k) \
;         acc[ai][bj][m][n] = __builtin_amdgcn_mfma_f32_16x16x32_bf16(Bt[n][k], At[m][k], acc[ai][bj][m][n], 0, 0, 0); __builtin_amdgcn_s_setprio(0); } while (0)
; #define PG8_WAIT_L(n) asm volatile("s_waitcnt lgkmcnt(" #n ")" ::: "memory")
; #define PG8_BAR __builtin_amdgcn_s_barrier()
; #define PG8_SCHED __builtin_amdgcn_sched_barrier(0)
; template <class Epi, class Sched>
; __device__ __forceinline__ void gemm_phase(LAS unsigned char* lds, const Gemm g, const Sched& S, const Epi& E) {
;     ...
;         for (int t = 0; t < nt; t += 2) {
;             const bool last = (t == nt - 2);
;             const char* a1 = cA + (size_t)(t + 1) * kstep;
;             const char* a2 = last ? nA : cA + (size_t)(t + 2) * kstep; const char* b2 = last ? nB : cB + (size_t)(t + 2) * kstep;
;             const char* a3 = a2 + kstep; const char* b3 = b2 + kstep;
;             PG8_LDB(B0, 0, 0); PG8_SCHED; PG8_LDA(At, 0, 0); PG8_STAGE(PG8_SA(1, 1), a1 + hstep, voffA);
;             PG8_WAIT_L(8); PG8_BAR; PG8_WAIT_L(0); PG8_MMA(0, 0, At, B0); PG8_BAR; PG8_SCHED;
;             PG8_LDB(B1, 0, 1); PG8_STAGE(PG8_SB(0, 0), b2, voffB);
;             PG8_BAR; PG8_WAIT_L(0); PG8_MMA(0, 1, At, B1); PG8_BAR;
;             PG8_LDA(At, 0, 1); PG8_STAGE(PG8_SA(0, 0), a2, voffA);
;             PG8_BAR; PG8_WAIT_L(0); PG8_MMA(1, 0, At, B0); PG8_BAR; PG8_SCHED;
.LBB0_1322:
	ds_read_b128 v[128:131], v189
	ds_read_b128 v[132:135], v189 offset:1024
	ds_read_b128 v[136:139], v189 offset:2048
	ds_read_b128 v[140:143], v189 offset:3072
	s_add_u32 s36, s34, 0x4000
	s_addc_u32 s37, s35, 0
	s_cmp_eq_u32 s61, 28
	s_cselect_b32 s40, s17, s36
	s_cselect_b32 s41, s9, s37
	s_cselect_b32 s36, s33, s59
	s_cselect_b32 s37, s19, s60
	s_add_u32 s38, s40, 0x8000
	s_addc_u32 s39, s41, 0
	v_lshl_add_u64 v[196:197], s[34:35], 0, v[170:171]
	s_add_i32 m0, s47, 0xc000
	ds_read_b128 v[144:147], v190
	ds_read_b128 v[148:151], v190 offset:1024
	ds_read_b128 v[152:155], v190 offset:2048
	ds_read_b128 v[156:159], v190 offset:3072
	ds_read_b128 v[174:177], v190 offset:4096
	ds_read_b128 v[178:181], v190 offset:5120
	ds_read_b128 v[182:185], v190 offset:6144
	ds_read_b128 v[192:195], v190 offset:7168
	global_load_lds_dwordx4 v[196:197], off
	v_lshl_add_u64 v[196:197], s[34:35], 0, v[172:173]
	s_add_i32 m0, s47, 0xe000
	s_nop 0
	global_load_lds_dwordx4 v[196:197], off
	s_waitcnt lgkmcnt(8)
	s_barrier
	s_waitcnt lgkmcnt(0)
	s_waitcnt lgkmcnt(0)
	v_mfma_f32_16x16x32_bf16 v[124:127], v[128:131], v[144:147], v[124:127]
	v_mfma_f32_16x16x32_bf16 v[120:123], v[136:139], v[144:147], v[120:123]
	v_mfma_f32_16x16x32_bf16 v[108:111], v[128:131], v[152:155], v[108:111]
	v_mfma_f32_16x16x32_bf16 v[104:107], v[136:139], v[152:155], v[104:107]
	v_mfma_f32_16x16x32_bf16 v[92:95], v[128:131], v[174:177], v[92:95]
	v_mfma_f32_16x16x32_bf16 v[88:91], v[136:139], v[174:177], v[88:91]
	v_mfma_f32_16x16x32_bf16 v[76:79], v[128:131], v[182:185], v[76:79]
	v_mfma_f32_16x16x32_bf16 v[72:75], v[136:139], v[182:185], v[72:75]
	v_mfma_f32_16x16x32_bf16 v[124:127], v[132:135], v[148:151], v[124:127]
	v_mfma_f32_16x16x32_bf16 v[120:123], v[140:143], v[148:151], v[120:123]
	v_mfma_f32_16x16x32_bf16 v[108:111], v[132:135], v[156:159], v[108:111]
	v_mfma_f32_16x16x32_bf16 v[104:107], v[140:143], v[156:159], v[104:107]
	v_mfma_f32_16x16x32_bf16 v[92:95], v[132:135], v[178:181], v[92:95]
	v_mfma_f32_16x16x32_bf16 v[88:91], v[140:143], v[178:181], v[88:91]
	v_mfma_f32_16x16x32_bf16 v[76:79], v[132:135], v[192:195], v[76:79]
	v_mfma_f32_16x16x32_bf16 v[72:75], v[140:143], v[192:195], v[72:75]
	s_barrier
	s_add_i32 s62, s71, s46
	v_lshl_add_u64 v[214:215], s[36:37], 0, v[162:163]
	s_mov_b32 m0, s62
	ds_read_b128 v[196:199], v191
	ds_read_b128 v[200:203], v191 offset:1024
	ds_read_b128 v[206:209], v191 offset:2048
	ds_read_b128 v[210:213], v191 offset:3072
	global_load_lds_dwordx4 v[214:215], off
	v_lshl_add_u64 v[214:215], s[36:37], 0, v[166:167]
	s_add_i32 m0, s62, 0x2000
	s_nop 0
	global_load_lds_dwordx4 v[214:215], off
	s_barrier
	s_waitcnt lgkmcnt(0)
	s_waitcnt lgkmcnt(0)
	v_mfma_f32_16x16x32_bf16 v[116:119], v[196:199], v[144:147], v[116:119]
	v_mfma_f32_16x16x32_bf16 v[112:115], v[206:209], v[144:147], v[112:115]
	v_mfma_f32_16x16x32_bf16 v[100:103], v[196:199], v[152:155], v[100:103]
	v_mfma_f32_16x16x32_bf16 v[96:99], v[206:209], v[152:155], v[96:99]
	v_mfma_f32_16x16x32_bf16 v[84:87], v[196:199], v[174:177], v[84:87]
	v_mfma_f32_16x16x32_bf16 v[80:83], v[206:209], v[174:177], v[80:83]
	v_mfma_f32_16x16x32_bf16 v[68:71], v[196:199], v[182:185], v[68:71]
	v_mfma_f32_16x16x32_bf16 v[64:67], v[206:209], v[182:185], v[64:67]
	v_mfma_f32_16x16x32_bf16 v[116:119], v[200:203], v[148:151], v[116:119]
	v_mfma_f32_16x16x32_bf16 v[112:115], v[210:213], v[148:151], v[112:115]
	v_mfma_f32_16x16x32_bf16 v[100:103], v[200:203], v[156:159], v[100:103]
	v_mfma_f32_16x16x32_bf16 v[96:99], v[210:213], v[156:159], v[96:99]
	v_mfma_f32_16x16x32_bf16 v[84:87], v[200:203], v[178:181], v[84:87]
	v_mfma_f32_16x16x32_bf16 v[80:83], v[210:213], v[178:181], v[80:83]
	v_mfma_f32_16x16x32_bf16 v[68:71], v[200:203], v[192:195], v[68:71]
	v_mfma_f32_16x16x32_bf16 v[64:67], v[210:213], v[192:195], v[64:67]
	s_mov_b32 m0, s47
	v_lshl_add_u64 v[214:215], s[40:41], 0, v[160:161]
	s_barrier
	ds_read_b128 v[144:147], v190 offset:16384
	ds_read_b128 v[148:151], v190 offset:17408
	ds_read_b128 v[152:155], v190 offset:18432
	ds_read_b128 v[156:159], v190 offset:19456
	ds_read_b128 v[174:177], v190 offset:20480
	ds_read_b128 v[178:181], v190 offset:21504
	ds_read_b128 v[182:185], v190 offset:22528
	ds_read_b128 v[192:195], v190 offset:23552
	global_load_lds_dwordx4 v[214:215], off
	v_lshl_add_u64 v[214:215], s[40:41], 0, v[164:165]
	s_mov_b32 m0, s48
	s_nop 0
	global_load_lds_dwordx4 v[214:215], off
	s_barrier
	s_waitcnt lgkmcnt(0)
	s_waitcnt lgkmcnt(0)
	v_mfma_f32_16x16x32_bf16 v[60:63], v[128:131], v[144:147], v[60:63]
	v_mfma_f32_16x16x32_bf16 v[56:59], v[136:139], v[144:147], v[56:59]
	v_mfma_f32_16x16x32_bf16 v[44:47], v[128:131], v[152:155], v[44:47]
	v_mfma_f32_16x16x32_bf16 v[40:43], v[136:139], v[152:155], v[40:43]
	v_mfma_f32_16x16x32_bf16 v[28:31], v[128:131], v[174:177], v[28:31]
	v_mfma_f32_16x16x32_bf16 v[24:27], v[136:139], v[174:177], v[24:27]
	v_mfma_f32_16x16x32_bf16 v[12:15], v[128:131], v[182:185], v[12:15]
	v_mfma_f32_16x16x32_bf16 v[8:11], v[136:139], v[182:185], v[8:11]
	v_mfma_f32_16x16x32_bf16 v[60:63], v[132:135], v[148:151], v[60:63]
	v_mfma_f32_16x16x32_bf16 v[56:59], v[140:143], v[148:151], v[56:59]
	v_mfma_f32_16x16x32_bf16 v[44:47], v[132:135], v[156:159], v[44:47]
	v_mfma_f32_16x16x32_bf16 v[40:43], v[140:143], v[156:159], v[40:43]
	v_mfma_f32_16x16x32_bf16 v[28:31], v[132:135], v[178:181], v[28:31]
	v_mfma_f32_16x16x32_bf16 v[24:27], v[140:143], v[178:181], v[24:27]
	v_mfma_f32_16x16x32_bf16 v[12:15], v[132:135], v[192:195], v[12:15]
	v_mfma_f32_16x16x32_bf16 v[8:11], v[140:143], v[192:195], v[8:11]
	s_barrier
; #define PG8_STAGE(bufoff, gbase, voff) do { _Pragma("unroll") for (int _i = 0; _i < 2; ++_i) \
;         __builtin_amdgcn_global_load_lds((const unsigned*)((const char*)(gbase) + (voff)[_i]), (LAS unsigned*)(lds + (bufoff) + ldsw + _i * 8192), 16, 0, 0); } while (0)
; #define PG8_LDA(dst, b, h) do { _Pragma("unroll") for (int m = 0; m < 4; ++m) _Pragma("unroll") for (int k = 0; k < 2; ++k) dst[m][k] = *(const LAS bf16x8*)(lds + PG8_SA(b, h) + aoff + m * 2048 + k * 1024); } while (0)
; #define PG8_LDB(dst, b, h) do { _Pragma("unroll") for (int n = 0; n < 2; ++n) _Pragma("unroll") for (int k = 0; k < 2; ++k) dst[n][k] = *(const LAS bf16x8*)(lds + PG8_SB(b, h) + boff + n * 2048 + k * 1024); } while (0)
; #define PG8_MMA(ai, bj, At, Bt) do { __builtin_amdgcn_s_setprio(1); _Pragma("unroll") for (int m = 0; m < 4; ++m) _Pragma("unroll") for (int n = 0; n < 2; ++n) _Pragma("unroll") for (int k = 0; k < 2; ++k) \
;         acc[ai][bj][m][n] = __builtin_amdgcn_mfma_f32_16x16x32_bf16(Bt[n][k], At[m][k], acc[ai][bj][m][n], 0, 0, 0); __builtin_amdgcn_s_setprio(0); } while (0)
; #define PG8_WAIT_V(n) asm volatile("s_waitcnt vmcnt(" #n ")" ::: "memory")
; #define PG8_WAIT_L(n) asm volatile("s_waitcnt lgkmcnt(" #n ")" ::: "memory")
; #define PG8_BAR __builtin_amdgcn_s_barrier()
; #define PG8_SCHED __builtin_amdgcn_sched_barrier(0)
; template <class Epi, class Sched>
; __device__ __forceinline__ void gemm_phase(LAS unsigned char* lds, const Gemm g, const Sched& S, const Epi& E) {
;     ...
;             PG8_STAGE(PG8_SB(0, 1), b2 + hstep, voffB);
;             PG8_WAIT_V(6); PG8_BAR; PG8_MMA(1, 1, At, B1); PG8_BAR;
;             PG8_LDB(B0, 1, 0); PG8_SCHED; PG8_LDA(At, 1, 0); PG8_STAGE(PG8_SA(0, 1), a2 + hstep, voffA);
;             PG8_WAIT_L(8); PG8_BAR; PG8_WAIT_L(0); PG8_MMA(0, 0, At, B0); PG8_BAR; PG8_SCHED;
;             PG8_LDB(B1, 1, 1); PG8_STAGE(PG8_SB(1, 0), b3, voffB);
;             PG8_BAR; PG8_WAIT_L(0); PG8_MMA(0, 1, At, B1); PG8_BAR;
;             PG8_LDA(At, 1, 1); PG8_STAGE(PG8_SA(1, 0), a3, voffA);
	s_add_u32 s62, s36, 0x4000
	s_addc_u32 s63, s37, 0
	s_add_i32 s64, s57, s46
	v_lshl_add_u64 v[128:129], s[62:63], 0, v[162:163]
	s_mov_b32 m0, s64
	s_nop 0
	global_load_lds_dwordx4 v[128:129], off
	v_lshl_add_u64 v[128:129], s[62:63], 0, v[166:167]
	s_add_i32 m0, s64, 0x2000
	s_nop 0
	global_load_lds_dwordx4 v[128:129], off
	s_waitcnt vmcnt(6)
	s_barrier
	v_mfma_f32_16x16x32_bf16 v[52:55], v[196:199], v[144:147], v[52:55]
	v_mfma_f32_16x16x32_bf16 v[48:51], v[206:209], v[144:147], v[48:51]
	v_mfma_f32_16x16x32_bf16 v[36:39], v[196:199], v[152:155], v[36:39]
	v_mfma_f32_16x16x32_bf16 v[32:35], v[206:209], v[152:155], v[32:35]
	v_mfma_f32_16x16x32_bf16 v[20:23], v[196:199], v[174:177], v[20:23]
	v_mfma_f32_16x16x32_bf16 v[16:19], v[206:209], v[174:177], v[16:19]
	v_mfma_f32_16x16x32_bf16 v[4:7], v[196:199], v[182:185], v[4:7]
	v_mfma_f32_16x16x32_bf16 v[0:3], v[206:209], v[182:185], v[0:3]
	v_mfma_f32_16x16x32_bf16 v[52:55], v[200:203], v[148:151], v[52:55]
	v_mfma_f32_16x16x32_bf16 v[48:51], v[210:213], v[148:151], v[48:51]
	v_mfma_f32_16x16x32_bf16 v[36:39], v[200:203], v[156:159], v[36:39]
	v_mfma_f32_16x16x32_bf16 v[32:35], v[210:213], v[156:159], v[32:35]
	v_mfma_f32_16x16x32_bf16 v[20:23], v[200:203], v[178:181], v[20:23]
	v_mfma_f32_16x16x32_bf16 v[16:19], v[210:213], v[178:181], v[16:19]
	v_mfma_f32_16x16x32_bf16 v[4:7], v[200:203], v[192:195], v[4:7]
	v_mfma_f32_16x16x32_bf16 v[0:3], v[210:213], v[192:195], v[0:3]
	s_add_i32 s62, 0, 0x18000
	v_add_u32_e32 v140, s62, v188
	s_barrier
	ds_read_b128 v[128:131], v140
	ds_read_b128 v[132:135], v140 offset:1024
	ds_read_b128 v[136:139], v140 offset:2048
	ds_read_b128 v[140:143], v140 offset:3072
	s_add_u32 s40, s40, 0x4000
	s_addc_u32 s41, s41, 0
	s_mov_b32 m0, s49
	v_lshl_add_u64 v[196:197], s[40:41], 0, v[160:161]
	ds_read_b128 v[144:147], v190 offset:32768
	ds_read_b128 v[148:151], v190 offset:33792
	ds_read_b128 v[152:155], v190 offset:34816
	ds_read_b128 v[156:159], v190 offset:35840
	ds_read_b128 v[174:177], v190 offset:36864
	ds_read_b128 v[178:181], v190 offset:37888
	ds_read_b128 v[182:185], v190 offset:38912
	ds_read_b128 v[192:195], v190 offset:39936
	global_load_lds_dwordx4 v[196:197], off
	v_lshl_add_u64 v[196:197], s[40:41], 0, v[164:165]
	s_mov_b32 m0, s50
	s_nop 0
	global_load_lds_dwordx4 v[196:197], off
	s_waitcnt lgkmcnt(8)
	s_barrier
	s_waitcnt lgkmcnt(0)
	s_waitcnt lgkmcnt(0)
	v_mfma_f32_16x16x32_bf16 v[124:127], v[128:131], v[144:147], v[124:127]
	v_mfma_f32_16x16x32_bf16 v[120:123], v[136:139], v[144:147], v[120:123]
	v_mfma_f32_16x16x32_bf16 v[108:111], v[128:131], v[152:155], v[108:111]
	v_mfma_f32_16x16x32_bf16 v[104:107], v[136:139], v[152:155], v[104:107]
	v_mfma_f32_16x16x32_bf16 v[92:95], v[128:131], v[174:177], v[92:95]
	v_mfma_f32_16x16x32_bf16 v[88:91], v[136:139], v[174:177], v[88:91]
	v_mfma_f32_16x16x32_bf16 v[76:79], v[128:131], v[182:185], v[76:79]
	v_mfma_f32_16x16x32_bf16 v[72:75], v[136:139], v[182:185], v[72:75]
	v_mfma_f32_16x16x32_bf16 v[124:127], v[132:135], v[148:151], v[124:127]
	v_mfma_f32_16x16x32_bf16 v[120:123], v[140:143], v[148:151], v[120:123]
	v_mfma_f32_16x16x32_bf16 v[108:111], v[132:135], v[156:159], v[108:111]
	v_mfma_f32_16x16x32_bf16 v[104:107], v[140:143], v[156:159], v[104:107]
	v_mfma_f32_16x16x32_bf16 v[92:95], v[132:135], v[178:181], v[92:95]
	v_mfma_f32_16x16x32_bf16 v[88:91], v[140:143], v[178:181], v[88:91]
	v_mfma_f32_16x16x32_bf16 v[76:79], v[132:135], v[192:195], v[76:79]
	v_mfma_f32_16x16x32_bf16 v[72:75], v[140:143], v[192:195], v[72:75]
	s_barrier
	s_add_i32 s63, 0, 0x1c000
	s_add_u32 s40, s36, 0x8000
	s_addc_u32 s41, s37, 0
	s_add_i32 s62, s62, s46
	v_add_u32_e32 v168, s63, v188
	v_lshl_add_u64 v[214:215], s[40:41], 0, v[162:163]
	s_mov_b32 m0, s62
	ds_read_b128 v[196:199], v168
	ds_read_b128 v[200:203], v168 offset:1024
	ds_read_b128 v[206:209], v168 offset:2048
	ds_read_b128 v[210:213], v168 offset:3072
	global_load_lds_dwordx4 v[214:215], off
	v_lshl_add_u64 v[214:215], s[40:41], 0, v[166:167]
	s_add_i32 m0, s62, 0x2000
	s_nop 0
	global_load_lds_dwordx4 v[214:215], off
	s_barrier
	s_waitcnt lgkmcnt(0)
	s_waitcnt lgkmcnt(0)
	v_mfma_f32_16x16x32_bf16 v[116:119], v[196:199], v[144:147], v[116:119]
	v_mfma_f32_16x16x32_bf16 v[112:115], v[206:209], v[144:147], v[112:115]
	v_mfma_f32_16x16x32_bf16 v[100:103], v[196:199], v[152:155], v[100:103]
	v_mfma_f32_16x16x32_bf16 v[96:99], v[206:209], v[152:155], v[96:99]
	v_mfma_f32_16x16x32_bf16 v[84:87], v[196:199], v[174:177], v[84:87]
	v_mfma_f32_16x16x32_bf16 v[80:83], v[206:209], v[174:177], v[80:83]
	v_mfma_f32_16x16x32_bf16 v[68:71], v[196:199], v[182:185], v[68:71]
	v_mfma_f32_16x16x32_bf16 v[64:67], v[206:209], v[182:185], v[64:67]
	v_mfma_f32_16x16x32_bf16 v[116:119], v[200:203], v[148:151], v[116:119]
	v_mfma_f32_16x16x32_bf16 v[112:115], v[210:213], v[148:151], v[112:115]
	v_mfma_f32_16x16x32_bf16 v[100:103], v[200:203], v[156:159], v[100:103]
	v_mfma_f32_16x16x32_bf16 v[96:99], v[210:213], v[156:159], v[96:99]
	v_mfma_f32_16x16x32_bf16 v[84:87], v[200:203], v[178:181], v[84:87]
	v_mfma_f32_16x16x32_bf16 v[80:83], v[210:213], v[178:181], v[80:83]
	v_mfma_f32_16x16x32_bf16 v[68:71], v[200:203], v[192:195], v[68:71]
	v_mfma_f32_16x16x32_bf16 v[64:67], v[210:213], v[192:195], v[64:67]
	s_mov_b32 m0, s55
	v_lshl_add_u64 v[214:215], s[38:39], 0, v[160:161]
	s_barrier
	ds_read_b128 v[144:147], v190 offset:49152
	ds_read_b128 v[148:151], v190 offset:50176
	ds_read_b128 v[152:155], v190 offset:51200
	ds_read_b128 v[156:159], v190 offset:52224
	ds_read_b128 v[174:177], v190 offset:53248
	ds_read_b128 v[178:181], v190 offset:54272
	ds_read_b128 v[182:185], v190 offset:55296
	ds_read_b128 v[192:195], v190 offset:56320
	global_load_lds_dwordx4 v[214:215], off
	v_lshl_add_u64 v[214:215], s[38:39], 0, v[164:165]
	s_mov_b32 m0, s56
	s_nop 0
	global_load_lds_dwordx4 v[214:215], off
	s_barrier
; __device__ __forceinline__ size_t tl(int r, int c, int K) { return ((size_t)(r >> 8) * (size_t)(K >> 6) + (size_t)(c >> 6)) * 16384 + (size_t)((r & 255) << 6) + (size_t)(c & 63); }
; #define PG8_STAGE(bufoff, gbase, voff) do { _Pragma("unroll") for (int _i = 0; _i < 2; ++_i) \
;         __builtin_amdgcn_global_load_lds((const unsigned*)((const char*)(gbase) + (voff)[_i]), (LAS unsigned*)(lds + (bufoff) + ldsw + _i * 8192), 16, 0, 0); } while (0)
; #define PG8_MMA(ai, bj, At, Bt) do { __builtin_amdgcn_s_setprio(1); _Pragma("unroll") for (int m = 0; m < 4; ++m) _Pragma("unroll") for (int n = 0; n < 2; ++n) _Pragma("unroll") for (int k = 0; k < 2; ++k) \
;         acc[ai][bj][m][n] = __builtin_amdgcn_mfma_f32_16x16x32_bf16(Bt[n][k], At[m][k], acc[ai][bj][m][n], 0, 0, 0); __builtin_amdgcn_s_setprio(0); } while (0)
; #define PG8_WAIT_V(n) asm volatile("s_waitcnt vmcnt(" #n ")" ::: "memory")
; template <class Epi, class Sched>
; __device__ __forceinline__ void gemm_phase(LAS unsigned char* lds, const Gemm g, const Sched& S, const Epi& E) {
;     ...
;             PG8_BAR; PG8_WAIT_L(0); PG8_MMA(1, 0, At, B0); PG8_BAR; PG8_SCHED;
;             PG8_STAGE(PG8_SB(1, 1), b3 + hstep, voffB);
;             PG8_WAIT_V(6); PG8_BAR; PG8_MMA(1, 1, At, B1); PG8_BAR;
;     __device__ __forceinline__ void operator()(const f32x4 (&acc)[2][2][4][2], const Unit& u, int wr, int wc, int fr, int fq) const {
;         const int br = u.pn >> 3, pn8 = u.pn & 7;
;         const bf16_t* y = y0 + (long)(br == 1) * d1 + (long)(br == 2) * d2;
;         const int row0 = u.pm * BM + wr * 64 + fr, col0 = pn8 * BM + wc * 32 + 8 * fq;
; #pragma unroll
;         for (int ai = 0; ai < 2; ++ai)
; #pragma unroll
;             for (int mh = 0; mh < 2; ++mh) {
;                 u32x4 yw[2][2], mw[2][2];
; #pragma unroll
;                 for (int mm = 0; mm < 2; ++mm) {
;                     const int rr = row0 + ai * HALF + (mh * 2 + mm) * 16;
;                     const size_t off = (size_t)rr * DM + col0;
; #pragma unroll
;                     for (int bj = 0; bj < 2; ++bj) {
;                         yw[mm][bj] = *(const u32x4*)(y + off + bj * HALF);
;                         mw[mm][bj] = (u32x4){0u, 0u, 0u, 0u};
;                         if (br != 0) mw[mm][bj] = *(const u32x4*)(merged + tl(rr, col0 + bj * HALF, DM));
;                     }
;                 }
	s_waitcnt lgkmcnt(0)
	s_waitcnt lgkmcnt(0)
	v_mfma_f32_16x16x32_bf16 v[60:63], v[128:131], v[144:147], v[60:63]
	v_mfma_f32_16x16x32_bf16 v[56:59], v[136:139], v[144:147], v[56:59]
	v_mfma_f32_16x16x32_bf16 v[44:47], v[128:131], v[152:155], v[44:47]
	v_mfma_f32_16x16x32_bf16 v[40:43], v[136:139], v[152:155], v[40:43]
	v_mfma_f32_16x16x32_bf16 v[28:31], v[128:131], v[174:177], v[28:31]
	v_mfma_f32_16x16x32_bf16 v[24:27], v[136:139], v[174:177], v[24:27]
	v_mfma_f32_16x16x32_bf16 v[12:15], v[128:131], v[182:185], v[12:15]
	v_mfma_f32_16x16x32_bf16 v[8:11], v[136:139], v[182:185], v[8:11]
	v_mfma_f32_16x16x32_bf16 v[60:63], v[132:135], v[148:151], v[60:63]
	v_mfma_f32_16x16x32_bf16 v[56:59], v[140:143], v[148:151], v[56:59]
	v_mfma_f32_16x16x32_bf16 v[44:47], v[132:135], v[156:159], v[44:47]
	v_mfma_f32_16x16x32_bf16 v[40:43], v[140:143], v[156:159], v[40:43]
	v_mfma_f32_16x16x32_bf16 v[28:31], v[132:135], v[178:181], v[28:31]
	v_mfma_f32_16x16x32_bf16 v[24:27], v[140:143], v[178:181], v[24:27]
	v_mfma_f32_16x16x32_bf16 v[12:15], v[132:135], v[192:195], v[12:15]
	v_mfma_f32_16x16x32_bf16 v[8:11], v[140:143], v[192:195], v[8:11]
	s_barrier
	s_add_u32 s36, s36, 0xc000
	s_addc_u32 s37, s37, 0
	s_add_i32 s38, s63, s46
	v_lshl_add_u64 v[128:129], s[36:37], 0, v[162:163]
	s_mov_b32 m0, s38
	s_nop 0
	global_load_lds_dwordx4 v[128:129], off
	v_lshl_add_u64 v[128:129], s[36:37], 0, v[166:167]
	s_add_i32 m0, s38, 0x2000
	s_nop 0
	global_load_lds_dwordx4 v[128:129], off
	s_waitcnt vmcnt(6)
	s_barrier
	v_mfma_f32_16x16x32_bf16 v[52:55], v[196:199], v[144:147], v[52:55]
	v_mfma_f32_16x16x32_bf16 v[48:51], v[206:209], v[144:147], v[48:51]
	v_mfma_f32_16x16x32_bf16 v[36:39], v[196:199], v[152:155], v[36:39]
	v_mfma_f32_16x16x32_bf16 v[32:35], v[206:209], v[152:155], v[32:35]
	v_mfma_f32_16x16x32_bf16 v[20:23], v[196:199], v[174:177], v[20:23]
	v_mfma_f32_16x16x32_bf16 v[16:19], v[206:209], v[174:177], v[16:19]
	v_mfma_f32_16x16x32_bf16 v[4:7], v[196:199], v[182:185], v[4:7]
	v_mfma_f32_16x16x32_bf16 v[0:3], v[206:209], v[182:185], v[0:3]
	v_mfma_f32_16x16x32_bf16 v[52:55], v[200:203], v[148:151], v[52:55]
	v_mfma_f32_16x16x32_bf16 v[48:51], v[210:213], v[148:151], v[48:51]
	v_mfma_f32_16x16x32_bf16 v[36:39], v[200:203], v[156:159], v[36:39]
	v_mfma_f32_16x16x32_bf16 v[32:35], v[210:213], v[156:159], v[32:35]
	v_mfma_f32_16x16x32_bf16 v[20:23], v[200:203], v[178:181], v[20:23]
	v_mfma_f32_16x16x32_bf16 v[16:19], v[210:213], v[178:181], v[16:19]
	v_mfma_f32_16x16x32_bf16 v[4:7], v[200:203], v[192:195], v[4:7]
	v_mfma_f32_16x16x32_bf16 v[0:3], v[210:213], v[192:195], v[0:3]
	s_add_i32 s61, s61, 2
	s_add_u32 s34, s34, 0x10000
	s_addc_u32 s35, s35, 0
	s_add_u32 s59, s59, 0x10000
	s_addc_u32 s60, s60, 0
	s_cmp_gt_u32 s61, 29
	s_barrier
	s_cbranch_scc0 .LBB0_1322
	s_nop 7
	s_ashr_i32 s9, s8, 3
	s_cmp_eq_u32 s9, 1
	s_cselect_b32 s17, 0x4000000, 0
	s_add_u32 s17, s51, s17
	s_addc_u32 s19, s52, 0
	s_cmp_eq_u32 s9, 2
	s_cselect_b32 s38, 0xac00000, 0
	s_add_u32 s34, s17, s38
	s_addc_u32 s35, s19, 0
	s_lshl_b32 s36, s10, 8
	s_add_i32 s36, s36, s53
	s_lshl_b32 s37, s8, 8
	s_and_b32 s37, s37, 0x700
	s_or_b32 s37, s37, s54
	v_or_b32_e32 v174, s36, v186
	v_or_b32_e32 v175, s37, v187
	v_lshlrev_b32_e32 v176, 12, v174
	v_lshl_add_u32 v176, v175, 1, v176
	v_lshrrev_b32_e32 v177, 6, v175
	v_lshl_add_u32 v177, s10, 5, v177
	v_lshlrev_b32_e32 v177, 14, v177
	v_and_b32_e32 v198, 0xff, v174
	v_lshl_add_u32 v177, v198, 6, v177
	v_and_b32_e32 v198, 63, v175
	v_add_u32_e32 v177, v177, v198
	v_lshlrev_b32_e32 v177, 1, v177
	s_cmp_eq_u32 s9, 0
	s_cbranch_scc1 .Lmy_p9_br0
	v_mov_b32_e32 v178, v176
	v_mov_b32_e32 v180, v177
	v_add_u32_e32 v181, 0x10000, v177
	v_add_u32_e32 v179, 0x10000, v176
	v_add_u32_e32 v182, 0x800, v177
	v_add_u32_e32 v183, 0x10800, v177
	global_load_dwordx4 v[216:219], v178, s[34:35]
	global_load_dwordx4 v[220:223], v180, s[12:13]
	global_load_dwordx4 v[224:227], v178, s[34:35] offset:256
	global_load_dwordx4 v[228:231], v181, s[12:13]
	global_load_dwordx4 v[232:235], v179, s[34:35]
	global_load_dwordx4 v[236:239], v182, s[12:13]
	global_load_dwordx4 v[240:243], v179, s[34:35] offset:256
	global_load_dwordx4 v[244:247], v183, s[12:13]
	v_add_u32_e32 v192, 0x20000, v176
	v_add_u32_e32 v194, 0x1000, v177
	v_add_u32_e32 v195, 0x11000, v177
	v_add_u32_e32 v193, 0x30000, v176
	v_add_u32_e32 v196, 0x1800, v177
	v_add_u32_e32 v197, 0x11800, v177
	global_load_dwordx4 v[128:131], v192, s[34:35]
	global_load_dwordx4 v[132:135], v194, s[12:13]
	global_load_dwordx4 v[136:139], v192, s[34:35] offset:256
	global_load_dwordx4 v[140:143], v195, s[12:13]
	global_load_dwordx4 v[144:147], v193, s[34:35]
	global_load_dwordx4 v[148:151], v196, s[12:13]
	global_load_dwordx4 v[152:155], v193, s[34:35] offset:256
	global_load_dwordx4 v[156:159], v197, s[12:13]
	v_mul_f32_e32 v124, 0xbfb8aa3b, v124
	v_mul_f32_e32 v125, 0xbfb8aa3b, v125
	v_mul_f32_e32 v126, 0xbfb8aa3b, v126
	v_mul_f32_e32 v127, 0xbfb8aa3b, v127
	v_mul_f32_e32 v120, 0xbfb8aa3b, v120
	v_mul_f32_e32 v121, 0xbfb8aa3b, v121
	v_mul_f32_e32 v122, 0xbfb8aa3b, v122
	v_mul_f32_e32 v123, 0xbfb8aa3b, v123
	v_exp_f32_e32 v124, v124
	v_exp_f32_e32 v125, v125
	v_exp_f32_e32 v126, v126
	v_exp_f32_e32 v127, v127
	v_exp_f32_e32 v120, v120
	v_exp_f32_e32 v121, v121
	v_exp_f32_e32 v122, v122
	v_exp_f32_e32 v123, v123
	v_add_f32_e32 v124, 1.0, v124
	v_add_f32_e32 v125, 1.0, v125
	v_add_f32_e32 v126, 1.0, v126
	v_add_f32_e32 v127, 1.0, v127
	v_add_f32_e32 v120, 1.0, v120
	v_add_f32_e32 v121, 1.0, v121
	v_add_f32_e32 v122, 1.0, v122
	v_add_f32_e32 v123, 1.0, v123
	v_rcp_f32_e32 v124, v124
	v_rcp_f32_e32 v125, v125
	v_rcp_f32_e32 v126, v126
; __device__ __forceinline__ unsigned cvt_pk_bf16(float lo, float hi) { f32x2 v = {lo, hi}; bf16x2_t b = __builtin_convertvector(v, bf16x2_t); return __builtin_bit_cast(unsigned, b); }
; __device__ __forceinline__ float bflo(unsigned w) { return __uint_as_float(w << 16); }
; __device__ __forceinline__ float bfhi(unsigned w) { return __uint_as_float(w & 0xffff0000u); }
; __device__ __forceinline__ float sigmoid_f(float x) { return __builtin_amdgcn_rcpf(1.0f + __expf(-x)); }
; __device__ __forceinline__ size_t tl(int r, int c, int K) { return ((size_t)(r >> 8) * (size_t)(K >> 6) + (size_t)(c >> 6)) * 16384 + (size_t)((r & 255) << 6) + (size_t)(c & 63); }
;     __device__ __forceinline__ void operator()(const f32x4 (&acc)[2][2][4][2], const Unit& u, int wr, int wc, int fr, int fq) const {
;     ...
;                 for (int mm = 0; mm < 2; ++mm) {
;                     const int m = mh * 2 + mm;
;                     const int rr = row0 + ai * HALF + m * 16;
; #pragma unroll
;                     for (int bj = 0; bj < 2; ++bj) {
;                         const f32x4 a0 = acc[ai][bj][m][0], a1 = acc[ai][bj][m][1];
;                         const u32x4 yv = yw[mm][bj], mv = mw[mm][bj];
;                         u32x4 w;
;                         w.x = cvt_pk_bf16(sigmoid_f(a0[0]) * bflo(yv.x) + bflo(mv.x), sigmoid_f(a0[1]) * bfhi(yv.x) + bfhi(mv.x));
;                         w.y = cvt_pk_bf16(sigmoid_f(a0[2]) * bflo(yv.y) + bflo(mv.y), sigmoid_f(a0[3]) * bfhi(yv.y) + bfhi(mv.y));
;                         w.z = cvt_pk_bf16(sigmoid_f(a1[0]) * bflo(yv.z) + bflo(mv.z), sigmoid_f(a1[1]) * bfhi(yv.z) + bfhi(mv.z));
;                         w.w = cvt_pk_bf16(sigmoid_f(a1[2]) * bflo(yv.w) + bflo(mv.w), sigmoid_f(a1[3]) * bfhi(yv.w) + bfhi(mv.w));
;                         *(u32x4*)(merged + tl(rr, col0 + bj * HALF, DM)) = w;
	v_rcp_f32_e32 v127, v127
	v_rcp_f32_e32 v120, v120
	v_rcp_f32_e32 v121, v121
	v_rcp_f32_e32 v122, v122
	v_rcp_f32_e32 v123, v123
	v_mul_f32_e32 v116, 0xbfb8aa3b, v116
	v_mul_f32_e32 v117, 0xbfb8aa3b, v117
	v_mul_f32_e32 v118, 0xbfb8aa3b, v118
	v_mul_f32_e32 v119, 0xbfb8aa3b, v119
	v_mul_f32_e32 v112, 0xbfb8aa3b, v112
	v_mul_f32_e32 v113, 0xbfb8aa3b, v113
	v_mul_f32_e32 v114, 0xbfb8aa3b, v114
	v_mul_f32_e32 v115, 0xbfb8aa3b, v115
	v_exp_f32_e32 v116, v116
	v_exp_f32_e32 v117, v117
	v_exp_f32_e32 v118, v118
	v_exp_f32_e32 v119, v119
	v_exp_f32_e32 v112, v112
	v_exp_f32_e32 v113, v113
	v_exp_f32_e32 v114, v114
	v_exp_f32_e32 v115, v115
	v_add_f32_e32 v116, 1.0, v116
	v_add_f32_e32 v117, 1.0, v117
	v_add_f32_e32 v118, 1.0, v118
	v_add_f32_e32 v119, 1.0, v119
	v_add_f32_e32 v112, 1.0, v112
	v_add_f32_e32 v113, 1.0, v113
	v_add_f32_e32 v114, 1.0, v114
	v_add_f32_e32 v115, 1.0, v115
	v_rcp_f32_e32 v116, v116
	v_rcp_f32_e32 v117, v117
	v_rcp_f32_e32 v118, v118
	v_rcp_f32_e32 v119, v119
	v_rcp_f32_e32 v112, v112
	v_rcp_f32_e32 v113, v113
	v_rcp_f32_e32 v114, v114
	v_rcp_f32_e32 v115, v115
	v_mul_f32_e32 v108, 0xbfb8aa3b, v108
	v_mul_f32_e32 v109, 0xbfb8aa3b, v109
	v_mul_f32_e32 v110, 0xbfb8aa3b, v110
	v_mul_f32_e32 v111, 0xbfb8aa3b, v111
	v_mul_f32_e32 v104, 0xbfb8aa3b, v104
	v_mul_f32_e32 v105, 0xbfb8aa3b, v105
	v_mul_f32_e32 v106, 0xbfb8aa3b, v106
	v_mul_f32_e32 v107, 0xbfb8aa3b, v107
	v_exp_f32_e32 v108, v108
	v_exp_f32_e32 v109, v109
	v_exp_f32_e32 v110, v110
	v_exp_f32_e32 v111, v111
	v_exp_f32_e32 v104, v104
	v_exp_f32_e32 v105, v105
	v_exp_f32_e32 v106, v106
	v_exp_f32_e32 v107, v107
	v_add_f32_e32 v108, 1.0, v108
	v_add_f32_e32 v109, 1.0, v109
	v_add_f32_e32 v110, 1.0, v110
	v_add_f32_e32 v111, 1.0, v111
	v_add_f32_e32 v104, 1.0, v104
	v_add_f32_e32 v105, 1.0, v105
	v_add_f32_e32 v106, 1.0, v106
	v_add_f32_e32 v107, 1.0, v107
	v_rcp_f32_e32 v108, v108
	v_rcp_f32_e32 v109, v109
	v_rcp_f32_e32 v110, v110
	v_rcp_f32_e32 v111, v111
	v_rcp_f32_e32 v104, v104
	v_rcp_f32_e32 v105, v105
	v_rcp_f32_e32 v106, v106
	v_rcp_f32_e32 v107, v107
	v_mul_f32_e32 v100, 0xbfb8aa3b, v100
	v_mul_f32_e32 v101, 0xbfb8aa3b, v101
	v_mul_f32_e32 v102, 0xbfb8aa3b, v102
	v_mul_f32_e32 v103, 0xbfb8aa3b, v103
	v_mul_f32_e32 v96, 0xbfb8aa3b, v96
	v_mul_f32_e32 v97, 0xbfb8aa3b, v97
	v_mul_f32_e32 v98, 0xbfb8aa3b, v98
	v_mul_f32_e32 v99, 0xbfb8aa3b, v99
	v_exp_f32_e32 v100, v100
	v_exp_f32_e32 v101, v101
	v_exp_f32_e32 v102, v102
	v_exp_f32_e32 v103, v103
	v_exp_f32_e32 v96, v96
	v_exp_f32_e32 v97, v97
	v_exp_f32_e32 v98, v98
	v_exp_f32_e32 v99, v99
	v_add_f32_e32 v100, 1.0, v100
	v_add_f32_e32 v101, 1.0, v101
	v_add_f32_e32 v102, 1.0, v102
	v_add_f32_e32 v103, 1.0, v103
	v_add_f32_e32 v96, 1.0, v96
	v_add_f32_e32 v97, 1.0, v97
	v_add_f32_e32 v98, 1.0, v98
	v_add_f32_e32 v99, 1.0, v99
	v_rcp_f32_e32 v100, v100
	v_rcp_f32_e32 v101, v101
	v_rcp_f32_e32 v102, v102
	v_rcp_f32_e32 v103, v103
	v_rcp_f32_e32 v96, v96
	v_rcp_f32_e32 v97, v97
	v_rcp_f32_e32 v98, v98
	v_rcp_f32_e32 v99, v99
	s_waitcnt vmcnt(8)
	v_lshlrev_b32_e32 v198, 16, v216
	v_and_b32_e32 v199, 0xffff0000, v216
	v_lshlrev_b32_e32 v200, 16, v220
	v_and_b32_e32 v201, 0xffff0000, v220
	v_fma_f32 v124, v124, v198, v200
	v_fma_f32 v125, v125, v199, v201
	v_cvt_pk_bf16_f32 v248, v124, v125
	v_lshlrev_b32_e32 v202, 16, v217
	v_and_b32_e32 v203, 0xffff0000, v217
	v_lshlrev_b32_e32 v214, 16, v221
	v_and_b32_e32 v215, 0xffff0000, v221
	v_fma_f32 v126, v126, v202, v214
	v_fma_f32 v127, v127, v203, v215
	v_cvt_pk_bf16_f32 v249, v126, v127
	v_lshlrev_b32_e32 v198, 16, v218
	v_and_b32_e32 v199, 0xffff0000, v218
	v_lshlrev_b32_e32 v200, 16, v222
	v_and_b32_e32 v201, 0xffff0000, v222
	v_fma_f32 v120, v120, v198, v200
	v_fma_f32 v121, v121, v199, v201
	v_cvt_pk_bf16_f32 v250, v120, v121
	v_lshlrev_b32_e32 v202, 16, v219
	v_and_b32_e32 v203, 0xffff0000, v219
	v_lshlrev_b32_e32 v214, 16, v223
	v_and_b32_e32 v215, 0xffff0000, v223
	v_fma_f32 v122, v122, v202, v214
	v_fma_f32 v123, v123, v203, v215
	v_cvt_pk_bf16_f32 v251, v122, v123
	global_store_dwordx4 v180, v[248:251], s[12:13]
	v_lshlrev_b32_e32 v198, 16, v224
	v_and_b32_e32 v199, 0xffff0000, v224
	v_lshlrev_b32_e32 v200, 16, v228
	v_and_b32_e32 v201, 0xffff0000, v228
	v_fma_f32 v116, v116, v198, v200
	v_fma_f32 v117, v117, v199, v201
	v_cvt_pk_bf16_f32 v252, v116, v117
	v_lshlrev_b32_e32 v202, 16, v225
	v_and_b32_e32 v203, 0xffff0000, v225
	v_lshlrev_b32_e32 v214, 16, v229
	v_and_b32_e32 v215, 0xffff0000, v229
	v_fma_f32 v118, v118, v202, v214
	v_fma_f32 v119, v119, v203, v215
	v_cvt_pk_bf16_f32 v253, v118, v119
	v_lshlrev_b32_e32 v198, 16, v226
	v_and_b32_e32 v199, 0xffff0000, v226
	v_lshlrev_b32_e32 v200, 16, v230
	v_and_b32_e32 v201, 0xffff0000, v230
	v_fma_f32 v112, v112, v198, v200
	v_fma_f32 v113, v113, v199, v201
	v_cvt_pk_bf16_f32 v254, v112, v113
	v_lshlrev_b32_e32 v202, 16, v227
	v_and_b32_e32 v203, 0xffff0000, v227
	v_lshlrev_b32_e32 v214, 16, v231
	v_and_b32_e32 v215, 0xffff0000, v231
	v_fma_f32 v114, v114, v202, v214
	v_fma_f32 v115, v115, v203, v215
	v_cvt_pk_bf16_f32 v255, v114, v115
	global_store_dwordx4 v181, v[252:255], s[12:13]
	v_lshlrev_b32_e32 v198, 16, v232
	v_and_b32_e32 v199, 0xffff0000, v232
	v_lshlrev_b32_e32 v200, 16, v236
	v_and_b32_e32 v201, 0xffff0000, v236
	v_fma_f32 v108, v108, v198, v200
	v_fma_f32 v109, v109, v199, v201
	v_cvt_pk_bf16_f32 v206, v108, v109
	v_lshlrev_b32_e32 v202, 16, v233
	v_and_b32_e32 v203, 0xffff0000, v233
	v_lshlrev_b32_e32 v214, 16, v237
	v_and_b32_e32 v215, 0xffff0000, v237
	v_fma_f32 v110, v110, v202, v214
	v_fma_f32 v111, v111, v203, v215
	v_cvt_pk_bf16_f32 v207, v110, v111
	v_lshlrev_b32_e32 v198, 16, v234
; __device__ __forceinline__ unsigned cvt_pk_bf16(float lo, float hi) { f32x2 v = {lo, hi}; bf16x2_t b = __builtin_convertvector(v, bf16x2_t); return __builtin_bit_cast(unsigned, b); }
; __device__ __forceinline__ float bflo(unsigned w) { return __uint_as_float(w << 16); }
; __device__ __forceinline__ float bfhi(unsigned w) { return __uint_as_float(w & 0xffff0000u); }
; __device__ __forceinline__ float sigmoid_f(float x) { return __builtin_amdgcn_rcpf(1.0f + __expf(-x)); }
; __device__ __forceinline__ size_t tl(int r, int c, int K) { return ((size_t)(r >> 8) * (size_t)(K >> 6) + (size_t)(c >> 6)) * 16384 + (size_t)((r & 255) << 6) + (size_t)(c & 63); }
;     __device__ __forceinline__ void operator()(const f32x4 (&acc)[2][2][4][2], const Unit& u, int wr, int wc, int fr, int fq) const {
;     ...
;                 for (int mm = 0; mm < 2; ++mm) {
;                     const int m = mh * 2 + mm;
;                     const int rr = row0 + ai * HALF + m * 16;
; #pragma unroll
;                     for (int bj = 0; bj < 2; ++bj) {
;                         const f32x4 a0 = acc[ai][bj][m][0], a1 = acc[ai][bj][m][1];
;                         const u32x4 yv = yw[mm][bj], mv = mw[mm][bj];
;                         u32x4 w;
;                         w.x = cvt_pk_bf16(sigmoid_f(a0[0]) * bflo(yv.x) + bflo(mv.x), sigmoid_f(a0[1]) * bfhi(yv.x) + bfhi(mv.x));
;                         w.y = cvt_pk_bf16(sigmoid_f(a0[2]) * bflo(yv.y) + bflo(mv.y), sigmoid_f(a0[3]) * bfhi(yv.y) + bfhi(mv.y));
;                         w.z = cvt_pk_bf16(sigmoid_f(a1[0]) * bflo(yv.z) + bflo(mv.z), sigmoid_f(a1[1]) * bfhi(yv.z) + bfhi(mv.z));
;                         w.w = cvt_pk_bf16(sigmoid_f(a1[2]) * bflo(yv.w) + bflo(mv.w), sigmoid_f(a1[3]) * bfhi(yv.w) + bfhi(mv.w));
;                         *(u32x4*)(merged + tl(rr, col0 + bj * HALF, DM)) = w;
	v_and_b32_e32 v199, 0xffff0000, v234
	v_lshlrev_b32_e32 v200, 16, v238
	v_and_b32_e32 v201, 0xffff0000, v238
	v_fma_f32 v104, v104, v198, v200
	v_fma_f32 v105, v105, v199, v201
	v_cvt_pk_bf16_f32 v208, v104, v105
	v_lshlrev_b32_e32 v202, 16, v235
	v_and_b32_e32 v203, 0xffff0000, v235
	v_lshlrev_b32_e32 v214, 16, v239
	v_and_b32_e32 v215, 0xffff0000, v239
	v_fma_f32 v106, v106, v202, v214
	v_fma_f32 v107, v107, v203, v215
	v_cvt_pk_bf16_f32 v209, v106, v107
	global_store_dwordx4 v182, v[206:209], s[12:13]
	v_lshlrev_b32_e32 v198, 16, v240
	v_and_b32_e32 v199, 0xffff0000, v240
	v_lshlrev_b32_e32 v200, 16, v244
	v_and_b32_e32 v201, 0xffff0000, v244
	v_fma_f32 v100, v100, v198, v200
	v_fma_f32 v101, v101, v199, v201
	v_cvt_pk_bf16_f32 v210, v100, v101
	v_lshlrev_b32_e32 v202, 16, v241
	v_and_b32_e32 v203, 0xffff0000, v241
	v_lshlrev_b32_e32 v214, 16, v245
	v_and_b32_e32 v215, 0xffff0000, v245
	v_fma_f32 v102, v102, v202, v214
	v_fma_f32 v103, v103, v203, v215
	v_cvt_pk_bf16_f32 v211, v102, v103
	v_lshlrev_b32_e32 v198, 16, v242
	v_and_b32_e32 v199, 0xffff0000, v242
	v_lshlrev_b32_e32 v200, 16, v246
	v_and_b32_e32 v201, 0xffff0000, v246
	v_fma_f32 v96, v96, v198, v200
	v_fma_f32 v97, v97, v199, v201
	v_cvt_pk_bf16_f32 v212, v96, v97
	v_lshlrev_b32_e32 v202, 16, v243
	v_and_b32_e32 v203, 0xffff0000, v243
	v_lshlrev_b32_e32 v214, 16, v247
	v_and_b32_e32 v215, 0xffff0000, v247
	v_fma_f32 v98, v98, v202, v214
	v_fma_f32 v99, v99, v203, v215
	v_cvt_pk_bf16_f32 v213, v98, v99
	global_store_dwordx4 v183, v[210:213], s[12:13]
	v_add_u32_e32 v178, 0x80000, v176
	v_add_u32_e32 v180, 0x4000, v177
	v_add_u32_e32 v181, 0x14000, v177
	v_add_u32_e32 v179, 0x90000, v176
	v_add_u32_e32 v182, 0x4800, v177
	v_add_u32_e32 v183, 0x14800, v177
	global_load_dwordx4 v[216:219], v178, s[34:35]
	global_load_dwordx4 v[220:223], v180, s[12:13]
	global_load_dwordx4 v[224:227], v178, s[34:35] offset:256
	global_load_dwordx4 v[228:231], v181, s[12:13]
	global_load_dwordx4 v[232:235], v179, s[34:35]
	global_load_dwordx4 v[236:239], v182, s[12:13]
	global_load_dwordx4 v[240:243], v179, s[34:35] offset:256
	global_load_dwordx4 v[244:247], v183, s[12:13]
	v_mul_f32_e32 v92, 0xbfb8aa3b, v92
	v_mul_f32_e32 v93, 0xbfb8aa3b, v93
	v_mul_f32_e32 v94, 0xbfb8aa3b, v94
	v_mul_f32_e32 v95, 0xbfb8aa3b, v95
	v_mul_f32_e32 v88, 0xbfb8aa3b, v88
	v_mul_f32_e32 v89, 0xbfb8aa3b, v89
	v_mul_f32_e32 v90, 0xbfb8aa3b, v90
	v_mul_f32_e32 v91, 0xbfb8aa3b, v91
	v_exp_f32_e32 v92, v92
	v_exp_f32_e32 v93, v93
	v_exp_f32_e32 v94, v94
	v_exp_f32_e32 v95, v95
	v_exp_f32_e32 v88, v88
	v_exp_f32_e32 v89, v89
	v_exp_f32_e32 v90, v90
	v_exp_f32_e32 v91, v91
	v_add_f32_e32 v92, 1.0, v92
	v_add_f32_e32 v93, 1.0, v93
	v_add_f32_e32 v94, 1.0, v94
	v_add_f32_e32 v95, 1.0, v95
	v_add_f32_e32 v88, 1.0, v88
	v_add_f32_e32 v89, 1.0, v89
	v_add_f32_e32 v90, 1.0, v90
	v_add_f32_e32 v91, 1.0, v91
	v_rcp_f32_e32 v92, v92
	v_rcp_f32_e32 v93, v93
	v_rcp_f32_e32 v94, v94
	v_rcp_f32_e32 v95, v95
	v_rcp_f32_e32 v88, v88
	v_rcp_f32_e32 v89, v89
	v_rcp_f32_e32 v90, v90
	v_rcp_f32_e32 v91, v91
	v_mul_f32_e32 v84, 0xbfb8aa3b, v84
	v_mul_f32_e32 v85, 0xbfb8aa3b, v85
	v_mul_f32_e32 v86, 0xbfb8aa3b, v86
	v_mul_f32_e32 v87, 0xbfb8aa3b, v87
	v_mul_f32_e32 v80, 0xbfb8aa3b, v80
	v_mul_f32_e32 v81, 0xbfb8aa3b, v81
	v_mul_f32_e32 v82, 0xbfb8aa3b, v82
	v_mul_f32_e32 v83, 0xbfb8aa3b, v83
	v_exp_f32_e32 v84, v84
	v_exp_f32_e32 v85, v85
	v_exp_f32_e32 v86, v86
	v_exp_f32_e32 v87, v87
	v_exp_f32_e32 v80, v80
	v_exp_f32_e32 v81, v81
	v_exp_f32_e32 v82, v82
	v_exp_f32_e32 v83, v83
	v_add_f32_e32 v84, 1.0, v84
	v_add_f32_e32 v85, 1.0, v85
	v_add_f32_e32 v86, 1.0, v86
	v_add_f32_e32 v87, 1.0, v87
	v_add_f32_e32 v80, 1.0, v80
	v_add_f32_e32 v81, 1.0, v81
	v_add_f32_e32 v82, 1.0, v82
	v_add_f32_e32 v83, 1.0, v83
	v_rcp_f32_e32 v84, v84
	v_rcp_f32_e32 v85, v85
	v_rcp_f32_e32 v86, v86
	v_rcp_f32_e32 v87, v87
	v_rcp_f32_e32 v80, v80
	v_rcp_f32_e32 v81, v81
	v_rcp_f32_e32 v82, v82
	v_rcp_f32_e32 v83, v83
	v_mul_f32_e32 v76, 0xbfb8aa3b, v76
	v_mul_f32_e32 v77, 0xbfb8aa3b, v77
	v_mul_f32_e32 v78, 0xbfb8aa3b, v78
	v_mul_f32_e32 v79, 0xbfb8aa3b, v79
	v_mul_f32_e32 v72, 0xbfb8aa3b, v72
	v_mul_f32_e32 v73, 0xbfb8aa3b, v73
	v_mul_f32_e32 v74, 0xbfb8aa3b, v74
	v_mul_f32_e32 v75, 0xbfb8aa3b, v75
	v_exp_f32_e32 v76, v76
	v_exp_f32_e32 v77, v77
	v_exp_f32_e32 v78, v78
	v_exp_f32_e32 v79, v79
	v_exp_f32_e32 v72, v72
	v_exp_f32_e32 v73, v73
	v_exp_f32_e32 v74, v74
	v_exp_f32_e32 v75, v75
	v_add_f32_e32 v76, 1.0, v76
	v_add_f32_e32 v77, 1.0, v77
	v_add_f32_e32 v78, 1.0, v78
	v_add_f32_e32 v79, 1.0, v79
	v_add_f32_e32 v72, 1.0, v72
	v_add_f32_e32 v73, 1.0, v73
	v_add_f32_e32 v74, 1.0, v74
	v_add_f32_e32 v75, 1.0, v75
	v_rcp_f32_e32 v76, v76
	v_rcp_f32_e32 v77, v77
	v_rcp_f32_e32 v78, v78
	v_rcp_f32_e32 v79, v79
	v_rcp_f32_e32 v72, v72
	v_rcp_f32_e32 v73, v73
	v_rcp_f32_e32 v74, v74
	v_rcp_f32_e32 v75, v75
	v_mul_f32_e32 v68, 0xbfb8aa3b, v68
	v_mul_f32_e32 v69, 0xbfb8aa3b, v69
	v_mul_f32_e32 v70, 0xbfb8aa3b, v70
	v_mul_f32_e32 v71, 0xbfb8aa3b, v71
	v_mul_f32_e32 v64, 0xbfb8aa3b, v64
	v_mul_f32_e32 v65, 0xbfb8aa3b, v65
	v_mul_f32_e32 v66, 0xbfb8aa3b, v66
	v_mul_f32_e32 v67, 0xbfb8aa3b, v67
	v_exp_f32_e32 v68, v68
	v_exp_f32_e32 v69, v69
	v_exp_f32_e32 v70, v70
	v_exp_f32_e32 v71, v71
	v_exp_f32_e32 v64, v64
	v_exp_f32_e32 v65, v65
	v_exp_f32_e32 v66, v66
	v_exp_f32_e32 v67, v67
	v_add_f32_e32 v68, 1.0, v68
	v_add_f32_e32 v69, 1.0, v69
	v_add_f32_e32 v70, 1.0, v70
	v_add_f32_e32 v71, 1.0, v71
	v_add_f32_e32 v64, 1.0, v64
	v_add_f32_e32 v65, 1.0, v65
	v_add_f32_e32 v66, 1.0, v66
	v_add_f32_e32 v67, 1.0, v67
	v_rcp_f32_e32 v68, v68
	v_rcp_f32_e32 v69, v69
	v_rcp_f32_e32 v70, v70
	v_rcp_f32_e32 v71, v71
	v_rcp_f32_e32 v64, v64
	v_rcp_f32_e32 v65, v65
	v_rcp_f32_e32 v66, v66
	v_rcp_f32_e32 v67, v67
	s_waitcnt vmcnt(12)
; __device__ __forceinline__ unsigned cvt_pk_bf16(float lo, float hi) { f32x2 v = {lo, hi}; bf16x2_t b = __builtin_convertvector(v, bf16x2_t); return __builtin_bit_cast(unsigned, b); }
; __device__ __forceinline__ float bflo(unsigned w) { return __uint_as_float(w << 16); }
; __device__ __forceinline__ float bfhi(unsigned w) { return __uint_as_float(w & 0xffff0000u); }
; __device__ __forceinline__ float sigmoid_f(float x) { return __builtin_amdgcn_rcpf(1.0f + __expf(-x)); }
; __device__ __forceinline__ size_t tl(int r, int c, int K) { return ((size_t)(r >> 8) * (size_t)(K >> 6) + (size_t)(c >> 6)) * 16384 + (size_t)((r & 255) << 6) + (size_t)(c & 63); }
;     __device__ __forceinline__ void operator()(const f32x4 (&acc)[2][2][4][2], const Unit& u, int wr, int wc, int fr, int fq) const {
;     ...
;                 for (int mm = 0; mm < 2; ++mm) {
;                     const int m = mh * 2 + mm;
;                     const int rr = row0 + ai * HALF + m * 16;
; #pragma unroll
;                     for (int bj = 0; bj < 2; ++bj) {
;                         const f32x4 a0 = acc[ai][bj][m][0], a1 = acc[ai][bj][m][1];
;                         const u32x4 yv = yw[mm][bj], mv = mw[mm][bj];
;                         u32x4 w;
;                         w.x = cvt_pk_bf16(sigmoid_f(a0[0]) * bflo(yv.x) + bflo(mv.x), sigmoid_f(a0[1]) * bfhi(yv.x) + bfhi(mv.x));
;                         w.y = cvt_pk_bf16(sigmoid_f(a0[2]) * bflo(yv.y) + bflo(mv.y), sigmoid_f(a0[3]) * bfhi(yv.y) + bfhi(mv.y));
;                         w.z = cvt_pk_bf16(sigmoid_f(a1[0]) * bflo(yv.z) + bflo(mv.z), sigmoid_f(a1[1]) * bfhi(yv.z) + bfhi(mv.z));
;                         w.w = cvt_pk_bf16(sigmoid_f(a1[2]) * bflo(yv.w) + bflo(mv.w), sigmoid_f(a1[3]) * bfhi(yv.w) + bfhi(mv.w));
;                         *(u32x4*)(merged + tl(rr, col0 + bj * HALF, DM)) = w;
	v_lshlrev_b32_e32 v198, 16, v128
	v_and_b32_e32 v199, 0xffff0000, v128
	v_lshlrev_b32_e32 v200, 16, v132
	v_and_b32_e32 v201, 0xffff0000, v132
	v_fma_f32 v92, v92, v198, v200
	v_fma_f32 v93, v93, v199, v201
	v_cvt_pk_bf16_f32 v248, v92, v93
	v_lshlrev_b32_e32 v202, 16, v129
	v_and_b32_e32 v203, 0xffff0000, v129
	v_lshlrev_b32_e32 v214, 16, v133
	v_and_b32_e32 v215, 0xffff0000, v133
	v_fma_f32 v94, v94, v202, v214
	v_fma_f32 v95, v95, v203, v215
	v_cvt_pk_bf16_f32 v249, v94, v95
	v_lshlrev_b32_e32 v198, 16, v130
	v_and_b32_e32 v199, 0xffff0000, v130
	v_lshlrev_b32_e32 v200, 16, v134
	v_and_b32_e32 v201, 0xffff0000, v134
	v_fma_f32 v88, v88, v198, v200
	v_fma_f32 v89, v89, v199, v201
	v_cvt_pk_bf16_f32 v250, v88, v89
	v_lshlrev_b32_e32 v202, 16, v131
	v_and_b32_e32 v203, 0xffff0000, v131
	v_lshlrev_b32_e32 v214, 16, v135
	v_and_b32_e32 v215, 0xffff0000, v135
	v_fma_f32 v90, v90, v202, v214
	v_fma_f32 v91, v91, v203, v215
	v_cvt_pk_bf16_f32 v251, v90, v91
	global_store_dwordx4 v194, v[248:251], s[12:13]
	v_lshlrev_b32_e32 v198, 16, v136
	v_and_b32_e32 v199, 0xffff0000, v136
	v_lshlrev_b32_e32 v200, 16, v140
	v_and_b32_e32 v201, 0xffff0000, v140
	v_fma_f32 v84, v84, v198, v200
	v_fma_f32 v85, v85, v199, v201
	v_cvt_pk_bf16_f32 v252, v84, v85
	v_lshlrev_b32_e32 v202, 16, v137
	v_and_b32_e32 v203, 0xffff0000, v137
	v_lshlrev_b32_e32 v214, 16, v141
	v_and_b32_e32 v215, 0xffff0000, v141
	v_fma_f32 v86, v86, v202, v214
	v_fma_f32 v87, v87, v203, v215
	v_cvt_pk_bf16_f32 v253, v86, v87
	v_lshlrev_b32_e32 v198, 16, v138
	v_and_b32_e32 v199, 0xffff0000, v138
	v_lshlrev_b32_e32 v200, 16, v142
	v_and_b32_e32 v201, 0xffff0000, v142
	v_fma_f32 v80, v80, v198, v200
	v_fma_f32 v81, v81, v199, v201
	v_cvt_pk_bf16_f32 v254, v80, v81
	v_lshlrev_b32_e32 v202, 16, v139
	v_and_b32_e32 v203, 0xffff0000, v139
	v_lshlrev_b32_e32 v214, 16, v143
	v_and_b32_e32 v215, 0xffff0000, v143
	v_fma_f32 v82, v82, v202, v214
	v_fma_f32 v83, v83, v203, v215
	v_cvt_pk_bf16_f32 v255, v82, v83
	global_store_dwordx4 v195, v[252:255], s[12:13]
	v_lshlrev_b32_e32 v198, 16, v144
	v_and_b32_e32 v199, 0xffff0000, v144
	v_lshlrev_b32_e32 v200, 16, v148
	v_and_b32_e32 v201, 0xffff0000, v148
	v_fma_f32 v76, v76, v198, v200
	v_fma_f32 v77, v77, v199, v201
	v_cvt_pk_bf16_f32 v206, v76, v77
	v_lshlrev_b32_e32 v202, 16, v145
	v_and_b32_e32 v203, 0xffff0000, v145
	v_lshlrev_b32_e32 v214, 16, v149
	v_and_b32_e32 v215, 0xffff0000, v149
	v_fma_f32 v78, v78, v202, v214
	v_fma_f32 v79, v79, v203, v215
	v_cvt_pk_bf16_f32 v207, v78, v79
	v_lshlrev_b32_e32 v198, 16, v146
	v_and_b32_e32 v199, 0xffff0000, v146
	v_lshlrev_b32_e32 v200, 16, v150
	v_and_b32_e32 v201, 0xffff0000, v150
	v_fma_f32 v72, v72, v198, v200
	v_fma_f32 v73, v73, v199, v201
	v_cvt_pk_bf16_f32 v208, v72, v73
	v_lshlrev_b32_e32 v202, 16, v147
	v_and_b32_e32 v203, 0xffff0000, v147
	v_lshlrev_b32_e32 v214, 16, v151
	v_and_b32_e32 v215, 0xffff0000, v151
	v_fma_f32 v74, v74, v202, v214
	v_fma_f32 v75, v75, v203, v215
	v_cvt_pk_bf16_f32 v209, v74, v75
	global_store_dwordx4 v196, v[206:209], s[12:13]
	v_lshlrev_b32_e32 v198, 16, v152
	v_and_b32_e32 v199, 0xffff0000, v152
	v_lshlrev_b32_e32 v200, 16, v156
	v_and_b32_e32 v201, 0xffff0000, v156
	v_fma_f32 v68, v68, v198, v200
	v_fma_f32 v69, v69, v199, v201
	v_cvt_pk_bf16_f32 v210, v68, v69
	v_lshlrev_b32_e32 v202, 16, v153
	v_and_b32_e32 v203, 0xffff0000, v153
	v_lshlrev_b32_e32 v214, 16, v157
	v_and_b32_e32 v215, 0xffff0000, v157
	v_fma_f32 v70, v70, v202, v214
	v_fma_f32 v71, v71, v203, v215
	v_cvt_pk_bf16_f32 v211, v70, v71
	v_lshlrev_b32_e32 v198, 16, v154
	v_and_b32_e32 v199, 0xffff0000, v154
	v_lshlrev_b32_e32 v200, 16, v158
	v_and_b32_e32 v201, 0xffff0000, v158
	v_fma_f32 v64, v64, v198, v200
	v_fma_f32 v65, v65, v199, v201
	v_cvt_pk_bf16_f32 v212, v64, v65
	v_lshlrev_b32_e32 v202, 16, v155
	v_and_b32_e32 v203, 0xffff0000, v155
	v_lshlrev_b32_e32 v214, 16, v159
	v_and_b32_e32 v215, 0xffff0000, v159
	v_fma_f32 v66, v66, v202, v214
	v_fma_f32 v67, v67, v203, v215
	v_cvt_pk_bf16_f32 v213, v66, v67
	global_store_dwordx4 v197, v[210:213], s[12:13]
	v_add_u32_e32 v192, 0xa0000, v176
	v_add_u32_e32 v194, 0x5000, v177
	v_add_u32_e32 v195, 0x15000, v177
	v_add_u32_e32 v193, 0xb0000, v176
	v_add_u32_e32 v196, 0x5800, v177
	v_add_u32_e32 v197, 0x15800, v177
	global_load_dwordx4 v[128:131], v192, s[34:35]
	global_load_dwordx4 v[132:135], v194, s[12:13]
	global_load_dwordx4 v[136:139], v192, s[34:35] offset:256
	global_load_dwordx4 v[140:143], v195, s[12:13]
	global_load_dwordx4 v[144:147], v193, s[34:35]
	global_load_dwordx4 v[148:151], v196, s[12:13]
	global_load_dwordx4 v[152:155], v193, s[34:35] offset:256
	global_load_dwordx4 v[156:159], v197, s[12:13]
	v_mul_f32_e32 v60, 0xbfb8aa3b, v60
	v_mul_f32_e32 v61, 0xbfb8aa3b, v61
	v_mul_f32_e32 v62, 0xbfb8aa3b, v62
	v_mul_f32_e32 v63, 0xbfb8aa3b, v63
	v_mul_f32_e32 v56, 0xbfb8aa3b, v56
	v_mul_f32_e32 v57, 0xbfb8aa3b, v57
	v_mul_f32_e32 v58, 0xbfb8aa3b, v58
	v_mul_f32_e32 v59, 0xbfb8aa3b, v59
	v_exp_f32_e32 v60, v60
	v_exp_f32_e32 v61, v61
	v_exp_f32_e32 v62, v62
	v_exp_f32_e32 v63, v63
	v_exp_f32_e32 v56, v56
	v_exp_f32_e32 v57, v57
	v_exp_f32_e32 v58, v58
	v_exp_f32_e32 v59, v59
	v_add_f32_e32 v60, 1.0, v60
	v_add_f32_e32 v61, 1.0, v61
	v_add_f32_e32 v62, 1.0, v62
	v_add_f32_e32 v63, 1.0, v63
	v_add_f32_e32 v56, 1.0, v56
	v_add_f32_e32 v57, 1.0, v57
	v_add_f32_e32 v58, 1.0, v58
	v_add_f32_e32 v59, 1.0, v59
	v_rcp_f32_e32 v60, v60
	v_rcp_f32_e32 v61, v61
	v_rcp_f32_e32 v62, v62
	v_rcp_f32_e32 v63, v63
	v_rcp_f32_e32 v56, v56
	v_rcp_f32_e32 v57, v57
	v_rcp_f32_e32 v58, v58
	v_rcp_f32_e32 v59, v59
	v_mul_f32_e32 v52, 0xbfb8aa3b, v52
; __device__ __forceinline__ unsigned cvt_pk_bf16(float lo, float hi) { f32x2 v = {lo, hi}; bf16x2_t b = __builtin_convertvector(v, bf16x2_t); return __builtin_bit_cast(unsigned, b); }
; __device__ __forceinline__ float bflo(unsigned w) { return __uint_as_float(w << 16); }
; __device__ __forceinline__ float bfhi(unsigned w) { return __uint_as_float(w & 0xffff0000u); }
; __device__ __forceinline__ float sigmoid_f(float x) { return __builtin_amdgcn_rcpf(1.0f + __expf(-x)); }
; __device__ __forceinline__ size_t tl(int r, int c, int K) { return ((size_t)(r >> 8) * (size_t)(K >> 6) + (size_t)(c >> 6)) * 16384 + (size_t)((r & 255) << 6) + (size_t)(c & 63); }
;     __device__ __forceinline__ void operator()(const f32x4 (&acc)[2][2][4][2], const Unit& u, int wr, int wc, int fr, int fq) const {
;     ...
;                 for (int mm = 0; mm < 2; ++mm) {
;                     const int m = mh * 2 + mm;
;                     const int rr = row0 + ai * HALF + m * 16;
; #pragma unroll
;                     for (int bj = 0; bj < 2; ++bj) {
;                         const f32x4 a0 = acc[ai][bj][m][0], a1 = acc[ai][bj][m][1];
;                         const u32x4 yv = yw[mm][bj], mv = mw[mm][bj];
;                         u32x4 w;
;                         w.x = cvt_pk_bf16(sigmoid_f(a0[0]) * bflo(yv.x) + bflo(mv.x), sigmoid_f(a0[1]) * bfhi(yv.x) + bfhi(mv.x));
;                         w.y = cvt_pk_bf16(sigmoid_f(a0[2]) * bflo(yv.y) + bflo(mv.y), sigmoid_f(a0[3]) * bfhi(yv.y) + bfhi(mv.y));
;                         w.z = cvt_pk_bf16(sigmoid_f(a1[0]) * bflo(yv.z) + bflo(mv.z), sigmoid_f(a1[1]) * bfhi(yv.z) + bfhi(mv.z));
;                         w.w = cvt_pk_bf16(sigmoid_f(a1[2]) * bflo(yv.w) + bflo(mv.w), sigmoid_f(a1[3]) * bfhi(yv.w) + bfhi(mv.w));
;                         *(u32x4*)(merged + tl(rr, col0 + bj * HALF, DM)) = w;
	v_mul_f32_e32 v53, 0xbfb8aa3b, v53
	v_mul_f32_e32 v54, 0xbfb8aa3b, v54
	v_mul_f32_e32 v55, 0xbfb8aa3b, v55
	v_mul_f32_e32 v48, 0xbfb8aa3b, v48
	v_mul_f32_e32 v49, 0xbfb8aa3b, v49
	v_mul_f32_e32 v50, 0xbfb8aa3b, v50
	v_mul_f32_e32 v51, 0xbfb8aa3b, v51
	v_exp_f32_e32 v52, v52
	v_exp_f32_e32 v53, v53
	v_exp_f32_e32 v54, v54
	v_exp_f32_e32 v55, v55
	v_exp_f32_e32 v48, v48
	v_exp_f32_e32 v49, v49
	v_exp_f32_e32 v50, v50
	v_exp_f32_e32 v51, v51
	v_add_f32_e32 v52, 1.0, v52
	v_add_f32_e32 v53, 1.0, v53
	v_add_f32_e32 v54, 1.0, v54
	v_add_f32_e32 v55, 1.0, v55
	v_add_f32_e32 v48, 1.0, v48
	v_add_f32_e32 v49, 1.0, v49
	v_add_f32_e32 v50, 1.0, v50
	v_add_f32_e32 v51, 1.0, v51
	v_rcp_f32_e32 v52, v52
	v_rcp_f32_e32 v53, v53
	v_rcp_f32_e32 v54, v54
	v_rcp_f32_e32 v55, v55
	v_rcp_f32_e32 v48, v48
	v_rcp_f32_e32 v49, v49
	v_rcp_f32_e32 v50, v50
	v_rcp_f32_e32 v51, v51
	v_mul_f32_e32 v44, 0xbfb8aa3b, v44
	v_mul_f32_e32 v45, 0xbfb8aa3b, v45
	v_mul_f32_e32 v46, 0xbfb8aa3b, v46
	v_mul_f32_e32 v47, 0xbfb8aa3b, v47
	v_mul_f32_e32 v40, 0xbfb8aa3b, v40
	v_mul_f32_e32 v41, 0xbfb8aa3b, v41
	v_mul_f32_e32 v42, 0xbfb8aa3b, v42
	v_mul_f32_e32 v43, 0xbfb8aa3b, v43
	v_exp_f32_e32 v44, v44
	v_exp_f32_e32 v45, v45
	v_exp_f32_e32 v46, v46
	v_exp_f32_e32 v47, v47
	v_exp_f32_e32 v40, v40
	v_exp_f32_e32 v41, v41
	v_exp_f32_e32 v42, v42
	v_exp_f32_e32 v43, v43
	v_add_f32_e32 v44, 1.0, v44
	v_add_f32_e32 v45, 1.0, v45
	v_add_f32_e32 v46, 1.0, v46
	v_add_f32_e32 v47, 1.0, v47
	v_add_f32_e32 v40, 1.0, v40
	v_add_f32_e32 v41, 1.0, v41
	v_add_f32_e32 v42, 1.0, v42
	v_add_f32_e32 v43, 1.0, v43
	v_rcp_f32_e32 v44, v44
	v_rcp_f32_e32 v45, v45
	v_rcp_f32_e32 v46, v46
	v_rcp_f32_e32 v47, v47
	v_rcp_f32_e32 v40, v40
	v_rcp_f32_e32 v41, v41
	v_rcp_f32_e32 v42, v42
	v_rcp_f32_e32 v43, v43
	v_mul_f32_e32 v36, 0xbfb8aa3b, v36
	v_mul_f32_e32 v37, 0xbfb8aa3b, v37
	v_mul_f32_e32 v38, 0xbfb8aa3b, v38
	v_mul_f32_e32 v39, 0xbfb8aa3b, v39
	v_mul_f32_e32 v32, 0xbfb8aa3b, v32
	v_mul_f32_e32 v33, 0xbfb8aa3b, v33
	v_mul_f32_e32 v34, 0xbfb8aa3b, v34
	v_mul_f32_e32 v35, 0xbfb8aa3b, v35
	v_exp_f32_e32 v36, v36
	v_exp_f32_e32 v37, v37
	v_exp_f32_e32 v38, v38
	v_exp_f32_e32 v39, v39
	v_exp_f32_e32 v32, v32
	v_exp_f32_e32 v33, v33
	v_exp_f32_e32 v34, v34
	v_exp_f32_e32 v35, v35
	v_add_f32_e32 v36, 1.0, v36
	v_add_f32_e32 v37, 1.0, v37
	v_add_f32_e32 v38, 1.0, v38
	v_add_f32_e32 v39, 1.0, v39
	v_add_f32_e32 v32, 1.0, v32
	v_add_f32_e32 v33, 1.0, v33
	v_add_f32_e32 v34, 1.0, v34
	v_add_f32_e32 v35, 1.0, v35
	v_rcp_f32_e32 v36, v36
	v_rcp_f32_e32 v37, v37
	v_rcp_f32_e32 v38, v38
	v_rcp_f32_e32 v39, v39
	v_rcp_f32_e32 v32, v32
	v_rcp_f32_e32 v33, v33
	v_rcp_f32_e32 v34, v34
	v_rcp_f32_e32 v35, v35
	s_waitcnt vmcnt(12)
	v_lshlrev_b32_e32 v198, 16, v216
	v_and_b32_e32 v199, 0xffff0000, v216
	v_lshlrev_b32_e32 v200, 16, v220
	v_and_b32_e32 v201, 0xffff0000, v220
	v_fma_f32 v60, v60, v198, v200
	v_fma_f32 v61, v61, v199, v201
	v_cvt_pk_bf16_f32 v248, v60, v61
	v_lshlrev_b32_e32 v202, 16, v217
	v_and_b32_e32 v203, 0xffff0000, v217
	v_lshlrev_b32_e32 v214, 16, v221
	v_and_b32_e32 v215, 0xffff0000, v221
	v_fma_f32 v62, v62, v202, v214
	v_fma_f32 v63, v63, v203, v215
	v_cvt_pk_bf16_f32 v249, v62, v63
	v_lshlrev_b32_e32 v198, 16, v218
	v_and_b32_e32 v199, 0xffff0000, v218
	v_lshlrev_b32_e32 v200, 16, v222
	v_and_b32_e32 v201, 0xffff0000, v222
	v_fma_f32 v56, v56, v198, v200
	v_fma_f32 v57, v57, v199, v201
	v_cvt_pk_bf16_f32 v250, v56, v57
	v_lshlrev_b32_e32 v202, 16, v219
	v_and_b32_e32 v203, 0xffff0000, v219
	v_lshlrev_b32_e32 v214, 16, v223
	v_and_b32_e32 v215, 0xffff0000, v223
	v_fma_f32 v58, v58, v202, v214
	v_fma_f32 v59, v59, v203, v215
	v_cvt_pk_bf16_f32 v251, v58, v59
	global_store_dwordx4 v180, v[248:251], s[12:13]
	v_lshlrev_b32_e32 v198, 16, v224
	v_and_b32_e32 v199, 0xffff0000, v224
	v_lshlrev_b32_e32 v200, 16, v228
	v_and_b32_e32 v201, 0xffff0000, v228
	v_fma_f32 v52, v52, v198, v200
	v_fma_f32 v53, v53, v199, v201
	v_cvt_pk_bf16_f32 v252, v52, v53
	v_lshlrev_b32_e32 v202, 16, v225
	v_and_b32_e32 v203, 0xffff0000, v225
	v_lshlrev_b32_e32 v214, 16, v229
	v_and_b32_e32 v215, 0xffff0000, v229
	v_fma_f32 v54, v54, v202, v214
	v_fma_f32 v55, v55, v203, v215
	v_cvt_pk_bf16_f32 v253, v54, v55
	v_lshlrev_b32_e32 v198, 16, v226
	v_and_b32_e32 v199, 0xffff0000, v226
	v_lshlrev_b32_e32 v200, 16, v230
	v_and_b32_e32 v201, 0xffff0000, v230
	v_fma_f32 v48, v48, v198, v200
	v_fma_f32 v49, v49, v199, v201
	v_cvt_pk_bf16_f32 v254, v48, v49
	v_lshlrev_b32_e32 v202, 16, v227
	v_and_b32_e32 v203, 0xffff0000, v227
	v_lshlrev_b32_e32 v214, 16, v231
	v_and_b32_e32 v215, 0xffff0000, v231
	v_fma_f32 v50, v50, v202, v214
	v_fma_f32 v51, v51, v203, v215
	v_cvt_pk_bf16_f32 v255, v50, v51
	global_store_dwordx4 v181, v[252:255], s[12:13]
	v_lshlrev_b32_e32 v198, 16, v232
	v_and_b32_e32 v199, 0xffff0000, v232
	v_lshlrev_b32_e32 v200, 16, v236
	v_and_b32_e32 v201, 0xffff0000, v236
	v_fma_f32 v44, v44, v198, v200
	v_fma_f32 v45, v45, v199, v201
	v_cvt_pk_bf16_f32 v206, v44, v45
	v_lshlrev_b32_e32 v202, 16, v233
	v_and_b32_e32 v203, 0xffff0000, v233
	v_lshlrev_b32_e32 v214, 16, v237
	v_and_b32_e32 v215, 0xffff0000, v237
	v_fma_f32 v46, v46, v202, v214
	v_fma_f32 v47, v47, v203, v215
	v_cvt_pk_bf16_f32 v207, v46, v47
	v_lshlrev_b32_e32 v198, 16, v234
	v_and_b32_e32 v199, 0xffff0000, v234
	v_lshlrev_b32_e32 v200, 16, v238
	v_and_b32_e32 v201, 0xffff0000, v238
	v_fma_f32 v40, v40, v198, v200
	v_fma_f32 v41, v41, v199, v201
	v_cvt_pk_bf16_f32 v208, v40, v41
	v_lshlrev_b32_e32 v202, 16, v235
	v_and_b32_e32 v203, 0xffff0000, v235
	v_lshlrev_b32_e32 v214, 16, v239
	v_and_b32_e32 v215, 0xffff0000, v239
	v_fma_f32 v42, v42, v202, v214
; __device__ __forceinline__ unsigned cvt_pk_bf16(float lo, float hi) { f32x2 v = {lo, hi}; bf16x2_t b = __builtin_convertvector(v, bf16x2_t); return __builtin_bit_cast(unsigned, b); }
; __device__ __forceinline__ float bflo(unsigned w) { return __uint_as_float(w << 16); }
; __device__ __forceinline__ float bfhi(unsigned w) { return __uint_as_float(w & 0xffff0000u); }
; __device__ __forceinline__ float sigmoid_f(float x) { return __builtin_amdgcn_rcpf(1.0f + __expf(-x)); }
; __device__ __forceinline__ size_t tl(int r, int c, int K) { return ((size_t)(r >> 8) * (size_t)(K >> 6) + (size_t)(c >> 6)) * 16384 + (size_t)((r & 255) << 6) + (size_t)(c & 63); }
;     __device__ __forceinline__ void operator()(const f32x4 (&acc)[2][2][4][2], const Unit& u, int wr, int wc, int fr, int fq) const {
;     ...
;                 for (int mm = 0; mm < 2; ++mm) {
;                     const int m = mh * 2 + mm;
;                     const int rr = row0 + ai * HALF + m * 16;
; #pragma unroll
;                     for (int bj = 0; bj < 2; ++bj) {
;                         const f32x4 a0 = acc[ai][bj][m][0], a1 = acc[ai][bj][m][1];
;                         const u32x4 yv = yw[mm][bj], mv = mw[mm][bj];
;                         u32x4 w;
;                         w.x = cvt_pk_bf16(sigmoid_f(a0[0]) * bflo(yv.x) + bflo(mv.x), sigmoid_f(a0[1]) * bfhi(yv.x) + bfhi(mv.x));
;                         w.y = cvt_pk_bf16(sigmoid_f(a0[2]) * bflo(yv.y) + bflo(mv.y), sigmoid_f(a0[3]) * bfhi(yv.y) + bfhi(mv.y));
;                         w.z = cvt_pk_bf16(sigmoid_f(a1[0]) * bflo(yv.z) + bflo(mv.z), sigmoid_f(a1[1]) * bfhi(yv.z) + bfhi(mv.z));
;                         w.w = cvt_pk_bf16(sigmoid_f(a1[2]) * bflo(yv.w) + bflo(mv.w), sigmoid_f(a1[3]) * bfhi(yv.w) + bfhi(mv.w));
;                         *(u32x4*)(merged + tl(rr, col0 + bj * HALF, DM)) = w;
	v_fma_f32 v43, v43, v203, v215
	v_cvt_pk_bf16_f32 v209, v42, v43
	global_store_dwordx4 v182, v[206:209], s[12:13]
	v_lshlrev_b32_e32 v198, 16, v240
	v_and_b32_e32 v199, 0xffff0000, v240
	v_lshlrev_b32_e32 v200, 16, v244
	v_and_b32_e32 v201, 0xffff0000, v244
	v_fma_f32 v36, v36, v198, v200
	v_fma_f32 v37, v37, v199, v201
	v_cvt_pk_bf16_f32 v210, v36, v37
	v_lshlrev_b32_e32 v202, 16, v241
	v_and_b32_e32 v203, 0xffff0000, v241
	v_lshlrev_b32_e32 v214, 16, v245
	v_and_b32_e32 v215, 0xffff0000, v245
	v_fma_f32 v38, v38, v202, v214
	v_fma_f32 v39, v39, v203, v215
	v_cvt_pk_bf16_f32 v211, v38, v39
	v_lshlrev_b32_e32 v198, 16, v242
	v_and_b32_e32 v199, 0xffff0000, v242
	v_lshlrev_b32_e32 v200, 16, v246
	v_and_b32_e32 v201, 0xffff0000, v246
	v_fma_f32 v32, v32, v198, v200
	v_fma_f32 v33, v33, v199, v201
	v_cvt_pk_bf16_f32 v212, v32, v33
	v_lshlrev_b32_e32 v202, 16, v243
	v_and_b32_e32 v203, 0xffff0000, v243
	v_lshlrev_b32_e32 v214, 16, v247
	v_and_b32_e32 v215, 0xffff0000, v247
	v_fma_f32 v34, v34, v202, v214
	v_fma_f32 v35, v35, v203, v215
	v_cvt_pk_bf16_f32 v213, v34, v35
	global_store_dwordx4 v183, v[210:213], s[12:13]
	v_mul_f32_e32 v28, 0xbfb8aa3b, v28
	v_mul_f32_e32 v29, 0xbfb8aa3b, v29
	v_mul_f32_e32 v30, 0xbfb8aa3b, v30
	v_mul_f32_e32 v31, 0xbfb8aa3b, v31
	v_mul_f32_e32 v24, 0xbfb8aa3b, v24
	v_mul_f32_e32 v25, 0xbfb8aa3b, v25
	v_mul_f32_e32 v26, 0xbfb8aa3b, v26
	v_mul_f32_e32 v27, 0xbfb8aa3b, v27
	v_exp_f32_e32 v28, v28
	v_exp_f32_e32 v29, v29
	v_exp_f32_e32 v30, v30
	v_exp_f32_e32 v31, v31
	v_exp_f32_e32 v24, v24
	v_exp_f32_e32 v25, v25
	v_exp_f32_e32 v26, v26
	v_exp_f32_e32 v27, v27
	v_add_f32_e32 v28, 1.0, v28
	v_add_f32_e32 v29, 1.0, v29
	v_add_f32_e32 v30, 1.0, v30
	v_add_f32_e32 v31, 1.0, v31
	v_add_f32_e32 v24, 1.0, v24
	v_add_f32_e32 v25, 1.0, v25
	v_add_f32_e32 v26, 1.0, v26
	v_add_f32_e32 v27, 1.0, v27
	v_rcp_f32_e32 v28, v28
	v_rcp_f32_e32 v29, v29
	v_rcp_f32_e32 v30, v30
	v_rcp_f32_e32 v31, v31
	v_rcp_f32_e32 v24, v24
	v_rcp_f32_e32 v25, v25
	v_rcp_f32_e32 v26, v26
	v_rcp_f32_e32 v27, v27
	v_mul_f32_e32 v20, 0xbfb8aa3b, v20
	v_mul_f32_e32 v21, 0xbfb8aa3b, v21
	v_mul_f32_e32 v22, 0xbfb8aa3b, v22
	v_mul_f32_e32 v23, 0xbfb8aa3b, v23
	v_mul_f32_e32 v16, 0xbfb8aa3b, v16
	v_mul_f32_e32 v17, 0xbfb8aa3b, v17
	v_mul_f32_e32 v18, 0xbfb8aa3b, v18
	v_mul_f32_e32 v19, 0xbfb8aa3b, v19
	v_exp_f32_e32 v20, v20
	v_exp_f32_e32 v21, v21
	v_exp_f32_e32 v22, v22
	v_exp_f32_e32 v23, v23
	v_exp_f32_e32 v16, v16
	v_exp_f32_e32 v17, v17
	v_exp_f32_e32 v18, v18
	v_exp_f32_e32 v19, v19
	v_add_f32_e32 v20, 1.0, v20
	v_add_f32_e32 v21, 1.0, v21
	v_add_f32_e32 v22, 1.0, v22
	v_add_f32_e32 v23, 1.0, v23
	v_add_f32_e32 v16, 1.0, v16
	v_add_f32_e32 v17, 1.0, v17
	v_add_f32_e32 v18, 1.0, v18
	v_add_f32_e32 v19, 1.0, v19
	v_rcp_f32_e32 v20, v20
	v_rcp_f32_e32 v21, v21
	v_rcp_f32_e32 v22, v22
	v_rcp_f32_e32 v23, v23
	v_rcp_f32_e32 v16, v16
	v_rcp_f32_e32 v17, v17
	v_rcp_f32_e32 v18, v18
	v_rcp_f32_e32 v19, v19
	v_mul_f32_e32 v12, 0xbfb8aa3b, v12
	v_mul_f32_e32 v13, 0xbfb8aa3b, v13
	v_mul_f32_e32 v14, 0xbfb8aa3b, v14
	v_mul_f32_e32 v15, 0xbfb8aa3b, v15
	v_mul_f32_e32 v8, 0xbfb8aa3b, v8
	v_mul_f32_e32 v9, 0xbfb8aa3b, v9
	v_mul_f32_e32 v10, 0xbfb8aa3b, v10
	v_mul_f32_e32 v11, 0xbfb8aa3b, v11
	v_exp_f32_e32 v12, v12
	v_exp_f32_e32 v13, v13
	v_exp_f32_e32 v14, v14
	v_exp_f32_e32 v15, v15
	v_exp_f32_e32 v8, v8
	v_exp_f32_e32 v9, v9
	v_exp_f32_e32 v10, v10
	v_exp_f32_e32 v11, v11
	v_add_f32_e32 v12, 1.0, v12
	v_add_f32_e32 v13, 1.0, v13
	v_add_f32_e32 v14, 1.0, v14
	v_add_f32_e32 v15, 1.0, v15
	v_add_f32_e32 v8, 1.0, v8
	v_add_f32_e32 v9, 1.0, v9
	v_add_f32_e32 v10, 1.0, v10
	v_add_f32_e32 v11, 1.0, v11
	v_rcp_f32_e32 v12, v12
	v_rcp_f32_e32 v13, v13
	v_rcp_f32_e32 v14, v14
	v_rcp_f32_e32 v15, v15
	v_rcp_f32_e32 v8, v8
	v_rcp_f32_e32 v9, v9
	v_rcp_f32_e32 v10, v10
	v_rcp_f32_e32 v11, v11
	v_mul_f32_e32 v4, 0xbfb8aa3b, v4
	v_mul_f32_e32 v5, 0xbfb8aa3b, v5
	v_mul_f32_e32 v6, 0xbfb8aa3b, v6
	v_mul_f32_e32 v7, 0xbfb8aa3b, v7
	v_mul_f32_e32 v0, 0xbfb8aa3b, v0
	v_mul_f32_e32 v1, 0xbfb8aa3b, v1
	v_mul_f32_e32 v2, 0xbfb8aa3b, v2
	v_mul_f32_e32 v3, 0xbfb8aa3b, v3
	v_exp_f32_e32 v4, v4
	v_exp_f32_e32 v5, v5
	v_exp_f32_e32 v6, v6
	v_exp_f32_e32 v7, v7
	v_exp_f32_e32 v0, v0
	v_exp_f32_e32 v1, v1
	v_exp_f32_e32 v2, v2
	v_exp_f32_e32 v3, v3
	v_add_f32_e32 v4, 1.0, v4
	v_add_f32_e32 v5, 1.0, v5
	v_add_f32_e32 v6, 1.0, v6
	v_add_f32_e32 v7, 1.0, v7
	v_add_f32_e32 v0, 1.0, v0
	v_add_f32_e32 v1, 1.0, v1
	v_add_f32_e32 v2, 1.0, v2
	v_add_f32_e32 v3, 1.0, v3
	v_rcp_f32_e32 v4, v4
	v_rcp_f32_e32 v5, v5
	v_rcp_f32_e32 v6, v6
	v_rcp_f32_e32 v7, v7
	v_rcp_f32_e32 v0, v0
	v_rcp_f32_e32 v1, v1
	v_rcp_f32_e32 v2, v2
	v_rcp_f32_e32 v3, v3
	s_waitcnt vmcnt(4)
; __device__ __forceinline__ unsigned cvt_pk_bf16(float lo, float hi) { f32x2 v = {lo, hi}; bf16x2_t b = __builtin_convertvector(v, bf16x2_t); return __builtin_bit_cast(unsigned, b); }
; __device__ __forceinline__ float bflo(unsigned w) { return __uint_as_float(w << 16); }
; __device__ __forceinline__ float bfhi(unsigned w) { return __uint_as_float(w & 0xffff0000u); }
; __device__ __forceinline__ float sigmoid_f(float x) { return __builtin_amdgcn_rcpf(1.0f + __expf(-x)); }
; __device__ __forceinline__ size_t tl(int r, int c, int K) { return ((size_t)(r >> 8) * (size_t)(K >> 6) + (size_t)(c >> 6)) * 16384 + (size_t)((r & 255) << 6) + (size_t)(c & 63); }
;     __device__ __forceinline__ void operator()(const f32x4 (&acc)[2][2][4][2], const Unit& u, int wr, int wc, int fr, int fq) const {
;     ...
;                 for (int mm = 0; mm < 2; ++mm) {
;                     const int m = mh * 2 + mm;
;                     const int rr = row0 + ai * HALF + m * 16;
; #pragma unroll
;                     for (int bj = 0; bj < 2; ++bj) {
;                         const f32x4 a0 = acc[ai][bj][m][0], a1 = acc[ai][bj][m][1];
;                         const u32x4 yv = yw[mm][bj], mv = mw[mm][bj];
;                         u32x4 w;
;                         w.x = cvt_pk_bf16(sigmoid_f(a0[0]) * bflo(yv.x) + bflo(mv.x), sigmoid_f(a0[1]) * bfhi(yv.x) + bfhi(mv.x));
;                         w.y = cvt_pk_bf16(sigmoid_f(a0[2]) * bflo(yv.y) + bflo(mv.y), sigmoid_f(a0[3]) * bfhi(yv.y) + bfhi(mv.y));
;                         w.z = cvt_pk_bf16(sigmoid_f(a1[0]) * bflo(yv.z) + bflo(mv.z), sigmoid_f(a1[1]) * bfhi(yv.z) + bfhi(mv.z));
;                         w.w = cvt_pk_bf16(sigmoid_f(a1[2]) * bflo(yv.w) + bflo(mv.w), sigmoid_f(a1[3]) * bfhi(yv.w) + bfhi(mv.w));
;                         *(u32x4*)(merged + tl(rr, col0 + bj * HALF, DM)) = w;
	v_lshlrev_b32_e32 v198, 16, v128
	v_and_b32_e32 v199, 0xffff0000, v128
	v_lshlrev_b32_e32 v200, 16, v132
	v_and_b32_e32 v201, 0xffff0000, v132
	v_fma_f32 v28, v28, v198, v200
	v_fma_f32 v29, v29, v199, v201
	v_cvt_pk_bf16_f32 v248, v28, v29
	v_lshlrev_b32_e32 v202, 16, v129
	v_and_b32_e32 v203, 0xffff0000, v129
	v_lshlrev_b32_e32 v214, 16, v133
	v_and_b32_e32 v215, 0xffff0000, v133
	v_fma_f32 v30, v30, v202, v214
	v_fma_f32 v31, v31, v203, v215
	v_cvt_pk_bf16_f32 v249, v30, v31
	v_lshlrev_b32_e32 v198, 16, v130
	v_and_b32_e32 v199, 0xffff0000, v130
	v_lshlrev_b32_e32 v200, 16, v134
	v_and_b32_e32 v201, 0xffff0000, v134
	v_fma_f32 v24, v24, v198, v200
	v_fma_f32 v25, v25, v199, v201
	v_cvt_pk_bf16_f32 v250, v24, v25
	v_lshlrev_b32_e32 v202, 16, v131
	v_and_b32_e32 v203, 0xffff0000, v131
	v_lshlrev_b32_e32 v214, 16, v135
	v_and_b32_e32 v215, 0xffff0000, v135
	v_fma_f32 v26, v26, v202, v214
	v_fma_f32 v27, v27, v203, v215
	v_cvt_pk_bf16_f32 v251, v26, v27
	global_store_dwordx4 v194, v[248:251], s[12:13]
	v_lshlrev_b32_e32 v198, 16, v136
	v_and_b32_e32 v199, 0xffff0000, v136
	v_lshlrev_b32_e32 v200, 16, v140
	v_and_b32_e32 v201, 0xffff0000, v140
	v_fma_f32 v20, v20, v198, v200
	v_fma_f32 v21, v21, v199, v201
	v_cvt_pk_bf16_f32 v252, v20, v21
	v_lshlrev_b32_e32 v202, 16, v137
	v_and_b32_e32 v203, 0xffff0000, v137
	v_lshlrev_b32_e32 v214, 16, v141
	v_and_b32_e32 v215, 0xffff0000, v141
	v_fma_f32 v22, v22, v202, v214
	v_fma_f32 v23, v23, v203, v215
	v_cvt_pk_bf16_f32 v253, v22, v23
	v_lshlrev_b32_e32 v198, 16, v138
	v_and_b32_e32 v199, 0xffff0000, v138
	v_lshlrev_b32_e32 v200, 16, v142
	v_and_b32_e32 v201, 0xffff0000, v142
	v_fma_f32 v16, v16, v198, v200
	v_fma_f32 v17, v17, v199, v201
	v_cvt_pk_bf16_f32 v254, v16, v17
	v_lshlrev_b32_e32 v202, 16, v139
	v_and_b32_e32 v203, 0xffff0000, v139
	v_lshlrev_b32_e32 v214, 16, v143
	v_and_b32_e32 v215, 0xffff0000, v143
	v_fma_f32 v18, v18, v202, v214
	v_fma_f32 v19, v19, v203, v215
	v_cvt_pk_bf16_f32 v255, v18, v19
	global_store_dwordx4 v195, v[252:255], s[12:13]
	v_lshlrev_b32_e32 v198, 16, v144
	v_and_b32_e32 v199, 0xffff0000, v144
	v_lshlrev_b32_e32 v200, 16, v148
	v_and_b32_e32 v201, 0xffff0000, v148
	v_fma_f32 v12, v12, v198, v200
	v_fma_f32 v13, v13, v199, v201
	v_cvt_pk_bf16_f32 v206, v12, v13
	v_lshlrev_b32_e32 v202, 16, v145
	v_and_b32_e32 v203, 0xffff0000, v145
	v_lshlrev_b32_e32 v214, 16, v149
	v_and_b32_e32 v215, 0xffff0000, v149
	v_fma_f32 v14, v14, v202, v214
	v_fma_f32 v15, v15, v203, v215
	v_cvt_pk_bf16_f32 v207, v14, v15
	v_lshlrev_b32_e32 v198, 16, v146
	v_and_b32_e32 v199, 0xffff0000, v146
	v_lshlrev_b32_e32 v200, 16, v150
	v_and_b32_e32 v201, 0xffff0000, v150
	v_fma_f32 v8, v8, v198, v200
	v_fma_f32 v9, v9, v199, v201
	v_cvt_pk_bf16_f32 v208, v8, v9
	v_lshlrev_b32_e32 v202, 16, v147
	v_and_b32_e32 v203, 0xffff0000, v147
	v_lshlrev_b32_e32 v214, 16, v151
	v_and_b32_e32 v215, 0xffff0000, v151
	v_fma_f32 v10, v10, v202, v214
	v_fma_f32 v11, v11, v203, v215
	v_cvt_pk_bf16_f32 v209, v10, v11
	global_store_dwordx4 v196, v[206:209], s[12:13]
	v_lshlrev_b32_e32 v198, 16, v152
	v_and_b32_e32 v199, 0xffff0000, v152
	v_lshlrev_b32_e32 v200, 16, v156
	v_and_b32_e32 v201, 0xffff0000, v156
	v_fma_f32 v4, v4, v198, v200
	v_fma_f32 v5, v5, v199, v201
	v_cvt_pk_bf16_f32 v210, v4, v5
	v_lshlrev_b32_e32 v202, 16, v153
	v_and_b32_e32 v203, 0xffff0000, v153
	v_lshlrev_b32_e32 v214, 16, v157
	v_and_b32_e32 v215, 0xffff0000, v157
	v_fma_f32 v6, v6, v202, v214
	v_fma_f32 v7, v7, v203, v215
	v_cvt_pk_bf16_f32 v211, v6, v7
	v_lshlrev_b32_e32 v198, 16, v154
	v_and_b32_e32 v199, 0xffff0000, v154
	v_lshlrev_b32_e32 v200, 16, v158
	v_and_b32_e32 v201, 0xffff0000, v158
	v_fma_f32 v0, v0, v198, v200
	v_fma_f32 v1, v1, v199, v201
	v_cvt_pk_bf16_f32 v212, v0, v1
	v_lshlrev_b32_e32 v202, 16, v155
	v_and_b32_e32 v203, 0xffff0000, v155
	v_lshlrev_b32_e32 v214, 16, v159
	v_and_b32_e32 v215, 0xffff0000, v159
	v_fma_f32 v2, v2, v202, v214
	v_fma_f32 v3, v3, v203, v215
	v_cvt_pk_bf16_f32 v213, v2, v3
	global_store_dwordx4 v197, v[210:213], s[12:13]
	s_branch .Lmy_p9_latch

; #define PG8_STAGE(bufoff, gbase, voff) do { _Pragma("unroll") for (int _i = 0; _i < 2; ++_i) \
;         __builtin_amdgcn_global_load_lds((const unsigned*)((const char*)(gbase) + (voff)[_i]), (LAS unsigned*)(lds + (bufoff) + ldsw + _i * 8192), 16, 0, 0); } while (0)
; #define PG8_LDA(dst, b, h) do { _Pragma("unroll") for (int m = 0; m < 4; ++m) _Pragma("unroll") for (int k = 0; k < 2; ++k) dst[m][k] = *(const LAS bf16x8*)(lds + PG8_SA(b, h) + aoff + m * 2048 + k * 1024); } while (0)
; #define PG8_LDB(dst, b, h) do { _Pragma("unroll") for (int n = 0; n < 2; ++n) _Pragma("unroll") for (int k = 0; k < 2; ++k) dst[n][k] = *(const LAS bf16x8*)(lds + PG8_SB(b, h) + boff + n * 2048 + k * 1024); } while (0)
; #define PG8_MMA(ai, bj, At, Bt) do { __builtin_amdgcn_s_setprio(1); _Pragma("unroll") for (int m = 0; m < 4; ++m) _Pragma("unroll") for (int n = 0; n < 2; ++n) _Pragma("unroll") for (int k = 0; k < 2; ++k) \
;         acc[ai][bj][m][n] = __builtin_amdgcn_mfma_f32_16x16x32_bf16(Bt[n][k], At[m][k], acc[ai][bj][m][n], 0, 0, 0); __builtin_amdgcn_s_setprio(0); } while (0)
; #define PG8_WAIT_L(n) asm volatile("s_waitcnt lgkmcnt(" #n ")" ::: "memory")
; #define PG8_BAR __builtin_amdgcn_s_barrier()
; #define PG8_SCHED __builtin_amdgcn_sched_barrier(0)
; template <class Epi, class Sched>
; __device__ __forceinline__ void gemm_phase(LAS unsigned char* lds, const Gemm g, const Sched& S, const Epi& E) {
;     ...
;         for (int t = 0; t < nt; t += 2) {
;             const bool last = (t == nt - 2);
;             const char* a1 = cA + (size_t)(t + 1) * kstep;
;             const char* a2 = last ? nA : cA + (size_t)(t + 2) * kstep; const char* b2 = last ? nB : cB + (size_t)(t + 2) * kstep;
;             const char* a3 = a2 + kstep; const char* b3 = b2 + kstep;
;             PG8_LDB(B0, 0, 0); PG8_SCHED; PG8_LDA(At, 0, 0); PG8_STAGE(PG8_SA(1, 1), a1 + hstep, voffA);
;             PG8_WAIT_L(8); PG8_BAR; PG8_WAIT_L(0); PG8_MMA(0, 0, At, B0); PG8_BAR; PG8_SCHED;
;             PG8_LDB(B1, 0, 1); PG8_STAGE(PG8_SB(0, 0), b2, voffB);
;             PG8_BAR; PG8_WAIT_L(0); PG8_MMA(0, 1, At, B1); PG8_BAR;
;             PG8_LDA(At, 0, 1); PG8_STAGE(PG8_SA(0, 0), a2, voffA);
;             PG8_BAR; PG8_WAIT_L(0); PG8_MMA(1, 0, At, B0); PG8_BAR; PG8_SCHED;
.LBB0_1429:
	ds_read_b128 v[128:131], v185
	ds_read_b128 v[132:135], v185 offset:1024
	ds_read_b128 v[136:139], v185 offset:2048
	ds_read_b128 v[140:143], v185 offset:3072
	s_add_u32 s50, s48, 0x4000
	s_addc_u32 s51, s49, 0
	s_cmp_eq_u32 s73, 28
	s_cselect_b32 s54, s67, s50
	s_cselect_b32 s55, s41, s51
	s_cselect_b32 s50, s68, s69
	s_cselect_b32 s51, s39, s72
	s_add_u32 s52, s54, 0x8000
	s_addc_u32 s53, s55, 0
	v_lshl_add_u64 v[180:181], s[48:49], 0, v[164:165]
	s_add_i32 m0, s47, 0xc000
	ds_read_b128 v[144:147], v186
	ds_read_b128 v[148:151], v186 offset:1024
	ds_read_b128 v[152:155], v186 offset:2048
	ds_read_b128 v[156:159], v186 offset:3072
	ds_read_b128 v[172:175], v186 offset:4096
	ds_read_b128 v[176:179], v186 offset:5120
	ds_read_b128 v[188:191], v186 offset:6144
	ds_read_b128 v[192:195], v186 offset:7168
	global_load_lds_dwordx4 v[180:181], off
	v_lshl_add_u64 v[180:181], s[48:49], 0, v[166:167]
	s_add_i32 m0, s47, 0xe000
	s_nop 0
	global_load_lds_dwordx4 v[180:181], off
	s_waitcnt lgkmcnt(8)
	s_barrier
	s_waitcnt lgkmcnt(0)
	s_waitcnt lgkmcnt(0)
	v_mfma_f32_16x16x32_bf16 v[124:127], v[128:131], v[144:147], v[124:127]
	v_mfma_f32_16x16x32_bf16 v[120:123], v[136:139], v[144:147], v[120:123]
	v_mfma_f32_16x16x32_bf16 v[116:119], v[128:131], v[152:155], v[116:119]
	v_mfma_f32_16x16x32_bf16 v[104:107], v[136:139], v[152:155], v[104:107]
	v_mfma_f32_16x16x32_bf16 v[92:95], v[128:131], v[172:175], v[92:95]
	v_mfma_f32_16x16x32_bf16 v[88:91], v[136:139], v[172:175], v[88:91]
	v_mfma_f32_16x16x32_bf16 v[76:79], v[128:131], v[188:191], v[76:79]
	v_mfma_f32_16x16x32_bf16 v[72:75], v[136:139], v[188:191], v[72:75]
	v_mfma_f32_16x16x32_bf16 v[124:127], v[132:135], v[148:151], v[124:127]
	v_mfma_f32_16x16x32_bf16 v[120:123], v[140:143], v[148:151], v[120:123]
	v_mfma_f32_16x16x32_bf16 v[116:119], v[132:135], v[156:159], v[116:119]
	v_mfma_f32_16x16x32_bf16 v[104:107], v[140:143], v[156:159], v[104:107]
	v_mfma_f32_16x16x32_bf16 v[92:95], v[132:135], v[176:179], v[92:95]
	v_mfma_f32_16x16x32_bf16 v[88:91], v[140:143], v[176:179], v[88:91]
	v_mfma_f32_16x16x32_bf16 v[76:79], v[132:135], v[192:195], v[76:79]
	v_mfma_f32_16x16x32_bf16 v[72:75], v[140:143], v[192:195], v[72:75]
	s_barrier
	s_add_i32 s74, s71, s60
	v_lshl_add_u64 v[180:181], s[50:51], 0, v[160:161]
	s_mov_b32 m0, s74
	ds_read_b128 v[196:199], v187
	ds_read_b128 v[200:203], v187 offset:1024
	ds_read_b128 v[206:209], v187 offset:2048
	ds_read_b128 v[210:213], v187 offset:3072
	global_load_lds_dwordx4 v[180:181], off
	v_lshl_add_u64 v[180:181], s[50:51], 0, v[162:163]
	s_add_i32 m0, s74, 0x2000
	s_nop 0
	global_load_lds_dwordx4 v[180:181], off
	s_barrier
	s_waitcnt lgkmcnt(0)
	s_waitcnt lgkmcnt(0)
	v_mfma_f32_16x16x32_bf16 v[112:115], v[196:199], v[144:147], v[112:115]
	v_mfma_f32_16x16x32_bf16 v[108:111], v[206:209], v[144:147], v[108:111]
	v_mfma_f32_16x16x32_bf16 v[100:103], v[196:199], v[152:155], v[100:103]
	v_mfma_f32_16x16x32_bf16 v[96:99], v[206:209], v[152:155], v[96:99]
	v_mfma_f32_16x16x32_bf16 v[84:87], v[196:199], v[172:175], v[84:87]
	v_mfma_f32_16x16x32_bf16 v[80:83], v[206:209], v[172:175], v[80:83]
	v_mfma_f32_16x16x32_bf16 v[68:71], v[196:199], v[188:191], v[68:71]
	v_mfma_f32_16x16x32_bf16 v[64:67], v[206:209], v[188:191], v[64:67]
	v_mfma_f32_16x16x32_bf16 v[112:115], v[200:203], v[148:151], v[112:115]
	v_mfma_f32_16x16x32_bf16 v[108:111], v[210:213], v[148:151], v[108:111]
	v_mfma_f32_16x16x32_bf16 v[100:103], v[200:203], v[156:159], v[100:103]
	v_mfma_f32_16x16x32_bf16 v[96:99], v[210:213], v[156:159], v[96:99]
	v_mfma_f32_16x16x32_bf16 v[84:87], v[200:203], v[176:179], v[84:87]
	v_mfma_f32_16x16x32_bf16 v[80:83], v[210:213], v[176:179], v[80:83]
	v_mfma_f32_16x16x32_bf16 v[68:71], v[200:203], v[192:195], v[68:71]
	v_mfma_f32_16x16x32_bf16 v[64:67], v[210:213], v[192:195], v[64:67]
	s_mov_b32 m0, s47
	v_lshl_add_u64 v[180:181], s[54:55], 0, v[160:161]
	s_barrier
	ds_read_b128 v[144:147], v186 offset:16384
	ds_read_b128 v[148:151], v186 offset:17408
	ds_read_b128 v[152:155], v186 offset:18432
	ds_read_b128 v[156:159], v186 offset:19456
	ds_read_b128 v[172:175], v186 offset:20480
	ds_read_b128 v[176:179], v186 offset:21504
	ds_read_b128 v[188:191], v186 offset:22528
	ds_read_b128 v[192:195], v186 offset:23552
	global_load_lds_dwordx4 v[180:181], off
	v_lshl_add_u64 v[180:181], s[54:55], 0, v[162:163]
	s_mov_b32 m0, s61
	s_nop 0
	global_load_lds_dwordx4 v[180:181], off
	s_barrier
	s_waitcnt lgkmcnt(0)
	s_waitcnt lgkmcnt(0)
	v_mfma_f32_16x16x32_bf16 v[60:63], v[128:131], v[144:147], v[60:63]
	v_mfma_f32_16x16x32_bf16 v[56:59], v[136:139], v[144:147], v[56:59]
	v_mfma_f32_16x16x32_bf16 v[48:51], v[128:131], v[152:155], v[48:51]
	v_mfma_f32_16x16x32_bf16 v[40:43], v[136:139], v[152:155], v[40:43]
	v_mfma_f32_16x16x32_bf16 v[28:31], v[128:131], v[172:175], v[28:31]
	v_mfma_f32_16x16x32_bf16 v[24:27], v[136:139], v[172:175], v[24:27]
	v_mfma_f32_16x16x32_bf16 v[16:19], v[128:131], v[188:191], v[16:19]
	v_mfma_f32_16x16x32_bf16 v[8:11], v[136:139], v[188:191], v[8:11]
	v_mfma_f32_16x16x32_bf16 v[60:63], v[132:135], v[148:151], v[60:63]
	v_mfma_f32_16x16x32_bf16 v[56:59], v[140:143], v[148:151], v[56:59]
	v_mfma_f32_16x16x32_bf16 v[48:51], v[132:135], v[156:159], v[48:51]
	v_mfma_f32_16x16x32_bf16 v[40:43], v[140:143], v[156:159], v[40:43]
	v_mfma_f32_16x16x32_bf16 v[28:31], v[132:135], v[176:179], v[28:31]
	v_mfma_f32_16x16x32_bf16 v[24:27], v[140:143], v[176:179], v[24:27]
	v_mfma_f32_16x16x32_bf16 v[16:19], v[132:135], v[192:195], v[16:19]
	v_mfma_f32_16x16x32_bf16 v[8:11], v[140:143], v[192:195], v[8:11]
	s_barrier
; #define PG8_STAGE(bufoff, gbase, voff) do { _Pragma("unroll") for (int _i = 0; _i < 2; ++_i) \
;         __builtin_amdgcn_global_load_lds((const unsigned*)((const char*)(gbase) + (voff)[_i]), (LAS unsigned*)(lds + (bufoff) + ldsw + _i * 8192), 16, 0, 0); } while (0)
; #define PG8_LDA(dst, b, h) do { _Pragma("unroll") for (int m = 0; m < 4; ++m) _Pragma("unroll") for (int k = 0; k < 2; ++k) dst[m][k] = *(const LAS bf16x8*)(lds + PG8_SA(b, h) + aoff + m * 2048 + k * 1024); } while (0)
; #define PG8_LDB(dst, b, h) do { _Pragma("unroll") for (int n = 0; n < 2; ++n) _Pragma("unroll") for (int k = 0; k < 2; ++k) dst[n][k] = *(const LAS bf16x8*)(lds + PG8_SB(b, h) + boff + n * 2048 + k * 1024); } while (0)
; #define PG8_MMA(ai, bj, At, Bt) do { __builtin_amdgcn_s_setprio(1); _Pragma("unroll") for (int m = 0; m < 4; ++m) _Pragma("unroll") for (int n = 0; n < 2; ++n) _Pragma("unroll") for (int k = 0; k < 2; ++k) \
;         acc[ai][bj][m][n] = __builtin_amdgcn_mfma_f32_16x16x32_bf16(Bt[n][k], At[m][k], acc[ai][bj][m][n], 0, 0, 0); __builtin_amdgcn_s_setprio(0); } while (0)
; #define PG8_WAIT_V(n) asm volatile("s_waitcnt vmcnt(" #n ")" ::: "memory")
; #define PG8_WAIT_L(n) asm volatile("s_waitcnt lgkmcnt(" #n ")" ::: "memory")
; #define PG8_BAR __builtin_amdgcn_s_barrier()
; #define PG8_SCHED __builtin_amdgcn_sched_barrier(0)
; template <class Epi, class Sched>
; __device__ __forceinline__ void gemm_phase(LAS unsigned char* lds, const Gemm g, const Sched& S, const Epi& E) {
;     ...
;             PG8_STAGE(PG8_SB(0, 1), b2 + hstep, voffB);
;             PG8_WAIT_V(6); PG8_BAR; PG8_MMA(1, 1, At, B1); PG8_BAR;
;             PG8_LDB(B0, 1, 0); PG8_SCHED; PG8_LDA(At, 1, 0); PG8_STAGE(PG8_SA(0, 1), a2 + hstep, voffA);
;             PG8_WAIT_L(8); PG8_BAR; PG8_WAIT_L(0); PG8_MMA(0, 0, At, B0); PG8_BAR; PG8_SCHED;
;             PG8_LDB(B1, 1, 1); PG8_STAGE(PG8_SB(1, 0), b3, voffB);
;             PG8_BAR; PG8_WAIT_L(0); PG8_MMA(0, 1, At, B1); PG8_BAR;
;             PG8_LDA(At, 1, 1); PG8_STAGE(PG8_SA(1, 0), a3, voffA);
	s_add_u32 s74, s50, 0x4000
	s_addc_u32 s75, s51, 0
	s_add_i32 s76, s66, s60
	v_lshl_add_u64 v[128:129], s[74:75], 0, v[160:161]
	s_mov_b32 m0, s76
	s_nop 0
	global_load_lds_dwordx4 v[128:129], off
	v_lshl_add_u64 v[128:129], s[74:75], 0, v[162:163]
	s_add_i32 m0, s76, 0x2000
	s_nop 0
	global_load_lds_dwordx4 v[128:129], off
	s_waitcnt vmcnt(6)
	s_barrier
	v_mfma_f32_16x16x32_bf16 v[52:55], v[196:199], v[144:147], v[52:55]
	v_mfma_f32_16x16x32_bf16 v[44:47], v[206:209], v[144:147], v[44:47]
	v_mfma_f32_16x16x32_bf16 v[36:39], v[196:199], v[152:155], v[36:39]
	v_mfma_f32_16x16x32_bf16 v[32:35], v[206:209], v[152:155], v[32:35]
	v_mfma_f32_16x16x32_bf16 v[20:23], v[196:199], v[172:175], v[20:23]
	v_mfma_f32_16x16x32_bf16 v[12:15], v[206:209], v[172:175], v[12:15]
	v_mfma_f32_16x16x32_bf16 v[4:7], v[196:199], v[188:191], v[4:7]
	v_mfma_f32_16x16x32_bf16 v[0:3], v[206:209], v[188:191], v[0:3]
	v_mfma_f32_16x16x32_bf16 v[52:55], v[200:203], v[148:151], v[52:55]
	v_mfma_f32_16x16x32_bf16 v[44:47], v[210:213], v[148:151], v[44:47]
	v_mfma_f32_16x16x32_bf16 v[36:39], v[200:203], v[156:159], v[36:39]
	v_mfma_f32_16x16x32_bf16 v[32:35], v[210:213], v[156:159], v[32:35]
	v_mfma_f32_16x16x32_bf16 v[20:23], v[200:203], v[176:179], v[20:23]
	v_mfma_f32_16x16x32_bf16 v[12:15], v[210:213], v[176:179], v[12:15]
	v_mfma_f32_16x16x32_bf16 v[4:7], v[200:203], v[192:195], v[4:7]
	v_mfma_f32_16x16x32_bf16 v[0:3], v[210:213], v[192:195], v[0:3]
	s_add_i32 s74, 0, 0x18000
	v_add_u32_e32 v140, s74, v183
	s_barrier
	ds_read_b128 v[128:131], v140
	ds_read_b128 v[132:135], v140 offset:1024
	ds_read_b128 v[136:139], v140 offset:2048
	ds_read_b128 v[140:143], v140 offset:3072
	s_add_u32 s54, s54, 0x4000
	s_addc_u32 s55, s55, 0
	s_mov_b32 m0, s62
	v_lshl_add_u64 v[180:181], s[54:55], 0, v[160:161]
	ds_read_b128 v[144:147], v186 offset:32768
	ds_read_b128 v[148:151], v186 offset:33792
	ds_read_b128 v[152:155], v186 offset:34816
	ds_read_b128 v[156:159], v186 offset:35840
	ds_read_b128 v[172:175], v186 offset:36864
	ds_read_b128 v[176:179], v186 offset:37888
	ds_read_b128 v[188:191], v186 offset:38912
	ds_read_b128 v[192:195], v186 offset:39936
	global_load_lds_dwordx4 v[180:181], off
	v_lshl_add_u64 v[180:181], s[54:55], 0, v[162:163]
	s_mov_b32 m0, s63
	s_nop 0
	global_load_lds_dwordx4 v[180:181], off
	s_waitcnt lgkmcnt(8)
	s_barrier
	s_waitcnt lgkmcnt(0)
	s_waitcnt lgkmcnt(0)
	v_mfma_f32_16x16x32_bf16 v[124:127], v[128:131], v[144:147], v[124:127]
	v_mfma_f32_16x16x32_bf16 v[120:123], v[136:139], v[144:147], v[120:123]
	v_mfma_f32_16x16x32_bf16 v[116:119], v[128:131], v[152:155], v[116:119]
	v_mfma_f32_16x16x32_bf16 v[104:107], v[136:139], v[152:155], v[104:107]
	v_mfma_f32_16x16x32_bf16 v[92:95], v[128:131], v[172:175], v[92:95]
	v_mfma_f32_16x16x32_bf16 v[88:91], v[136:139], v[172:175], v[88:91]
	v_mfma_f32_16x16x32_bf16 v[76:79], v[128:131], v[188:191], v[76:79]
	v_mfma_f32_16x16x32_bf16 v[72:75], v[136:139], v[188:191], v[72:75]
	v_mfma_f32_16x16x32_bf16 v[124:127], v[132:135], v[148:151], v[124:127]
	v_mfma_f32_16x16x32_bf16 v[120:123], v[140:143], v[148:151], v[120:123]
	v_mfma_f32_16x16x32_bf16 v[116:119], v[132:135], v[156:159], v[116:119]
	v_mfma_f32_16x16x32_bf16 v[104:107], v[140:143], v[156:159], v[104:107]
	v_mfma_f32_16x16x32_bf16 v[92:95], v[132:135], v[176:179], v[92:95]
	v_mfma_f32_16x16x32_bf16 v[88:91], v[140:143], v[176:179], v[88:91]
	v_mfma_f32_16x16x32_bf16 v[76:79], v[132:135], v[192:195], v[76:79]
	v_mfma_f32_16x16x32_bf16 v[72:75], v[140:143], v[192:195], v[72:75]
	s_barrier
	s_add_i32 s75, 0, 0x1c000
	s_add_u32 s54, s50, 0x8000
	v_add_u32_e32 v180, s75, v183
	s_addc_u32 s55, s51, 0
	s_add_i32 s74, s74, s60
	ds_read_b128 v[196:199], v180
	ds_read_b128 v[200:203], v180 offset:1024
	ds_read_b128 v[206:209], v180 offset:2048
	ds_read_b128 v[210:213], v180 offset:3072
	v_lshl_add_u64 v[180:181], s[54:55], 0, v[160:161]
	s_mov_b32 m0, s74
	s_nop 0
	global_load_lds_dwordx4 v[180:181], off
	v_lshl_add_u64 v[180:181], s[54:55], 0, v[162:163]
	s_add_i32 m0, s74, 0x2000
	s_nop 0
	global_load_lds_dwordx4 v[180:181], off
	s_barrier
	s_waitcnt lgkmcnt(0)
	s_waitcnt lgkmcnt(0)
	v_mfma_f32_16x16x32_bf16 v[112:115], v[196:199], v[144:147], v[112:115]
	v_mfma_f32_16x16x32_bf16 v[108:111], v[206:209], v[144:147], v[108:111]
	v_mfma_f32_16x16x32_bf16 v[100:103], v[196:199], v[152:155], v[100:103]
	v_mfma_f32_16x16x32_bf16 v[96:99], v[206:209], v[152:155], v[96:99]
	v_mfma_f32_16x16x32_bf16 v[84:87], v[196:199], v[172:175], v[84:87]
	v_mfma_f32_16x16x32_bf16 v[80:83], v[206:209], v[172:175], v[80:83]
	v_mfma_f32_16x16x32_bf16 v[68:71], v[196:199], v[188:191], v[68:71]
	v_mfma_f32_16x16x32_bf16 v[64:67], v[206:209], v[188:191], v[64:67]
	v_mfma_f32_16x16x32_bf16 v[112:115], v[200:203], v[148:151], v[112:115]
	v_mfma_f32_16x16x32_bf16 v[108:111], v[210:213], v[148:151], v[108:111]
	v_mfma_f32_16x16x32_bf16 v[100:103], v[200:203], v[156:159], v[100:103]
	v_mfma_f32_16x16x32_bf16 v[96:99], v[210:213], v[156:159], v[96:99]
	v_mfma_f32_16x16x32_bf16 v[84:87], v[200:203], v[176:179], v[84:87]
	v_mfma_f32_16x16x32_bf16 v[80:83], v[210:213], v[176:179], v[80:83]
	v_mfma_f32_16x16x32_bf16 v[68:71], v[200:203], v[192:195], v[68:71]
	v_mfma_f32_16x16x32_bf16 v[64:67], v[210:213], v[192:195], v[64:67]
	s_mov_b32 m0, s15
	v_lshl_add_u64 v[180:181], s[52:53], 0, v[160:161]
	s_barrier
	ds_read_b128 v[144:147], v186 offset:49152
	ds_read_b128 v[148:151], v186 offset:50176
	ds_read_b128 v[152:155], v186 offset:51200
	ds_read_b128 v[156:159], v186 offset:52224
	ds_read_b128 v[172:175], v186 offset:53248
	ds_read_b128 v[176:179], v186 offset:54272
	ds_read_b128 v[188:191], v186 offset:55296
	ds_read_b128 v[192:195], v186 offset:56320
	global_load_lds_dwordx4 v[180:181], off
	v_lshl_add_u64 v[180:181], s[52:53], 0, v[162:163]
	s_mov_b32 m0, s65
	s_nop 0
	global_load_lds_dwordx4 v[180:181], off
	s_barrier
; #define PG8_STAGE(bufoff, gbase, voff) do { _Pragma("unroll") for (int _i = 0; _i < 2; ++_i) \
;         __builtin_amdgcn_global_load_lds((const unsigned*)((const char*)(gbase) + (voff)[_i]), (LAS unsigned*)(lds + (bufoff) + ldsw + _i * 8192), 16, 0, 0); } while (0)
; #define PG8_MMA(ai, bj, At, Bt) do { __builtin_amdgcn_s_setprio(1); _Pragma("unroll") for (int m = 0; m < 4; ++m) _Pragma("unroll") for (int n = 0; n < 2; ++n) _Pragma("unroll") for (int k = 0; k < 2; ++k) \
;         acc[ai][bj][m][n] = __builtin_amdgcn_mfma_f32_16x16x32_bf16(Bt[n][k], At[m][k], acc[ai][bj][m][n], 0, 0, 0); __builtin_amdgcn_s_setprio(0); } while (0)
; #define PG8_WAIT_V(n) asm volatile("s_waitcnt vmcnt(" #n ")" ::: "memory")
; template <class Epi, class Sched>
; __device__ __forceinline__ void gemm_phase(LAS unsigned char* lds, const Gemm g, const Sched& S, const Epi& E) {
;     ...
;             PG8_BAR; PG8_WAIT_L(0); PG8_MMA(1, 0, At, B0); PG8_BAR; PG8_SCHED;
;             PG8_STAGE(PG8_SB(1, 1), b3 + hstep, voffB);
;             PG8_WAIT_V(6); PG8_BAR; PG8_MMA(1, 1, At, B1); PG8_BAR;
;     __device__ __forceinline__ void operator()(const f32x4 (&acc)[2][2][4][2], const Unit& u, int wr, int wc, int fr, int fq) const {
;         const int row0 = u.pm * BM + wr * 64 + fr, col0 = u.pn * BM + wc * 32 + 4 * fq;
;         f32x4 gv[2][2], bv[2][2];
;         if (MODE == 1) {
; #pragma unroll
;             for (int bj = 0; bj < 2; ++bj)
; #pragma unroll
;                 for (int n = 0; n < 2; ++n) { gv[bj][n] = *(const f32x4*)(g + col0 + bj * HALF + n * 16); bv[bj][n] = *(const f32x4*)(b + col0 + bj * HALF + n * 16); }
;         }
; #pragma unroll
;         for (int ai = 0; ai < 2; ++ai)
; #pragma unroll
;             for (int mh = 0; mh < 2; ++mh) {
;                 f32x4 rv[2][2][2]; f32x2 st[2];
; #pragma unroll
;                 for (int mm = 0; mm < 2; ++mm) {
;                     const int r = row0 + ai * HALF + (mh * 2 + mm) * 16;
;                     const float* rp = MODE == 0 ? ((r < 8192 ? x0 + (size_t)r * DM : x1 + (size_t)(r - 8192) * DM) + col0) : (Z + (size_t)r * DM + col0);
;                     if (MODE == 1) st[mm] = stats[r];
; #pragma unroll
;                     for (int bj = 0; bj < 2; ++bj)
; #pragma unroll
;                         for (int n = 0; n < 2; ++n) rv[mm][bj][n] = *(const f32x4*)(rp + bj * HALF + n * 16);
	s_waitcnt lgkmcnt(0)
	s_waitcnt lgkmcnt(0)
	v_mfma_f32_16x16x32_bf16 v[60:63], v[128:131], v[144:147], v[60:63]
	v_mfma_f32_16x16x32_bf16 v[56:59], v[136:139], v[144:147], v[56:59]
	v_mfma_f32_16x16x32_bf16 v[48:51], v[128:131], v[152:155], v[48:51]
	v_mfma_f32_16x16x32_bf16 v[40:43], v[136:139], v[152:155], v[40:43]
	v_mfma_f32_16x16x32_bf16 v[28:31], v[128:131], v[172:175], v[28:31]
	v_mfma_f32_16x16x32_bf16 v[24:27], v[136:139], v[172:175], v[24:27]
	v_mfma_f32_16x16x32_bf16 v[16:19], v[128:131], v[188:191], v[16:19]
	v_mfma_f32_16x16x32_bf16 v[8:11], v[136:139], v[188:191], v[8:11]
	v_mfma_f32_16x16x32_bf16 v[60:63], v[132:135], v[148:151], v[60:63]
	v_mfma_f32_16x16x32_bf16 v[56:59], v[140:143], v[148:151], v[56:59]
	v_mfma_f32_16x16x32_bf16 v[48:51], v[132:135], v[156:159], v[48:51]
	v_mfma_f32_16x16x32_bf16 v[40:43], v[140:143], v[156:159], v[40:43]
	v_mfma_f32_16x16x32_bf16 v[28:31], v[132:135], v[176:179], v[28:31]
	v_mfma_f32_16x16x32_bf16 v[24:27], v[140:143], v[176:179], v[24:27]
	v_mfma_f32_16x16x32_bf16 v[16:19], v[132:135], v[192:195], v[16:19]
	v_mfma_f32_16x16x32_bf16 v[8:11], v[140:143], v[192:195], v[8:11]
	s_barrier
	s_add_u32 s50, s50, 0xc000
	s_addc_u32 s51, s51, 0
	s_add_i32 s52, s75, s60
	v_lshl_add_u64 v[128:129], s[50:51], 0, v[160:161]
	s_mov_b32 m0, s52
	s_nop 0
	global_load_lds_dwordx4 v[128:129], off
	v_lshl_add_u64 v[128:129], s[50:51], 0, v[162:163]
	s_add_i32 m0, s52, 0x2000
	s_nop 0
	global_load_lds_dwordx4 v[128:129], off
	s_waitcnt vmcnt(6)
	s_barrier
	v_mfma_f32_16x16x32_bf16 v[52:55], v[196:199], v[144:147], v[52:55]
	v_mfma_f32_16x16x32_bf16 v[44:47], v[206:209], v[144:147], v[44:47]
	v_mfma_f32_16x16x32_bf16 v[36:39], v[196:199], v[152:155], v[36:39]
	v_mfma_f32_16x16x32_bf16 v[32:35], v[206:209], v[152:155], v[32:35]
	v_mfma_f32_16x16x32_bf16 v[20:23], v[196:199], v[172:175], v[20:23]
	v_mfma_f32_16x16x32_bf16 v[12:15], v[206:209], v[172:175], v[12:15]
	v_mfma_f32_16x16x32_bf16 v[4:7], v[196:199], v[188:191], v[4:7]
	v_mfma_f32_16x16x32_bf16 v[0:3], v[206:209], v[188:191], v[0:3]
	v_mfma_f32_16x16x32_bf16 v[52:55], v[200:203], v[148:151], v[52:55]
	v_mfma_f32_16x16x32_bf16 v[44:47], v[210:213], v[148:151], v[44:47]
	v_mfma_f32_16x16x32_bf16 v[36:39], v[200:203], v[156:159], v[36:39]
	v_mfma_f32_16x16x32_bf16 v[32:35], v[210:213], v[156:159], v[32:35]
	v_mfma_f32_16x16x32_bf16 v[20:23], v[200:203], v[176:179], v[20:23]
	v_mfma_f32_16x16x32_bf16 v[12:15], v[210:213], v[176:179], v[12:15]
	v_mfma_f32_16x16x32_bf16 v[4:7], v[200:203], v[192:195], v[4:7]
	v_mfma_f32_16x16x32_bf16 v[0:3], v[210:213], v[192:195], v[0:3]
	s_add_i32 s73, s73, 2
	s_add_u32 s48, s48, 0x10000
	s_addc_u32 s49, s49, 0
	s_add_u32 s69, s69, 0x10000
	s_addc_u32 s72, s72, 0
	s_cmp_gt_u32 s73, 29
	s_barrier
	s_cbranch_scc0 .LBB0_1429
	v_lshl_or_b32 v128, s33, 8, v184
	v_ashrrev_i32_e32 v129, 31, v128
	v_lshl_add_u32 v180, s46, 8, v182
	v_lshlrev_b64 v[172:173], 2, v[128:129]
	v_ashrrev_i32_e32 v181, 31, v180
	v_lshl_add_u64 v[174:175], s[12:13], 0, v[172:173]
	v_lshlrev_b64 v[176:177], 13, v[180:181]
	v_or_b32_e32 v130, 16, v180
	v_lshl_add_u64 v[128:129], v[174:175], 0, v[176:177]
	v_lshl_add_u64 v[178:179], v[180:181], 3, s[10:11]
	v_ashrrev_i32_e32 v131, 31, v130
	global_load_dwordx2 v[222:223], v[178:179], off
	global_load_dwordx4 v[188:191], v[128:129], off
	global_load_dwordx4 v[192:195], v[128:129], off offset:64
	global_load_dwordx4 v[196:199], v[128:129], off offset:512
	v_lshlrev_b64 v[224:225], 13, v[130:131]
	global_load_dwordx4 v[200:203], v[128:129], off offset:576
	v_lshl_add_u64 v[128:129], v[130:131], 3, s[10:11]
	v_lshl_add_u64 v[218:219], v[174:175], 0, v[224:225]
	global_load_dwordx2 v[226:227], v[128:129], off
	global_load_dwordx4 v[206:209], v[218:219], off
	v_lshl_add_u64 v[128:129], s[16:17], 0, v[172:173]
	v_lshl_add_u64 v[132:133], s[18:19], 0, v[172:173]
	global_load_dwordx4 v[152:155], v[132:133], off
	global_load_dwordx4 v[156:159], v[128:129], off
	global_load_dwordx4 v[144:147], v[128:129], off offset:64
	global_load_dwordx4 v[148:151], v[132:133], off offset:64
	global_load_dwordx4 v[136:139], v[132:133], off offset:512
	global_load_dwordx4 v[140:143], v[128:129], off offset:512
	s_nop 0
	global_load_dwordx4 v[128:131], v[128:129], off offset:576
	s_nop 0
	global_load_dwordx4 v[132:135], v[132:133], off offset:576
	s_nop 0
	global_load_dwordx4 v[210:213], v[218:219], off offset:64
	global_load_dwordx4 v[214:217], v[218:219], off offset:512
	v_lshl_add_u64 v[220:221], s[12:13], 0, v[176:177]
	v_lshl_add_u64 v[228:229], v[220:221], 0, v[172:173]
	global_load_dwordx4 v[218:221], v[218:219], off offset:576
	v_lshl_add_u64 v[224:225], s[12:13], 0, v[224:225]
	v_lshl_add_u64 v[224:225], v[224:225], 0, v[172:173]
	s_and_b64 vcc, exec, s[8:9]
	s_mov_b32 s33, s38
	s_mov_b32 s46, s40
	s_mov_b64 s[50:51], s[44:45]
	s_mov_b64 s[48:49], s[42:43]
	s_waitcnt vmcnt(0)
;     __device__ __forceinline__ void operator()(const f32x4 (&acc)[2][2][4][2], const Unit& u, int wr, int wc, int fr, int fq) const {
;     ...
; #pragma unroll
;                 for (int mm = 0; mm < 2; ++mm) {
;                     const int m = mh * 2 + mm, r = row0 + ai * HALF + m * 16;
;                     float* zp = Z + (size_t)r * DM + col0;
; #pragma unroll
;                     for (int bj = 0; bj < 2; ++bj)
; #pragma unroll
;                         for (int n = 0; n < 2; ++n) {
;                             f32x4 res = rv[mm][bj][n];
;                             if (MODE == 1) res = (res - st[mm].x) * st[mm].y * gv[bj][n] + bv[bj][n];
;                             *(f32x4*)(zp + bj * HALF + n * 16) = res * ALPHA + acc[ai][bj][m][n] * scale;
;                         }
	v_sub_f32_e32 v189, v189, v222
	v_sub_f32_e32 v188, v188, v222
	v_sub_f32_e32 v191, v191, v222
	v_sub_f32_e32 v190, v190, v222
	v_sub_f32_e32 v201, v201, v222
	v_sub_f32_e32 v200, v200, v222
	v_sub_f32_e32 v203, v203, v222
	v_sub_f32_e32 v202, v202, v222
	v_sub_f32_e32 v193, v193, v222
	v_sub_f32_e32 v192, v192, v222
	v_sub_f32_e32 v195, v195, v222
	v_sub_f32_e32 v194, v194, v222
	v_sub_f32_e32 v197, v197, v222
	v_sub_f32_e32 v196, v196, v222
	v_sub_f32_e32 v199, v199, v222
	v_sub_f32_e32 v198, v198, v222
	v_sub_f32_e32 v207, v207, v226
	v_sub_f32_e32 v206, v206, v226
	v_sub_f32_e32 v209, v209, v226
	v_sub_f32_e32 v208, v208, v226
	v_pk_mul_f32 v[190:191], v[222:223], v[190:191] op_sel:[1,0]
	v_pk_mul_f32 v[188:189], v[222:223], v[188:189] op_sel:[1,0]
	v_pk_mul_f32 v[202:203], v[222:223], v[202:203] op_sel:[1,0]
	v_pk_mul_f32 v[200:201], v[222:223], v[200:201] op_sel:[1,0]
	v_pk_mul_f32 v[194:195], v[222:223], v[194:195] op_sel:[1,0]
	v_pk_mul_f32 v[192:193], v[222:223], v[192:193] op_sel:[1,0]
	v_pk_mul_f32 v[198:199], v[222:223], v[198:199] op_sel:[1,0]
	v_pk_mul_f32 v[196:197], v[222:223], v[196:197] op_sel:[1,0]
	v_pk_mul_f32 v[208:209], v[226:227], v[208:209] op_sel:[1,0]
	v_pk_mul_f32 v[206:207], v[226:227], v[206:207] op_sel:[1,0]
	v_pk_fma_f32 v[188:189], v[156:157], v[188:189], v[152:153]
	v_pk_fma_f32 v[190:191], v[158:159], v[190:191], v[154:155]
	v_pk_fma_f32 v[200:201], v[128:129], v[200:201], v[132:133]
	v_pk_fma_f32 v[202:203], v[130:131], v[202:203], v[134:135]
	v_pk_fma_f32 v[192:193], v[144:145], v[192:193], v[148:149]
	v_pk_fma_f32 v[194:195], v[146:147], v[194:195], v[150:151]
	v_pk_fma_f32 v[196:197], v[140:141], v[196:197], v[136:137]
	v_pk_fma_f32 v[198:199], v[142:143], v[198:199], v[138:139]
	v_pk_fma_f32 v[206:207], v[156:157], v[206:207], v[152:153]
	v_pk_fma_f32 v[208:209], v[158:159], v[208:209], v[154:155]
	v_pk_fma_f32 v[126:127], v[190:191], s[14:15], v[126:127] op_sel_hi:[1,0,1]
	v_pk_fma_f32 v[124:125], v[188:189], s[14:15], v[124:125] op_sel_hi:[1,0,1]
	v_pk_fma_f32 v[110:111], v[202:203], s[14:15], v[110:111] op_sel_hi:[1,0,1]
	v_pk_fma_f32 v[108:109], v[200:201], s[14:15], v[108:109] op_sel_hi:[1,0,1]
	v_pk_fma_f32 v[122:123], v[194:195], s[14:15], v[122:123] op_sel_hi:[1,0,1]
	v_pk_fma_f32 v[120:121], v[192:193], s[14:15], v[120:121] op_sel_hi:[1,0,1]
	v_pk_fma_f32 v[114:115], v[198:199], s[14:15], v[114:115] op_sel_hi:[1,0,1]
	v_pk_fma_f32 v[112:113], v[196:197], s[14:15], v[112:113] op_sel_hi:[1,0,1]
	global_store_dwordx4 v[228:229], v[124:127], off
	global_store_dwordx4 v[228:229], v[120:123], off offset:64
	global_store_dwordx4 v[228:229], v[112:115], off offset:512
	global_store_dwordx4 v[228:229], v[108:111], off offset:576
	s_nop 0
	v_or_b32_e32 v112, 48, v180
	v_pk_fma_f32 v[110:111], v[208:209], s[14:15], v[118:119] op_sel_hi:[1,0,1]
	v_pk_fma_f32 v[108:109], v[206:207], s[14:15], v[116:117] op_sel_hi:[1,0,1]
	global_store_dwordx4 v[224:225], v[108:111], off
	v_ashrrev_i32_e32 v113, 31, v112
	s_nop 0
	v_sub_f32_e32 v109, v211, v226
	v_sub_f32_e32 v108, v210, v226
	v_sub_f32_e32 v111, v213, v226
	v_sub_f32_e32 v110, v212, v226
	v_pk_mul_f32 v[110:111], v[226:227], v[110:111] op_sel:[1,0]
	v_pk_mul_f32 v[108:109], v[226:227], v[108:109] op_sel:[1,0]
	v_pk_fma_f32 v[110:111], v[146:147], v[110:111], v[150:151]
	v_pk_fma_f32 v[108:109], v[144:145], v[108:109], v[148:149]
	v_pk_fma_f32 v[106:107], v[110:111], s[14:15], v[106:107] op_sel_hi:[1,0,1]
	v_pk_fma_f32 v[104:105], v[108:109], s[14:15], v[104:105] op_sel_hi:[1,0,1]
	global_store_dwordx4 v[224:225], v[104:107], off offset:64
	s_nop 1
	v_sub_f32_e32 v105, v215, v226
	v_sub_f32_e32 v104, v214, v226
	v_sub_f32_e32 v107, v217, v226
	v_sub_f32_e32 v106, v216, v226
	v_pk_mul_f32 v[106:107], v[226:227], v[106:107] op_sel:[1,0]
	v_pk_mul_f32 v[104:105], v[226:227], v[104:105] op_sel:[1,0]
	v_pk_fma_f32 v[106:107], v[142:143], v[106:107], v[138:139]
	v_pk_fma_f32 v[104:105], v[140:141], v[104:105], v[136:137]
	v_pk_fma_f32 v[102:103], v[106:107], s[14:15], v[102:103] op_sel_hi:[1,0,1]
	v_pk_fma_f32 v[100:101], v[104:105], s[14:15], v[100:101] op_sel_hi:[1,0,1]
	global_store_dwordx4 v[224:225], v[100:103], off offset:512
	s_nop 1
	v_sub_f32_e32 v101, v219, v226
	v_sub_f32_e32 v100, v218, v226
	v_sub_f32_e32 v103, v221, v226
	v_sub_f32_e32 v102, v220, v226
	v_pk_mul_f32 v[102:103], v[226:227], v[102:103] op_sel:[1,0]
	v_pk_mul_f32 v[100:101], v[226:227], v[100:101] op_sel:[1,0]
	v_pk_fma_f32 v[102:103], v[130:131], v[102:103], v[134:135]
	v_pk_fma_f32 v[100:101], v[128:129], v[100:101], v[132:133]
	v_pk_fma_f32 v[98:99], v[102:103], s[14:15], v[98:99] op_sel_hi:[1,0,1]
	v_pk_fma_f32 v[96:97], v[100:101], s[14:15], v[96:97] op_sel_hi:[1,0,1]
	global_store_dwordx4 v[224:225], v[96:99], off offset:576
	s_nop 1
	v_or_b32_e32 v96, 32, v180
	v_ashrrev_i32_e32 v97, 31, v96
	v_lshlrev_b64 v[124:125], 13, v[96:97]
	v_lshl_add_u64 v[108:109], v[174:175], 0, v[124:125]
	v_lshl_add_u64 v[96:97], v[96:97], 3, s[10:11]
	global_load_dwordx2 v[188:189], v[96:97], off
	s_nop 0
	global_load_dwordx4 v[96:99], v[108:109], off
	global_load_dwordx4 v[100:103], v[108:109], off offset:64
	global_load_dwordx4 v[104:107], v[108:109], off offset:512
	s_nop 0
	global_load_dwordx4 v[108:111], v[108:109], off offset:576
	v_lshlrev_b64 v[180:181], 13, v[112:113]
	v_lshl_add_u64 v[112:113], v[112:113], 3, s[10:11]
	v_lshl_add_u64 v[126:127], v[174:175], 0, v[180:181]
	global_load_dwordx2 v[190:191], v[112:113], off
	s_nop 0
	global_load_dwordx4 v[112:115], v[126:127], off
	global_load_dwordx4 v[116:119], v[126:127], off offset:64
	global_load_dwordx4 v[120:123], v[126:127], off offset:512
	v_lshl_add_u64 v[192:193], s[12:13], 0, v[124:125]
	global_load_dwordx4 v[124:127], v[126:127], off offset:576
	v_lshl_add_u64 v[192:193], v[192:193], 0, v[172:173]
	s_waitcnt vmcnt(0)
;     __device__ __forceinline__ void operator()(const f32x4 (&acc)[2][2][4][2], const Unit& u, int wr, int wc, int fr, int fq) const {
;     ...
; #pragma unroll
;                 for (int mm = 0; mm < 2; ++mm) {
;                     const int m = mh * 2 + mm, r = row0 + ai * HALF + m * 16;
;                     float* zp = Z + (size_t)r * DM + col0;
; #pragma unroll
;                     for (int bj = 0; bj < 2; ++bj)
; #pragma unroll
;                         for (int n = 0; n < 2; ++n) {
;                             f32x4 res = rv[mm][bj][n];
;                             if (MODE == 1) res = (res - st[mm].x) * st[mm].y * gv[bj][n] + bv[bj][n];
;                             *(f32x4*)(zp + bj * HALF + n * 16) = res * ALPHA + acc[ai][bj][m][n] * scale;
;                         }
	v_sub_f32_e32 v97, v97, v188
	v_sub_f32_e32 v96, v96, v188
	v_sub_f32_e32 v99, v99, v188
	v_sub_f32_e32 v98, v98, v188
	v_sub_f32_e32 v101, v101, v188
	v_sub_f32_e32 v100, v100, v188
	v_sub_f32_e32 v103, v103, v188
	v_sub_f32_e32 v102, v102, v188
	v_pk_mul_f32 v[98:99], v[188:189], v[98:99] op_sel:[1,0]
	v_pk_mul_f32 v[96:97], v[188:189], v[96:97] op_sel:[1,0]
	v_pk_mul_f32 v[100:101], v[188:189], v[100:101] op_sel:[1,0]
	v_pk_mul_f32 v[102:103], v[188:189], v[102:103] op_sel:[1,0]
	v_pk_fma_f32 v[96:97], v[156:157], v[96:97], v[152:153]
	v_pk_fma_f32 v[98:99], v[158:159], v[98:99], v[154:155]
	v_pk_fma_f32 v[100:101], v[144:145], v[100:101], v[148:149]
	v_sub_f32_e32 v105, v105, v188
	v_sub_f32_e32 v104, v104, v188
	v_sub_f32_e32 v107, v107, v188
	v_sub_f32_e32 v106, v106, v188
	v_pk_fma_f32 v[102:103], v[146:147], v[102:103], v[150:151]
	v_pk_fma_f32 v[94:95], v[98:99], s[14:15], v[94:95] op_sel_hi:[1,0,1]
	v_pk_fma_f32 v[92:93], v[96:97], s[14:15], v[92:93] op_sel_hi:[1,0,1]
	v_pk_fma_f32 v[88:89], v[100:101], s[14:15], v[88:89] op_sel_hi:[1,0,1]
	v_pk_mul_f32 v[106:107], v[188:189], v[106:107] op_sel:[1,0]
	v_pk_fma_f32 v[90:91], v[102:103], s[14:15], v[90:91] op_sel_hi:[1,0,1]
	global_store_dwordx4 v[192:193], v[92:95], off
	global_store_dwordx4 v[192:193], v[88:91], off offset:64
	v_lshl_add_u64 v[98:99], v[176:177], 0, s[30:31]
	v_lshl_add_u64 v[92:93], v[176:177], 0, s[28:29]
	v_pk_mul_f32 v[88:89], v[188:189], v[104:105] op_sel:[1,0]
	v_pk_fma_f32 v[90:91], v[142:143], v[106:107], v[138:139]
	v_pk_fma_f32 v[88:89], v[140:141], v[88:89], v[136:137]
	v_pk_fma_f32 v[86:87], v[90:91], s[14:15], v[86:87] op_sel_hi:[1,0,1]
	v_pk_fma_f32 v[84:85], v[88:89], s[14:15], v[84:85] op_sel_hi:[1,0,1]
	global_store_dwordx4 v[192:193], v[84:87], off offset:512
	v_lshl_add_u64 v[94:95], v[174:175], 0, v[98:99]
	v_lshl_add_u64 v[102:103], s[12:13], 0, v[92:93]
	v_sub_f32_e32 v85, v109, v188
	v_sub_f32_e32 v84, v108, v188
	v_sub_f32_e32 v87, v111, v188
	v_sub_f32_e32 v86, v110, v188
	v_pk_mul_f32 v[86:87], v[188:189], v[86:87] op_sel:[1,0]
	v_pk_mul_f32 v[84:85], v[188:189], v[84:85] op_sel:[1,0]
	v_pk_fma_f32 v[86:87], v[130:131], v[86:87], v[134:135]
	v_pk_fma_f32 v[84:85], v[128:129], v[84:85], v[132:133]
	v_pk_fma_f32 v[82:83], v[86:87], s[14:15], v[82:83] op_sel_hi:[1,0,1]
	v_pk_fma_f32 v[80:81], v[84:85], s[14:15], v[80:81] op_sel_hi:[1,0,1]
	global_store_dwordx4 v[192:193], v[80:83], off offset:576
	v_sub_f32_e32 v85, v115, v190
	v_sub_f32_e32 v84, v114, v190
	v_sub_f32_e32 v83, v113, v190
	v_sub_f32_e32 v82, v112, v190
	v_pk_mul_f32 v[84:85], v[190:191], v[84:85] op_sel:[1,0]
	v_pk_mul_f32 v[82:83], v[190:191], v[82:83] op_sel:[1,0]
	v_lshl_add_u64 v[80:81], s[12:13], 0, v[180:181]
	v_pk_fma_f32 v[82:83], v[156:157], v[82:83], v[152:153]
	v_pk_fma_f32 v[84:85], v[158:159], v[84:85], v[154:155]
	v_lshl_add_u64 v[80:81], v[80:81], 0, v[172:173]
	v_pk_fma_f32 v[78:79], v[84:85], s[14:15], v[78:79] op_sel_hi:[1,0,1]
	v_pk_fma_f32 v[76:77], v[82:83], s[14:15], v[76:77] op_sel_hi:[1,0,1]
	global_store_dwordx4 v[80:81], v[76:79], off
	v_lshl_add_u64 v[102:103], v[102:103], 0, v[172:173]
	s_nop 0
	v_sub_f32_e32 v77, v117, v190
	v_sub_f32_e32 v76, v116, v190
	v_sub_f32_e32 v79, v119, v190
	v_sub_f32_e32 v78, v118, v190
	v_pk_mul_f32 v[78:79], v[190:191], v[78:79] op_sel:[1,0]
	v_pk_mul_f32 v[76:77], v[190:191], v[76:77] op_sel:[1,0]
	v_pk_fma_f32 v[78:79], v[146:147], v[78:79], v[150:151]
	v_pk_fma_f32 v[76:77], v[144:145], v[76:77], v[148:149]
	v_pk_fma_f32 v[74:75], v[78:79], s[14:15], v[74:75] op_sel_hi:[1,0,1]
	v_pk_fma_f32 v[72:73], v[76:77], s[14:15], v[72:73] op_sel_hi:[1,0,1]
	global_store_dwordx4 v[80:81], v[72:75], off offset:64
	v_lshl_add_u64 v[76:77], v[174:175], 0, v[92:93]
	s_nop 0
	v_sub_f32_e32 v73, v121, v190
	v_sub_f32_e32 v72, v120, v190
	v_sub_f32_e32 v75, v123, v190
	v_sub_f32_e32 v74, v122, v190
	v_pk_mul_f32 v[74:75], v[190:191], v[74:75] op_sel:[1,0]
	v_pk_mul_f32 v[72:73], v[190:191], v[72:73] op_sel:[1,0]
	v_pk_fma_f32 v[74:75], v[142:143], v[74:75], v[138:139]
	v_pk_fma_f32 v[72:73], v[140:141], v[72:73], v[136:137]
	v_pk_fma_f32 v[70:71], v[74:75], s[14:15], v[70:71] op_sel_hi:[1,0,1]
	v_pk_fma_f32 v[68:69], v[72:73], s[14:15], v[68:69] op_sel_hi:[1,0,1]
	global_store_dwordx4 v[80:81], v[68:71], off offset:512
	s_nop 1
	v_sub_f32_e32 v69, v125, v190
	v_sub_f32_e32 v68, v124, v190
	v_sub_f32_e32 v71, v127, v190
	v_sub_f32_e32 v70, v126, v190
	v_pk_mul_f32 v[70:71], v[190:191], v[70:71] op_sel:[1,0]
	v_pk_mul_f32 v[68:69], v[190:191], v[68:69] op_sel:[1,0]
	v_pk_fma_f32 v[70:71], v[130:131], v[70:71], v[134:135]
	v_pk_fma_f32 v[68:69], v[128:129], v[68:69], v[132:133]
	v_pk_fma_f32 v[66:67], v[70:71], s[14:15], v[66:67] op_sel_hi:[1,0,1]
	v_pk_fma_f32 v[64:65], v[68:69], s[14:15], v[64:65] op_sel_hi:[1,0,1]
	global_store_dwordx4 v[80:81], v[64:67], off offset:576
	global_load_dwordx2 v[96:97], v[178:179], off offset:1024
	s_nop 0
	global_load_dwordx4 v[64:67], v[76:77], off
	global_load_dwordx4 v[68:71], v[76:77], off offset:64
	global_load_dwordx4 v[72:75], v[76:77], off offset:512
	s_nop 0
	global_load_dwordx4 v[76:79], v[76:77], off offset:576
	s_nop 0
	global_load_dwordx2 v[100:101], v[178:179], off offset:1152
	global_load_dwordx4 v[80:83], v[94:95], off
	global_load_dwordx4 v[84:87], v[94:95], off offset:64
	global_load_dwordx4 v[88:91], v[94:95], off offset:512
	s_waitcnt vmcnt(0)
;     __device__ __forceinline__ void operator()(const f32x4 (&acc)[2][2][4][2], const Unit& u, int wr, int wc, int fr, int fq) const {
;     ...
; #pragma unroll
;                 for (int mm = 0; mm < 2; ++mm) {
;                     const int m = mh * 2 + mm, r = row0 + ai * HALF + m * 16;
;                     float* zp = Z + (size_t)r * DM + col0;
; #pragma unroll
;                     for (int bj = 0; bj < 2; ++bj)
; #pragma unroll
;                         for (int n = 0; n < 2; ++n) {
;                             f32x4 res = rv[mm][bj][n];
;                             if (MODE == 1) res = (res - st[mm].x) * st[mm].y * gv[bj][n] + bv[bj][n];
;                             *(f32x4*)(zp + bj * HALF + n * 16) = res * ALPHA + acc[ai][bj][m][n] * scale;
;                         }
	v_sub_f32_e32 v65, v65, v96
	global_load_dwordx4 v[92:95], v[94:95], off offset:576
	v_sub_f32_e32 v64, v64, v96
	v_sub_f32_e32 v67, v67, v96
	v_sub_f32_e32 v66, v66, v96
	v_pk_mul_f32 v[66:67], v[96:97], v[66:67] op_sel:[1,0]
	v_pk_mul_f32 v[64:65], v[96:97], v[64:65] op_sel:[1,0]
	v_pk_fma_f32 v[66:67], v[158:159], v[66:67], v[154:155]
	v_pk_fma_f32 v[64:65], v[156:157], v[64:65], v[152:153]
	v_pk_fma_f32 v[62:63], v[66:67], s[14:15], v[62:63] op_sel_hi:[1,0,1]
	v_pk_fma_f32 v[60:61], v[64:65], s[14:15], v[60:61] op_sel_hi:[1,0,1]
	global_store_dwordx4 v[102:103], v[60:63], off
	v_lshl_add_u64 v[64:65], v[176:177], 0, s[34:35]
	s_nop 0
	v_sub_f32_e32 v61, v69, v96
	v_sub_f32_e32 v60, v68, v96
	v_sub_f32_e32 v63, v71, v96
	v_sub_f32_e32 v62, v70, v96
	v_pk_mul_f32 v[62:63], v[96:97], v[62:63] op_sel:[1,0]
	v_pk_mul_f32 v[60:61], v[96:97], v[60:61] op_sel:[1,0]
	v_pk_fma_f32 v[62:63], v[146:147], v[62:63], v[150:151]
	v_pk_fma_f32 v[60:61], v[144:145], v[60:61], v[148:149]
	v_pk_fma_f32 v[58:59], v[62:63], s[14:15], v[58:59] op_sel_hi:[1,0,1]
	v_pk_fma_f32 v[56:57], v[60:61], s[14:15], v[56:57] op_sel_hi:[1,0,1]
	global_store_dwordx4 v[102:103], v[56:59], off offset:64
	v_lshl_add_u64 v[68:69], v[176:177], 0, s[36:37]
	v_lshl_add_u64 v[60:61], v[174:175], 0, v[68:69]
	v_sub_f32_e32 v57, v73, v96
	v_sub_f32_e32 v56, v72, v96
	v_sub_f32_e32 v59, v75, v96
	v_sub_f32_e32 v58, v74, v96
	v_pk_mul_f32 v[58:59], v[96:97], v[58:59] op_sel:[1,0]
	v_pk_mul_f32 v[56:57], v[96:97], v[56:57] op_sel:[1,0]
	v_pk_fma_f32 v[58:59], v[142:143], v[58:59], v[138:139]
	v_pk_fma_f32 v[56:57], v[140:141], v[56:57], v[136:137]
	v_pk_fma_f32 v[54:55], v[58:59], s[14:15], v[54:55] op_sel_hi:[1,0,1]
	v_pk_fma_f32 v[52:53], v[56:57], s[14:15], v[52:53] op_sel_hi:[1,0,1]
	global_store_dwordx4 v[102:103], v[52:55], off offset:512
	s_nop 1
	v_sub_f32_e32 v53, v77, v96
	v_sub_f32_e32 v52, v76, v96
	v_sub_f32_e32 v55, v79, v96
	v_sub_f32_e32 v54, v78, v96
	v_pk_mul_f32 v[54:55], v[96:97], v[54:55] op_sel:[1,0]
	v_pk_mul_f32 v[52:53], v[96:97], v[52:53] op_sel:[1,0]
	v_pk_fma_f32 v[54:55], v[130:131], v[54:55], v[134:135]
	v_pk_fma_f32 v[52:53], v[128:129], v[52:53], v[132:133]
	v_pk_fma_f32 v[46:47], v[54:55], s[14:15], v[46:47] op_sel_hi:[1,0,1]
	v_pk_fma_f32 v[44:45], v[52:53], s[14:15], v[44:45] op_sel_hi:[1,0,1]
	global_store_dwordx4 v[102:103], v[44:47], off offset:576
	s_nop 1
	v_lshl_add_u64 v[44:45], s[12:13], 0, v[98:99]
	v_lshl_add_u64 v[52:53], v[44:45], 0, v[172:173]
	v_sub_f32_e32 v45, v81, v100
	v_sub_f32_e32 v44, v80, v100
	v_sub_f32_e32 v47, v83, v100
	v_sub_f32_e32 v46, v82, v100
	v_pk_mul_f32 v[46:47], v[100:101], v[46:47] op_sel:[1,0]
	v_pk_mul_f32 v[44:45], v[100:101], v[44:45] op_sel:[1,0]
	v_pk_fma_f32 v[46:47], v[158:159], v[46:47], v[154:155]
	v_pk_fma_f32 v[44:45], v[156:157], v[44:45], v[152:153]
	v_pk_fma_f32 v[46:47], v[46:47], s[14:15], v[50:51] op_sel_hi:[1,0,1]
	v_pk_fma_f32 v[44:45], v[44:45], s[14:15], v[48:49] op_sel_hi:[1,0,1]
	global_store_dwordx4 v[52:53], v[44:47], off
	s_nop 1
	v_sub_f32_e32 v45, v85, v100
	v_sub_f32_e32 v44, v84, v100
	v_sub_f32_e32 v47, v87, v100
	v_sub_f32_e32 v46, v86, v100
	v_pk_mul_f32 v[46:47], v[100:101], v[46:47] op_sel:[1,0]
	v_pk_mul_f32 v[44:45], v[100:101], v[44:45] op_sel:[1,0]
	v_pk_fma_f32 v[46:47], v[146:147], v[46:47], v[150:151]
	v_pk_fma_f32 v[44:45], v[144:145], v[44:45], v[148:149]
	v_pk_fma_f32 v[42:43], v[46:47], s[14:15], v[42:43] op_sel_hi:[1,0,1]
	v_pk_fma_f32 v[40:41], v[44:45], s[14:15], v[40:41] op_sel_hi:[1,0,1]
	global_store_dwordx4 v[52:53], v[40:43], off offset:64
	v_lshl_add_u64 v[44:45], v[174:175], 0, v[64:65]
	v_lshl_add_u64 v[64:65], s[12:13], 0, v[64:65]
	v_sub_f32_e32 v41, v89, v100
	v_sub_f32_e32 v40, v88, v100
	v_sub_f32_e32 v43, v91, v100
	v_sub_f32_e32 v42, v90, v100
	v_pk_mul_f32 v[42:43], v[100:101], v[42:43] op_sel:[1,0]
	v_pk_mul_f32 v[40:41], v[100:101], v[40:41] op_sel:[1,0]
	v_pk_fma_f32 v[42:43], v[142:143], v[42:43], v[138:139]
	v_pk_fma_f32 v[40:41], v[140:141], v[40:41], v[136:137]
	v_pk_fma_f32 v[38:39], v[42:43], s[14:15], v[38:39] op_sel_hi:[1,0,1]
	v_pk_fma_f32 v[36:37], v[40:41], s[14:15], v[36:37] op_sel_hi:[1,0,1]
	global_store_dwordx4 v[52:53], v[36:39], off offset:512
	v_lshl_add_u64 v[64:65], v[64:65], 0, v[172:173]
	s_waitcnt vmcnt(0)
	v_sub_f32_e32 v37, v93, v100
	v_sub_f32_e32 v36, v92, v100
	v_sub_f32_e32 v39, v95, v100
	v_sub_f32_e32 v38, v94, v100
	v_pk_mul_f32 v[38:39], v[100:101], v[38:39] op_sel:[1,0]
	v_pk_mul_f32 v[36:37], v[100:101], v[36:37] op_sel:[1,0]
	v_pk_fma_f32 v[38:39], v[130:131], v[38:39], v[134:135]
	v_pk_fma_f32 v[36:37], v[128:129], v[36:37], v[132:133]
	v_pk_fma_f32 v[34:35], v[38:39], s[14:15], v[34:35] op_sel_hi:[1,0,1]
	v_pk_fma_f32 v[32:33], v[36:37], s[14:15], v[32:33] op_sel_hi:[1,0,1]
	global_store_dwordx4 v[52:53], v[32:35], off offset:576
	global_load_dwordx2 v[66:67], v[178:179], off offset:1280
	s_nop 0
	global_load_dwordx4 v[32:35], v[44:45], off
	global_load_dwordx4 v[36:39], v[44:45], off offset:64
	global_load_dwordx4 v[40:43], v[44:45], off offset:512
	s_nop 0
	global_load_dwordx4 v[44:47], v[44:45], off offset:576
	s_nop 0
	global_load_dwordx2 v[70:71], v[178:179], off offset:1408
	global_load_dwordx4 v[48:51], v[60:61], off
	global_load_dwordx4 v[52:55], v[60:61], off offset:64
	global_load_dwordx4 v[56:59], v[60:61], off offset:512
	s_nop 0
	global_load_dwordx4 v[60:63], v[60:61], off offset:576
	s_waitcnt vmcnt(0)
;     __device__ __forceinline__ void operator()(const f32x4 (&acc)[2][2][4][2], const Unit& u, int wr, int wc, int fr, int fq) const {
;     ...
; #pragma unroll
;                 for (int mm = 0; mm < 2; ++mm) {
;                     const int m = mh * 2 + mm, r = row0 + ai * HALF + m * 16;
;                     float* zp = Z + (size_t)r * DM + col0;
; #pragma unroll
;                     for (int bj = 0; bj < 2; ++bj)
; #pragma unroll
;                         for (int n = 0; n < 2; ++n) {
;                             f32x4 res = rv[mm][bj][n];
;                             if (MODE == 1) res = (res - st[mm].x) * st[mm].y * gv[bj][n] + bv[bj][n];
;                             *(f32x4*)(zp + bj * HALF + n * 16) = res * ALPHA + acc[ai][bj][m][n] * scale;
;                         }
	v_sub_f32_e32 v33, v33, v66
	v_sub_f32_e32 v32, v32, v66
	v_sub_f32_e32 v35, v35, v66
	v_sub_f32_e32 v34, v34, v66
	v_pk_mul_f32 v[34:35], v[66:67], v[34:35] op_sel:[1,0]
	v_pk_mul_f32 v[32:33], v[66:67], v[32:33] op_sel:[1,0]
	v_pk_fma_f32 v[34:35], v[158:159], v[34:35], v[154:155]
	v_pk_fma_f32 v[32:33], v[156:157], v[32:33], v[152:153]
	v_pk_fma_f32 v[30:31], v[34:35], s[14:15], v[30:31] op_sel_hi:[1,0,1]
	v_pk_fma_f32 v[28:29], v[32:33], s[14:15], v[28:29] op_sel_hi:[1,0,1]
	global_store_dwordx4 v[64:65], v[28:31], off
	s_nop 1
	v_sub_f32_e32 v29, v37, v66
	v_sub_f32_e32 v28, v36, v66
	v_sub_f32_e32 v31, v39, v66
	v_sub_f32_e32 v30, v38, v66
	v_pk_mul_f32 v[30:31], v[66:67], v[30:31] op_sel:[1,0]
	v_pk_mul_f32 v[28:29], v[66:67], v[28:29] op_sel:[1,0]
	v_pk_fma_f32 v[30:31], v[146:147], v[30:31], v[150:151]
	v_pk_fma_f32 v[28:29], v[144:145], v[28:29], v[148:149]
	v_pk_fma_f32 v[26:27], v[30:31], s[14:15], v[26:27] op_sel_hi:[1,0,1]
	v_pk_fma_f32 v[24:25], v[28:29], s[14:15], v[24:25] op_sel_hi:[1,0,1]
	global_store_dwordx4 v[64:65], v[24:27], off offset:64
	s_nop 1
	v_sub_f32_e32 v25, v41, v66
	v_sub_f32_e32 v24, v40, v66
	v_sub_f32_e32 v27, v43, v66
	v_sub_f32_e32 v26, v42, v66
	v_pk_mul_f32 v[26:27], v[66:67], v[26:27] op_sel:[1,0]
	v_pk_mul_f32 v[24:25], v[66:67], v[24:25] op_sel:[1,0]
	v_pk_fma_f32 v[26:27], v[142:143], v[26:27], v[138:139]
	v_pk_fma_f32 v[24:25], v[140:141], v[24:25], v[136:137]
	v_pk_fma_f32 v[22:23], v[26:27], s[14:15], v[22:23] op_sel_hi:[1,0,1]
	v_pk_fma_f32 v[20:21], v[24:25], s[14:15], v[20:21] op_sel_hi:[1,0,1]
	global_store_dwordx4 v[64:65], v[20:23], off offset:512
	s_nop 1
	v_sub_f32_e32 v21, v45, v66
	v_sub_f32_e32 v20, v44, v66
	v_sub_f32_e32 v23, v47, v66
	v_sub_f32_e32 v22, v46, v66
	v_pk_mul_f32 v[22:23], v[66:67], v[22:23] op_sel:[1,0]
	v_pk_mul_f32 v[20:21], v[66:67], v[20:21] op_sel:[1,0]
	v_pk_fma_f32 v[22:23], v[130:131], v[22:23], v[134:135]
	v_pk_fma_f32 v[20:21], v[128:129], v[20:21], v[132:133]
	v_pk_fma_f32 v[14:15], v[22:23], s[14:15], v[14:15] op_sel_hi:[1,0,1]
	v_pk_fma_f32 v[12:13], v[20:21], s[14:15], v[12:13] op_sel_hi:[1,0,1]
	global_store_dwordx4 v[64:65], v[12:15], off offset:576
	s_nop 1
	v_lshl_add_u64 v[12:13], s[12:13], 0, v[68:69]
	v_lshl_add_u64 v[20:21], v[12:13], 0, v[172:173]
	v_sub_f32_e32 v13, v49, v70
	v_sub_f32_e32 v12, v48, v70
	v_sub_f32_e32 v15, v51, v70
	v_sub_f32_e32 v14, v50, v70
	v_pk_mul_f32 v[14:15], v[70:71], v[14:15] op_sel:[1,0]
	v_pk_mul_f32 v[12:13], v[70:71], v[12:13] op_sel:[1,0]
	v_pk_fma_f32 v[14:15], v[158:159], v[14:15], v[154:155]
	v_pk_fma_f32 v[12:13], v[156:157], v[12:13], v[152:153]
	v_pk_fma_f32 v[14:15], v[14:15], s[14:15], v[18:19] op_sel_hi:[1,0,1]
	v_pk_fma_f32 v[12:13], v[12:13], s[14:15], v[16:17] op_sel_hi:[1,0,1]
	global_store_dwordx4 v[20:21], v[12:15], off
	s_nop 1
	v_sub_f32_e32 v13, v53, v70
	v_sub_f32_e32 v12, v52, v70
	v_sub_f32_e32 v15, v55, v70
	v_sub_f32_e32 v14, v54, v70
	v_pk_mul_f32 v[14:15], v[70:71], v[14:15] op_sel:[1,0]
	v_pk_mul_f32 v[12:13], v[70:71], v[12:13] op_sel:[1,0]
	v_pk_fma_f32 v[14:15], v[146:147], v[14:15], v[150:151]
	v_pk_fma_f32 v[12:13], v[144:145], v[12:13], v[148:149]
	v_pk_fma_f32 v[10:11], v[14:15], s[14:15], v[10:11] op_sel_hi:[1,0,1]
	v_pk_fma_f32 v[8:9], v[12:13], s[14:15], v[8:9] op_sel_hi:[1,0,1]
	global_store_dwordx4 v[20:21], v[8:11], off offset:64
	s_nop 1
	v_sub_f32_e32 v9, v57, v70
	v_sub_f32_e32 v8, v56, v70
	v_sub_f32_e32 v11, v59, v70
	v_sub_f32_e32 v10, v58, v70
	v_pk_mul_f32 v[10:11], v[70:71], v[10:11] op_sel:[1,0]
	v_pk_mul_f32 v[8:9], v[70:71], v[8:9] op_sel:[1,0]
	v_pk_fma_f32 v[10:11], v[142:143], v[10:11], v[138:139]
	v_pk_fma_f32 v[8:9], v[140:141], v[8:9], v[136:137]
	v_pk_fma_f32 v[6:7], v[10:11], s[14:15], v[6:7] op_sel_hi:[1,0,1]
	v_pk_fma_f32 v[4:5], v[8:9], s[14:15], v[4:5] op_sel_hi:[1,0,1]
	global_store_dwordx4 v[20:21], v[4:7], off offset:512
	s_nop 1
	v_sub_f32_e32 v5, v61, v70
	v_sub_f32_e32 v4, v60, v70
	v_sub_f32_e32 v7, v63, v70
	v_sub_f32_e32 v6, v62, v70
	v_pk_mul_f32 v[6:7], v[70:71], v[6:7] op_sel:[1,0]
	v_pk_mul_f32 v[4:5], v[70:71], v[4:5] op_sel:[1,0]
	v_pk_fma_f32 v[6:7], v[130:131], v[6:7], v[134:135]
	v_pk_fma_f32 v[4:5], v[128:129], v[4:5], v[132:133]
	v_pk_fma_f32 v[2:3], v[6:7], s[14:15], v[2:3] op_sel_hi:[1,0,1]
	v_pk_fma_f32 v[0:1], v[4:5], s[14:15], v[0:1] op_sel_hi:[1,0,1]
	global_store_dwordx4 v[20:21], v[0:3], off offset:576
	s_cbranch_vccz .LBB0_1422
	s_waitcnt vmcnt(0)
	s_cmpk_gt_u32 s25, 0xff
	s_cbranch_scc1 .LBB0_1433
	s_barrier

; #define PG8_STAGE(bufoff, gbase, voff) do { _Pragma("unroll") for (int _i = 0; _i < 2; ++_i) \
;         __builtin_amdgcn_global_load_lds((const unsigned*)((const char*)(gbase) + (voff)[_i]), (LAS unsigned*)(lds + (bufoff) + ldsw + _i * 8192), 16, 0, 0); } while (0)
; #define PG8_LDA(dst, b, h) do { _Pragma("unroll") for (int m = 0; m < 4; ++m) _Pragma("unroll") for (int k = 0; k < 2; ++k) dst[m][k] = *(const LAS bf16x8*)(lds + PG8_SA(b, h) + aoff + m * 2048 + k * 1024); } while (0)
; #define PG8_LDB(dst, b, h) do { _Pragma("unroll") for (int n = 0; n < 2; ++n) _Pragma("unroll") for (int k = 0; k < 2; ++k) dst[n][k] = *(const LAS bf16x8*)(lds + PG8_SB(b, h) + boff + n * 2048 + k * 1024); } while (0)
; #define PG8_MMA(ai, bj, At, Bt) do { __builtin_amdgcn_s_setprio(1); _Pragma("unroll") for (int m = 0; m < 4; ++m) _Pragma("unroll") for (int n = 0; n < 2; ++n) _Pragma("unroll") for (int k = 0; k < 2; ++k) \
;         acc[ai][bj][m][n] = __builtin_amdgcn_mfma_f32_16x16x32_bf16(Bt[n][k], At[m][k], acc[ai][bj][m][n], 0, 0, 0); __builtin_amdgcn_s_setprio(0); } while (0)
; #define PG8_WAIT_L(n) asm volatile("s_waitcnt lgkmcnt(" #n ")" ::: "memory")
; #define PG8_BAR __builtin_amdgcn_s_barrier()
; #define PG8_SCHED __builtin_amdgcn_sched_barrier(0)
; template <class Epi, class Sched>
; __device__ __forceinline__ void gemm_phase(LAS unsigned char* lds, const Gemm g, const Sched& S, const Epi& E) {
;     ...
;         for (int t = 0; t < nt; t += 2) {
;             const bool last = (t == nt - 2);
;             const char* a1 = cA + (size_t)(t + 1) * kstep;
;             const char* a2 = last ? nA : cA + (size_t)(t + 2) * kstep; const char* b2 = last ? nB : cB + (size_t)(t + 2) * kstep;
;             const char* a3 = a2 + kstep; const char* b3 = b2 + kstep;
;             PG8_LDB(B0, 0, 0); PG8_SCHED; PG8_LDA(At, 0, 0); PG8_STAGE(PG8_SA(1, 1), a1 + hstep, voffA);
;             PG8_WAIT_L(8); PG8_BAR; PG8_WAIT_L(0); PG8_MMA(0, 0, At, B0); PG8_BAR; PG8_SCHED;
;             PG8_LDB(B1, 0, 1); PG8_STAGE(PG8_SB(0, 0), b2, voffB);
;             PG8_BAR; PG8_WAIT_L(0); PG8_MMA(0, 1, At, B1); PG8_BAR;
;             PG8_LDA(At, 0, 1); PG8_STAGE(PG8_SA(0, 0), a2, voffA);
;             PG8_BAR; PG8_WAIT_L(0); PG8_MMA(1, 0, At, B0); PG8_BAR; PG8_SCHED;
.LBB0_1562:
	ds_read_b128 v[154:157], v150
	ds_read_b128 v[158:161], v150 offset:1024
	ds_read_b128 v[162:165], v150 offset:2048
	ds_read_b128 v[166:169], v150 offset:3072
	s_add_u32 s28, s26, 0x4000
	s_addc_u32 s29, s27, 0
	s_cmp_eq_u32 s57, 28
	s_cselect_b32 s34, s33, s28
	s_cselect_b32 s35, s15, s29
	s_cselect_b32 s28, s54, s55
	s_cselect_b32 s29, s13, s56
	s_add_u32 s30, s34, 0x8000
	s_addc_u32 s31, s35, 0
	v_lshl_add_u64 v[202:203], s[26:27], 0, v[138:139]
	s_add_i32 m0, s43, 0xc000
	ds_read_b128 v[170:173], v151
	ds_read_b128 v[174:177], v151 offset:1024
	ds_read_b128 v[178:181], v151 offset:2048
	ds_read_b128 v[182:185], v151 offset:3072
	ds_read_b128 v[186:189], v151 offset:4096
	ds_read_b128 v[190:193], v151 offset:5120
	ds_read_b128 v[194:197], v151 offset:6144
	ds_read_b128 v[198:201], v151 offset:7168
	global_load_lds_dwordx4 v[202:203], off
	v_lshl_add_u64 v[202:203], s[26:27], 0, v[140:141]
	s_add_i32 m0, s43, 0xe000
	s_nop 0
	global_load_lds_dwordx4 v[202:203], off
	s_waitcnt lgkmcnt(8)
	s_barrier
	s_waitcnt lgkmcnt(0)
	s_waitcnt lgkmcnt(0)
	v_mfma_f32_16x16x32_bf16 v[124:127], v[154:157], v[170:173], v[124:127]
	v_mfma_f32_16x16x32_bf16 v[120:123], v[162:165], v[170:173], v[120:123]
	v_mfma_f32_16x16x32_bf16 v[108:111], v[154:157], v[178:181], v[108:111]
	v_mfma_f32_16x16x32_bf16 v[104:107], v[162:165], v[178:181], v[104:107]
	v_mfma_f32_16x16x32_bf16 v[92:95], v[154:157], v[186:189], v[92:95]
	v_mfma_f32_16x16x32_bf16 v[88:91], v[162:165], v[186:189], v[88:91]
	v_mfma_f32_16x16x32_bf16 v[76:79], v[154:157], v[194:197], v[76:79]
	v_mfma_f32_16x16x32_bf16 v[72:75], v[162:165], v[194:197], v[72:75]
	v_mfma_f32_16x16x32_bf16 v[124:127], v[158:161], v[174:177], v[124:127]
	v_mfma_f32_16x16x32_bf16 v[120:123], v[166:169], v[174:177], v[120:123]
	v_mfma_f32_16x16x32_bf16 v[108:111], v[158:161], v[182:185], v[108:111]
	v_mfma_f32_16x16x32_bf16 v[104:107], v[166:169], v[182:185], v[104:107]
	v_mfma_f32_16x16x32_bf16 v[92:95], v[158:161], v[190:193], v[92:95]
	v_mfma_f32_16x16x32_bf16 v[88:91], v[166:169], v[190:193], v[88:91]
	v_mfma_f32_16x16x32_bf16 v[76:79], v[158:161], v[198:201], v[76:79]
	v_mfma_f32_16x16x32_bf16 v[72:75], v[166:169], v[198:201], v[72:75]
	s_barrier
	s_add_i32 s58, s71, s41
	v_lshl_add_u64 v[202:203], s[28:29], 0, v[132:133]
	s_mov_b32 m0, s58
	ds_read_b128 v[206:209], v152
	ds_read_b128 v[210:213], v152 offset:1024
	ds_read_b128 v[214:217], v152 offset:2048
	ds_read_b128 v[218:221], v152 offset:3072
	global_load_lds_dwordx4 v[202:203], off
	v_lshl_add_u64 v[202:203], s[28:29], 0, v[128:129]
	s_add_i32 m0, s58, 0x2000
	s_nop 0
	global_load_lds_dwordx4 v[202:203], off
	s_barrier
	s_waitcnt lgkmcnt(0)
	s_waitcnt lgkmcnt(0)
	v_mfma_f32_16x16x32_bf16 v[116:119], v[206:209], v[170:173], v[116:119]
	v_mfma_f32_16x16x32_bf16 v[112:115], v[214:217], v[170:173], v[112:115]
	v_mfma_f32_16x16x32_bf16 v[100:103], v[206:209], v[178:181], v[100:103]
	v_mfma_f32_16x16x32_bf16 v[96:99], v[214:217], v[178:181], v[96:99]
	v_mfma_f32_16x16x32_bf16 v[84:87], v[206:209], v[186:189], v[84:87]
	v_mfma_f32_16x16x32_bf16 v[80:83], v[214:217], v[186:189], v[80:83]
	v_mfma_f32_16x16x32_bf16 v[68:71], v[206:209], v[194:197], v[68:71]
	v_mfma_f32_16x16x32_bf16 v[64:67], v[214:217], v[194:197], v[64:67]
	v_mfma_f32_16x16x32_bf16 v[116:119], v[210:213], v[174:177], v[116:119]
	v_mfma_f32_16x16x32_bf16 v[112:115], v[218:221], v[174:177], v[112:115]
	v_mfma_f32_16x16x32_bf16 v[100:103], v[210:213], v[182:185], v[100:103]
	v_mfma_f32_16x16x32_bf16 v[96:99], v[218:221], v[182:185], v[96:99]
	v_mfma_f32_16x16x32_bf16 v[84:87], v[210:213], v[190:193], v[84:87]
	v_mfma_f32_16x16x32_bf16 v[80:83], v[218:221], v[190:193], v[80:83]
	v_mfma_f32_16x16x32_bf16 v[68:71], v[210:213], v[198:201], v[68:71]
	v_mfma_f32_16x16x32_bf16 v[64:67], v[218:221], v[198:201], v[64:67]
	s_mov_b32 m0, s43
	v_lshl_add_u64 v[202:203], s[34:35], 0, v[134:135]
	s_barrier
	ds_read_b128 v[170:173], v151 offset:16384
	ds_read_b128 v[174:177], v151 offset:17408
	ds_read_b128 v[178:181], v151 offset:18432
	ds_read_b128 v[182:185], v151 offset:19456
	ds_read_b128 v[186:189], v151 offset:20480
	ds_read_b128 v[190:193], v151 offset:21504
	ds_read_b128 v[194:197], v151 offset:22528
	ds_read_b128 v[198:201], v151 offset:23552
	global_load_lds_dwordx4 v[202:203], off
	v_lshl_add_u64 v[202:203], s[34:35], 0, v[130:131]
	s_mov_b32 m0, s44
	s_nop 0
	global_load_lds_dwordx4 v[202:203], off
	s_barrier
	s_waitcnt lgkmcnt(0)
	s_waitcnt lgkmcnt(0)
	v_mfma_f32_16x16x32_bf16 v[60:63], v[154:157], v[170:173], v[60:63]
	v_mfma_f32_16x16x32_bf16 v[56:59], v[162:165], v[170:173], v[56:59]
	v_mfma_f32_16x16x32_bf16 v[44:47], v[154:157], v[178:181], v[44:47]
	v_mfma_f32_16x16x32_bf16 v[40:43], v[162:165], v[178:181], v[40:43]
	v_mfma_f32_16x16x32_bf16 v[28:31], v[154:157], v[186:189], v[28:31]
	v_mfma_f32_16x16x32_bf16 v[24:27], v[162:165], v[186:189], v[24:27]
	v_mfma_f32_16x16x32_bf16 v[12:15], v[154:157], v[194:197], v[12:15]
	v_mfma_f32_16x16x32_bf16 v[8:11], v[162:165], v[194:197], v[8:11]
	v_mfma_f32_16x16x32_bf16 v[60:63], v[158:161], v[174:177], v[60:63]
	v_mfma_f32_16x16x32_bf16 v[56:59], v[166:169], v[174:177], v[56:59]
	v_mfma_f32_16x16x32_bf16 v[44:47], v[158:161], v[182:185], v[44:47]
	v_mfma_f32_16x16x32_bf16 v[40:43], v[166:169], v[182:185], v[40:43]
	v_mfma_f32_16x16x32_bf16 v[28:31], v[158:161], v[190:193], v[28:31]
	v_mfma_f32_16x16x32_bf16 v[24:27], v[166:169], v[190:193], v[24:27]
	v_mfma_f32_16x16x32_bf16 v[12:15], v[158:161], v[198:201], v[12:15]
	v_mfma_f32_16x16x32_bf16 v[8:11], v[166:169], v[198:201], v[8:11]
	s_barrier
; #define PG8_STAGE(bufoff, gbase, voff) do { _Pragma("unroll") for (int _i = 0; _i < 2; ++_i) \
;         __builtin_amdgcn_global_load_lds((const unsigned*)((const char*)(gbase) + (voff)[_i]), (LAS unsigned*)(lds + (bufoff) + ldsw + _i * 8192), 16, 0, 0); } while (0)
; #define PG8_LDA(dst, b, h) do { _Pragma("unroll") for (int m = 0; m < 4; ++m) _Pragma("unroll") for (int k = 0; k < 2; ++k) dst[m][k] = *(const LAS bf16x8*)(lds + PG8_SA(b, h) + aoff + m * 2048 + k * 1024); } while (0)
; #define PG8_LDB(dst, b, h) do { _Pragma("unroll") for (int n = 0; n < 2; ++n) _Pragma("unroll") for (int k = 0; k < 2; ++k) dst[n][k] = *(const LAS bf16x8*)(lds + PG8_SB(b, h) + boff + n * 2048 + k * 1024); } while (0)
; #define PG8_MMA(ai, bj, At, Bt) do { __builtin_amdgcn_s_setprio(1); _Pragma("unroll") for (int m = 0; m < 4; ++m) _Pragma("unroll") for (int n = 0; n < 2; ++n) _Pragma("unroll") for (int k = 0; k < 2; ++k) \
;         acc[ai][bj][m][n] = __builtin_amdgcn_mfma_f32_16x16x32_bf16(Bt[n][k], At[m][k], acc[ai][bj][m][n], 0, 0, 0); __builtin_amdgcn_s_setprio(0); } while (0)
; #define PG8_WAIT_V(n) asm volatile("s_waitcnt vmcnt(" #n ")" ::: "memory")
; #define PG8_WAIT_L(n) asm volatile("s_waitcnt lgkmcnt(" #n ")" ::: "memory")
; #define PG8_BAR __builtin_amdgcn_s_barrier()
; #define PG8_SCHED __builtin_amdgcn_sched_barrier(0)
; template <class Epi, class Sched>
; __device__ __forceinline__ void gemm_phase(LAS unsigned char* lds, const Gemm g, const Sched& S, const Epi& E) {
;     ...
;             PG8_STAGE(PG8_SB(0, 1), b2 + hstep, voffB);
;             PG8_WAIT_V(6); PG8_BAR; PG8_MMA(1, 1, At, B1); PG8_BAR;
;             PG8_LDB(B0, 1, 0); PG8_SCHED; PG8_LDA(At, 1, 0); PG8_STAGE(PG8_SA(0, 1), a2 + hstep, voffA);
;             PG8_WAIT_L(8); PG8_BAR; PG8_WAIT_L(0); PG8_MMA(0, 0, At, B0); PG8_BAR; PG8_SCHED;
;             PG8_LDB(B1, 1, 1); PG8_STAGE(PG8_SB(1, 0), b3, voffB);
;             PG8_BAR; PG8_WAIT_L(0); PG8_MMA(0, 1, At, B1); PG8_BAR;
;             PG8_LDA(At, 1, 1); PG8_STAGE(PG8_SA(1, 0), a3, voffA);
	s_add_u32 s58, s28, 0x4000
	s_addc_u32 s59, s29, 0
	s_add_i32 s60, s52, s41
	v_lshl_add_u64 v[154:155], s[58:59], 0, v[132:133]
	s_mov_b32 m0, s60
	s_nop 0
	global_load_lds_dwordx4 v[154:155], off
	v_lshl_add_u64 v[154:155], s[58:59], 0, v[128:129]
	s_add_i32 m0, s60, 0x2000
	s_nop 0
	global_load_lds_dwordx4 v[154:155], off
	s_waitcnt vmcnt(6)
	s_barrier
	v_mfma_f32_16x16x32_bf16 v[52:55], v[206:209], v[170:173], v[52:55]
	v_mfma_f32_16x16x32_bf16 v[48:51], v[214:217], v[170:173], v[48:51]
	v_mfma_f32_16x16x32_bf16 v[36:39], v[206:209], v[178:181], v[36:39]
	v_mfma_f32_16x16x32_bf16 v[32:35], v[214:217], v[178:181], v[32:35]
	v_mfma_f32_16x16x32_bf16 v[20:23], v[206:209], v[186:189], v[20:23]
	v_mfma_f32_16x16x32_bf16 v[16:19], v[214:217], v[186:189], v[16:19]
	v_mfma_f32_16x16x32_bf16 v[4:7], v[206:209], v[194:197], v[4:7]
	v_mfma_f32_16x16x32_bf16 v[0:3], v[214:217], v[194:197], v[0:3]
	v_mfma_f32_16x16x32_bf16 v[52:55], v[210:213], v[174:177], v[52:55]
	v_mfma_f32_16x16x32_bf16 v[48:51], v[218:221], v[174:177], v[48:51]
	v_mfma_f32_16x16x32_bf16 v[36:39], v[210:213], v[182:185], v[36:39]
	v_mfma_f32_16x16x32_bf16 v[32:35], v[218:221], v[182:185], v[32:35]
	v_mfma_f32_16x16x32_bf16 v[20:23], v[210:213], v[190:193], v[20:23]
	v_mfma_f32_16x16x32_bf16 v[16:19], v[218:221], v[190:193], v[16:19]
	v_mfma_f32_16x16x32_bf16 v[4:7], v[210:213], v[198:201], v[4:7]
	v_mfma_f32_16x16x32_bf16 v[0:3], v[218:221], v[198:201], v[0:3]
	s_add_i32 s58, 0, 0x18000
	v_add_u32_e32 v136, s58, v149
	s_barrier
	ds_read_b128 v[154:157], v136
	ds_read_b128 v[158:161], v136 offset:1024
	ds_read_b128 v[162:165], v136 offset:2048
	ds_read_b128 v[166:169], v136 offset:3072
	s_add_u32 s34, s34, 0x4000
	s_addc_u32 s35, s35, 0
	s_mov_b32 m0, s45
	v_lshl_add_u64 v[202:203], s[34:35], 0, v[134:135]
	ds_read_b128 v[170:173], v151 offset:32768
	ds_read_b128 v[174:177], v151 offset:33792
	ds_read_b128 v[178:181], v151 offset:34816
	ds_read_b128 v[182:185], v151 offset:35840
	ds_read_b128 v[186:189], v151 offset:36864
	ds_read_b128 v[190:193], v151 offset:37888
	ds_read_b128 v[194:197], v151 offset:38912
	ds_read_b128 v[198:201], v151 offset:39936
	global_load_lds_dwordx4 v[202:203], off
	v_lshl_add_u64 v[202:203], s[34:35], 0, v[130:131]
	s_mov_b32 m0, s46
	s_nop 0
	global_load_lds_dwordx4 v[202:203], off
	s_waitcnt lgkmcnt(8)
	s_barrier
	s_waitcnt lgkmcnt(0)
	s_waitcnt lgkmcnt(0)
	v_mfma_f32_16x16x32_bf16 v[124:127], v[154:157], v[170:173], v[124:127]
	v_mfma_f32_16x16x32_bf16 v[120:123], v[162:165], v[170:173], v[120:123]
	v_mfma_f32_16x16x32_bf16 v[108:111], v[154:157], v[178:181], v[108:111]
	v_mfma_f32_16x16x32_bf16 v[104:107], v[162:165], v[178:181], v[104:107]
	v_mfma_f32_16x16x32_bf16 v[92:95], v[154:157], v[186:189], v[92:95]
	v_mfma_f32_16x16x32_bf16 v[88:91], v[162:165], v[186:189], v[88:91]
	v_mfma_f32_16x16x32_bf16 v[76:79], v[154:157], v[194:197], v[76:79]
	v_mfma_f32_16x16x32_bf16 v[72:75], v[162:165], v[194:197], v[72:75]
	v_mfma_f32_16x16x32_bf16 v[124:127], v[158:161], v[174:177], v[124:127]
	v_mfma_f32_16x16x32_bf16 v[120:123], v[166:169], v[174:177], v[120:123]
	v_mfma_f32_16x16x32_bf16 v[108:111], v[158:161], v[182:185], v[108:111]
	v_mfma_f32_16x16x32_bf16 v[104:107], v[166:169], v[182:185], v[104:107]
	v_mfma_f32_16x16x32_bf16 v[92:95], v[158:161], v[190:193], v[92:95]
	v_mfma_f32_16x16x32_bf16 v[88:91], v[166:169], v[190:193], v[88:91]
	v_mfma_f32_16x16x32_bf16 v[76:79], v[158:161], v[198:201], v[76:79]
	v_mfma_f32_16x16x32_bf16 v[72:75], v[166:169], v[198:201], v[72:75]
	s_barrier
	s_add_i32 s59, 0, 0x1c000
	s_add_u32 s34, s28, 0x8000
	s_addc_u32 s35, s29, 0
	s_add_i32 s58, s58, s41
	v_add_u32_e32 v136, s59, v149
	v_lshl_add_u64 v[202:203], s[34:35], 0, v[132:133]
	s_mov_b32 m0, s58
	ds_read_b128 v[206:209], v136
	ds_read_b128 v[210:213], v136 offset:1024
	ds_read_b128 v[214:217], v136 offset:2048
	ds_read_b128 v[218:221], v136 offset:3072
	global_load_lds_dwordx4 v[202:203], off
	v_lshl_add_u64 v[202:203], s[34:35], 0, v[128:129]
	s_add_i32 m0, s58, 0x2000
	s_nop 0
	global_load_lds_dwordx4 v[202:203], off
	s_barrier
	s_waitcnt lgkmcnt(0)
	s_waitcnt lgkmcnt(0)
	v_mfma_f32_16x16x32_bf16 v[116:119], v[206:209], v[170:173], v[116:119]
	v_mfma_f32_16x16x32_bf16 v[112:115], v[214:217], v[170:173], v[112:115]
	v_mfma_f32_16x16x32_bf16 v[100:103], v[206:209], v[178:181], v[100:103]
	v_mfma_f32_16x16x32_bf16 v[96:99], v[214:217], v[178:181], v[96:99]
	v_mfma_f32_16x16x32_bf16 v[84:87], v[206:209], v[186:189], v[84:87]
	v_mfma_f32_16x16x32_bf16 v[80:83], v[214:217], v[186:189], v[80:83]
	v_mfma_f32_16x16x32_bf16 v[68:71], v[206:209], v[194:197], v[68:71]
	v_mfma_f32_16x16x32_bf16 v[64:67], v[214:217], v[194:197], v[64:67]
	v_mfma_f32_16x16x32_bf16 v[116:119], v[210:213], v[174:177], v[116:119]
	v_mfma_f32_16x16x32_bf16 v[112:115], v[218:221], v[174:177], v[112:115]
	v_mfma_f32_16x16x32_bf16 v[100:103], v[210:213], v[182:185], v[100:103]
	v_mfma_f32_16x16x32_bf16 v[96:99], v[218:221], v[182:185], v[96:99]
	v_mfma_f32_16x16x32_bf16 v[84:87], v[210:213], v[190:193], v[84:87]
	v_mfma_f32_16x16x32_bf16 v[80:83], v[218:221], v[190:193], v[80:83]
	v_mfma_f32_16x16x32_bf16 v[68:71], v[210:213], v[198:201], v[68:71]
	v_mfma_f32_16x16x32_bf16 v[64:67], v[218:221], v[198:201], v[64:67]
	s_mov_b32 m0, s50
	v_lshl_add_u64 v[202:203], s[30:31], 0, v[134:135]
	s_barrier
	ds_read_b128 v[170:173], v151 offset:49152
	ds_read_b128 v[174:177], v151 offset:50176
	ds_read_b128 v[178:181], v151 offset:51200
	ds_read_b128 v[182:185], v151 offset:52224
	ds_read_b128 v[186:189], v151 offset:53248
	ds_read_b128 v[190:193], v151 offset:54272
	ds_read_b128 v[194:197], v151 offset:55296
	ds_read_b128 v[198:201], v151 offset:56320
	global_load_lds_dwordx4 v[202:203], off
	v_lshl_add_u64 v[202:203], s[30:31], 0, v[130:131]
	s_mov_b32 m0, s51
	s_nop 0
	global_load_lds_dwordx4 v[202:203], off
	s_barrier
; __device__ __forceinline__ unsigned cvt_pk_bf16(float lo, float hi) { f32x2 v = {lo, hi}; bf16x2_t b = __builtin_convertvector(v, bf16x2_t); return __builtin_bit_cast(unsigned, b); }
; __device__ __forceinline__ float sigmoid_f(float x) { return __builtin_amdgcn_rcpf(1.0f + __expf(-x)); }
; __device__ __forceinline__ float silu_f(float x) { return x * sigmoid_f(x); }
; __device__ __forceinline__ size_t tl(int r, int c, int K) { return ((size_t)(r >> 8) * (size_t)(K >> 6) + (size_t)(c >> 6)) * 16384 + (size_t)((r & 255) << 6) + (size_t)(c & 63); }
; #define PG8_STAGE(bufoff, gbase, voff) do { _Pragma("unroll") for (int _i = 0; _i < 2; ++_i) \
;         __builtin_amdgcn_global_load_lds((const unsigned*)((const char*)(gbase) + (voff)[_i]), (LAS unsigned*)(lds + (bufoff) + ldsw + _i * 8192), 16, 0, 0); } while (0)
; #define PG8_WAIT_V(n) asm volatile("s_waitcnt vmcnt(" #n ")" ::: "memory")
; #define PG8_WAIT_L(n) asm volatile("s_waitcnt lgkmcnt(" #n ")" ::: "memory")
; #define PG8_BAR __builtin_amdgcn_s_barrier()
; template <class Epi, class Sched>
; __device__ __forceinline__ void gemm_phase(LAS unsigned char* lds, const Gemm g, const Sched& S, const Epi& E) {
;     ...
;             PG8_BAR; PG8_WAIT_L(0); PG8_MMA(1, 0, At, B0); PG8_BAR; PG8_SCHED;
;             PG8_STAGE(PG8_SB(1, 1), b3 + hstep, voffB);
;             PG8_WAIT_V(6); PG8_BAR; PG8_MMA(1, 1, At, B1); PG8_BAR;
;     __device__ __forceinline__ void operator()(const f32x4 (&acc)[2][2][4][2], const Unit& u, int wr, int wc, int fr, int fq) const {
;         const int row0 = u.pm * BM + wr * 64 + fr, col0 = u.pn * 128 + wc * 32 + 8 * fq;
; #pragma unroll
;         for (int ai = 0; ai < 2; ++ai)
; #pragma unroll
;             for (int m = 0; m < 4; ++m) {
;                 bf16_t* rowp = MODE == 0 ? O + tl(row0 + ai * HALF + m * 16, col0, ldo) : O + (size_t)(row0 + ai * HALF + m * 16) * ldo + col0;
;                 float v[8];
; #pragma unroll
;                 for (int n = 0; n < 2; ++n)
; #pragma unroll
;                     for (int j = 0; j < 4; ++j) { const float a = acc[ai][0][m][n][j], b = acc[ai][1][m][n][j]; v[n * 4 + j] = MODE == 0 ? silu_f(a) * b : a * sigmoid_f(b); }
;                 u32x4 w; w.x = cvt_pk_bf16(v[0], v[1]); w.y = cvt_pk_bf16(v[2], v[3]); w.z = cvt_pk_bf16(v[4], v[5]); w.w = cvt_pk_bf16(v[6], v[7]);
;                 *(u32x4*)rowp = w;
	s_waitcnt lgkmcnt(0)
	s_waitcnt lgkmcnt(0)
	v_mfma_f32_16x16x32_bf16 v[60:63], v[154:157], v[170:173], v[60:63]
	v_mfma_f32_16x16x32_bf16 v[56:59], v[162:165], v[170:173], v[56:59]
	v_mfma_f32_16x16x32_bf16 v[44:47], v[154:157], v[178:181], v[44:47]
	v_mfma_f32_16x16x32_bf16 v[40:43], v[162:165], v[178:181], v[40:43]
	v_mfma_f32_16x16x32_bf16 v[28:31], v[154:157], v[186:189], v[28:31]
	v_mfma_f32_16x16x32_bf16 v[24:27], v[162:165], v[186:189], v[24:27]
	v_mfma_f32_16x16x32_bf16 v[12:15], v[154:157], v[194:197], v[12:15]
	v_mfma_f32_16x16x32_bf16 v[8:11], v[162:165], v[194:197], v[8:11]
	v_mfma_f32_16x16x32_bf16 v[60:63], v[158:161], v[174:177], v[60:63]
	v_mfma_f32_16x16x32_bf16 v[56:59], v[166:169], v[174:177], v[56:59]
	v_mfma_f32_16x16x32_bf16 v[44:47], v[158:161], v[182:185], v[44:47]
	v_mfma_f32_16x16x32_bf16 v[40:43], v[166:169], v[182:185], v[40:43]
	v_mfma_f32_16x16x32_bf16 v[28:31], v[158:161], v[190:193], v[28:31]
	v_mfma_f32_16x16x32_bf16 v[24:27], v[166:169], v[190:193], v[24:27]
	v_mfma_f32_16x16x32_bf16 v[12:15], v[158:161], v[198:201], v[12:15]
	v_mfma_f32_16x16x32_bf16 v[8:11], v[166:169], v[198:201], v[8:11]
	s_barrier
	s_add_u32 s28, s28, 0xc000
	s_addc_u32 s29, s29, 0
	s_add_i32 s30, s59, s41
	v_lshl_add_u64 v[154:155], s[28:29], 0, v[132:133]
	s_mov_b32 m0, s30
	s_nop 0
	global_load_lds_dwordx4 v[154:155], off
	v_lshl_add_u64 v[154:155], s[28:29], 0, v[128:129]
	s_add_i32 m0, s30, 0x2000
	s_nop 0
	global_load_lds_dwordx4 v[154:155], off
	s_waitcnt vmcnt(6)
	s_barrier
	v_mfma_f32_16x16x32_bf16 v[52:55], v[206:209], v[170:173], v[52:55]
	v_mfma_f32_16x16x32_bf16 v[48:51], v[214:217], v[170:173], v[48:51]
	v_mfma_f32_16x16x32_bf16 v[36:39], v[206:209], v[178:181], v[36:39]
	v_mfma_f32_16x16x32_bf16 v[32:35], v[214:217], v[178:181], v[32:35]
	v_mfma_f32_16x16x32_bf16 v[20:23], v[206:209], v[186:189], v[20:23]
	v_mfma_f32_16x16x32_bf16 v[16:19], v[214:217], v[186:189], v[16:19]
	v_mfma_f32_16x16x32_bf16 v[4:7], v[206:209], v[194:197], v[4:7]
	v_mfma_f32_16x16x32_bf16 v[0:3], v[214:217], v[194:197], v[0:3]
	v_mfma_f32_16x16x32_bf16 v[52:55], v[210:213], v[174:177], v[52:55]
	v_mfma_f32_16x16x32_bf16 v[48:51], v[218:221], v[174:177], v[48:51]
	v_mfma_f32_16x16x32_bf16 v[36:39], v[210:213], v[182:185], v[36:39]
	v_mfma_f32_16x16x32_bf16 v[32:35], v[218:221], v[182:185], v[32:35]
	v_mfma_f32_16x16x32_bf16 v[20:23], v[210:213], v[190:193], v[20:23]
	v_mfma_f32_16x16x32_bf16 v[16:19], v[218:221], v[190:193], v[16:19]
	v_mfma_f32_16x16x32_bf16 v[4:7], v[210:213], v[198:201], v[4:7]
	v_mfma_f32_16x16x32_bf16 v[0:3], v[218:221], v[198:201], v[0:3]
	s_add_i32 s57, s57, 2
	s_add_u32 s26, s26, 0x10000
	s_addc_u32 s27, s27, 0
	s_add_u32 s55, s55, 0x10000
	s_addc_u32 s56, s56, 0
	s_cmp_gt_u32 s57, 29
	s_barrier
	s_cbranch_scc0 .LBB0_1562
	s_lshl_b32 s13, s24, 8
	s_add_i32 s13, s13, s48
	s_lshl_b32 s15, s25, 7
	v_mul_f32_e32 v136, 0xbfb8aa3b, v124
	v_or_b32_e32 v153, s13, v148
	s_or_b32 s15, s15, s49
	s_ashr_i32 s13, s13, 8
	v_exp_f32_e32 v136, v136
	v_mul_f32_e32 v147, 0xbfb8aa3b, v125
	s_ashr_i32 s24, s15, 6
	s_mulk_i32 s13, 0x56
	v_exp_f32_e32 v147, v147
	s_ashr_i32 s25, s24, 31
	s_ashr_i32 s15, s13, 31
	s_add_u32 s26, s13, s24
	s_addc_u32 s27, s15, s25
	v_add_f32_e32 v136, 1.0, v136
	s_lshl_b64 s[26:27], s[26:27], 15
	v_rcp_f32_e32 v154, v136
	v_add_f32_e32 v136, 1.0, v147
	s_add_u32 s26, s10, s26
	v_rcp_f32_e32 v155, v136
	v_lshlrev_b32_e32 v136, 7, v153
	s_addc_u32 s27, s11, s27
	v_and_b32_e32 v136, 0x6780, v136
	v_lshl_add_u64 v[156:157], s[26:27], 0, v[136:137]
	v_mul_f32_e32 v136, 0xbfb8aa3b, v126
	v_mul_f32_e32 v147, 0xbfb8aa3b, v127
	v_exp_f32_e32 v136, v136
	v_exp_f32_e32 v147, v147
	v_pk_mul_f32 v[124:125], v[124:125], v[154:155]
	s_mov_b64 s[28:29], s[18:19]
	v_pk_mul_f32 v[116:117], v[124:125], v[116:117]
	v_add_f32_e32 v124, 1.0, v136
	v_add_f32_e32 v125, 1.0, v147
	v_mul_f32_e32 v136, 0xbfb8aa3b, v120
	v_rcp_f32_e32 v124, v124
	v_rcp_f32_e32 v125, v125
	v_exp_f32_e32 v136, v136
	v_mul_f32_e32 v147, 0xbfb8aa3b, v121
	v_exp_f32_e32 v147, v147
	v_pk_mul_f32 v[124:125], v[126:127], v[124:125]
	v_add_f32_e32 v126, 1.0, v136
	v_mul_f32_e32 v136, 0xbfb8aa3b, v122
	v_add_f32_e32 v127, 1.0, v147
	v_exp_f32_e32 v136, v136
	v_mul_f32_e32 v147, 0xbfb8aa3b, v123
	v_exp_f32_e32 v147, v147
	v_rcp_f32_e32 v126, v126
	v_add_f32_e32 v136, 1.0, v136
	v_rcp_f32_e32 v127, v127
	v_rcp_f32_e32 v154, v136
	v_add_f32_e32 v136, 1.0, v147
	v_rcp_f32_e32 v155, v136
	v_pk_mul_f32 v[120:121], v[120:121], v[126:127]
	v_pk_mul_f32 v[118:119], v[124:125], v[118:119]
	v_pk_mul_f32 v[120:121], v[120:121], v[112:113]
	v_pk_mul_f32 v[112:113], v[122:123], v[154:155]
	v_mov_b32_e32 v147, v137
	v_pk_mul_f32 v[122:123], v[112:113], v[114:115]
	v_mul_f32_e32 v113, 0xbfb8aa3b, v108
	v_exp_f32_e32 v114, v113
	v_mul_f32_e32 v113, 0xbfb8aa3b, v109
	v_exp_f32_e32 v115, v113
	v_cvt_pk_bf16_f32 v112, v116, v117
	v_add_f32_e32 v114, 1.0, v114
	v_rcp_f32_e32 v116, v114
	v_add_f32_e32 v114, 1.0, v115
	v_lshl_add_u64 v[124:125], v[156:157], 0, v[146:147]
	v_cvt_pk_bf16_f32 v113, v118, v119
	v_rcp_f32_e32 v117, v114
	v_cvt_pk_bf16_f32 v114, v120, v121
	v_cvt_pk_bf16_f32 v115, v122, v123
	global_store_dwordx4 v[124:125], v[112:115], off
	v_pk_mul_f32 v[108:109], v[108:109], v[116:117]
	s_mov_b64 s[26:27], s[16:17]
	v_mul_f32_e32 v112, 0xbfb8aa3b, v110
	v_mul_f32_e32 v113, 0xbfb8aa3b, v111
	v_exp_f32_e32 v112, v112
	v_exp_f32_e32 v113, v113
	v_pk_mul_f32 v[100:101], v[108:109], v[100:101]
	v_add_f32_e32 v108, 1.0, v112
	v_add_f32_e32 v109, 1.0, v113
	v_mul_f32_e32 v112, 0xbfb8aa3b, v104
	v_mul_f32_e32 v113, 0xbfb8aa3b, v105
	v_rcp_f32_e32 v108, v108
	v_rcp_f32_e32 v109, v109
; __device__ __forceinline__ unsigned cvt_pk_bf16(float lo, float hi) { f32x2 v = {lo, hi}; bf16x2_t b = __builtin_convertvector(v, bf16x2_t); return __builtin_bit_cast(unsigned, b); }
; __device__ __forceinline__ float sigmoid_f(float x) { return __builtin_amdgcn_rcpf(1.0f + __expf(-x)); }
; __device__ __forceinline__ float silu_f(float x) { return x * sigmoid_f(x); }
; __device__ __forceinline__ size_t tl(int r, int c, int K) { return ((size_t)(r >> 8) * (size_t)(K >> 6) + (size_t)(c >> 6)) * 16384 + (size_t)((r & 255) << 6) + (size_t)(c & 63); }
;     __device__ __forceinline__ void operator()(const f32x4 (&acc)[2][2][4][2], const Unit& u, int wr, int wc, int fr, int fq) const {
;         const int row0 = u.pm * BM + wr * 64 + fr, col0 = u.pn * 128 + wc * 32 + 8 * fq;
; #pragma unroll
;         for (int ai = 0; ai < 2; ++ai)
; #pragma unroll
;             for (int m = 0; m < 4; ++m) {
;                 bf16_t* rowp = MODE == 0 ? O + tl(row0 + ai * HALF + m * 16, col0, ldo) : O + (size_t)(row0 + ai * HALF + m * 16) * ldo + col0;
;                 float v[8];
; #pragma unroll
;                 for (int n = 0; n < 2; ++n)
; #pragma unroll
;                     for (int j = 0; j < 4; ++j) { const float a = acc[ai][0][m][n][j], b = acc[ai][1][m][n][j]; v[n * 4 + j] = MODE == 0 ? silu_f(a) * b : a * sigmoid_f(b); }
;                 u32x4 w; w.x = cvt_pk_bf16(v[0], v[1]); w.y = cvt_pk_bf16(v[2], v[3]); w.z = cvt_pk_bf16(v[4], v[5]); w.w = cvt_pk_bf16(v[6], v[7]);
;                 *(u32x4*)rowp = w;
	v_exp_f32_e32 v112, v112
	v_exp_f32_e32 v113, v113
	v_pk_mul_f32 v[108:109], v[110:111], v[108:109]
	v_add_f32_e32 v110, 1.0, v112
	v_add_f32_e32 v111, 1.0, v113
	v_mul_f32_e32 v112, 0xbfb8aa3b, v106
	v_mul_f32_e32 v113, 0xbfb8aa3b, v107
	v_exp_f32_e32 v112, v112
	v_exp_f32_e32 v113, v113
	v_rcp_f32_e32 v110, v110
	v_rcp_f32_e32 v111, v111
	v_add_f32_e32 v112, 1.0, v112
	v_add_f32_e32 v113, 1.0, v113
	v_rcp_f32_e32 v112, v112
	v_rcp_f32_e32 v113, v113
	v_pk_mul_f32 v[104:105], v[104:105], v[110:111]
	v_pk_mul_f32 v[102:103], v[108:109], v[102:103]
	v_pk_mul_f32 v[104:105], v[104:105], v[96:97]
	v_pk_mul_f32 v[96:97], v[106:107], v[112:113]
	s_nop 0
	v_pk_mul_f32 v[106:107], v[96:97], v[98:99]
	v_mul_f32_e32 v97, 0xbfb8aa3b, v92
	v_exp_f32_e32 v98, v97
	v_mul_f32_e32 v97, 0xbfb8aa3b, v93
	v_exp_f32_e32 v99, v97
	v_cvt_pk_bf16_f32 v96, v100, v101
	v_add_f32_e32 v98, 1.0, v98
	v_rcp_f32_e32 v100, v98
	v_add_f32_e32 v98, 1.0, v99
	v_cvt_pk_bf16_f32 v97, v102, v103
	v_rcp_f32_e32 v101, v98
	v_cvt_pk_bf16_f32 v98, v104, v105
	v_cvt_pk_bf16_f32 v99, v106, v107
	global_store_dwordx4 v[124:125], v[96:99], off offset:2048
	v_pk_mul_f32 v[92:93], v[92:93], v[100:101]
	s_nop 0
	v_mul_f32_e32 v96, 0xbfb8aa3b, v94
	v_mul_f32_e32 v97, 0xbfb8aa3b, v95
	v_exp_f32_e32 v96, v96
	v_exp_f32_e32 v97, v97
	v_pk_mul_f32 v[84:85], v[92:93], v[84:85]
	v_add_f32_e32 v92, 1.0, v96
	v_add_f32_e32 v93, 1.0, v97
	v_mul_f32_e32 v96, 0xbfb8aa3b, v88
	v_mul_f32_e32 v97, 0xbfb8aa3b, v89
	v_rcp_f32_e32 v92, v92
	v_rcp_f32_e32 v93, v93
	v_exp_f32_e32 v96, v96
	v_exp_f32_e32 v97, v97
	v_pk_mul_f32 v[92:93], v[94:95], v[92:93]
	v_add_f32_e32 v94, 1.0, v96
	v_add_f32_e32 v95, 1.0, v97
	v_mul_f32_e32 v96, 0xbfb8aa3b, v90
	v_mul_f32_e32 v97, 0xbfb8aa3b, v91
	v_exp_f32_e32 v96, v96
	v_exp_f32_e32 v97, v97
	v_rcp_f32_e32 v94, v94
	v_rcp_f32_e32 v95, v95
	v_add_f32_e32 v96, 1.0, v96
	v_add_f32_e32 v97, 1.0, v97
	v_rcp_f32_e32 v96, v96
	v_rcp_f32_e32 v97, v97
	v_pk_mul_f32 v[88:89], v[88:89], v[94:95]
	v_pk_mul_f32 v[86:87], v[92:93], v[86:87]
	v_pk_mul_f32 v[88:89], v[88:89], v[80:81]
	v_pk_mul_f32 v[80:81], v[90:91], v[96:97]
	s_nop 0
	v_pk_mul_f32 v[90:91], v[80:81], v[82:83]
	v_mul_f32_e32 v83, 0xbfb8aa3b, v76
	v_cvt_pk_bf16_f32 v80, v84, v85
	v_exp_f32_e32 v84, v83
	v_mul_f32_e32 v83, 0xbfb8aa3b, v77
	v_exp_f32_e32 v85, v83
	v_cvt_pk_bf16_f32 v81, v86, v87
	v_add_co_u32_e32 v86, vcc, s53, v124
	v_cvt_pk_bf16_f32 v82, v88, v89
	v_cvt_pk_bf16_f32 v83, v90, v91
	v_add_f32_e32 v84, 1.0, v84
	v_add_f32_e32 v85, 1.0, v85
	v_addc_co_u32_e32 v87, vcc, 0, v125, vcc
	v_rcp_f32_e32 v84, v84
	v_rcp_f32_e32 v85, v85
	global_store_dwordx4 v[86:87], v[80:83], off
	v_pk_mul_f32 v[76:77], v[76:77], v[84:85]
	s_nop 0
	v_mul_f32_e32 v80, 0xbfb8aa3b, v78
	v_mul_f32_e32 v81, 0xbfb8aa3b, v79
	v_exp_f32_e32 v80, v80
	v_exp_f32_e32 v81, v81
	v_pk_mul_f32 v[68:69], v[76:77], v[68:69]
	v_add_f32_e32 v76, 1.0, v80
	v_add_f32_e32 v77, 1.0, v81
	v_mul_f32_e32 v80, 0xbfb8aa3b, v72
	v_mul_f32_e32 v81, 0xbfb8aa3b, v73
	v_rcp_f32_e32 v76, v76
	v_rcp_f32_e32 v77, v77
	v_exp_f32_e32 v80, v80
	v_exp_f32_e32 v81, v81
	v_pk_mul_f32 v[76:77], v[78:79], v[76:77]
	v_add_f32_e32 v78, 1.0, v80
	v_add_f32_e32 v79, 1.0, v81
	v_mul_f32_e32 v80, 0xbfb8aa3b, v74
	v_mul_f32_e32 v81, 0xbfb8aa3b, v75
	v_exp_f32_e32 v80, v80
	v_exp_f32_e32 v81, v81
	v_rcp_f32_e32 v78, v78
	v_rcp_f32_e32 v79, v79
	v_add_f32_e32 v80, 1.0, v80
	v_add_f32_e32 v81, 1.0, v81
	v_rcp_f32_e32 v80, v80
	v_rcp_f32_e32 v81, v81
	v_pk_mul_f32 v[72:73], v[72:73], v[78:79]
	v_pk_mul_f32 v[70:71], v[76:77], v[70:71]
	v_pk_mul_f32 v[72:73], v[72:73], v[64:65]
	v_pk_mul_f32 v[64:65], v[74:75], v[80:81]
	s_nop 0
	v_pk_mul_f32 v[74:75], v[64:65], v[66:67]
	v_cvt_pk_bf16_f32 v64, v68, v69
	v_cvt_pk_bf16_f32 v65, v70, v71
	v_cvt_pk_bf16_f32 v66, v72, v73
	v_cvt_pk_bf16_f32 v67, v74, v75
	global_store_dwordx4 v[86:87], v[64:67], off offset:2048
	v_add_u32_e32 v68, 0x80, v153
	s_nop 0
	v_mul_f32_e32 v66, 0xbfb8aa3b, v60
	v_mul_f32_e32 v67, 0xbfb8aa3b, v61
	v_exp_f32_e32 v66, v66
	v_exp_f32_e32 v67, v67
	v_lshrrev_b32_e32 v64, 8, v68
	v_mul_i32_i24_e32 v64, 0x56, v64
	v_add_f32_e32 v66, 1.0, v66
	v_add_f32_e32 v67, 1.0, v67
	v_rcp_f32_e32 v66, v66
	v_rcp_f32_e32 v67, v67
	v_ashrrev_i32_e32 v65, 31, v64
	v_lshl_add_u64 v[64:65], v[64:65], 0, s[24:25]
	v_lshlrev_b64 v[64:65], 15, v[64:65]
	v_pk_mul_f32 v[60:61], v[60:61], v[66:67]
	v_mul_f32_e32 v66, 0xbfb8aa3b, v62
	v_mul_f32_e32 v67, 0xbfb8aa3b, v63
	v_exp_f32_e32 v66, v66
	v_exp_f32_e32 v67, v67
	v_pk_mul_f32 v[52:53], v[60:61], v[52:53]
	v_lshlrev_b32_e32 v68, 7, v68
	v_add_f32_e32 v60, 1.0, v66
	v_add_f32_e32 v61, 1.0, v67
	v_mul_f32_e32 v66, 0xbfb8aa3b, v56
	v_mul_f32_e32 v67, 0xbfb8aa3b, v57
	v_rcp_f32_e32 v60, v60
	v_rcp_f32_e32 v61, v61
	v_exp_f32_e32 v66, v66
	v_exp_f32_e32 v67, v67
	v_lshl_add_u64 v[64:65], s[10:11], 0, v[64:65]
	v_pk_mul_f32 v[60:61], v[62:63], v[60:61]
	v_add_f32_e32 v62, 1.0, v66
	v_add_f32_e32 v63, 1.0, v67
	v_mul_f32_e32 v66, 0xbfb8aa3b, v58
	v_mul_f32_e32 v67, 0xbfb8aa3b, v59
	v_exp_f32_e32 v66, v66
	v_exp_f32_e32 v67, v67
	v_rcp_f32_e32 v62, v62
	v_rcp_f32_e32 v63, v63
	v_add_f32_e32 v66, 1.0, v66
; __device__ __forceinline__ unsigned cvt_pk_bf16(float lo, float hi) { f32x2 v = {lo, hi}; bf16x2_t b = __builtin_convertvector(v, bf16x2_t); return __builtin_bit_cast(unsigned, b); }
; __device__ __forceinline__ float sigmoid_f(float x) { return __builtin_amdgcn_rcpf(1.0f + __expf(-x)); }
; __device__ __forceinline__ float silu_f(float x) { return x * sigmoid_f(x); }
; __device__ __forceinline__ size_t tl(int r, int c, int K) { return ((size_t)(r >> 8) * (size_t)(K >> 6) + (size_t)(c >> 6)) * 16384 + (size_t)((r & 255) << 6) + (size_t)(c & 63); }
;     __device__ __forceinline__ void operator()(const f32x4 (&acc)[2][2][4][2], const Unit& u, int wr, int wc, int fr, int fq) const {
;         const int row0 = u.pm * BM + wr * 64 + fr, col0 = u.pn * 128 + wc * 32 + 8 * fq;
; #pragma unroll
;         for (int ai = 0; ai < 2; ++ai)
; #pragma unroll
;             for (int m = 0; m < 4; ++m) {
;                 bf16_t* rowp = MODE == 0 ? O + tl(row0 + ai * HALF + m * 16, col0, ldo) : O + (size_t)(row0 + ai * HALF + m * 16) * ldo + col0;
;                 float v[8];
; #pragma unroll
;                 for (int n = 0; n < 2; ++n)
; #pragma unroll
;                     for (int j = 0; j < 4; ++j) { const float a = acc[ai][0][m][n][j], b = acc[ai][1][m][n][j]; v[n * 4 + j] = MODE == 0 ? silu_f(a) * b : a * sigmoid_f(b); }
;                 u32x4 w; w.x = cvt_pk_bf16(v[0], v[1]); w.y = cvt_pk_bf16(v[2], v[3]); w.z = cvt_pk_bf16(v[4], v[5]); w.w = cvt_pk_bf16(v[6], v[7]);
;                 *(u32x4*)rowp = w;
	v_add_f32_e32 v67, 1.0, v67
	v_rcp_f32_e32 v66, v66
	v_rcp_f32_e32 v67, v67
	v_pk_mul_f32 v[56:57], v[56:57], v[62:63]
	v_and_b32_e32 v136, 0x6780, v68
	v_pk_mul_f32 v[56:57], v[56:57], v[48:49]
	v_pk_mul_f32 v[48:49], v[58:59], v[66:67]
	v_lshl_add_u64 v[64:65], v[64:65], 0, v[136:137]
	v_pk_mul_f32 v[58:59], v[48:49], v[50:51]
	v_mul_f32_e32 v49, 0xbfb8aa3b, v44
	v_exp_f32_e32 v50, v49
	v_mul_f32_e32 v49, 0xbfb8aa3b, v45
	v_exp_f32_e32 v51, v49
	v_pk_mul_f32 v[54:55], v[60:61], v[54:55]
	v_add_f32_e32 v50, 1.0, v50
	v_cvt_pk_bf16_f32 v48, v52, v53
	v_rcp_f32_e32 v52, v50
	v_add_f32_e32 v50, 1.0, v51
	v_lshl_add_u64 v[60:61], v[64:65], 0, v[146:147]
	v_cvt_pk_bf16_f32 v49, v54, v55
	v_rcp_f32_e32 v53, v50
	v_cvt_pk_bf16_f32 v50, v56, v57
	v_cvt_pk_bf16_f32 v51, v58, v59
	global_store_dwordx4 v[60:61], v[48:51], off
	v_pk_mul_f32 v[44:45], v[44:45], v[52:53]
	s_mov_b32 s25, s12
	v_mul_f32_e32 v48, 0xbfb8aa3b, v46
	v_mul_f32_e32 v49, 0xbfb8aa3b, v47
	v_exp_f32_e32 v48, v48
	v_exp_f32_e32 v49, v49
	v_pk_mul_f32 v[36:37], v[44:45], v[36:37]
	s_mov_b32 s24, s14
	v_add_f32_e32 v44, 1.0, v48
	v_add_f32_e32 v45, 1.0, v49
	v_mul_f32_e32 v48, 0xbfb8aa3b, v40
	v_mul_f32_e32 v49, 0xbfb8aa3b, v41
	v_rcp_f32_e32 v44, v44
	v_rcp_f32_e32 v45, v45
	v_exp_f32_e32 v48, v48
	v_exp_f32_e32 v49, v49
	v_pk_mul_f32 v[44:45], v[46:47], v[44:45]
	v_add_f32_e32 v46, 1.0, v48
	v_add_f32_e32 v47, 1.0, v49
	v_mul_f32_e32 v48, 0xbfb8aa3b, v42
	v_mul_f32_e32 v49, 0xbfb8aa3b, v43
	v_exp_f32_e32 v48, v48
	v_exp_f32_e32 v49, v49
	v_rcp_f32_e32 v46, v46
	v_rcp_f32_e32 v47, v47
	v_add_f32_e32 v48, 1.0, v48
	v_add_f32_e32 v49, 1.0, v49
	v_rcp_f32_e32 v48, v48
	v_rcp_f32_e32 v49, v49
	v_pk_mul_f32 v[40:41], v[40:41], v[46:47]
	v_pk_mul_f32 v[38:39], v[44:45], v[38:39]
	v_pk_mul_f32 v[40:41], v[40:41], v[32:33]
	v_pk_mul_f32 v[32:33], v[42:43], v[48:49]
	s_nop 0
	v_pk_mul_f32 v[42:43], v[32:33], v[34:35]
	v_mul_f32_e32 v33, 0xbfb8aa3b, v28
	v_exp_f32_e32 v34, v33
	v_mul_f32_e32 v33, 0xbfb8aa3b, v29
	v_exp_f32_e32 v35, v33
	v_cvt_pk_bf16_f32 v32, v36, v37
	v_add_f32_e32 v34, 1.0, v34
	v_rcp_f32_e32 v36, v34
	v_add_f32_e32 v34, 1.0, v35
	v_cvt_pk_bf16_f32 v33, v38, v39
	v_rcp_f32_e32 v37, v34
	v_cvt_pk_bf16_f32 v34, v40, v41
	v_cvt_pk_bf16_f32 v35, v42, v43
	global_store_dwordx4 v[60:61], v[32:35], off offset:2048
	v_pk_mul_f32 v[28:29], v[28:29], v[36:37]
	s_nop 0
	v_mul_f32_e32 v32, 0xbfb8aa3b, v30
	v_mul_f32_e32 v33, 0xbfb8aa3b, v31
	v_exp_f32_e32 v32, v32
	v_exp_f32_e32 v33, v33
	v_pk_mul_f32 v[20:21], v[28:29], v[20:21]
	v_add_f32_e32 v28, 1.0, v32
	v_add_f32_e32 v29, 1.0, v33
	v_mul_f32_e32 v32, 0xbfb8aa3b, v24
	v_mul_f32_e32 v33, 0xbfb8aa3b, v25
	v_rcp_f32_e32 v28, v28
	v_rcp_f32_e32 v29, v29
	v_exp_f32_e32 v32, v32
	v_exp_f32_e32 v33, v33
	v_pk_mul_f32 v[28:29], v[30:31], v[28:29]
	v_add_f32_e32 v30, 1.0, v32
	v_add_f32_e32 v31, 1.0, v33
	v_mul_f32_e32 v32, 0xbfb8aa3b, v26
	v_mul_f32_e32 v33, 0xbfb8aa3b, v27
	v_exp_f32_e32 v32, v32
	v_exp_f32_e32 v33, v33
	v_rcp_f32_e32 v30, v30
	v_rcp_f32_e32 v31, v31
	v_add_f32_e32 v32, 1.0, v32
	v_add_f32_e32 v33, 1.0, v33
	v_rcp_f32_e32 v32, v32
	v_rcp_f32_e32 v33, v33
	v_pk_mul_f32 v[24:25], v[24:25], v[30:31]
	v_pk_mul_f32 v[22:23], v[28:29], v[22:23]
	v_pk_mul_f32 v[24:25], v[24:25], v[16:17]
	v_pk_mul_f32 v[16:17], v[26:27], v[32:33]
	s_nop 0
	v_pk_mul_f32 v[26:27], v[16:17], v[18:19]
	v_mul_f32_e32 v19, 0xbfb8aa3b, v12
	v_cvt_pk_bf16_f32 v16, v20, v21
	v_exp_f32_e32 v20, v19
	v_mul_f32_e32 v19, 0xbfb8aa3b, v13
	v_exp_f32_e32 v21, v19
	v_cvt_pk_bf16_f32 v17, v22, v23
	v_add_co_u32_e32 v22, vcc, s53, v60
	v_cvt_pk_bf16_f32 v18, v24, v25
	v_cvt_pk_bf16_f32 v19, v26, v27
	v_add_f32_e32 v20, 1.0, v20
	v_add_f32_e32 v21, 1.0, v21
	v_addc_co_u32_e32 v23, vcc, 0, v61, vcc
	v_rcp_f32_e32 v20, v20
	v_rcp_f32_e32 v21, v21
	global_store_dwordx4 v[22:23], v[16:19], off
	s_and_b64 vcc, exec, s[8:9]
	v_pk_mul_f32 v[12:13], v[12:13], v[20:21]
	v_mul_f32_e32 v16, 0xbfb8aa3b, v14
	v_mul_f32_e32 v17, 0xbfb8aa3b, v15
	v_exp_f32_e32 v16, v16
	v_exp_f32_e32 v17, v17
	v_pk_mul_f32 v[4:5], v[12:13], v[4:5]
	v_add_f32_e32 v12, 1.0, v16
	v_add_f32_e32 v13, 1.0, v17
	v_mul_f32_e32 v16, 0xbfb8aa3b, v8
	v_mul_f32_e32 v17, 0xbfb8aa3b, v9
	v_rcp_f32_e32 v12, v12
	v_rcp_f32_e32 v13, v13
	v_exp_f32_e32 v16, v16
	v_exp_f32_e32 v17, v17
	v_pk_mul_f32 v[12:13], v[14:15], v[12:13]
	v_add_f32_e32 v14, 1.0, v16
	v_add_f32_e32 v15, 1.0, v17
	v_mul_f32_e32 v16, 0xbfb8aa3b, v10
	v_mul_f32_e32 v17, 0xbfb8aa3b, v11
	v_exp_f32_e32 v16, v16
	v_exp_f32_e32 v17, v17
	v_rcp_f32_e32 v14, v14
	v_rcp_f32_e32 v15, v15
	v_add_f32_e32 v16, 1.0, v16
	v_add_f32_e32 v17, 1.0, v17
	v_rcp_f32_e32 v16, v16
	v_rcp_f32_e32 v17, v17
	v_pk_mul_f32 v[8:9], v[8:9], v[14:15]
	v_pk_mul_f32 v[6:7], v[12:13], v[6:7]
	v_pk_mul_f32 v[8:9], v[8:9], v[0:1]
	v_pk_mul_f32 v[0:1], v[10:11], v[16:17]
	s_nop 0
	v_pk_mul_f32 v[10:11], v[0:1], v[2:3]
	v_cvt_pk_bf16_f32 v0, v4, v5
	v_cvt_pk_bf16_f32 v1, v6, v7
	v_cvt_pk_bf16_f32 v2, v8, v9
	v_cvt_pk_bf16_f32 v3, v10, v11
	global_store_dwordx4 v[22:23], v[0:3], off offset:2048
	s_cbranch_vccz .LBB0_1559
	s_waitcnt vmcnt(0)
	s_cmpk_gt_u32 s36, 0xff
	s_cbranch_scc1 .LBB0_1566
	s_barrier

; #define PG8_STAGE(bufoff, gbase, voff) do { _Pragma("unroll") for (int _i = 0; _i < 2; ++_i) \
;         __builtin_amdgcn_global_load_lds((const unsigned*)((const char*)(gbase) + (voff)[_i]), (LAS unsigned*)(lds + (bufoff) + ldsw + _i * 8192), 16, 0, 0); } while (0)
; #define PG8_LDA(dst, b, h) do { _Pragma("unroll") for (int m = 0; m < 4; ++m) _Pragma("unroll") for (int k = 0; k < 2; ++k) dst[m][k] = *(const LAS bf16x8*)(lds + PG8_SA(b, h) + aoff + m * 2048 + k * 1024); } while (0)
; #define PG8_LDB(dst, b, h) do { _Pragma("unroll") for (int n = 0; n < 2; ++n) _Pragma("unroll") for (int k = 0; k < 2; ++k) dst[n][k] = *(const LAS bf16x8*)(lds + PG8_SB(b, h) + boff + n * 2048 + k * 1024); } while (0)
; #define PG8_MMA(ai, bj, At, Bt) do { __builtin_amdgcn_s_setprio(1); _Pragma("unroll") for (int m = 0; m < 4; ++m) _Pragma("unroll") for (int n = 0; n < 2; ++n) _Pragma("unroll") for (int k = 0; k < 2; ++k) \
;         acc[ai][bj][m][n] = __builtin_amdgcn_mfma_f32_16x16x32_bf16(Bt[n][k], At[m][k], acc[ai][bj][m][n], 0, 0, 0); __builtin_amdgcn_s_setprio(0); } while (0)
; #define PG8_WAIT_L(n) asm volatile("s_waitcnt lgkmcnt(" #n ")" ::: "memory")
; #define PG8_BAR __builtin_amdgcn_s_barrier()
; #define PG8_SCHED __builtin_amdgcn_sched_barrier(0)
; template <class Epi, class Sched>
; __device__ __forceinline__ void gemm_phase(LAS unsigned char* lds, const Gemm g, const Sched& S, const Epi& E) {
;     ...
;         for (int t = 0; t < nt; t += 2) {
;             const bool last = (t == nt - 2);
;             const char* a1 = cA + (size_t)(t + 1) * kstep;
;             const char* a2 = last ? nA : cA + (size_t)(t + 2) * kstep; const char* b2 = last ? nB : cB + (size_t)(t + 2) * kstep;
;             const char* a3 = a2 + kstep; const char* b3 = b2 + kstep;
;             PG8_LDB(B0, 0, 0); PG8_SCHED; PG8_LDA(At, 0, 0); PG8_STAGE(PG8_SA(1, 1), a1 + hstep, voffA);
;             PG8_WAIT_L(8); PG8_BAR; PG8_WAIT_L(0); PG8_MMA(0, 0, At, B0); PG8_BAR; PG8_SCHED;
;             PG8_LDB(B1, 0, 1); PG8_STAGE(PG8_SB(0, 0), b2, voffB);
;             PG8_BAR; PG8_WAIT_L(0); PG8_MMA(0, 1, At, B1); PG8_BAR;
;             PG8_LDA(At, 0, 1); PG8_STAGE(PG8_SA(0, 0), a2, voffA);
;             PG8_BAR; PG8_WAIT_L(0); PG8_MMA(1, 0, At, B0); PG8_BAR; PG8_SCHED;
.LBB0_1640:
	ds_read_b128 v[128:131], v187
	ds_read_b128 v[132:135], v187 offset:1024
	ds_read_b128 v[136:139], v187 offset:2048
	ds_read_b128 v[140:143], v187 offset:3072
	s_add_u32 s38, s36, 0x4000
	s_addc_u32 s39, s37, 0
	s_cmpk_eq_i32 s62, 0x52
	s_cselect_b32 s42, s8, s38
	s_cselect_b32 s43, s9, s39
	s_cselect_b32 s38, s10, s60
	s_cselect_b32 s39, s11, s61
	s_add_u32 s40, s42, 0x8000
	s_addc_u32 s41, s43, 0
	v_lshl_add_u64 v[194:195], s[36:37], 0, v[164:165]
	s_add_i32 m0, s49, 0xc000
	ds_read_b128 v[144:147], v188
	ds_read_b128 v[148:151], v188 offset:1024
	ds_read_b128 v[152:155], v188 offset:2048
	ds_read_b128 v[156:159], v188 offset:3072
	ds_read_b128 v[172:175], v188 offset:4096
	ds_read_b128 v[176:179], v188 offset:5120
	ds_read_b128 v[180:183], v188 offset:6144
	ds_read_b128 v[190:193], v188 offset:7168
	global_load_lds_dwordx4 v[194:195], off
	v_lshl_add_u64 v[194:195], s[36:37], 0, v[166:167]
	s_add_i32 m0, s49, 0xe000
	s_nop 0
	global_load_lds_dwordx4 v[194:195], off
	s_waitcnt lgkmcnt(8)
	s_barrier
	s_waitcnt lgkmcnt(0)
	s_waitcnt lgkmcnt(0)
	v_mfma_f32_16x16x32_bf16 v[124:127], v[128:131], v[144:147], v[124:127]
	v_mfma_f32_16x16x32_bf16 v[120:123], v[136:139], v[144:147], v[120:123]
	v_mfma_f32_16x16x32_bf16 v[112:115], v[128:131], v[152:155], v[112:115]
	v_mfma_f32_16x16x32_bf16 v[104:107], v[136:139], v[152:155], v[104:107]
	v_mfma_f32_16x16x32_bf16 v[92:95], v[128:131], v[172:175], v[92:95]
	v_mfma_f32_16x16x32_bf16 v[88:91], v[136:139], v[172:175], v[88:91]
	v_mfma_f32_16x16x32_bf16 v[76:79], v[128:131], v[180:183], v[76:79]
	v_mfma_f32_16x16x32_bf16 v[72:75], v[136:139], v[180:183], v[72:75]
	v_mfma_f32_16x16x32_bf16 v[124:127], v[132:135], v[148:151], v[124:127]
	v_mfma_f32_16x16x32_bf16 v[120:123], v[140:143], v[148:151], v[120:123]
	v_mfma_f32_16x16x32_bf16 v[112:115], v[132:135], v[156:159], v[112:115]
	v_mfma_f32_16x16x32_bf16 v[104:107], v[140:143], v[156:159], v[104:107]
	v_mfma_f32_16x16x32_bf16 v[92:95], v[132:135], v[176:179], v[92:95]
	v_mfma_f32_16x16x32_bf16 v[88:91], v[140:143], v[176:179], v[88:91]
	v_mfma_f32_16x16x32_bf16 v[76:79], v[132:135], v[190:193], v[76:79]
	v_mfma_f32_16x16x32_bf16 v[72:75], v[140:143], v[190:193], v[72:75]
	s_barrier
	s_add_i32 s63, s71, s48
	v_lshl_add_u64 v[202:203], s[38:39], 0, v[160:161]
	s_mov_b32 m0, s63
	ds_read_b128 v[194:197], v189
	ds_read_b128 v[198:201], v189 offset:1024
	ds_read_b128 v[206:209], v189 offset:2048
	ds_read_b128 v[210:213], v189 offset:3072
	global_load_lds_dwordx4 v[202:203], off
	v_lshl_add_u64 v[202:203], s[38:39], 0, v[162:163]
	s_add_i32 m0, s63, 0x2000
	s_nop 0
	global_load_lds_dwordx4 v[202:203], off
	s_barrier
	s_waitcnt lgkmcnt(0)
	s_waitcnt lgkmcnt(0)
	v_mfma_f32_16x16x32_bf16 v[116:119], v[194:197], v[144:147], v[116:119]
	v_mfma_f32_16x16x32_bf16 v[108:111], v[206:209], v[144:147], v[108:111]
	v_mfma_f32_16x16x32_bf16 v[100:103], v[194:197], v[152:155], v[100:103]
	v_mfma_f32_16x16x32_bf16 v[96:99], v[206:209], v[152:155], v[96:99]
	v_mfma_f32_16x16x32_bf16 v[84:87], v[194:197], v[172:175], v[84:87]
	v_mfma_f32_16x16x32_bf16 v[80:83], v[206:209], v[172:175], v[80:83]
	v_mfma_f32_16x16x32_bf16 v[68:71], v[194:197], v[180:183], v[68:71]
	v_mfma_f32_16x16x32_bf16 v[64:67], v[206:209], v[180:183], v[64:67]
	v_mfma_f32_16x16x32_bf16 v[116:119], v[198:201], v[148:151], v[116:119]
	v_mfma_f32_16x16x32_bf16 v[108:111], v[210:213], v[148:151], v[108:111]
	v_mfma_f32_16x16x32_bf16 v[100:103], v[198:201], v[156:159], v[100:103]
	v_mfma_f32_16x16x32_bf16 v[96:99], v[210:213], v[156:159], v[96:99]
	v_mfma_f32_16x16x32_bf16 v[84:87], v[198:201], v[176:179], v[84:87]
	v_mfma_f32_16x16x32_bf16 v[80:83], v[210:213], v[176:179], v[80:83]
	v_mfma_f32_16x16x32_bf16 v[68:71], v[198:201], v[190:193], v[68:71]
	v_mfma_f32_16x16x32_bf16 v[64:67], v[210:213], v[190:193], v[64:67]
	s_mov_b32 m0, s49
	v_lshl_add_u64 v[202:203], s[42:43], 0, v[160:161]
	s_barrier
	ds_read_b128 v[144:147], v188 offset:16384
	ds_read_b128 v[148:151], v188 offset:17408
	ds_read_b128 v[152:155], v188 offset:18432
	ds_read_b128 v[156:159], v188 offset:19456
	ds_read_b128 v[172:175], v188 offset:20480
	ds_read_b128 v[176:179], v188 offset:21504
	ds_read_b128 v[180:183], v188 offset:22528
	ds_read_b128 v[190:193], v188 offset:23552
	global_load_lds_dwordx4 v[202:203], off
	v_lshl_add_u64 v[202:203], s[42:43], 0, v[162:163]
	s_mov_b32 m0, s50
	s_nop 0
	global_load_lds_dwordx4 v[202:203], off
	s_barrier
	s_waitcnt lgkmcnt(0)
	s_waitcnt lgkmcnt(0)
	v_mfma_f32_16x16x32_bf16 v[60:63], v[128:131], v[144:147], v[60:63]
	v_mfma_f32_16x16x32_bf16 v[56:59], v[136:139], v[144:147], v[56:59]
	v_mfma_f32_16x16x32_bf16 v[48:51], v[128:131], v[152:155], v[48:51]
	v_mfma_f32_16x16x32_bf16 v[40:43], v[136:139], v[152:155], v[40:43]
	v_mfma_f32_16x16x32_bf16 v[28:31], v[128:131], v[172:175], v[28:31]
	v_mfma_f32_16x16x32_bf16 v[24:27], v[136:139], v[172:175], v[24:27]
	v_mfma_f32_16x16x32_bf16 v[16:19], v[128:131], v[180:183], v[16:19]
	v_mfma_f32_16x16x32_bf16 v[8:11], v[136:139], v[180:183], v[8:11]
	v_mfma_f32_16x16x32_bf16 v[60:63], v[132:135], v[148:151], v[60:63]
	v_mfma_f32_16x16x32_bf16 v[56:59], v[140:143], v[148:151], v[56:59]
	v_mfma_f32_16x16x32_bf16 v[48:51], v[132:135], v[156:159], v[48:51]
	v_mfma_f32_16x16x32_bf16 v[40:43], v[140:143], v[156:159], v[40:43]
	v_mfma_f32_16x16x32_bf16 v[28:31], v[132:135], v[176:179], v[28:31]
	v_mfma_f32_16x16x32_bf16 v[24:27], v[140:143], v[176:179], v[24:27]
	v_mfma_f32_16x16x32_bf16 v[16:19], v[132:135], v[190:193], v[16:19]
	v_mfma_f32_16x16x32_bf16 v[8:11], v[140:143], v[190:193], v[8:11]
	s_barrier
; #define PG8_STAGE(bufoff, gbase, voff) do { _Pragma("unroll") for (int _i = 0; _i < 2; ++_i) \
;         __builtin_amdgcn_global_load_lds((const unsigned*)((const char*)(gbase) + (voff)[_i]), (LAS unsigned*)(lds + (bufoff) + ldsw + _i * 8192), 16, 0, 0); } while (0)
; #define PG8_LDA(dst, b, h) do { _Pragma("unroll") for (int m = 0; m < 4; ++m) _Pragma("unroll") for (int k = 0; k < 2; ++k) dst[m][k] = *(const LAS bf16x8*)(lds + PG8_SA(b, h) + aoff + m * 2048 + k * 1024); } while (0)
; #define PG8_LDB(dst, b, h) do { _Pragma("unroll") for (int n = 0; n < 2; ++n) _Pragma("unroll") for (int k = 0; k < 2; ++k) dst[n][k] = *(const LAS bf16x8*)(lds + PG8_SB(b, h) + boff + n * 2048 + k * 1024); } while (0)
; #define PG8_MMA(ai, bj, At, Bt) do { __builtin_amdgcn_s_setprio(1); _Pragma("unroll") for (int m = 0; m < 4; ++m) _Pragma("unroll") for (int n = 0; n < 2; ++n) _Pragma("unroll") for (int k = 0; k < 2; ++k) \
;         acc[ai][bj][m][n] = __builtin_amdgcn_mfma_f32_16x16x32_bf16(Bt[n][k], At[m][k], acc[ai][bj][m][n], 0, 0, 0); __builtin_amdgcn_s_setprio(0); } while (0)
; #define PG8_WAIT_V(n) asm volatile("s_waitcnt vmcnt(" #n ")" ::: "memory")
; #define PG8_WAIT_L(n) asm volatile("s_waitcnt lgkmcnt(" #n ")" ::: "memory")
; #define PG8_BAR __builtin_amdgcn_s_barrier()
; #define PG8_SCHED __builtin_amdgcn_sched_barrier(0)
; template <class Epi, class Sched>
; __device__ __forceinline__ void gemm_phase(LAS unsigned char* lds, const Gemm g, const Sched& S, const Epi& E) {
;     ...
;             PG8_STAGE(PG8_SB(0, 1), b2 + hstep, voffB);
;             PG8_WAIT_V(6); PG8_BAR; PG8_MMA(1, 1, At, B1); PG8_BAR;
;             PG8_LDB(B0, 1, 0); PG8_SCHED; PG8_LDA(At, 1, 0); PG8_STAGE(PG8_SA(0, 1), a2 + hstep, voffA);
;             PG8_WAIT_L(8); PG8_BAR; PG8_WAIT_L(0); PG8_MMA(0, 0, At, B0); PG8_BAR; PG8_SCHED;
;             PG8_LDB(B1, 1, 1); PG8_STAGE(PG8_SB(1, 0), b3, voffB);
;             PG8_BAR; PG8_WAIT_L(0); PG8_MMA(0, 1, At, B1); PG8_BAR;
;             PG8_LDA(At, 1, 1); PG8_STAGE(PG8_SA(1, 0), a3, voffA);
;             PG8_BAR; PG8_WAIT_L(0); PG8_MMA(1, 0, At, B0); PG8_BAR; PG8_SCHED;
	s_add_u32 s64, s38, 0x4000
	s_addc_u32 s65, s39, 0
	s_add_i32 s63, s56, s48
	v_lshl_add_u64 v[128:129], s[64:65], 0, v[160:161]
	s_mov_b32 m0, s63
	s_nop 0
	global_load_lds_dwordx4 v[128:129], off
	v_lshl_add_u64 v[128:129], s[64:65], 0, v[162:163]
	s_add_i32 m0, s63, 0x2000
	s_nop 0
	global_load_lds_dwordx4 v[128:129], off
	s_waitcnt vmcnt(6)
	s_barrier
	v_mfma_f32_16x16x32_bf16 v[52:55], v[194:197], v[144:147], v[52:55]
	v_mfma_f32_16x16x32_bf16 v[44:47], v[206:209], v[144:147], v[44:47]
	v_mfma_f32_16x16x32_bf16 v[36:39], v[194:197], v[152:155], v[36:39]
	v_mfma_f32_16x16x32_bf16 v[32:35], v[206:209], v[152:155], v[32:35]
	v_mfma_f32_16x16x32_bf16 v[20:23], v[194:197], v[172:175], v[20:23]
	v_mfma_f32_16x16x32_bf16 v[12:15], v[206:209], v[172:175], v[12:15]
	v_mfma_f32_16x16x32_bf16 v[4:7], v[194:197], v[180:183], v[4:7]
	v_mfma_f32_16x16x32_bf16 v[0:3], v[206:209], v[180:183], v[0:3]
	v_mfma_f32_16x16x32_bf16 v[52:55], v[198:201], v[148:151], v[52:55]
	v_mfma_f32_16x16x32_bf16 v[44:47], v[210:213], v[148:151], v[44:47]
	v_mfma_f32_16x16x32_bf16 v[36:39], v[198:201], v[156:159], v[36:39]
	v_mfma_f32_16x16x32_bf16 v[32:35], v[210:213], v[156:159], v[32:35]
	v_mfma_f32_16x16x32_bf16 v[20:23], v[198:201], v[176:179], v[20:23]
	v_mfma_f32_16x16x32_bf16 v[12:15], v[210:213], v[176:179], v[12:15]
	v_mfma_f32_16x16x32_bf16 v[4:7], v[198:201], v[190:193], v[4:7]
	v_mfma_f32_16x16x32_bf16 v[0:3], v[210:213], v[190:193], v[0:3]
	s_add_i32 s63, 0, 0x18000
	v_add_u32_e32 v140, s63, v185
	s_barrier
	ds_read_b128 v[128:131], v140
	ds_read_b128 v[132:135], v140 offset:1024
	ds_read_b128 v[136:139], v140 offset:2048
	ds_read_b128 v[140:143], v140 offset:3072
	s_add_u32 s42, s42, 0x4000
	s_addc_u32 s43, s43, 0
	s_mov_b32 m0, s51
	v_lshl_add_u64 v[194:195], s[42:43], 0, v[160:161]
	ds_read_b128 v[144:147], v188 offset:32768
	ds_read_b128 v[148:151], v188 offset:33792
	ds_read_b128 v[152:155], v188 offset:34816
	ds_read_b128 v[156:159], v188 offset:35840
	ds_read_b128 v[172:175], v188 offset:36864
	ds_read_b128 v[176:179], v188 offset:37888
	ds_read_b128 v[180:183], v188 offset:38912
	ds_read_b128 v[190:193], v188 offset:39936
	global_load_lds_dwordx4 v[194:195], off
	v_lshl_add_u64 v[194:195], s[42:43], 0, v[162:163]
	s_mov_b32 m0, s52
	s_nop 0
	global_load_lds_dwordx4 v[194:195], off
	s_waitcnt lgkmcnt(8)
	s_barrier
	s_waitcnt lgkmcnt(0)
	s_waitcnt lgkmcnt(0)
	v_mfma_f32_16x16x32_bf16 v[124:127], v[128:131], v[144:147], v[124:127]
	v_mfma_f32_16x16x32_bf16 v[120:123], v[136:139], v[144:147], v[120:123]
	v_mfma_f32_16x16x32_bf16 v[112:115], v[128:131], v[152:155], v[112:115]
	v_mfma_f32_16x16x32_bf16 v[104:107], v[136:139], v[152:155], v[104:107]
	v_mfma_f32_16x16x32_bf16 v[92:95], v[128:131], v[172:175], v[92:95]
	v_mfma_f32_16x16x32_bf16 v[88:91], v[136:139], v[172:175], v[88:91]
	v_mfma_f32_16x16x32_bf16 v[76:79], v[128:131], v[180:183], v[76:79]
	v_mfma_f32_16x16x32_bf16 v[72:75], v[136:139], v[180:183], v[72:75]
	v_mfma_f32_16x16x32_bf16 v[124:127], v[132:135], v[148:151], v[124:127]
	v_mfma_f32_16x16x32_bf16 v[120:123], v[140:143], v[148:151], v[120:123]
	v_mfma_f32_16x16x32_bf16 v[112:115], v[132:135], v[156:159], v[112:115]
	v_mfma_f32_16x16x32_bf16 v[104:107], v[140:143], v[156:159], v[104:107]
	v_mfma_f32_16x16x32_bf16 v[92:95], v[132:135], v[176:179], v[92:95]
	v_mfma_f32_16x16x32_bf16 v[88:91], v[140:143], v[176:179], v[88:91]
	v_mfma_f32_16x16x32_bf16 v[76:79], v[132:135], v[190:193], v[76:79]
	v_mfma_f32_16x16x32_bf16 v[72:75], v[140:143], v[190:193], v[72:75]
	s_barrier
	s_add_i32 s64, 0, 0x1c000
	s_add_u32 s42, s38, 0x8000
	v_add_u32_e32 v202, s64, v185
	s_addc_u32 s43, s39, 0
	s_add_i32 s63, s63, s48
	ds_read_b128 v[194:197], v202
	ds_read_b128 v[198:201], v202 offset:1024
	ds_read_b128 v[206:209], v202 offset:2048
	ds_read_b128 v[210:213], v202 offset:3072
	v_lshl_add_u64 v[202:203], s[42:43], 0, v[160:161]
	s_mov_b32 m0, s63
	s_nop 0
	global_load_lds_dwordx4 v[202:203], off
	v_lshl_add_u64 v[202:203], s[42:43], 0, v[162:163]
	s_add_i32 m0, s63, 0x2000
	s_nop 0
	global_load_lds_dwordx4 v[202:203], off
	s_barrier
	s_waitcnt lgkmcnt(0)
	s_waitcnt lgkmcnt(0)
	v_mfma_f32_16x16x32_bf16 v[116:119], v[194:197], v[144:147], v[116:119]
	v_mfma_f32_16x16x32_bf16 v[108:111], v[206:209], v[144:147], v[108:111]
	v_mfma_f32_16x16x32_bf16 v[100:103], v[194:197], v[152:155], v[100:103]
	v_mfma_f32_16x16x32_bf16 v[96:99], v[206:209], v[152:155], v[96:99]
	v_mfma_f32_16x16x32_bf16 v[84:87], v[194:197], v[172:175], v[84:87]
	v_mfma_f32_16x16x32_bf16 v[80:83], v[206:209], v[172:175], v[80:83]
	v_mfma_f32_16x16x32_bf16 v[68:71], v[194:197], v[180:183], v[68:71]
	v_mfma_f32_16x16x32_bf16 v[64:67], v[206:209], v[180:183], v[64:67]
	v_mfma_f32_16x16x32_bf16 v[116:119], v[198:201], v[148:151], v[116:119]
	v_mfma_f32_16x16x32_bf16 v[108:111], v[210:213], v[148:151], v[108:111]
	v_mfma_f32_16x16x32_bf16 v[100:103], v[198:201], v[156:159], v[100:103]
	v_mfma_f32_16x16x32_bf16 v[96:99], v[210:213], v[156:159], v[96:99]
	v_mfma_f32_16x16x32_bf16 v[84:87], v[198:201], v[176:179], v[84:87]
	v_mfma_f32_16x16x32_bf16 v[80:83], v[210:213], v[176:179], v[80:83]
	v_mfma_f32_16x16x32_bf16 v[68:71], v[198:201], v[190:193], v[68:71]
	v_mfma_f32_16x16x32_bf16 v[64:67], v[210:213], v[190:193], v[64:67]
	s_mov_b32 m0, s54
	v_lshl_add_u64 v[202:203], s[40:41], 0, v[160:161]
	s_barrier
	ds_read_b128 v[144:147], v188 offset:49152
	ds_read_b128 v[148:151], v188 offset:50176
	ds_read_b128 v[152:155], v188 offset:51200
	ds_read_b128 v[156:159], v188 offset:52224
	ds_read_b128 v[172:175], v188 offset:53248
	ds_read_b128 v[176:179], v188 offset:54272
	ds_read_b128 v[180:183], v188 offset:55296
	ds_read_b128 v[190:193], v188 offset:56320
	global_load_lds_dwordx4 v[202:203], off
	v_lshl_add_u64 v[202:203], s[40:41], 0, v[162:163]
	s_mov_b32 m0, s55
	s_nop 0
	global_load_lds_dwordx4 v[202:203], off
	s_barrier
; #define PG8_STAGE(bufoff, gbase, voff) do { _Pragma("unroll") for (int _i = 0; _i < 2; ++_i) \
;         __builtin_amdgcn_global_load_lds((const unsigned*)((const char*)(gbase) + (voff)[_i]), (LAS unsigned*)(lds + (bufoff) + ldsw + _i * 8192), 16, 0, 0); } while (0)
; #define PG8_MMA(ai, bj, At, Bt) do { __builtin_amdgcn_s_setprio(1); _Pragma("unroll") for (int m = 0; m < 4; ++m) _Pragma("unroll") for (int n = 0; n < 2; ++n) _Pragma("unroll") for (int k = 0; k < 2; ++k) \
;         acc[ai][bj][m][n] = __builtin_amdgcn_mfma_f32_16x16x32_bf16(Bt[n][k], At[m][k], acc[ai][bj][m][n], 0, 0, 0); __builtin_amdgcn_s_setprio(0); } while (0)
; #define PG8_WAIT_V(n) asm volatile("s_waitcnt vmcnt(" #n ")" ::: "memory")
; template <class Epi, class Sched>
; __device__ __forceinline__ void gemm_phase(LAS unsigned char* lds, const Gemm g, const Sched& S, const Epi& E) {
;     ...
;             PG8_BAR; PG8_WAIT_L(0); PG8_MMA(1, 0, At, B0); PG8_BAR; PG8_SCHED;
;             PG8_STAGE(PG8_SB(1, 1), b3 + hstep, voffB);
;             PG8_WAIT_V(6); PG8_BAR; PG8_MMA(1, 1, At, B1); PG8_BAR;
;     __device__ __forceinline__ void operator()(const f32x4 (&acc)[2][2][4][2], const Unit& u, int wr, int wc, int fr, int fq) const {
;         const int row0 = u.pm * BM + wr * 64 + fr, col0 = u.pn * BM + wc * 32 + 4 * fq;
;         f32x4 gv[2][2], bv[2][2];
;         if (MODE == 1) {
; #pragma unroll
;             for (int bj = 0; bj < 2; ++bj)
; #pragma unroll
;                 for (int n = 0; n < 2; ++n) { gv[bj][n] = *(const f32x4*)(g + col0 + bj * HALF + n * 16); bv[bj][n] = *(const f32x4*)(b + col0 + bj * HALF + n * 16); }
;         }
; #pragma unroll
;         for (int ai = 0; ai < 2; ++ai)
; #pragma unroll
;             for (int mh = 0; mh < 2; ++mh) {
;                 f32x4 rv[2][2][2]; f32x2 st[2];
; #pragma unroll
;                 for (int mm = 0; mm < 2; ++mm) {
;                     const int r = row0 + ai * HALF + (mh * 2 + mm) * 16;
;                     const float* rp = MODE == 0 ? ((r < 8192 ? x0 + (size_t)r * DM : x1 + (size_t)(r - 8192) * DM) + col0) : (Z + (size_t)r * DM + col0);
;                     if (MODE == 1) st[mm] = stats[r];
; #pragma unroll
;                     for (int bj = 0; bj < 2; ++bj)
; #pragma unroll
;                         for (int n = 0; n < 2; ++n) rv[mm][bj][n] = *(const f32x4*)(rp + bj * HALF + n * 16);
	s_waitcnt lgkmcnt(0)
	s_waitcnt lgkmcnt(0)
	v_mfma_f32_16x16x32_bf16 v[60:63], v[128:131], v[144:147], v[60:63]
	v_mfma_f32_16x16x32_bf16 v[56:59], v[136:139], v[144:147], v[56:59]
	v_mfma_f32_16x16x32_bf16 v[48:51], v[128:131], v[152:155], v[48:51]
	v_mfma_f32_16x16x32_bf16 v[40:43], v[136:139], v[152:155], v[40:43]
	v_mfma_f32_16x16x32_bf16 v[28:31], v[128:131], v[172:175], v[28:31]
	v_mfma_f32_16x16x32_bf16 v[24:27], v[136:139], v[172:175], v[24:27]
	v_mfma_f32_16x16x32_bf16 v[16:19], v[128:131], v[180:183], v[16:19]
	v_mfma_f32_16x16x32_bf16 v[8:11], v[136:139], v[180:183], v[8:11]
	v_mfma_f32_16x16x32_bf16 v[60:63], v[132:135], v[148:151], v[60:63]
	v_mfma_f32_16x16x32_bf16 v[56:59], v[140:143], v[148:151], v[56:59]
	v_mfma_f32_16x16x32_bf16 v[48:51], v[132:135], v[156:159], v[48:51]
	v_mfma_f32_16x16x32_bf16 v[40:43], v[140:143], v[156:159], v[40:43]
	v_mfma_f32_16x16x32_bf16 v[28:31], v[132:135], v[176:179], v[28:31]
	v_mfma_f32_16x16x32_bf16 v[24:27], v[140:143], v[176:179], v[24:27]
	v_mfma_f32_16x16x32_bf16 v[16:19], v[132:135], v[190:193], v[16:19]
	v_mfma_f32_16x16x32_bf16 v[8:11], v[140:143], v[190:193], v[8:11]
	s_barrier
	s_add_u32 s38, s38, 0xc000
	s_addc_u32 s39, s39, 0
	s_add_i32 s40, s64, s48
	v_lshl_add_u64 v[128:129], s[38:39], 0, v[160:161]
	s_mov_b32 m0, s40
	s_nop 0
	global_load_lds_dwordx4 v[128:129], off
	v_lshl_add_u64 v[128:129], s[38:39], 0, v[162:163]
	s_add_i32 m0, s40, 0x2000
	s_nop 0
	global_load_lds_dwordx4 v[128:129], off
	s_waitcnt vmcnt(6)
	s_barrier
	v_mfma_f32_16x16x32_bf16 v[52:55], v[194:197], v[144:147], v[52:55]
	v_mfma_f32_16x16x32_bf16 v[44:47], v[206:209], v[144:147], v[44:47]
	v_mfma_f32_16x16x32_bf16 v[36:39], v[194:197], v[152:155], v[36:39]
	v_mfma_f32_16x16x32_bf16 v[32:35], v[206:209], v[152:155], v[32:35]
	v_mfma_f32_16x16x32_bf16 v[20:23], v[194:197], v[172:175], v[20:23]
	v_mfma_f32_16x16x32_bf16 v[12:15], v[206:209], v[172:175], v[12:15]
	v_mfma_f32_16x16x32_bf16 v[4:7], v[194:197], v[180:183], v[4:7]
	v_mfma_f32_16x16x32_bf16 v[0:3], v[206:209], v[180:183], v[0:3]
	v_mfma_f32_16x16x32_bf16 v[52:55], v[198:201], v[148:151], v[52:55]
	v_mfma_f32_16x16x32_bf16 v[44:47], v[210:213], v[148:151], v[44:47]
	v_mfma_f32_16x16x32_bf16 v[36:39], v[198:201], v[156:159], v[36:39]
	v_mfma_f32_16x16x32_bf16 v[32:35], v[210:213], v[156:159], v[32:35]
	v_mfma_f32_16x16x32_bf16 v[20:23], v[198:201], v[176:179], v[20:23]
	v_mfma_f32_16x16x32_bf16 v[12:15], v[210:213], v[176:179], v[12:15]
	v_mfma_f32_16x16x32_bf16 v[4:7], v[198:201], v[190:193], v[4:7]
	v_mfma_f32_16x16x32_bf16 v[0:3], v[210:213], v[190:193], v[0:3]
	s_add_i32 s62, s62, 2
	s_add_u32 s36, s36, 0x10000
	s_addc_u32 s37, s37, 0
	s_add_u32 s60, s60, 0x10000
	s_addc_u32 s61, s61, 0
	s_cmpk_gt_u32 s62, 0x53
	s_barrier
	s_cbranch_scc0 .LBB0_1640
	v_lshl_or_b32 v128, s59, 8, v186
	v_ashrrev_i32_e32 v129, 31, v128
	v_lshl_add_u32 v180, s33, 8, v184
	v_lshlrev_b64 v[172:173], 2, v[128:129]
	v_ashrrev_i32_e32 v181, 31, v180
	v_lshl_add_u64 v[174:175], s[12:13], 0, v[172:173]
	v_lshlrev_b64 v[176:177], 13, v[180:181]
	v_lshl_add_u64 v[128:129], v[174:175], 0, v[176:177]
	v_lshl_add_u64 v[178:179], v[180:181], 3, s[14:15]
	v_or_b32_e32 v130, 16, v180
	global_load_dwordx2 v[202:203], v[178:179], off
	global_load_dwordx4 v[190:193], v[128:129], off
	global_load_dwordx4 v[194:197], v[128:129], off offset:64
	global_load_dwordx4 v[198:201], v[128:129], off offset:512
	v_ashrrev_i32_e32 v131, 31, v130
	global_load_dwordx4 v[206:209], v[128:129], off offset:576
	v_lshlrev_b64 v[218:219], 13, v[130:131]
	v_lshl_add_u64 v[128:129], v[130:131], 3, s[14:15]
	v_lshl_add_u64 v[222:223], v[174:175], 0, v[218:219]
	global_load_dwordx2 v[182:183], v[128:129], off
	global_load_dwordx4 v[210:213], v[222:223], off
	v_lshl_add_u64 v[128:129], s[16:17], 0, v[172:173]
	v_lshl_add_u64 v[132:133], s[18:19], 0, v[172:173]
	global_load_dwordx4 v[152:155], v[132:133], off
	global_load_dwordx4 v[156:159], v[128:129], off
	global_load_dwordx4 v[144:147], v[128:129], off offset:64
	global_load_dwordx4 v[148:151], v[132:133], off offset:64
	global_load_dwordx4 v[136:139], v[132:133], off offset:512
	global_load_dwordx4 v[140:143], v[128:129], off offset:512
	s_nop 0
	global_load_dwordx4 v[128:131], v[128:129], off offset:576
	s_nop 0
	global_load_dwordx4 v[132:135], v[132:133], off offset:576
	s_nop 0
	global_load_dwordx4 v[214:217], v[222:223], off offset:64
	v_lshl_add_u64 v[220:221], s[12:13], 0, v[176:177]
	v_lshl_add_u64 v[226:227], v[220:221], 0, v[172:173]
	v_lshl_add_u64 v[228:229], s[12:13], 0, v[218:219]
	global_load_dwordx4 v[218:221], v[222:223], off offset:512
	s_nop 0
	global_load_dwordx4 v[222:225], v[222:223], off offset:576
	v_lshl_add_u64 v[228:229], v[228:229], 0, v[172:173]
	s_and_b64 vcc, exec, s[6:7]
	s_mov_b32 s59, s57
	s_mov_b32 s33, s58
	s_mov_b64 s[38:39], s[10:11]
	s_mov_b64 s[36:37], s[8:9]
	s_waitcnt vmcnt(0)
;     __device__ __forceinline__ void operator()(const f32x4 (&acc)[2][2][4][2], const Unit& u, int wr, int wc, int fr, int fq) const {
;     ...
; #pragma unroll
;                 for (int mm = 0; mm < 2; ++mm) {
;                     const int m = mh * 2 + mm, r = row0 + ai * HALF + m * 16;
;                     float* zp = Z + (size_t)r * DM + col0;
; #pragma unroll
;                     for (int bj = 0; bj < 2; ++bj)
; #pragma unroll
;                         for (int n = 0; n < 2; ++n) {
;                             f32x4 res = rv[mm][bj][n];
;                             if (MODE == 1) res = (res - st[mm].x) * st[mm].y * gv[bj][n] + bv[bj][n];
;                             *(f32x4*)(zp + bj * HALF + n * 16) = res * ALPHA + acc[ai][bj][m][n] * scale;
;                         }
;                 }
	v_sub_f32_e32 v193, v193, v202
	v_sub_f32_e32 v192, v192, v202
	v_sub_f32_e32 v191, v191, v202
	v_sub_f32_e32 v190, v190, v202
	v_sub_f32_e32 v207, v207, v202
	v_sub_f32_e32 v206, v206, v202
	v_sub_f32_e32 v197, v197, v202
	v_sub_f32_e32 v196, v196, v202
	v_sub_f32_e32 v195, v195, v202
	v_sub_f32_e32 v194, v194, v202
	v_sub_f32_e32 v201, v201, v202
	v_sub_f32_e32 v200, v200, v202
	v_sub_f32_e32 v199, v199, v202
	v_sub_f32_e32 v198, v198, v202
	v_sub_f32_e32 v209, v209, v202
	v_sub_f32_e32 v208, v208, v202
	v_pk_mul_f32 v[190:191], v[202:203], v[190:191] op_sel:[1,0]
	v_pk_mul_f32 v[192:193], v[202:203], v[192:193] op_sel:[1,0]
	v_pk_mul_f32 v[206:207], v[202:203], v[206:207] op_sel:[1,0]
	v_pk_mul_f32 v[194:195], v[202:203], v[194:195] op_sel:[1,0]
	v_pk_mul_f32 v[196:197], v[202:203], v[196:197] op_sel:[1,0]
	v_pk_mul_f32 v[198:199], v[202:203], v[198:199] op_sel:[1,0]
	v_pk_mul_f32 v[200:201], v[202:203], v[200:201] op_sel:[1,0]
	v_pk_mul_f32 v[202:203], v[202:203], v[208:209] op_sel:[1,0]
	v_pk_fma_f32 v[192:193], v[158:159], v[192:193], v[154:155]
	v_pk_fma_f32 v[190:191], v[156:157], v[190:191], v[152:153]
	v_pk_fma_f32 v[206:207], v[128:129], v[206:207], v[132:133]
	v_pk_fma_f32 v[196:197], v[146:147], v[196:197], v[150:151]
	v_pk_fma_f32 v[194:195], v[144:145], v[194:195], v[148:149]
	v_pk_fma_f32 v[200:201], v[142:143], v[200:201], v[138:139]
	v_pk_fma_f32 v[198:199], v[140:141], v[198:199], v[136:137]
	v_pk_fma_f32 v[202:203], v[130:131], v[202:203], v[134:135]
	v_pk_mul_f32 v[190:191], v[190:191], s[24:25] op_sel_hi:[1,0]
	v_pk_mul_f32 v[192:193], v[192:193], s[24:25] op_sel_hi:[1,0]
	v_pk_mul_f32 v[206:207], v[206:207], s[24:25] op_sel_hi:[1,0]
	v_pk_mul_f32 v[194:195], v[194:195], s[24:25] op_sel_hi:[1,0]
	v_pk_mul_f32 v[196:197], v[196:197], s[24:25] op_sel_hi:[1,0]
	v_pk_mul_f32 v[198:199], v[198:199], s[24:25] op_sel_hi:[1,0]
	v_pk_mul_f32 v[200:201], v[200:201], s[24:25] op_sel_hi:[1,0]
	v_pk_mul_f32 v[202:203], v[202:203], s[24:25] op_sel_hi:[1,0]
	v_pk_fma_f32 v[126:127], v[126:127], 0.5, v[192:193] op_sel_hi:[1,0,1]
	v_pk_fma_f32 v[124:125], v[124:125], 0.5, v[190:191] op_sel_hi:[1,0,1]
	v_pk_fma_f32 v[108:109], v[108:109], 0.5, v[206:207] op_sel_hi:[1,0,1]
	v_sub_f32_e32 v213, v213, v182
	v_pk_fma_f32 v[122:123], v[122:123], 0.5, v[196:197] op_sel_hi:[1,0,1]
	v_pk_fma_f32 v[120:121], v[120:121], 0.5, v[194:195] op_sel_hi:[1,0,1]
	v_pk_fma_f32 v[118:119], v[118:119], 0.5, v[200:201] op_sel_hi:[1,0,1]
	v_pk_fma_f32 v[116:117], v[116:117], 0.5, v[198:199] op_sel_hi:[1,0,1]
	v_pk_fma_f32 v[110:111], v[110:111], 0.5, v[202:203] op_sel_hi:[1,0,1]
	global_store_dwordx4 v[226:227], v[124:127], off
	global_store_dwordx4 v[226:227], v[120:123], off offset:64
	global_store_dwordx4 v[226:227], v[116:119], off offset:512
	global_store_dwordx4 v[226:227], v[108:111], off offset:576
	v_sub_f32_e32 v212, v212, v182
	s_nop 0
	v_sub_f32_e32 v109, v211, v182
	v_sub_f32_e32 v108, v210, v182
	v_pk_mul_f32 v[108:109], v[182:183], v[108:109] op_sel:[1,0]
	v_pk_mul_f32 v[110:111], v[182:183], v[212:213] op_sel:[1,0]
	v_pk_fma_f32 v[108:109], v[156:157], v[108:109], v[152:153]
	v_pk_fma_f32 v[110:111], v[158:159], v[110:111], v[154:155]
	v_pk_mul_f32 v[108:109], v[108:109], s[24:25] op_sel_hi:[1,0]
	v_pk_mul_f32 v[110:111], v[110:111], s[24:25] op_sel_hi:[1,0]
	v_pk_fma_f32 v[108:109], v[112:113], 0.5, v[108:109] op_sel_hi:[1,0,1]
	v_pk_fma_f32 v[110:111], v[114:115], 0.5, v[110:111] op_sel_hi:[1,0,1]
	global_store_dwordx4 v[228:229], v[108:111], off
	v_or_b32_e32 v112, 48, v180
	v_ashrrev_i32_e32 v113, 31, v112
	v_sub_f32_e32 v109, v217, v182
	v_sub_f32_e32 v108, v216, v182
	v_sub_f32_e32 v111, v215, v182
	v_sub_f32_e32 v110, v214, v182
	v_pk_mul_f32 v[110:111], v[182:183], v[110:111] op_sel:[1,0]
	v_pk_mul_f32 v[108:109], v[182:183], v[108:109] op_sel:[1,0]
	v_pk_fma_f32 v[110:111], v[144:145], v[110:111], v[148:149]
	v_pk_fma_f32 v[108:109], v[146:147], v[108:109], v[150:151]
	v_pk_mul_f32 v[110:111], v[110:111], s[24:25] op_sel_hi:[1,0]
	v_pk_mul_f32 v[108:109], v[108:109], s[24:25] op_sel_hi:[1,0]
	v_pk_fma_f32 v[104:105], v[104:105], 0.5, v[110:111] op_sel_hi:[1,0,1]
	v_pk_fma_f32 v[106:107], v[106:107], 0.5, v[108:109] op_sel_hi:[1,0,1]
	global_store_dwordx4 v[228:229], v[104:107], off offset:64
	s_nop 1
	v_sub_f32_e32 v105, v221, v182
	v_sub_f32_e32 v104, v220, v182
	v_sub_f32_e32 v107, v219, v182
	v_sub_f32_e32 v106, v218, v182
	v_pk_mul_f32 v[106:107], v[182:183], v[106:107] op_sel:[1,0]
	v_pk_mul_f32 v[104:105], v[182:183], v[104:105] op_sel:[1,0]
	v_pk_fma_f32 v[106:107], v[140:141], v[106:107], v[136:137]
	v_pk_fma_f32 v[104:105], v[142:143], v[104:105], v[138:139]
	v_pk_mul_f32 v[106:107], v[106:107], s[24:25] op_sel_hi:[1,0]
	v_pk_mul_f32 v[104:105], v[104:105], s[24:25] op_sel_hi:[1,0]
	v_pk_fma_f32 v[100:101], v[100:101], 0.5, v[106:107] op_sel_hi:[1,0,1]
	v_pk_fma_f32 v[102:103], v[102:103], 0.5, v[104:105] op_sel_hi:[1,0,1]
	global_store_dwordx4 v[228:229], v[100:103], off offset:512
	s_nop 1
	v_sub_f32_e32 v101, v225, v182
	v_sub_f32_e32 v100, v224, v182
	v_sub_f32_e32 v103, v223, v182
	v_sub_f32_e32 v102, v222, v182
	v_pk_mul_f32 v[102:103], v[182:183], v[102:103] op_sel:[1,0]
	v_pk_mul_f32 v[100:101], v[182:183], v[100:101] op_sel:[1,0]
	v_pk_fma_f32 v[102:103], v[128:129], v[102:103], v[132:133]
	v_pk_fma_f32 v[100:101], v[130:131], v[100:101], v[134:135]
	v_pk_mul_f32 v[102:103], v[102:103], s[24:25] op_sel_hi:[1,0]
	v_pk_mul_f32 v[100:101], v[100:101], s[24:25] op_sel_hi:[1,0]
	v_pk_fma_f32 v[96:97], v[96:97], 0.5, v[102:103] op_sel_hi:[1,0,1]
	v_pk_fma_f32 v[98:99], v[98:99], 0.5, v[100:101] op_sel_hi:[1,0,1]
	global_store_dwordx4 v[228:229], v[96:99], off offset:576
	s_nop 1
	v_or_b32_e32 v96, 32, v180
	v_ashrrev_i32_e32 v97, 31, v96
	v_lshlrev_b64 v[120:121], 13, v[96:97]
	v_lshl_add_u64 v[108:109], v[174:175], 0, v[120:121]
	v_lshl_add_u64 v[96:97], v[96:97], 3, s[14:15]
	global_load_dwordx2 v[182:183], v[96:97], off
	s_nop 0
	global_load_dwordx4 v[96:99], v[108:109], off
	global_load_dwordx4 v[100:103], v[108:109], off offset:64
	global_load_dwordx4 v[104:107], v[108:109], off offset:512
	s_nop 0
	global_load_dwordx4 v[108:111], v[108:109], off offset:576
	v_lshlrev_b64 v[180:181], 13, v[112:113]
	v_lshl_add_u64 v[112:113], v[112:113], 3, s[14:15]
	v_lshl_add_u64 v[124:125], v[174:175], 0, v[180:181]
	global_load_dwordx2 v[190:191], v[112:113], off
	s_nop 0
	global_load_dwordx4 v[112:115], v[124:125], off
	global_load_dwordx4 v[116:119], v[124:125], off offset:64
	v_lshl_add_u64 v[192:193], s[12:13], 0, v[120:121]
	global_load_dwordx4 v[120:123], v[124:125], off offset:512
	s_nop 0
	global_load_dwordx4 v[124:127], v[124:125], off offset:576
	v_lshl_add_u64 v[192:193], v[192:193], 0, v[172:173]
	s_waitcnt vmcnt(0)
;     __device__ __forceinline__ void operator()(const f32x4 (&acc)[2][2][4][2], const Unit& u, int wr, int wc, int fr, int fq) const {
;     ...
;                 for (int mm = 0; mm < 2; ++mm) {
;                     const int r = row0 + ai * HALF + (mh * 2 + mm) * 16;
;                     const float* rp = MODE == 0 ? ((r < 8192 ? x0 + (size_t)r * DM : x1 + (size_t)(r - 8192) * DM) + col0) : (Z + (size_t)r * DM + col0);
;                     if (MODE == 1) st[mm] = stats[r];
; #pragma unroll
;                     for (int bj = 0; bj < 2; ++bj)
; #pragma unroll
;                         for (int n = 0; n < 2; ++n) rv[mm][bj][n] = *(const f32x4*)(rp + bj * HALF + n * 16);
;     ...
; #pragma unroll
;                 for (int mm = 0; mm < 2; ++mm) {
;                     const int m = mh * 2 + mm, r = row0 + ai * HALF + m * 16;
;                     float* zp = Z + (size_t)r * DM + col0;
; #pragma unroll
;                     for (int bj = 0; bj < 2; ++bj)
; #pragma unroll
;                         for (int n = 0; n < 2; ++n) {
;                             f32x4 res = rv[mm][bj][n];
;                             if (MODE == 1) res = (res - st[mm].x) * st[mm].y * gv[bj][n] + bv[bj][n];
;                             *(f32x4*)(zp + bj * HALF + n * 16) = res * ALPHA + acc[ai][bj][m][n] * scale;
;                         }
;                 }
	v_sub_f32_e32 v99, v99, v182
	v_sub_f32_e32 v98, v98, v182
	v_sub_f32_e32 v97, v97, v182
	v_sub_f32_e32 v96, v96, v182
	v_pk_mul_f32 v[96:97], v[182:183], v[96:97] op_sel:[1,0]
	v_pk_mul_f32 v[98:99], v[182:183], v[98:99] op_sel:[1,0]
	v_pk_fma_f32 v[96:97], v[156:157], v[96:97], v[152:153]
	v_pk_fma_f32 v[98:99], v[158:159], v[98:99], v[154:155]
	v_pk_mul_f32 v[96:97], v[96:97], s[24:25] op_sel_hi:[1,0]
	v_pk_mul_f32 v[98:99], v[98:99], s[24:25] op_sel_hi:[1,0]
	v_pk_fma_f32 v[92:93], v[92:93], 0.5, v[96:97] op_sel_hi:[1,0,1]
	v_pk_fma_f32 v[94:95], v[94:95], 0.5, v[98:99] op_sel_hi:[1,0,1]
	global_store_dwordx4 v[192:193], v[92:95], off
	v_lshl_add_u64 v[96:97], v[176:177], 0, s[26:27]
	s_nop 0
	v_sub_f32_e32 v93, v103, v182
	v_sub_f32_e32 v92, v102, v182
	v_sub_f32_e32 v95, v101, v182
	v_sub_f32_e32 v94, v100, v182
	v_pk_mul_f32 v[94:95], v[182:183], v[94:95] op_sel:[1,0]
	v_pk_mul_f32 v[92:93], v[182:183], v[92:93] op_sel:[1,0]
	v_pk_fma_f32 v[94:95], v[144:145], v[94:95], v[148:149]
	v_pk_fma_f32 v[92:93], v[146:147], v[92:93], v[150:151]
	v_pk_mul_f32 v[94:95], v[94:95], s[24:25] op_sel_hi:[1,0]
	v_pk_mul_f32 v[92:93], v[92:93], s[24:25] op_sel_hi:[1,0]
	v_pk_fma_f32 v[88:89], v[88:89], 0.5, v[94:95] op_sel_hi:[1,0,1]
	v_pk_fma_f32 v[90:91], v[90:91], 0.5, v[92:93] op_sel_hi:[1,0,1]
	global_store_dwordx4 v[192:193], v[88:91], off offset:64
	v_lshl_add_u64 v[100:101], v[176:177], 0, s[28:29]
	v_lshl_add_u64 v[92:93], v[174:175], 0, v[100:101]
	v_sub_f32_e32 v89, v107, v182
	v_sub_f32_e32 v88, v106, v182
	v_sub_f32_e32 v91, v105, v182
	v_sub_f32_e32 v90, v104, v182
	v_pk_mul_f32 v[90:91], v[182:183], v[90:91] op_sel:[1,0]
	v_pk_mul_f32 v[88:89], v[182:183], v[88:89] op_sel:[1,0]
	v_pk_fma_f32 v[90:91], v[140:141], v[90:91], v[136:137]
	v_pk_fma_f32 v[88:89], v[142:143], v[88:89], v[138:139]
	v_pk_mul_f32 v[90:91], v[90:91], s[24:25] op_sel_hi:[1,0]
	v_pk_mul_f32 v[88:89], v[88:89], s[24:25] op_sel_hi:[1,0]
	v_pk_fma_f32 v[84:85], v[84:85], 0.5, v[90:91] op_sel_hi:[1,0,1]
	v_pk_fma_f32 v[86:87], v[86:87], 0.5, v[88:89] op_sel_hi:[1,0,1]
	global_store_dwordx4 v[192:193], v[84:87], off offset:512
	s_nop 1
	v_sub_f32_e32 v85, v111, v182
	v_sub_f32_e32 v84, v110, v182
	v_sub_f32_e32 v87, v109, v182
	v_sub_f32_e32 v86, v108, v182
	v_pk_mul_f32 v[86:87], v[182:183], v[86:87] op_sel:[1,0]
	v_pk_mul_f32 v[84:85], v[182:183], v[84:85] op_sel:[1,0]
	v_pk_fma_f32 v[86:87], v[128:129], v[86:87], v[132:133]
	v_pk_fma_f32 v[84:85], v[130:131], v[84:85], v[134:135]
	v_pk_mul_f32 v[86:87], v[86:87], s[24:25] op_sel_hi:[1,0]
	v_pk_mul_f32 v[84:85], v[84:85], s[24:25] op_sel_hi:[1,0]
	v_pk_fma_f32 v[80:81], v[80:81], 0.5, v[86:87] op_sel_hi:[1,0,1]
	v_pk_fma_f32 v[82:83], v[82:83], 0.5, v[84:85] op_sel_hi:[1,0,1]
	global_store_dwordx4 v[192:193], v[80:83], off offset:576
	v_sub_f32_e32 v85, v113, v190
	v_sub_f32_e32 v84, v112, v190
	v_sub_f32_e32 v83, v115, v190
	v_sub_f32_e32 v82, v114, v190
	v_pk_mul_f32 v[84:85], v[190:191], v[84:85] op_sel:[1,0]
	v_pk_mul_f32 v[82:83], v[190:191], v[82:83] op_sel:[1,0]
	v_pk_fma_f32 v[84:85], v[156:157], v[84:85], v[152:153]
	v_pk_fma_f32 v[82:83], v[158:159], v[82:83], v[154:155]
	v_lshl_add_u64 v[80:81], s[12:13], 0, v[180:181]
	v_pk_mul_f32 v[84:85], v[84:85], s[24:25] op_sel_hi:[1,0]
	v_pk_mul_f32 v[82:83], v[82:83], s[24:25] op_sel_hi:[1,0]
	v_lshl_add_u64 v[80:81], v[80:81], 0, v[172:173]
	v_pk_fma_f32 v[78:79], v[78:79], 0.5, v[82:83] op_sel_hi:[1,0,1]
	v_pk_fma_f32 v[76:77], v[76:77], 0.5, v[84:85] op_sel_hi:[1,0,1]
	global_store_dwordx4 v[80:81], v[76:79], off
	s_nop 1
	v_sub_f32_e32 v77, v119, v190
	v_sub_f32_e32 v76, v118, v190
	v_sub_f32_e32 v79, v117, v190
	v_sub_f32_e32 v78, v116, v190
	v_pk_mul_f32 v[78:79], v[190:191], v[78:79] op_sel:[1,0]
	v_pk_mul_f32 v[76:77], v[190:191], v[76:77] op_sel:[1,0]
	v_pk_fma_f32 v[78:79], v[144:145], v[78:79], v[148:149]
	v_pk_fma_f32 v[76:77], v[146:147], v[76:77], v[150:151]
	v_pk_mul_f32 v[78:79], v[78:79], s[24:25] op_sel_hi:[1,0]
	v_pk_mul_f32 v[76:77], v[76:77], s[24:25] op_sel_hi:[1,0]
	v_pk_fma_f32 v[72:73], v[72:73], 0.5, v[78:79] op_sel_hi:[1,0,1]
	v_pk_fma_f32 v[74:75], v[74:75], 0.5, v[76:77] op_sel_hi:[1,0,1]
	global_store_dwordx4 v[80:81], v[72:75], off offset:64
	v_lshl_add_u64 v[76:77], v[174:175], 0, v[96:97]
	v_lshl_add_u64 v[96:97], s[12:13], 0, v[96:97]
	v_sub_f32_e32 v73, v123, v190
	v_sub_f32_e32 v72, v122, v190
	v_sub_f32_e32 v75, v121, v190
	v_sub_f32_e32 v74, v120, v190
	v_pk_mul_f32 v[74:75], v[190:191], v[74:75] op_sel:[1,0]
	v_pk_mul_f32 v[72:73], v[190:191], v[72:73] op_sel:[1,0]
	v_pk_fma_f32 v[74:75], v[140:141], v[74:75], v[136:137]
	v_pk_fma_f32 v[72:73], v[142:143], v[72:73], v[138:139]
	v_pk_mul_f32 v[74:75], v[74:75], s[24:25] op_sel_hi:[1,0]
	v_pk_mul_f32 v[72:73], v[72:73], s[24:25] op_sel_hi:[1,0]
	v_pk_fma_f32 v[68:69], v[68:69], 0.5, v[74:75] op_sel_hi:[1,0,1]
	v_pk_fma_f32 v[70:71], v[70:71], 0.5, v[72:73] op_sel_hi:[1,0,1]
	global_store_dwordx4 v[80:81], v[68:71], off offset:512
	v_lshl_add_u64 v[96:97], v[96:97], 0, v[172:173]
	s_nop 0
	v_sub_f32_e32 v69, v127, v190
	v_sub_f32_e32 v68, v126, v190
	v_sub_f32_e32 v71, v125, v190
	v_sub_f32_e32 v70, v124, v190
	v_pk_mul_f32 v[70:71], v[190:191], v[70:71] op_sel:[1,0]
	v_pk_mul_f32 v[68:69], v[190:191], v[68:69] op_sel:[1,0]
	v_pk_fma_f32 v[70:71], v[128:129], v[70:71], v[132:133]
	v_pk_fma_f32 v[68:69], v[130:131], v[68:69], v[134:135]
	v_pk_mul_f32 v[70:71], v[70:71], s[24:25] op_sel_hi:[1,0]
	v_pk_mul_f32 v[68:69], v[68:69], s[24:25] op_sel_hi:[1,0]
	v_pk_fma_f32 v[64:65], v[64:65], 0.5, v[70:71] op_sel_hi:[1,0,1]
	v_pk_fma_f32 v[66:67], v[66:67], 0.5, v[68:69] op_sel_hi:[1,0,1]
	global_store_dwordx4 v[80:81], v[64:67], off offset:576
	global_load_dwordx2 v[98:99], v[178:179], off offset:1024
	s_nop 0
	global_load_dwordx4 v[64:67], v[76:77], off
	global_load_dwordx4 v[68:71], v[76:77], off offset:64
	global_load_dwordx4 v[72:75], v[76:77], off offset:512
	s_nop 0
	global_load_dwordx4 v[76:79], v[76:77], off offset:576
	s_nop 0
	global_load_dwordx2 v[102:103], v[178:179], off offset:1152
	global_load_dwordx4 v[80:83], v[92:93], off
	global_load_dwordx4 v[84:87], v[92:93], off offset:64
	global_load_dwordx4 v[88:91], v[92:93], off offset:512
	s_nop 0
	global_load_dwordx4 v[92:95], v[92:93], off offset:576
	s_waitcnt vmcnt(0)
;     __device__ __forceinline__ void operator()(const f32x4 (&acc)[2][2][4][2], const Unit& u, int wr, int wc, int fr, int fq) const {
;     ...
;                 for (int mm = 0; mm < 2; ++mm) {
;                     const int r = row0 + ai * HALF + (mh * 2 + mm) * 16;
;                     const float* rp = MODE == 0 ? ((r < 8192 ? x0 + (size_t)r * DM : x1 + (size_t)(r - 8192) * DM) + col0) : (Z + (size_t)r * DM + col0);
;                     if (MODE == 1) st[mm] = stats[r];
; #pragma unroll
;                     for (int bj = 0; bj < 2; ++bj)
; #pragma unroll
;                         for (int n = 0; n < 2; ++n) rv[mm][bj][n] = *(const f32x4*)(rp + bj * HALF + n * 16);
;     ...
; #pragma unroll
;                 for (int mm = 0; mm < 2; ++mm) {
;                     const int m = mh * 2 + mm, r = row0 + ai * HALF + m * 16;
;                     float* zp = Z + (size_t)r * DM + col0;
; #pragma unroll
;                     for (int bj = 0; bj < 2; ++bj)
; #pragma unroll
;                         for (int n = 0; n < 2; ++n) {
;                             f32x4 res = rv[mm][bj][n];
;                             if (MODE == 1) res = (res - st[mm].x) * st[mm].y * gv[bj][n] + bv[bj][n];
;                             *(f32x4*)(zp + bj * HALF + n * 16) = res * ALPHA + acc[ai][bj][m][n] * scale;
;                         }
;                 }
	v_sub_f32_e32 v67, v67, v98
	v_sub_f32_e32 v66, v66, v98
	v_sub_f32_e32 v65, v65, v98
	v_sub_f32_e32 v64, v64, v98
	v_pk_mul_f32 v[64:65], v[98:99], v[64:65] op_sel:[1,0]
	v_pk_mul_f32 v[66:67], v[98:99], v[66:67] op_sel:[1,0]
	v_pk_fma_f32 v[64:65], v[156:157], v[64:65], v[152:153]
	v_pk_fma_f32 v[66:67], v[158:159], v[66:67], v[154:155]
	v_pk_mul_f32 v[64:65], v[64:65], s[24:25] op_sel_hi:[1,0]
	v_pk_mul_f32 v[66:67], v[66:67], s[24:25] op_sel_hi:[1,0]
	v_pk_fma_f32 v[60:61], v[60:61], 0.5, v[64:65] op_sel_hi:[1,0,1]
	v_pk_fma_f32 v[62:63], v[62:63], 0.5, v[66:67] op_sel_hi:[1,0,1]
	global_store_dwordx4 v[96:97], v[60:63], off
	v_lshl_add_u64 v[64:65], v[176:177], 0, s[30:31]
	s_nop 0
	v_sub_f32_e32 v61, v71, v98
	v_sub_f32_e32 v60, v70, v98
	v_sub_f32_e32 v63, v69, v98
	v_sub_f32_e32 v62, v68, v98
	v_pk_mul_f32 v[62:63], v[98:99], v[62:63] op_sel:[1,0]
	v_pk_mul_f32 v[60:61], v[98:99], v[60:61] op_sel:[1,0]
	v_pk_fma_f32 v[62:63], v[144:145], v[62:63], v[148:149]
	v_pk_fma_f32 v[60:61], v[146:147], v[60:61], v[150:151]
	v_pk_mul_f32 v[62:63], v[62:63], s[24:25] op_sel_hi:[1,0]
	v_pk_mul_f32 v[60:61], v[60:61], s[24:25] op_sel_hi:[1,0]
	v_pk_fma_f32 v[56:57], v[56:57], 0.5, v[62:63] op_sel_hi:[1,0,1]
	v_pk_fma_f32 v[58:59], v[58:59], 0.5, v[60:61] op_sel_hi:[1,0,1]
	global_store_dwordx4 v[96:97], v[56:59], off offset:64
	v_lshl_add_u64 v[68:69], v[176:177], 0, s[34:35]
	v_lshl_add_u64 v[60:61], v[174:175], 0, v[68:69]
	v_sub_f32_e32 v57, v75, v98
	v_sub_f32_e32 v56, v74, v98
	v_sub_f32_e32 v59, v73, v98
	v_sub_f32_e32 v58, v72, v98
	v_pk_mul_f32 v[58:59], v[98:99], v[58:59] op_sel:[1,0]
	v_pk_mul_f32 v[56:57], v[98:99], v[56:57] op_sel:[1,0]
	v_pk_fma_f32 v[58:59], v[140:141], v[58:59], v[136:137]
	v_pk_fma_f32 v[56:57], v[142:143], v[56:57], v[138:139]
	v_pk_mul_f32 v[58:59], v[58:59], s[24:25] op_sel_hi:[1,0]
	v_pk_mul_f32 v[56:57], v[56:57], s[24:25] op_sel_hi:[1,0]
	v_pk_fma_f32 v[52:53], v[52:53], 0.5, v[58:59] op_sel_hi:[1,0,1]
	v_pk_fma_f32 v[54:55], v[54:55], 0.5, v[56:57] op_sel_hi:[1,0,1]
	global_store_dwordx4 v[96:97], v[52:55], off offset:512
	s_nop 1
	v_sub_f32_e32 v53, v79, v98
	v_sub_f32_e32 v52, v78, v98
	v_sub_f32_e32 v55, v77, v98
	v_sub_f32_e32 v54, v76, v98
	v_pk_mul_f32 v[54:55], v[98:99], v[54:55] op_sel:[1,0]
	v_pk_mul_f32 v[52:53], v[98:99], v[52:53] op_sel:[1,0]
	v_pk_fma_f32 v[54:55], v[128:129], v[54:55], v[132:133]
	v_pk_fma_f32 v[52:53], v[130:131], v[52:53], v[134:135]
	v_pk_mul_f32 v[54:55], v[54:55], s[24:25] op_sel_hi:[1,0]
	v_pk_mul_f32 v[52:53], v[52:53], s[24:25] op_sel_hi:[1,0]
	v_pk_fma_f32 v[44:45], v[44:45], 0.5, v[54:55] op_sel_hi:[1,0,1]
	v_pk_fma_f32 v[46:47], v[46:47], 0.5, v[52:53] op_sel_hi:[1,0,1]
	global_store_dwordx4 v[96:97], v[44:47], off offset:576
	s_nop 1
	v_lshl_add_u64 v[44:45], s[12:13], 0, v[100:101]
	v_lshl_add_u64 v[52:53], v[44:45], 0, v[172:173]
	v_sub_f32_e32 v45, v83, v102
	v_sub_f32_e32 v44, v82, v102
	v_sub_f32_e32 v47, v81, v102
	v_sub_f32_e32 v46, v80, v102
	v_pk_mul_f32 v[46:47], v[102:103], v[46:47] op_sel:[1,0]
	v_pk_mul_f32 v[44:45], v[102:103], v[44:45] op_sel:[1,0]
	v_pk_fma_f32 v[46:47], v[156:157], v[46:47], v[152:153]
	v_pk_fma_f32 v[44:45], v[158:159], v[44:45], v[154:155]
	v_pk_mul_f32 v[54:55], v[46:47], s[24:25] op_sel_hi:[1,0]
	v_pk_mul_f32 v[44:45], v[44:45], s[24:25] op_sel_hi:[1,0]
	s_nop 0
	v_pk_fma_f32 v[46:47], v[50:51], 0.5, v[44:45] op_sel_hi:[1,0,1]
	v_pk_fma_f32 v[44:45], v[48:49], 0.5, v[54:55] op_sel_hi:[1,0,1]
	global_store_dwordx4 v[52:53], v[44:47], off
	s_nop 1
	v_sub_f32_e32 v45, v87, v102
	v_sub_f32_e32 v44, v86, v102
	v_sub_f32_e32 v47, v85, v102
	v_sub_f32_e32 v46, v84, v102
	v_pk_mul_f32 v[46:47], v[102:103], v[46:47] op_sel:[1,0]
	v_pk_mul_f32 v[44:45], v[102:103], v[44:45] op_sel:[1,0]
	v_pk_fma_f32 v[46:47], v[144:145], v[46:47], v[148:149]
	v_pk_fma_f32 v[44:45], v[146:147], v[44:45], v[150:151]
	v_pk_mul_f32 v[46:47], v[46:47], s[24:25] op_sel_hi:[1,0]
	v_pk_mul_f32 v[44:45], v[44:45], s[24:25] op_sel_hi:[1,0]
	v_pk_fma_f32 v[40:41], v[40:41], 0.5, v[46:47] op_sel_hi:[1,0,1]
	v_pk_fma_f32 v[42:43], v[42:43], 0.5, v[44:45] op_sel_hi:[1,0,1]
	global_store_dwordx4 v[52:53], v[40:43], off offset:64
	v_lshl_add_u64 v[44:45], v[174:175], 0, v[64:65]
	v_lshl_add_u64 v[64:65], s[12:13], 0, v[64:65]
	v_sub_f32_e32 v41, v91, v102
	v_sub_f32_e32 v40, v90, v102
	v_sub_f32_e32 v43, v89, v102
	v_sub_f32_e32 v42, v88, v102
	v_pk_mul_f32 v[42:43], v[102:103], v[42:43] op_sel:[1,0]
	v_pk_mul_f32 v[40:41], v[102:103], v[40:41] op_sel:[1,0]
	v_pk_fma_f32 v[42:43], v[140:141], v[42:43], v[136:137]
	v_pk_fma_f32 v[40:41], v[142:143], v[40:41], v[138:139]
	v_pk_mul_f32 v[42:43], v[42:43], s[24:25] op_sel_hi:[1,0]
	v_pk_mul_f32 v[40:41], v[40:41], s[24:25] op_sel_hi:[1,0]
	v_pk_fma_f32 v[36:37], v[36:37], 0.5, v[42:43] op_sel_hi:[1,0,1]
	v_pk_fma_f32 v[38:39], v[38:39], 0.5, v[40:41] op_sel_hi:[1,0,1]
	global_store_dwordx4 v[52:53], v[36:39], off offset:512
	v_lshl_add_u64 v[64:65], v[64:65], 0, v[172:173]
	s_nop 0
	v_sub_f32_e32 v37, v95, v102
	v_sub_f32_e32 v36, v94, v102
	v_sub_f32_e32 v39, v93, v102
	v_sub_f32_e32 v38, v92, v102
	v_pk_mul_f32 v[38:39], v[102:103], v[38:39] op_sel:[1,0]
	v_pk_mul_f32 v[36:37], v[102:103], v[36:37] op_sel:[1,0]
	v_pk_fma_f32 v[38:39], v[128:129], v[38:39], v[132:133]
	v_pk_fma_f32 v[36:37], v[130:131], v[36:37], v[134:135]
	v_pk_mul_f32 v[38:39], v[38:39], s[24:25] op_sel_hi:[1,0]
	v_pk_mul_f32 v[36:37], v[36:37], s[24:25] op_sel_hi:[1,0]
	v_pk_fma_f32 v[32:33], v[32:33], 0.5, v[38:39] op_sel_hi:[1,0,1]
	v_pk_fma_f32 v[34:35], v[34:35], 0.5, v[36:37] op_sel_hi:[1,0,1]
	global_store_dwordx4 v[52:53], v[32:35], off offset:576
	global_load_dwordx2 v[66:67], v[178:179], off offset:1280
	s_nop 0
	global_load_dwordx4 v[32:35], v[44:45], off
	global_load_dwordx4 v[36:39], v[44:45], off offset:64
	global_load_dwordx4 v[40:43], v[44:45], off offset:512
	s_nop 0
	global_load_dwordx4 v[44:47], v[44:45], off offset:576
	s_nop 0
	global_load_dwordx2 v[70:71], v[178:179], off offset:1408
	global_load_dwordx4 v[48:51], v[60:61], off
	global_load_dwordx4 v[52:55], v[60:61], off offset:64
	global_load_dwordx4 v[56:59], v[60:61], off offset:512
	s_nop 0
	global_load_dwordx4 v[60:63], v[60:61], off offset:576
	s_waitcnt vmcnt(0)
; #define PG8_WAIT_V(n) asm volatile("s_waitcnt vmcnt(" #n ")" ::: "memory")
; #define PG8_BAR __builtin_amdgcn_s_barrier()
; template <class Epi, class Sched>
; __device__ __forceinline__ void gemm_phase(LAS unsigned char* lds, const Gemm g, const Sched& S, const Epi& E) {
;     ...
;         if (!has_next) break;
; #pragma unroll
;         for (int a = 0; a < 2; ++a)
; #pragma unroll
;             for (int b = 0; b < 2; ++b)
; #pragma unroll
;                 for (int m = 0; m < 4; ++m)
; #pragma unroll
;                     for (int n = 0; n < 2; ++n) acc[a][b][m][n] = (f32x4){0.f, 0.f, 0.f, 0.f};
;         cur = nxt; cA = nA; cB = nB; ++ui;
;     }
;     PG8_WAIT_V(0);
;     if (wr == 0) PG8_BAR;
;     PG8_BAR;
;     __device__ __forceinline__ void operator()(const f32x4 (&acc)[2][2][4][2], const Unit& u, int wr, int wc, int fr, int fq) const {
;     ...
; #pragma unroll
;                 for (int mm = 0; mm < 2; ++mm) {
;                     const int m = mh * 2 + mm, r = row0 + ai * HALF + m * 16;
;                     float* zp = Z + (size_t)r * DM + col0;
; #pragma unroll
;                     for (int bj = 0; bj < 2; ++bj)
; #pragma unroll
;                         for (int n = 0; n < 2; ++n) {
;                             f32x4 res = rv[mm][bj][n];
;                             if (MODE == 1) res = (res - st[mm].x) * st[mm].y * gv[bj][n] + bv[bj][n];
;                             *(f32x4*)(zp + bj * HALF + n * 16) = res * ALPHA + acc[ai][bj][m][n] * scale;
;                         }
;                 }
	v_sub_f32_e32 v35, v35, v66
	v_sub_f32_e32 v34, v34, v66
	v_sub_f32_e32 v33, v33, v66
	v_sub_f32_e32 v32, v32, v66
	v_pk_mul_f32 v[32:33], v[66:67], v[32:33] op_sel:[1,0]
	v_pk_mul_f32 v[34:35], v[66:67], v[34:35] op_sel:[1,0]
	v_pk_fma_f32 v[32:33], v[156:157], v[32:33], v[152:153]
	v_pk_fma_f32 v[34:35], v[158:159], v[34:35], v[154:155]
	v_pk_mul_f32 v[32:33], v[32:33], s[24:25] op_sel_hi:[1,0]
	v_pk_mul_f32 v[34:35], v[34:35], s[24:25] op_sel_hi:[1,0]
	v_pk_fma_f32 v[28:29], v[28:29], 0.5, v[32:33] op_sel_hi:[1,0,1]
	v_pk_fma_f32 v[30:31], v[30:31], 0.5, v[34:35] op_sel_hi:[1,0,1]
	global_store_dwordx4 v[64:65], v[28:31], off
	s_nop 1
	v_sub_f32_e32 v29, v39, v66
	v_sub_f32_e32 v28, v38, v66
	v_sub_f32_e32 v31, v37, v66
	v_sub_f32_e32 v30, v36, v66
	v_pk_mul_f32 v[30:31], v[66:67], v[30:31] op_sel:[1,0]
	v_pk_mul_f32 v[28:29], v[66:67], v[28:29] op_sel:[1,0]
	v_pk_fma_f32 v[30:31], v[144:145], v[30:31], v[148:149]
	v_pk_fma_f32 v[28:29], v[146:147], v[28:29], v[150:151]
	v_pk_mul_f32 v[30:31], v[30:31], s[24:25] op_sel_hi:[1,0]
	v_pk_mul_f32 v[28:29], v[28:29], s[24:25] op_sel_hi:[1,0]
	v_pk_fma_f32 v[24:25], v[24:25], 0.5, v[30:31] op_sel_hi:[1,0,1]
	v_pk_fma_f32 v[26:27], v[26:27], 0.5, v[28:29] op_sel_hi:[1,0,1]
	global_store_dwordx4 v[64:65], v[24:27], off offset:64
	s_nop 1
	v_sub_f32_e32 v25, v43, v66
	v_sub_f32_e32 v24, v42, v66
	v_sub_f32_e32 v27, v41, v66
	v_sub_f32_e32 v26, v40, v66
	v_pk_mul_f32 v[26:27], v[66:67], v[26:27] op_sel:[1,0]
	v_pk_mul_f32 v[24:25], v[66:67], v[24:25] op_sel:[1,0]
	v_pk_fma_f32 v[26:27], v[140:141], v[26:27], v[136:137]
	v_pk_fma_f32 v[24:25], v[142:143], v[24:25], v[138:139]
	v_pk_mul_f32 v[26:27], v[26:27], s[24:25] op_sel_hi:[1,0]
	v_pk_mul_f32 v[24:25], v[24:25], s[24:25] op_sel_hi:[1,0]
	v_pk_fma_f32 v[20:21], v[20:21], 0.5, v[26:27] op_sel_hi:[1,0,1]
	v_pk_fma_f32 v[22:23], v[22:23], 0.5, v[24:25] op_sel_hi:[1,0,1]
	global_store_dwordx4 v[64:65], v[20:23], off offset:512
	s_nop 1
	v_sub_f32_e32 v21, v47, v66
	v_sub_f32_e32 v20, v46, v66
	v_sub_f32_e32 v23, v45, v66
	v_sub_f32_e32 v22, v44, v66
	v_pk_mul_f32 v[22:23], v[66:67], v[22:23] op_sel:[1,0]
	v_pk_mul_f32 v[20:21], v[66:67], v[20:21] op_sel:[1,0]
	v_pk_fma_f32 v[22:23], v[128:129], v[22:23], v[132:133]
	v_pk_fma_f32 v[20:21], v[130:131], v[20:21], v[134:135]
	v_pk_mul_f32 v[22:23], v[22:23], s[24:25] op_sel_hi:[1,0]
	v_pk_mul_f32 v[20:21], v[20:21], s[24:25] op_sel_hi:[1,0]
	v_pk_fma_f32 v[12:13], v[12:13], 0.5, v[22:23] op_sel_hi:[1,0,1]
	v_pk_fma_f32 v[14:15], v[14:15], 0.5, v[20:21] op_sel_hi:[1,0,1]
	global_store_dwordx4 v[64:65], v[12:15], off offset:576
	s_nop 1
	v_lshl_add_u64 v[12:13], s[12:13], 0, v[68:69]
	v_lshl_add_u64 v[20:21], v[12:13], 0, v[172:173]
	v_sub_f32_e32 v13, v51, v70
	v_sub_f32_e32 v12, v50, v70
	v_sub_f32_e32 v15, v49, v70
	v_sub_f32_e32 v14, v48, v70
	v_pk_mul_f32 v[14:15], v[70:71], v[14:15] op_sel:[1,0]
	v_pk_mul_f32 v[12:13], v[70:71], v[12:13] op_sel:[1,0]
	v_pk_fma_f32 v[14:15], v[156:157], v[14:15], v[152:153]
	v_pk_fma_f32 v[12:13], v[158:159], v[12:13], v[154:155]
	v_pk_mul_f32 v[22:23], v[14:15], s[24:25] op_sel_hi:[1,0]
	v_pk_mul_f32 v[12:13], v[12:13], s[24:25] op_sel_hi:[1,0]
	s_nop 0
	v_pk_fma_f32 v[14:15], v[18:19], 0.5, v[12:13] op_sel_hi:[1,0,1]
	v_pk_fma_f32 v[12:13], v[16:17], 0.5, v[22:23] op_sel_hi:[1,0,1]
	global_store_dwordx4 v[20:21], v[12:15], off
	s_nop 1
	v_sub_f32_e32 v13, v55, v70
	v_sub_f32_e32 v12, v54, v70
	v_sub_f32_e32 v15, v53, v70
	v_sub_f32_e32 v14, v52, v70
	v_pk_mul_f32 v[14:15], v[70:71], v[14:15] op_sel:[1,0]
	v_pk_mul_f32 v[12:13], v[70:71], v[12:13] op_sel:[1,0]
	v_pk_fma_f32 v[14:15], v[144:145], v[14:15], v[148:149]
	v_pk_fma_f32 v[12:13], v[146:147], v[12:13], v[150:151]
	v_pk_mul_f32 v[14:15], v[14:15], s[24:25] op_sel_hi:[1,0]
	v_pk_mul_f32 v[12:13], v[12:13], s[24:25] op_sel_hi:[1,0]
	v_pk_fma_f32 v[8:9], v[8:9], 0.5, v[14:15] op_sel_hi:[1,0,1]
	v_pk_fma_f32 v[10:11], v[10:11], 0.5, v[12:13] op_sel_hi:[1,0,1]
	global_store_dwordx4 v[20:21], v[8:11], off offset:64
	s_nop 1
	v_sub_f32_e32 v9, v59, v70
	v_sub_f32_e32 v8, v58, v70
	v_sub_f32_e32 v11, v57, v70
	v_sub_f32_e32 v10, v56, v70
	v_pk_mul_f32 v[10:11], v[70:71], v[10:11] op_sel:[1,0]
	v_pk_mul_f32 v[8:9], v[70:71], v[8:9] op_sel:[1,0]
	v_pk_fma_f32 v[10:11], v[140:141], v[10:11], v[136:137]
	v_pk_fma_f32 v[8:9], v[142:143], v[8:9], v[138:139]
	v_pk_mul_f32 v[10:11], v[10:11], s[24:25] op_sel_hi:[1,0]
	v_pk_mul_f32 v[8:9], v[8:9], s[24:25] op_sel_hi:[1,0]
	v_pk_fma_f32 v[4:5], v[4:5], 0.5, v[10:11] op_sel_hi:[1,0,1]
	v_pk_fma_f32 v[6:7], v[6:7], 0.5, v[8:9] op_sel_hi:[1,0,1]
	global_store_dwordx4 v[20:21], v[4:7], off offset:512
	s_nop 1
	v_sub_f32_e32 v5, v63, v70
	v_sub_f32_e32 v4, v62, v70
	v_sub_f32_e32 v7, v61, v70
	v_sub_f32_e32 v6, v60, v70
	v_pk_mul_f32 v[6:7], v[70:71], v[6:7] op_sel:[1,0]
	v_pk_mul_f32 v[4:5], v[70:71], v[4:5] op_sel:[1,0]
	v_pk_fma_f32 v[6:7], v[128:129], v[6:7], v[132:133]
	v_pk_fma_f32 v[4:5], v[130:131], v[4:5], v[134:135]
	v_pk_mul_f32 v[6:7], v[6:7], s[24:25] op_sel_hi:[1,0]
	v_pk_mul_f32 v[4:5], v[4:5], s[24:25] op_sel_hi:[1,0]
	v_pk_fma_f32 v[0:1], v[0:1], 0.5, v[6:7] op_sel_hi:[1,0,1]
	v_pk_fma_f32 v[2:3], v[2:3], 0.5, v[4:5] op_sel_hi:[1,0,1]
	global_store_dwordx4 v[20:21], v[0:3], off offset:576
	s_cbranch_vccz .LBB0_1629
	s_waitcnt vmcnt(0)
	s_cmpk_gt_u32 s25, 0xff
	s_cbranch_scc1 .LBB0_1644
	s_barrier
